# flat->global memory ops (LDS waits no longer cover global loads), pipelined EpiResid epilogues, prep S3 rewrite
# baseline (speedup 1.0000x reference)
.LBB0_43:
	s_or_b64 exec, exec, s[20:21]
	s_waitcnt lgkmcnt(0)
	s_barrier
	ds_read_b128 v[2:5], v172
	v_lshl_add_u64 v[6:7], v[82:83], 0, v[38:39]
	v_lshlrev_b64 v[6:7], 13, v[6:7]
	v_lshl_add_u64 v[6:7], s[74:75], 0, v[6:7]
	v_lshlrev_b64 v[8:9], 1, v[84:85]
	v_lshl_add_u64 v[6:7], v[6:7], 0, v[8:9]
	v_mov_b32_e32 v81, v1
	v_lshl_add_u64 v[6:7], v[6:7], 0, v[80:81]
	s_waitcnt lgkmcnt(0)
	global_store_dwordx4 v[6:7], v[2:5], off offset:2048
	ds_read_b128 v[2:5], v173
	v_lshl_add_u64 v[6:7], v[82:83], 0, v[44:45]
	v_lshlrev_b64 v[6:7], 13, v[6:7]
	v_lshl_add_u64 v[6:7], s[74:75], 0, v[6:7]
	s_movk_i32 s0, 0xfff
	v_lshl_add_u64 v[6:7], v[6:7], 0, v[8:9]
	s_add_i32 s70, s70, s71
	v_cmp_lt_i32_e32 vcc, s0, v46
	v_lshl_add_u64 v[6:7], v[6:7], 0, v[80:81]
	s_or_b64 s[84:85], vcc, s[84:85]
	s_waitcnt lgkmcnt(0)
	global_store_dwordx4 v[6:7], v[2:5], off offset:2048
	s_andn2_b64 exec, exec, s[84:85]
	s_cbranch_execz .LBB0_198

.LBB0_61:
	s_or_b64 exec, exec, s[0:1]
	v_mov_b32_e32 v2, 0
	v_mov_b32_e32 v3, 0
	v_mov_b32_e32 v4, 0
	v_mov_b32_e32 v5, 0
	s_and_saveexec_b64 s[0:1], s[26:27]
	s_cbranch_execz .LBB0_46
	v_ashrrev_i32_e32 v11, 31, v10
	v_lshl_add_u64 v[2:3], v[10:11], 1, v[12:13]
	global_load_dwordx4 v[2:5], v[2:3], off
	s_branch .LBB0_46
.LBB0_63:
	s_or_b64 exec, exec, s[20:21]
	s_and_saveexec_b64 s[0:1], s[8:9]
	s_cbranch_execz .LBB0_65
	v_lshl_add_u64 v[2:3], v[82:83], 0, v[166:167]
	v_lshlrev_b64 v[2:3], 6, v[2:3]
	v_lshl_add_u64 v[2:3], s[68:69], 0, v[2:3]
	v_lshlrev_b32_e32 v0, 2, v7
	v_lshl_add_u64 v[2:3], v[2:3], 0, v[0:1]
	global_load_dword v4, v[2:3], off
	global_load_dword v5, v0, s[12:13]
	s_nop 0
	global_load_dword v0, v0, s[10:11]
	s_nop 0
	global_load_dword v2, v[2:3], off offset:32
	s_mov_b32 s18, 0x800000
	v_mov_b32_e32 v3, v222
	v_mov_b32_e32 v6, v222
	v_lshl_add_u32 v3, v3, 2, -4
	v_mov_b32_e32 v7, v222
	v_lshl_add_u32 v6, v6, 2, -8
	v_mov_b32_e32 v8, v222
	v_mov_b32_e32 v9, v222
	v_mov_b32_e32 v10, v222
	s_waitcnt vmcnt(0) lgkmcnt(0)
	v_add_f32_e32 v4, v4, v5
	v_mul_f32_e32 v5, 0x3fb8aa3b, v4
	v_exp_f32_e32 v5, v5
	v_mul_f32_e32 v0, 0x3fb8aa3b, v0
	v_exp_f32_e32 v0, v0
	v_mul_f32_e32 v2, 0xbfb8aa3b, v2
	v_add_f32_e32 v5, 1.0, v5
	v_cmp_gt_f32_e32 vcc, s18, v5
	s_mov_b32 s18, 0x3f317217
	v_exp_f32_e32 v2, v2
	v_cndmask_b32_e64 v11, 0, 32, vcc
	v_ldexp_f32 v5, v5, v11
	v_log_f32_e32 v5, v5
	v_mov_b32_e32 v11, 0x41b17218
	v_cndmask_b32_e32 v11, 0, v11, vcc
	v_add_f32_e32 v2, 1.0, v2
	v_mul_f32_e32 v12, 0x3f317217, v5
	v_fma_f32 v12, v5, s18, -v12
	v_fmac_f32_e32 v12, 0x3377d1cf, v5
	s_mov_b32 s18, 0x7f800000
	v_fmac_f32_e32 v12, 0x3f317217, v5
	v_cmp_lt_f32_e64 vcc, |v5|, s18
	s_mov_b32 s18, 0x41a00000
	s_nop 0
	v_cndmask_b32_e32 v5, v5, v12, vcc
	v_sub_f32_e32 v5, v5, v11
	v_cmp_lt_f32_e32 vcc, s18, v4
	s_nop 1
	v_cndmask_b32_e32 v4, v5, v4, vcc
	v_mul_f32_e64 v5, v4, -v0
	ds_bpermute_b32 v3, v3, v5
	s_waitcnt lgkmcnt(0)
	v_fma_f32 v0, v4, -v0, v3
	v_cndmask_b32_e64 v0, v0, v5, s[42:43]
	ds_bpermute_b32 v3, v6, v0
	v_lshl_add_u32 v4, v7, 2, -16
	v_not_b32_e32 v5, 31
	v_lshl_add_u32 v5, v8, 2, v5
	v_lshl_add_u32 v6, v10, 2, v225
	s_waitcnt lgkmcnt(0)
	v_add_f32_e32 v3, v0, v3
	v_cndmask_b32_e64 v0, v3, v0, s[44:45]
	ds_bpermute_b32 v3, v4, v0
	v_lshl_add_u32 v4, v9, 2, v224
	s_waitcnt lgkmcnt(0)
	v_add_f32_e32 v3, v0, v3
	v_cndmask_b32_e64 v0, v3, v0, s[46:47]
	ds_bpermute_b32 v3, v5, v0
	v_div_scale_f32 v5, s[18:19], v2, v2, 1.0
	v_rcp_f32_e32 v7, v5
	s_waitcnt lgkmcnt(0)
	v_add_f32_e32 v3, v0, v3
	v_cndmask_b32_e64 v0, v3, v0, s[48:49]
	ds_bpermute_b32 v3, v4, v0
	v_fma_f32 v8, -v5, v7, 1.0
	v_div_scale_f32 v4, vcc, 1.0, v2, 1.0
	v_fmac_f32_e32 v7, v8, v7
	s_waitcnt lgkmcnt(0)
	v_add_f32_e32 v3, v0, v3
	v_cndmask_b32_e64 v0, v3, v0, s[50:51]
	ds_bpermute_b32 v3, v6, v0
	v_mul_f32_e32 v6, v4, v7
	v_fma_f32 v8, -v5, v6, v4
	v_fmac_f32_e32 v6, v8, v7
	v_fma_f32 v4, -v5, v6, v4
	s_waitcnt lgkmcnt(0)
	v_add_f32_e32 v3, v0, v3
	v_cndmask_b32_e64 v0, v3, v0, s[52:53]
	v_div_fmas_f32 v3, v4, v7, v6
	v_mul_f32_e32 v4, 0x3fb8aa3b, v0
	v_exp_f32_e32 v4, v4
	v_div_fixup_f32 v2, v3, v2, 1.0
	ds_write_b32 v114, v2
	ds_write2st64_b32 v41, v0, v2 offset1:2
	v_mul_f32_e32 v0, v2, v4
	ds_write_b32 v41, v0 offset:768

.LBB0_71:
	ds_read_b32 v0, v119
	ds_read_b32 v20, v121
	v_ashrrev_i32_e32 v47, 31, v46
	v_lshlrev_b64 v[18:19], 13, v[46:47]
	v_lshl_add_u64 v[18:19], v[42:43], 0, v[18:19]
	s_mov_b64 s[0:1], -1
	s_waitcnt lgkmcnt(0)
	v_sub_f32_e32 v20, v20, v0
	v_mul_f32_e32 v20, 0x3fb8aa3b, v20
	v_exp_f32_e32 v20, v20
	s_and_b64 vcc, exec, s[4:5]
	s_cbranch_vccz .LBB0_73
	v_mul_f32_e32 v21, v2, v20
	v_cndmask_b32_e64 v21, v21, 0, s[54:55]
	v_bfe_u32 v22, v21, 16, 1
	v_mov_b32_e32 v49, v1
	v_add3_u32 v21, v21, v22, s33
	v_lshl_add_u64 v[22:23], v[18:19], 0, v[48:49]
	global_store_short_d16_hi v[22:23], v21, off
	s_mov_b64 s[0:1], 0

.LBB0_77:
	ds_read_b32 v2, v124
	v_cndmask_b32_e64 v20, 0, 1, s[4:5]
	v_cmp_ne_u32_e64 s[20:21], 1, v20
	s_andn2_b64 vcc, exec, s[4:5]
	s_mov_b64 s[0:1], -1
	s_waitcnt lgkmcnt(0)
	v_sub_f32_e32 v2, v2, v0
	v_mul_f32_e32 v2, 0x3fb8aa3b, v2
	v_exp_f32_e32 v2, v2
	s_cbranch_vccnz .LBB0_79
	v_readlane_b32 s0, v254, 33
	v_mul_f32_e32 v20, v3, v2
	v_readlane_b32 s1, v254, 34
	v_mov_b32_e32 v51, v1
	s_nop 0
	v_cndmask_b32_e64 v20, v20, 0, s[0:1]
	v_bfe_u32 v21, v20, 16, 1
	v_add3_u32 v22, v20, v21, s33
	v_lshl_add_u64 v[20:21], v[18:19], 0, v[50:51]
	s_mov_b64 s[0:1], 0
	global_store_short_d16_hi v[20:21], v22, off

.LBB0_83:
	ds_read_b32 v2, v126
	s_and_b64 vcc, exec, s[20:21]
	s_mov_b64 s[0:1], -1
	s_waitcnt lgkmcnt(0)
	v_sub_f32_e32 v2, v2, v0
	v_mul_f32_e32 v2, 0x3fb8aa3b, v2
	v_exp_f32_e32 v2, v2
	s_cbranch_vccnz .LBB0_85
	v_readlane_b32 s0, v254, 52
	v_mul_f32_e32 v3, v4, v2
	v_readlane_b32 s1, v254, 53
	v_mov_b32_e32 v53, v1
	s_nop 0
	v_cndmask_b32_e64 v3, v3, 0, s[0:1]
	v_bfe_u32 v20, v3, 16, 1
	v_add3_u32 v3, v3, v20, s33
	v_lshl_add_u64 v[20:21], v[18:19], 0, v[52:53]
	s_mov_b64 s[0:1], 0
	global_store_short_d16_hi v[20:21], v3, off

.LBB0_89:
	ds_read_b32 v2, v128
	s_and_b64 vcc, exec, s[20:21]
	s_mov_b64 s[0:1], -1
	s_waitcnt lgkmcnt(0)
	v_sub_f32_e32 v2, v2, v0
	v_mul_f32_e32 v2, 0x3fb8aa3b, v2
	v_exp_f32_e32 v2, v2
	s_cbranch_vccnz .LBB0_91
	v_readlane_b32 s0, v254, 56
	v_mul_f32_e32 v3, v5, v2
	v_readlane_b32 s1, v254, 57
	v_mov_b32_e32 v55, v1
	v_lshl_add_u64 v[20:21], v[18:19], 0, v[54:55]
	v_cndmask_b32_e64 v3, v3, 0, s[0:1]
	v_bfe_u32 v4, v3, 16, 1
	v_add3_u32 v3, v3, v4, s33
	s_mov_b64 s[0:1], 0
	global_store_short_d16_hi v[20:21], v3, off

.LBB0_95:
	ds_read_b32 v2, v130
	s_and_b64 vcc, exec, s[20:21]
	s_mov_b64 s[0:1], -1
	s_waitcnt lgkmcnt(0)
	v_sub_f32_e32 v2, v2, v0
	v_mul_f32_e32 v2, 0x3fb8aa3b, v2
	v_exp_f32_e32 v2, v2
	s_cbranch_vccnz .LBB0_97
	v_readlane_b32 s0, v254, 60
	v_mul_f32_e32 v3, v6, v2
	v_readlane_b32 s1, v254, 61
	v_mov_b32_e32 v57, v1
	s_nop 0
	v_cndmask_b32_e64 v3, v3, 0, s[0:1]
	v_bfe_u32 v4, v3, 16, 1
	v_add3_u32 v3, v3, v4, s33
	v_lshl_add_u64 v[4:5], v[18:19], 0, v[56:57]
	s_mov_b64 s[0:1], 0
	global_store_short_d16_hi v[4:5], v3, off

.LBB0_101:
	ds_read_b32 v2, v132
	s_and_b64 vcc, exec, s[20:21]
	s_mov_b64 s[0:1], -1
	s_waitcnt lgkmcnt(0)
	v_sub_f32_e32 v2, v2, v0
	v_mul_f32_e32 v2, 0x3fb8aa3b, v2
	v_exp_f32_e32 v2, v2
	s_cbranch_vccnz .LBB0_103
	v_readlane_b32 s0, v255, 0
	v_mul_f32_e32 v3, v7, v2
	v_readlane_b32 s1, v255, 1
	v_mov_b32_e32 v59, v1
	s_nop 0
	v_cndmask_b32_e64 v3, v3, 0, s[0:1]
	v_bfe_u32 v4, v3, 16, 1
	v_add3_u32 v3, v3, v4, s33
	v_lshl_add_u64 v[4:5], v[18:19], 0, v[58:59]
	s_mov_b64 s[0:1], 0
	global_store_short_d16_hi v[4:5], v3, off

.LBB0_107:
	ds_read_b32 v2, v134
	s_and_b64 vcc, exec, s[20:21]
	s_mov_b64 s[0:1], -1
	s_waitcnt lgkmcnt(0)
	v_sub_f32_e32 v2, v2, v0
	v_mul_f32_e32 v2, 0x3fb8aa3b, v2
	v_exp_f32_e32 v2, v2
	s_cbranch_vccnz .LBB0_109
	v_readlane_b32 s0, v255, 4
	v_mul_f32_e32 v3, v8, v2
	v_readlane_b32 s1, v255, 5
	v_mov_b32_e32 v61, v1
	s_nop 0
	v_cndmask_b32_e64 v3, v3, 0, s[0:1]
	v_bfe_u32 v4, v3, 16, 1
	v_add3_u32 v3, v3, v4, s33
	v_lshl_add_u64 v[4:5], v[18:19], 0, v[60:61]
	s_mov_b64 s[0:1], 0
	global_store_short_d16_hi v[4:5], v3, off

.LBB0_113:
	ds_read_b32 v2, v136
	s_and_b64 vcc, exec, s[20:21]
	s_mov_b64 s[0:1], -1
	s_waitcnt lgkmcnt(0)
	v_sub_f32_e32 v2, v2, v0
	v_mul_f32_e32 v2, 0x3fb8aa3b, v2
	v_exp_f32_e32 v2, v2
	s_cbranch_vccnz .LBB0_115
	v_readlane_b32 s0, v255, 8
	v_mul_f32_e32 v3, v9, v2
	v_readlane_b32 s1, v255, 9
	v_mov_b32_e32 v63, v1
	s_nop 0
	v_cndmask_b32_e64 v3, v3, 0, s[0:1]
	v_bfe_u32 v4, v3, 16, 1
	v_add3_u32 v3, v3, v4, s33
	v_lshl_add_u64 v[4:5], v[18:19], 0, v[62:63]
	s_mov_b64 s[0:1], 0
	global_store_short_d16_hi v[4:5], v3, off

.LBB0_119:
	ds_read_b32 v2, v138
	s_and_b64 vcc, exec, s[20:21]
	s_mov_b64 s[0:1], -1
	s_waitcnt lgkmcnt(0)
	v_sub_f32_e32 v2, v2, v0
	v_mul_f32_e32 v2, 0x3fb8aa3b, v2
	v_exp_f32_e32 v2, v2
	s_cbranch_vccnz .LBB0_121
	v_readlane_b32 s0, v255, 12
	v_mul_f32_e32 v3, v10, v2
	v_readlane_b32 s1, v255, 13
	v_mov_b32_e32 v65, v1
	s_nop 0
	v_cndmask_b32_e64 v3, v3, 0, s[0:1]
	v_bfe_u32 v4, v3, 16, 1
	v_add3_u32 v3, v3, v4, s33
	v_lshl_add_u64 v[4:5], v[18:19], 0, v[64:65]
	s_mov_b64 s[0:1], 0
	global_store_short_d16_hi v[4:5], v3, off

.LBB0_125:
	ds_read_b32 v2, v140
	s_and_b64 vcc, exec, s[20:21]
	s_mov_b64 s[0:1], -1
	s_waitcnt lgkmcnt(0)
	v_sub_f32_e32 v2, v2, v0
	v_mul_f32_e32 v2, 0x3fb8aa3b, v2
	v_exp_f32_e32 v2, v2
	s_cbranch_vccnz .LBB0_127
	v_readlane_b32 s0, v255, 16
	v_mul_f32_e32 v3, v11, v2
	v_readlane_b32 s1, v255, 17
	v_mov_b32_e32 v67, v1
	s_nop 0
	v_cndmask_b32_e64 v3, v3, 0, s[0:1]
	v_bfe_u32 v4, v3, 16, 1
	v_add3_u32 v3, v3, v4, s33
	v_lshl_add_u64 v[4:5], v[18:19], 0, v[66:67]
	s_mov_b64 s[0:1], 0
	global_store_short_d16_hi v[4:5], v3, off

.LBB0_131:
	ds_read_b32 v2, v142
	s_and_b64 vcc, exec, s[20:21]
	s_mov_b64 s[0:1], -1
	s_waitcnt lgkmcnt(0)
	v_sub_f32_e32 v2, v2, v0
	v_mul_f32_e32 v2, 0x3fb8aa3b, v2
	v_exp_f32_e32 v2, v2
	s_cbranch_vccnz .LBB0_133
	v_readlane_b32 s0, v255, 20
	v_mul_f32_e32 v3, v12, v2
	v_readlane_b32 s1, v255, 21
	v_mov_b32_e32 v69, v1
	s_nop 0
	v_cndmask_b32_e64 v3, v3, 0, s[0:1]
	v_bfe_u32 v4, v3, 16, 1
	v_add3_u32 v3, v3, v4, s33
	v_lshl_add_u64 v[4:5], v[18:19], 0, v[68:69]
	s_mov_b64 s[0:1], 0
	global_store_short_d16_hi v[4:5], v3, off

.LBB0_137:
	ds_read_b32 v2, v144
	s_and_b64 vcc, exec, s[20:21]
	s_mov_b64 s[0:1], -1
	s_waitcnt lgkmcnt(0)
	v_sub_f32_e32 v2, v2, v0
	v_mul_f32_e32 v2, 0x3fb8aa3b, v2
	v_exp_f32_e32 v2, v2
	s_cbranch_vccnz .LBB0_139
	v_readlane_b32 s0, v255, 24
	v_mul_f32_e32 v3, v13, v2
	v_readlane_b32 s1, v255, 25
	v_mov_b32_e32 v71, v1
	s_nop 0
	v_cndmask_b32_e64 v3, v3, 0, s[0:1]
	v_bfe_u32 v4, v3, 16, 1
	v_add3_u32 v3, v3, v4, s33
	v_lshl_add_u64 v[4:5], v[18:19], 0, v[70:71]
	s_mov_b64 s[0:1], 0
	global_store_short_d16_hi v[4:5], v3, off

.LBB0_143:
	ds_read_b32 v2, v146
	s_and_b64 vcc, exec, s[20:21]
	s_mov_b64 s[0:1], -1
	s_waitcnt lgkmcnt(0)
	v_sub_f32_e32 v2, v2, v0
	v_mul_f32_e32 v2, 0x3fb8aa3b, v2
	v_exp_f32_e32 v2, v2
	s_cbranch_vccnz .LBB0_145
	v_readlane_b32 s0, v255, 28
	v_mul_f32_e32 v3, v14, v2
	v_readlane_b32 s1, v255, 29
	v_mov_b32_e32 v73, v1
	s_nop 0
	v_cndmask_b32_e64 v3, v3, 0, s[0:1]
	v_bfe_u32 v4, v3, 16, 1
	v_add3_u32 v3, v3, v4, s33
	v_lshl_add_u64 v[4:5], v[18:19], 0, v[72:73]
	s_mov_b64 s[0:1], 0
	global_store_short_d16_hi v[4:5], v3, off

.LBB0_149:
	ds_read_b32 v2, v148
	s_and_b64 vcc, exec, s[20:21]
	s_mov_b64 s[0:1], -1
	s_waitcnt lgkmcnt(0)
	v_sub_f32_e32 v2, v2, v0
	v_mul_f32_e32 v2, 0x3fb8aa3b, v2
	v_exp_f32_e32 v2, v2
	s_cbranch_vccnz .LBB0_151
	v_readlane_b32 s0, v255, 32
	v_mul_f32_e32 v3, v15, v2
	v_readlane_b32 s1, v255, 33
	v_mov_b32_e32 v75, v1
	s_nop 0
	v_cndmask_b32_e64 v3, v3, 0, s[0:1]
	v_bfe_u32 v4, v3, 16, 1
	v_add3_u32 v3, v3, v4, s33
	v_lshl_add_u64 v[4:5], v[18:19], 0, v[74:75]
	s_mov_b64 s[0:1], 0
	global_store_short_d16_hi v[4:5], v3, off

.LBB0_155:
	ds_read_b32 v2, v150
	s_and_b64 vcc, exec, s[20:21]
	s_mov_b64 s[0:1], -1
	s_waitcnt lgkmcnt(0)
	v_sub_f32_e32 v2, v2, v0
	v_mul_f32_e32 v2, 0x3fb8aa3b, v2
	v_exp_f32_e32 v2, v2
	s_cbranch_vccnz .LBB0_157
	v_readlane_b32 s0, v255, 36
	v_mul_f32_e32 v3, v16, v2
	v_readlane_b32 s1, v255, 37
	v_mov_b32_e32 v77, v1
	s_nop 0
	v_cndmask_b32_e64 v3, v3, 0, s[0:1]
	v_bfe_u32 v4, v3, 16, 1
	v_add3_u32 v3, v3, v4, s33
	v_lshl_add_u64 v[4:5], v[18:19], 0, v[76:77]
	s_mov_b64 s[0:1], 0
	global_store_short_d16_hi v[4:5], v3, off

.LBB0_161:
	ds_read_b32 v2, v152
	s_and_b64 vcc, exec, s[20:21]
	s_mov_b64 s[0:1], -1
	s_waitcnt lgkmcnt(0)
	v_sub_f32_e32 v0, v2, v0
	v_mul_f32_e32 v0, 0x3fb8aa3b, v0
	v_exp_f32_e32 v0, v0
	s_cbranch_vccnz .LBB0_163
	v_readlane_b32 s0, v255, 40
	v_mul_f32_e32 v2, v17, v0
	v_readlane_b32 s1, v255, 41
	v_mov_b32_e32 v79, v1
	s_nop 0
	v_cndmask_b32_e64 v2, v2, 0, s[0:1]
	v_bfe_u32 v3, v2, 16, 1
	v_add3_u32 v4, v2, v3, s33
	v_lshl_add_u64 v[2:3], v[18:19], 0, v[78:79]
	s_mov_b64 s[0:1], 0
	global_store_short_d16_hi v[2:3], v4, off

.Lrl_early_done:
	s_movk_i32 s0, 0x180
	v_cmp_gt_u32_e32 vcc, s0, v49
	v_add_u32_e32 v6, 0xffffff00, v49
	s_and_saveexec_b64 s[0:1], vcc
	s_cbranch_execz .LBB0_172
	v_readlane_b32 s18, v253, 38
	v_lshlrev_b64 v[2:3], 14, v[46:47]
	v_cmp_eq_u32_e32 vcc, 0, v6
	v_mov_b32_e32 v0, s18
	v_readlane_b32 s18, v254, 21
	v_readlane_b32 s19, v254, 22
	ds_read_b32 v7, v0
	s_nop 0
	v_lshl_add_u64 v[2:3], s[18:19], 0, v[2:3]
	v_readlane_b32 s18, v253, 31
	s_nop 1
	v_mov_b32_e32 v4, s18
	ds_read_b128 v[8:11], v4
	v_lshlrev_b32_e32 v0, 7, v6
	v_lshl_add_u64 v[2:3], v[2:3], 0, v[0:1]
	v_lshl_add_u32 v0, v6, 1, 0
	v_add_u32_e32 v0, 0x10d00, v0
	s_waitcnt lgkmcnt(0)
	v_sub_f32_e32 v4, v7, v8
	v_sub_f32_e32 v5, v7, v9
	ds_read_u16 v8, v0
	ds_read_u16 v9, v0 offset:272
	v_mul_f32_e32 v4, 0x3fb8aa3b, v4
	v_mul_f32_e32 v5, 0x3fb8aa3b, v5
	v_exp_f32_e32 v4, v4
	v_exp_f32_e32 v5, v5
	s_waitcnt lgkmcnt(0)
	v_lshlrev_b32_e32 v9, 16, v9
	v_lshlrev_b32_e32 v8, 16, v8
	v_readlane_b32 s18, v253, 39
	v_pk_mul_f32 v[4:5], v[4:5], v[8:9]
	v_sub_f32_e32 v8, v7, v10
	v_sub_f32_e32 v9, v7, v11
	ds_read_u16 v10, v0 offset:544
	ds_read_u16 v11, v0 offset:816
	v_mul_f32_e32 v8, 0x3fb8aa3b, v8
	v_mul_f32_e32 v9, 0x3fb8aa3b, v9
	v_exp_f32_e32 v8, v8
	v_exp_f32_e32 v9, v9
	s_waitcnt lgkmcnt(0)
	v_lshlrev_b32_e32 v11, 16, v11
	v_lshlrev_b32_e32 v10, 16, v10
	v_pk_mul_f32 v[12:13], v[8:9], v[10:11]
	v_mov_b32_e32 v8, s18
	ds_read_b128 v[8:11], v8
	ds_read_u16 v14, v0 offset:1088
	ds_read_u16 v15, v0 offset:1360
	v_readlane_b32 s18, v253, 40
	s_waitcnt lgkmcnt(0)
	v_sub_f32_e32 v8, v7, v8
	v_sub_f32_e32 v9, v7, v9
	v_mul_f32_e32 v8, 0x3fb8aa3b, v8
	v_mul_f32_e32 v9, 0x3fb8aa3b, v9
	v_exp_f32_e32 v8, v8
	v_exp_f32_e32 v9, v9
	v_lshlrev_b32_e32 v15, 16, v15
	v_lshlrev_b32_e32 v14, 16, v14
	v_pk_mul_f32 v[14:15], v[8:9], v[14:15]
	v_sub_f32_e32 v8, v7, v10
	v_sub_f32_e32 v9, v7, v11
	ds_read_u16 v10, v0 offset:1632
	ds_read_u16 v11, v0 offset:1904
	v_mul_f32_e32 v8, 0x3fb8aa3b, v8
	v_mul_f32_e32 v9, 0x3fb8aa3b, v9
	v_exp_f32_e32 v8, v8
	v_exp_f32_e32 v9, v9
	s_waitcnt lgkmcnt(0)
	v_lshlrev_b32_e32 v11, 16, v11
	v_lshlrev_b32_e32 v10, 16, v10
	v_pk_mul_f32 v[16:17], v[8:9], v[10:11]
	v_cvt_pk_bf16_f32 v8, v4, v5
	v_cvt_pk_bf16_f32 v9, v12, v13
	v_cvt_pk_bf16_f32 v10, v14, v15
	v_cvt_pk_bf16_f32 v11, v16, v17
	global_store_dwordx4 v[2:3], v[8:11], off
	v_mov_b32_e32 v4, s18
	ds_read_b128 v[8:11], v4
	v_readlane_b32 s18, v253, 41
	s_waitcnt lgkmcnt(0)
	v_sub_f32_e32 v4, v7, v8
	v_sub_f32_e32 v5, v7, v9
	ds_read_u16 v8, v0 offset:2176
	ds_read_u16 v9, v0 offset:2448
	v_mul_f32_e32 v4, 0x3fb8aa3b, v4
	v_mul_f32_e32 v5, 0x3fb8aa3b, v5
	v_exp_f32_e32 v4, v4
	v_exp_f32_e32 v5, v5
	s_waitcnt lgkmcnt(0)
	v_lshlrev_b32_e32 v9, 16, v9
	v_lshlrev_b32_e32 v8, 16, v8
	v_pk_mul_f32 v[4:5], v[4:5], v[8:9]
	v_sub_f32_e32 v8, v7, v10
	v_sub_f32_e32 v9, v7, v11
	ds_read_u16 v10, v0 offset:2720
	ds_read_u16 v11, v0 offset:2992
	v_mul_f32_e32 v8, 0x3fb8aa3b, v8
	v_mul_f32_e32 v9, 0x3fb8aa3b, v9
	v_exp_f32_e32 v8, v8
	v_exp_f32_e32 v9, v9
	s_waitcnt lgkmcnt(0)
	v_lshlrev_b32_e32 v11, 16, v11
	v_lshlrev_b32_e32 v10, 16, v10
	v_pk_mul_f32 v[8:9], v[8:9], v[10:11]
	v_mov_b32_e32 v10, s18
	ds_read_b128 v[10:13], v10
	ds_read_u16 v14, v0 offset:3264
	ds_read_u16 v15, v0 offset:3536
	v_readlane_b32 s18, v253, 42
	s_waitcnt lgkmcnt(0)
	v_sub_f32_e32 v10, v7, v10
	v_sub_f32_e32 v11, v7, v11
	v_mul_f32_e32 v10, 0x3fb8aa3b, v10
	v_mul_f32_e32 v11, 0x3fb8aa3b, v11
	v_exp_f32_e32 v10, v10
	v_exp_f32_e32 v11, v11
	v_lshlrev_b32_e32 v15, 16, v15
	v_lshlrev_b32_e32 v14, 16, v14
	v_pk_mul_f32 v[14:15], v[10:11], v[14:15]
	v_sub_f32_e32 v10, v7, v12
	v_sub_f32_e32 v11, v7, v13
	ds_read_u16 v12, v0 offset:3808
	ds_read_u16 v13, v0 offset:4080
	v_mul_f32_e32 v10, 0x3fb8aa3b, v10
	v_mul_f32_e32 v11, 0x3fb8aa3b, v11
	v_exp_f32_e32 v10, v10
	v_exp_f32_e32 v11, v11
	s_waitcnt lgkmcnt(0)
	v_lshlrev_b32_e32 v13, 16, v13
	v_lshlrev_b32_e32 v12, 16, v12
	v_pk_mul_f32 v[16:17], v[10:11], v[12:13]
	v_cvt_pk_bf16_f32 v10, v4, v5
	v_cvt_pk_bf16_f32 v11, v8, v9
	v_cvt_pk_bf16_f32 v12, v14, v15
	v_cvt_pk_bf16_f32 v13, v16, v17
	global_store_dwordx4 v[2:3], v[10:13], off offset:16
	v_mov_b32_e32 v4, s18
	ds_read_b128 v[8:11], v4
	v_readlane_b32 s18, v253, 43
	s_waitcnt lgkmcnt(0)
	v_sub_f32_e32 v4, v7, v8
	v_sub_f32_e32 v5, v7, v9
	ds_read_u16 v8, v0 offset:4352
	ds_read_u16 v9, v0 offset:4624
	v_mul_f32_e32 v4, 0x3fb8aa3b, v4
	v_mul_f32_e32 v5, 0x3fb8aa3b, v5
	v_exp_f32_e32 v4, v4
	v_exp_f32_e32 v5, v5
	s_waitcnt lgkmcnt(0)
	v_lshlrev_b32_e32 v9, 16, v9
	v_lshlrev_b32_e32 v8, 16, v8
	v_pk_mul_f32 v[4:5], v[4:5], v[8:9]
	v_sub_f32_e32 v8, v7, v10
	v_sub_f32_e32 v9, v7, v11
	ds_read_u16 v10, v0 offset:4896
	ds_read_u16 v11, v0 offset:5168
	v_mul_f32_e32 v8, 0x3fb8aa3b, v8
	v_mul_f32_e32 v9, 0x3fb8aa3b, v9
	v_exp_f32_e32 v8, v8
	v_exp_f32_e32 v9, v9
	s_waitcnt lgkmcnt(0)
	v_lshlrev_b32_e32 v11, 16, v11
	v_lshlrev_b32_e32 v10, 16, v10
	v_pk_mul_f32 v[8:9], v[8:9], v[10:11]
	v_mov_b32_e32 v10, s18
	ds_read_b128 v[10:13], v10
	ds_read_u16 v14, v0 offset:5440
	ds_read_u16 v15, v0 offset:5712
	v_readlane_b32 s18, v253, 44
	s_waitcnt lgkmcnt(0)
	v_sub_f32_e32 v10, v7, v10
	v_sub_f32_e32 v11, v7, v11
	v_mul_f32_e32 v10, 0x3fb8aa3b, v10
	v_mul_f32_e32 v11, 0x3fb8aa3b, v11
	v_exp_f32_e32 v10, v10
	v_exp_f32_e32 v11, v11
	v_lshlrev_b32_e32 v15, 16, v15
	v_lshlrev_b32_e32 v14, 16, v14
	v_pk_mul_f32 v[14:15], v[10:11], v[14:15]
	v_sub_f32_e32 v10, v7, v12
	v_sub_f32_e32 v11, v7, v13
	ds_read_u16 v12, v0 offset:5984
	ds_read_u16 v13, v0 offset:6256
	v_mul_f32_e32 v10, 0x3fb8aa3b, v10
	v_mul_f32_e32 v11, 0x3fb8aa3b, v11
	v_exp_f32_e32 v10, v10
	v_exp_f32_e32 v11, v11
	s_waitcnt lgkmcnt(0)
	v_lshlrev_b32_e32 v13, 16, v13
	v_lshlrev_b32_e32 v12, 16, v12
	v_pk_mul_f32 v[16:17], v[10:11], v[12:13]
	v_cvt_pk_bf16_f32 v10, v4, v5
	v_cvt_pk_bf16_f32 v11, v8, v9
	v_cvt_pk_bf16_f32 v12, v14, v15
	v_cvt_pk_bf16_f32 v13, v16, v17
	global_store_dwordx4 v[2:3], v[10:13], off offset:32
	v_mov_b32_e32 v4, s18
	ds_read_b128 v[8:11], v4
	v_readlane_b32 s18, v253, 45
	s_waitcnt lgkmcnt(0)
	v_sub_f32_e32 v4, v7, v8
	v_sub_f32_e32 v5, v7, v9
	ds_read_u16 v8, v0 offset:6528
	ds_read_u16 v9, v0 offset:6800
	v_mul_f32_e32 v4, 0x3fb8aa3b, v4
	v_mul_f32_e32 v5, 0x3fb8aa3b, v5
	v_exp_f32_e32 v4, v4
	v_exp_f32_e32 v5, v5
	s_waitcnt lgkmcnt(0)
	v_lshlrev_b32_e32 v9, 16, v9
	v_lshlrev_b32_e32 v8, 16, v8
	v_pk_mul_f32 v[4:5], v[4:5], v[8:9]
	v_sub_f32_e32 v8, v7, v10
	v_sub_f32_e32 v9, v7, v11
	ds_read_u16 v10, v0 offset:7072
	ds_read_u16 v11, v0 offset:7344
	v_mul_f32_e32 v8, 0x3fb8aa3b, v8
	v_mul_f32_e32 v9, 0x3fb8aa3b, v9
	v_exp_f32_e32 v8, v8
	v_exp_f32_e32 v9, v9
	s_waitcnt lgkmcnt(0)
	v_lshlrev_b32_e32 v11, 16, v11
	v_lshlrev_b32_e32 v10, 16, v10
	v_pk_mul_f32 v[8:9], v[8:9], v[10:11]
	v_mov_b32_e32 v10, s18
	ds_read_b128 v[10:13], v10
	ds_read_u16 v14, v0 offset:7616
	ds_read_u16 v15, v0 offset:7888
	v_readlane_b32 s18, v253, 46
	s_waitcnt lgkmcnt(0)
	v_sub_f32_e32 v10, v7, v10
	v_sub_f32_e32 v11, v7, v11
	v_mul_f32_e32 v10, 0x3fb8aa3b, v10
	v_mul_f32_e32 v11, 0x3fb8aa3b, v11
	v_exp_f32_e32 v10, v10
	v_exp_f32_e32 v11, v11
	v_lshlrev_b32_e32 v15, 16, v15
	v_lshlrev_b32_e32 v14, 16, v14
	v_pk_mul_f32 v[14:15], v[10:11], v[14:15]
	v_sub_f32_e32 v10, v7, v12
	v_sub_f32_e32 v11, v7, v13
	ds_read_u16 v12, v0 offset:8160
	ds_read_u16 v13, v0 offset:8432
	v_mul_f32_e32 v10, 0x3fb8aa3b, v10
	v_mul_f32_e32 v11, 0x3fb8aa3b, v11
	v_exp_f32_e32 v10, v10
	v_exp_f32_e32 v11, v11
	s_waitcnt lgkmcnt(0)
	v_lshlrev_b32_e32 v13, 16, v13
	v_lshlrev_b32_e32 v12, 16, v12
	v_pk_mul_f32 v[16:17], v[10:11], v[12:13]
	v_cvt_pk_bf16_f32 v10, v4, v5
	v_cvt_pk_bf16_f32 v11, v8, v9
	v_cvt_pk_bf16_f32 v12, v14, v15
	v_cvt_pk_bf16_f32 v13, v16, v17
	global_store_dwordx4 v[2:3], v[10:13], off offset:48
	v_mov_b32_e32 v4, s18
	ds_read_b128 v[8:11], v4
	v_readlane_b32 s18, v253, 47
	s_waitcnt lgkmcnt(0)
	v_sub_f32_e32 v4, v7, v8
	v_sub_f32_e32 v5, v7, v9
	ds_read_u16 v8, v0 offset:8704
	ds_read_u16 v9, v0 offset:8976
	v_mul_f32_e32 v4, 0x3fb8aa3b, v4
	v_mul_f32_e32 v5, 0x3fb8aa3b, v5
	v_exp_f32_e32 v4, v4
	v_exp_f32_e32 v5, v5
	s_waitcnt lgkmcnt(0)
	v_lshlrev_b32_e32 v9, 16, v9
	v_lshlrev_b32_e32 v8, 16, v8
	v_pk_mul_f32 v[4:5], v[4:5], v[8:9]
	v_sub_f32_e32 v8, v7, v10
	v_sub_f32_e32 v9, v7, v11
	ds_read_u16 v10, v0 offset:9248
	ds_read_u16 v11, v0 offset:9520
	v_mul_f32_e32 v8, 0x3fb8aa3b, v8
	v_mul_f32_e32 v9, 0x3fb8aa3b, v9
	v_exp_f32_e32 v8, v8
	v_exp_f32_e32 v9, v9
	s_waitcnt lgkmcnt(0)
	v_lshlrev_b32_e32 v11, 16, v11
	v_lshlrev_b32_e32 v10, 16, v10
	v_pk_mul_f32 v[8:9], v[8:9], v[10:11]
	v_mov_b32_e32 v10, s18
	ds_read_b128 v[10:13], v10
	ds_read_u16 v14, v0 offset:9792
	ds_read_u16 v15, v0 offset:10064
	v_readlane_b32 s18, v253, 48
	s_waitcnt lgkmcnt(0)
	v_sub_f32_e32 v10, v7, v10
	v_sub_f32_e32 v11, v7, v11
	v_mul_f32_e32 v10, 0x3fb8aa3b, v10
	v_mul_f32_e32 v11, 0x3fb8aa3b, v11
	v_exp_f32_e32 v10, v10
	v_exp_f32_e32 v11, v11
	v_lshlrev_b32_e32 v15, 16, v15
	v_lshlrev_b32_e32 v14, 16, v14
	v_pk_mul_f32 v[14:15], v[10:11], v[14:15]
	v_sub_f32_e32 v10, v7, v12
	v_sub_f32_e32 v11, v7, v13
	ds_read_u16 v12, v0 offset:10336
	ds_read_u16 v13, v0 offset:10608
	v_mul_f32_e32 v10, 0x3fb8aa3b, v10
	v_mul_f32_e32 v11, 0x3fb8aa3b, v11
	v_exp_f32_e32 v10, v10
	v_exp_f32_e32 v11, v11
	s_waitcnt lgkmcnt(0)
	v_lshlrev_b32_e32 v13, 16, v13
	v_lshlrev_b32_e32 v12, 16, v12
	v_pk_mul_f32 v[16:17], v[10:11], v[12:13]
	v_cvt_pk_bf16_f32 v10, v4, v5
	v_cvt_pk_bf16_f32 v11, v8, v9
	v_cvt_pk_bf16_f32 v12, v14, v15
	v_cvt_pk_bf16_f32 v13, v16, v17
	global_store_dwordx4 v[2:3], v[10:13], off offset:64
	v_mov_b32_e32 v4, s18
	ds_read_b128 v[8:11], v4
	v_readlane_b32 s18, v253, 49
	s_waitcnt lgkmcnt(0)
	v_sub_f32_e32 v4, v7, v8
	v_sub_f32_e32 v5, v7, v9
	ds_read_u16 v8, v0 offset:10880
	ds_read_u16 v9, v0 offset:11152
	v_mul_f32_e32 v4, 0x3fb8aa3b, v4
	v_mul_f32_e32 v5, 0x3fb8aa3b, v5
	v_exp_f32_e32 v4, v4
	v_exp_f32_e32 v5, v5
	s_waitcnt lgkmcnt(0)
	v_lshlrev_b32_e32 v9, 16, v9
	v_lshlrev_b32_e32 v8, 16, v8
	v_pk_mul_f32 v[4:5], v[4:5], v[8:9]
	v_sub_f32_e32 v8, v7, v10
	v_sub_f32_e32 v9, v7, v11
	ds_read_u16 v10, v0 offset:11424
	ds_read_u16 v11, v0 offset:11696
	v_mul_f32_e32 v8, 0x3fb8aa3b, v8
	v_mul_f32_e32 v9, 0x3fb8aa3b, v9
	v_exp_f32_e32 v8, v8
	v_exp_f32_e32 v9, v9
	s_waitcnt lgkmcnt(0)
	v_lshlrev_b32_e32 v11, 16, v11
	v_lshlrev_b32_e32 v10, 16, v10
	v_pk_mul_f32 v[8:9], v[8:9], v[10:11]
	v_mov_b32_e32 v10, s18
	ds_read_b128 v[10:13], v10
	ds_read_u16 v14, v0 offset:11968
	ds_read_u16 v15, v0 offset:12240
	v_readlane_b32 s18, v253, 50
	s_waitcnt lgkmcnt(0)
	v_sub_f32_e32 v10, v7, v10
	v_sub_f32_e32 v11, v7, v11
	v_mul_f32_e32 v10, 0x3fb8aa3b, v10
	v_mul_f32_e32 v11, 0x3fb8aa3b, v11
	v_exp_f32_e32 v10, v10
	v_exp_f32_e32 v11, v11
	v_lshlrev_b32_e32 v15, 16, v15
	v_lshlrev_b32_e32 v14, 16, v14
	v_pk_mul_f32 v[14:15], v[10:11], v[14:15]
	v_sub_f32_e32 v10, v7, v12
	v_sub_f32_e32 v11, v7, v13
	ds_read_u16 v12, v0 offset:12512
	ds_read_u16 v13, v0 offset:12784
	v_mul_f32_e32 v10, 0x3fb8aa3b, v10
	v_mul_f32_e32 v11, 0x3fb8aa3b, v11
	v_exp_f32_e32 v10, v10
	v_exp_f32_e32 v11, v11
	s_waitcnt lgkmcnt(0)
	v_lshlrev_b32_e32 v13, 16, v13
	v_lshlrev_b32_e32 v12, 16, v12
	v_pk_mul_f32 v[16:17], v[10:11], v[12:13]
	v_cvt_pk_bf16_f32 v10, v4, v5
	v_cvt_pk_bf16_f32 v11, v8, v9
	v_cvt_pk_bf16_f32 v12, v14, v15
	v_cvt_pk_bf16_f32 v13, v16, v17
	global_store_dwordx4 v[2:3], v[10:13], off offset:80
	v_mov_b32_e32 v4, s18
	ds_read_b128 v[8:11], v4
	v_readlane_b32 s18, v253, 51
	s_waitcnt lgkmcnt(0)
	v_sub_f32_e32 v4, v7, v8
	v_sub_f32_e32 v5, v7, v9
	ds_read_u16 v8, v0 offset:13056
	ds_read_u16 v9, v0 offset:13328
	v_mul_f32_e32 v4, 0x3fb8aa3b, v4
	v_mul_f32_e32 v5, 0x3fb8aa3b, v5
	v_exp_f32_e32 v4, v4
	v_exp_f32_e32 v5, v5
	s_waitcnt lgkmcnt(0)
	v_lshlrev_b32_e32 v9, 16, v9
	v_lshlrev_b32_e32 v8, 16, v8
	v_pk_mul_f32 v[4:5], v[4:5], v[8:9]
	v_sub_f32_e32 v8, v7, v10
	v_sub_f32_e32 v9, v7, v11
	ds_read_u16 v10, v0 offset:13600
	ds_read_u16 v11, v0 offset:13872
	v_mul_f32_e32 v8, 0x3fb8aa3b, v8
	v_mul_f32_e32 v9, 0x3fb8aa3b, v9
	v_exp_f32_e32 v8, v8
	v_exp_f32_e32 v9, v9
	s_waitcnt lgkmcnt(0)
	v_lshlrev_b32_e32 v11, 16, v11
	v_lshlrev_b32_e32 v10, 16, v10
	v_pk_mul_f32 v[8:9], v[8:9], v[10:11]
	v_mov_b32_e32 v10, s18
	ds_read_b128 v[10:13], v10
	ds_read_u16 v14, v0 offset:14144
	ds_read_u16 v15, v0 offset:14416
	v_readlane_b32 s18, v253, 52
	s_waitcnt lgkmcnt(0)
	v_sub_f32_e32 v10, v7, v10
	v_sub_f32_e32 v11, v7, v11
	v_mul_f32_e32 v10, 0x3fb8aa3b, v10
	v_mul_f32_e32 v11, 0x3fb8aa3b, v11
	v_exp_f32_e32 v10, v10
	v_exp_f32_e32 v11, v11
	v_lshlrev_b32_e32 v15, 16, v15
	v_lshlrev_b32_e32 v14, 16, v14
	v_pk_mul_f32 v[14:15], v[10:11], v[14:15]
	v_sub_f32_e32 v10, v7, v12
	v_sub_f32_e32 v11, v7, v13
	ds_read_u16 v12, v0 offset:14688
	ds_read_u16 v13, v0 offset:14960
	v_mul_f32_e32 v10, 0x3fb8aa3b, v10
	v_mul_f32_e32 v11, 0x3fb8aa3b, v11
	v_exp_f32_e32 v10, v10
	v_exp_f32_e32 v11, v11
	s_waitcnt lgkmcnt(0)
	v_lshlrev_b32_e32 v13, 16, v13
	v_lshlrev_b32_e32 v12, 16, v12
	v_pk_mul_f32 v[16:17], v[10:11], v[12:13]
	v_cvt_pk_bf16_f32 v10, v4, v5
	v_cvt_pk_bf16_f32 v11, v8, v9
	v_cvt_pk_bf16_f32 v12, v14, v15
	v_cvt_pk_bf16_f32 v13, v16, v17
	global_store_dwordx4 v[2:3], v[10:13], off offset:96
	v_mov_b32_e32 v4, s18
	ds_read_b128 v[8:11], v4
	v_readlane_b32 s18, v253, 53
	s_waitcnt lgkmcnt(0)
	v_sub_f32_e32 v4, v7, v8
	v_sub_f32_e32 v5, v7, v9
	ds_read_u16 v8, v0 offset:15232
	ds_read_u16 v9, v0 offset:15504
	v_mul_f32_e32 v4, 0x3fb8aa3b, v4
	v_mul_f32_e32 v5, 0x3fb8aa3b, v5
	v_exp_f32_e32 v4, v4
	v_exp_f32_e32 v5, v5
	s_waitcnt lgkmcnt(0)
	v_lshlrev_b32_e32 v9, 16, v9
	v_lshlrev_b32_e32 v8, 16, v8
	v_pk_mul_f32 v[4:5], v[4:5], v[8:9]
	v_sub_f32_e32 v8, v7, v10
	v_sub_f32_e32 v9, v7, v11
	ds_read_u16 v10, v0 offset:15776
	ds_read_u16 v11, v0 offset:16048
	v_mul_f32_e32 v8, 0x3fb8aa3b, v8
	v_mul_f32_e32 v9, 0x3fb8aa3b, v9
	v_exp_f32_e32 v8, v8
	v_exp_f32_e32 v9, v9
	s_waitcnt lgkmcnt(0)
	v_lshlrev_b32_e32 v11, 16, v11
	v_lshlrev_b32_e32 v10, 16, v10
	v_pk_mul_f32 v[8:9], v[8:9], v[10:11]
	v_mov_b32_e32 v10, s18
	ds_read_b128 v[10:13], v10
	ds_read_u16 v14, v0 offset:16320
	ds_read_u16 v15, v0 offset:16592
	s_waitcnt lgkmcnt(0)
	v_sub_f32_e32 v10, v7, v10
	v_sub_f32_e32 v11, v7, v11
	v_mul_f32_e32 v10, 0x3fb8aa3b, v10
	v_mul_f32_e32 v11, 0x3fb8aa3b, v11
	v_exp_f32_e32 v10, v10
	v_exp_f32_e32 v11, v11
	v_lshlrev_b32_e32 v15, 16, v15
	v_lshlrev_b32_e32 v14, 16, v14
	v_pk_mul_f32 v[14:15], v[10:11], v[14:15]
	v_sub_f32_e32 v10, v7, v12
	v_sub_f32_e32 v11, v7, v13
	ds_read_u16 v12, v0 offset:16864
	ds_read_u16 v0, v0 offset:17136
	v_mul_f32_e32 v10, 0x3fb8aa3b, v10
	v_mul_f32_e32 v11, 0x3fb8aa3b, v11
	v_exp_f32_e32 v10, v10
	v_exp_f32_e32 v11, v11
	s_waitcnt lgkmcnt(0)
	v_lshlrev_b32_e32 v13, 16, v0
	v_lshlrev_b32_e32 v12, 16, v12
	v_pk_mul_f32 v[16:17], v[10:11], v[12:13]
	v_cvt_pk_bf16_f32 v10, v4, v5
	v_cvt_pk_bf16_f32 v11, v8, v9
	v_cvt_pk_bf16_f32 v12, v14, v15
	v_cvt_pk_bf16_f32 v13, v16, v17
	global_store_dwordx4 v[2:3], v[10:13], off offset:112
	s_and_saveexec_b64 s[24:25], vcc
	s_cbranch_execz .LBB0_171
	v_mul_f32_e32 v0, 0x3fb8aa3b, v7
	v_exp_f32_e32 v0, v0
	v_lshl_add_u64 v[2:3], v[46:47], 2, s[40:41]
	v_mov_b32_e32 v6, 0
	global_store_dword v[2:3], v0, off

.LBB0_172:
	s_or_b64 exec, exec, s[0:1]
	v_lshlrev_b32_e32 v0, 4, v49
	v_and_b32_e32 v2, 0xf0, v0
	v_lshlrev_b32_e32 v0, 1, v84
	v_add_u32_e32 v4, 0, v2
	v_lshl_add_u64 v[8:9], s[74:75], 0, v[0:1]
	v_mov_b32_e32 v3, v1
	v_lshrrev_b32_e32 v0, 4, v6
	s_movk_i32 s19, 0x110
	v_readlane_b32 s18, v253, 31
	v_lshl_add_u64 v[2:3], v[8:9], 0, v[2:3]
	v_mad_u64_u32 v[8:9], s[0:1], v0, s19, v[4:5]
	v_lshl_add_u32 v5, v0, 2, s18
	ds_read_b128 v[8:11], v8 offset:51456
	ds_read_b32 v5, v5
	v_add_u32_e32 v46, s63, v46
	s_waitcnt lgkmcnt(0)
	v_lshlrev_b32_e32 v14, 16, v8
	v_mul_f32_e32 v5, 0x3fb8aa3b, v5
	v_exp_f32_e32 v12, v5
	v_and_b32_e32 v15, 0xffff0000, v8
	v_pk_mul_f32 v[14:15], v[12:13], v[14:15] op_sel_hi:[0,1]
	v_cvt_pk_bf16_f32 v8, v14, v15
	v_lshlrev_b32_e32 v14, 16, v9
	v_and_b32_e32 v15, 0xffff0000, v9
	v_pk_mul_f32 v[14:15], v[12:13], v[14:15] op_sel_hi:[0,1]
	v_cvt_pk_bf16_f32 v9, v14, v15
	v_lshlrev_b32_e32 v14, 16, v10
	v_and_b32_e32 v15, 0xffff0000, v10
	v_pk_mul_f32 v[14:15], v[12:13], v[14:15] op_sel_hi:[0,1]
	v_cvt_pk_bf16_f32 v10, v14, v15
	v_lshlrev_b32_e32 v14, 16, v11
	v_and_b32_e32 v15, 0xffff0000, v11
	v_pk_mul_f32 v[12:13], v[12:13], v[14:15] op_sel_hi:[0,1]
	v_cvt_pk_bf16_f32 v11, v12, v13
	v_lshl_add_u64 v[12:13], v[82:83], 0, v[0:1]
	v_lshlrev_b64 v[12:13], 13, v[12:13]
	v_lshl_add_u64 v[12:13], v[2:3], 0, v[12:13]
	v_lshrrev_b32_e32 v0, 4, v49
	global_store_dwordx4 v[12:13], v[8:11], off
	s_nop 1
	v_mad_u64_u32 v[8:9], s[0:1], v0, s19, v[4:5]
	v_lshl_add_u32 v5, v0, 2, s18
	ds_read_b128 v[8:11], v8 offset:51456
	ds_read_b32 v5, v5
	s_waitcnt lgkmcnt(0)
	v_lshlrev_b32_e32 v14, 16, v8
	v_mul_f32_e32 v5, 0x3fb8aa3b, v5
	v_exp_f32_e32 v12, v5
	v_and_b32_e32 v15, 0xffff0000, v8
	v_pk_mul_f32 v[14:15], v[12:13], v[14:15] op_sel_hi:[0,1]
	v_cvt_pk_bf16_f32 v8, v14, v15
	v_lshlrev_b32_e32 v14, 16, v9
	v_and_b32_e32 v15, 0xffff0000, v9
	v_pk_mul_f32 v[14:15], v[12:13], v[14:15] op_sel_hi:[0,1]
	v_cvt_pk_bf16_f32 v9, v14, v15
	v_lshlrev_b32_e32 v14, 16, v10
	v_and_b32_e32 v15, 0xffff0000, v10
	v_pk_mul_f32 v[14:15], v[12:13], v[14:15] op_sel_hi:[0,1]
	v_cvt_pk_bf16_f32 v10, v14, v15
	v_lshlrev_b32_e32 v14, 16, v11
	v_and_b32_e32 v15, 0xffff0000, v11
	v_pk_mul_f32 v[12:13], v[12:13], v[14:15] op_sel_hi:[0,1]
	v_cvt_pk_bf16_f32 v11, v12, v13
	v_lshl_add_u64 v[12:13], v[82:83], 0, v[0:1]
	v_lshlrev_b64 v[12:13], 13, v[12:13]
	v_add_u32_e32 v0, 0x100, v49
	v_lshl_add_u64 v[12:13], v[2:3], 0, v[12:13]
	v_lshrrev_b32_e32 v0, 4, v0
	global_store_dwordx4 v[12:13], v[8:11], off
	s_nop 1
	v_mad_u64_u32 v[8:9], s[0:1], v0, s19, v[4:5]
	v_lshl_add_u32 v5, v0, 2, s18
	ds_read_b128 v[8:11], v8 offset:51456
	ds_read_b32 v5, v5
	s_waitcnt lgkmcnt(0)
	v_lshlrev_b32_e32 v14, 16, v8
	v_mul_f32_e32 v5, 0x3fb8aa3b, v5
	v_exp_f32_e32 v12, v5
	v_and_b32_e32 v15, 0xffff0000, v8
	v_pk_mul_f32 v[14:15], v[12:13], v[14:15] op_sel_hi:[0,1]
	v_cvt_pk_bf16_f32 v8, v14, v15
	v_lshlrev_b32_e32 v14, 16, v9
	v_and_b32_e32 v15, 0xffff0000, v9
	v_pk_mul_f32 v[14:15], v[12:13], v[14:15] op_sel_hi:[0,1]
	v_cvt_pk_bf16_f32 v9, v14, v15
	v_lshlrev_b32_e32 v14, 16, v10
	v_and_b32_e32 v15, 0xffff0000, v10
	v_pk_mul_f32 v[14:15], v[12:13], v[14:15] op_sel_hi:[0,1]
	v_cvt_pk_bf16_f32 v10, v14, v15
	v_lshlrev_b32_e32 v14, 16, v11
	v_and_b32_e32 v15, 0xffff0000, v11
	v_pk_mul_f32 v[12:13], v[12:13], v[14:15] op_sel_hi:[0,1]
	v_cvt_pk_bf16_f32 v11, v12, v13
	v_lshl_add_u64 v[12:13], v[82:83], 0, v[0:1]
	v_lshlrev_b64 v[12:13], 13, v[12:13]
	v_add_u32_e32 v0, 0x200, v49
	v_lshl_add_u64 v[12:13], v[2:3], 0, v[12:13]
	v_lshrrev_b32_e32 v0, 4, v0
	global_store_dwordx4 v[12:13], v[8:11], off
	v_mad_u64_u32 v[4:5], s[0:1], v0, s19, v[4:5]
	ds_read_b128 v[8:11], v4 offset:51456
	v_lshl_add_u32 v4, v0, 2, s18
	ds_read_b32 v4, v4
	s_movk_i32 s0, 0x1000
	v_cmp_gt_i32_e32 vcc, s0, v46
	s_waitcnt lgkmcnt(0)
	v_lshlrev_b32_e32 v12, 16, v8
	v_and_b32_e32 v13, 0xffff0000, v8
	v_mul_f32_e32 v4, 0x3fb8aa3b, v4
	v_exp_f32_e32 v4, v4
	s_nop 0
	v_pk_mul_f32 v[12:13], v[4:5], v[12:13] op_sel_hi:[0,1]
	v_cvt_pk_bf16_f32 v8, v12, v13
	v_lshlrev_b32_e32 v12, 16, v9
	v_and_b32_e32 v13, 0xffff0000, v9
	v_pk_mul_f32 v[12:13], v[4:5], v[12:13] op_sel_hi:[0,1]
	v_cvt_pk_bf16_f32 v9, v12, v13
	v_lshlrev_b32_e32 v12, 16, v10
	v_and_b32_e32 v13, 0xffff0000, v10
	v_pk_mul_f32 v[12:13], v[4:5], v[12:13] op_sel_hi:[0,1]
	v_cvt_pk_bf16_f32 v10, v12, v13
	v_lshlrev_b32_e32 v12, 16, v11
	v_and_b32_e32 v13, 0xffff0000, v11
	v_pk_mul_f32 v[4:5], v[4:5], v[12:13] op_sel_hi:[0,1]
	v_cvt_pk_bf16_f32 v11, v4, v5
	v_lshl_add_u64 v[4:5], v[82:83], 0, v[0:1]
	v_lshlrev_b64 v[4:5], 13, v[4:5]
	v_lshl_add_u64 v[2:3], v[2:3], 0, v[4:5]
	global_store_dwordx4 v[2:3], v[8:11], off
	s_and_saveexec_b64 s[24:25], vcc
	s_cbranch_execz .LBB0_190
	v_readfirstlane_b32 s26, v46
	s_and_b32 s27, s26, 63
	s_bfe_u32 s28, s26, 0x30006
	s_lshl_b32 s28, s28, 8
	s_lshr_b32 s29, s26, 9
	s_lshl_b32 s30, s29, 12
	s_lshl_b32 s31, s27, 6
	s_add_i32 s30, s30, s31
	s_add_i32 s30, s30, -3
	s_lshl_b32 s34, s30, 13
	s_ashr_i32 s35, s30, 31
	s_add_u32 s34, s34, s74
	s_addc_u32 s35, s35, s75
	s_add_u32 s34, s34, s28
	s_addc_u32 s35, s35, 0
	s_mov_b32 s26, 0xaaaaaaab
	v_add_u32_e32 v202, 0xffffff00, v49
	v_lshlrev_b32_e32 v227, 4, v202
	v_add_u32_e32 v203, 2304, v202
	v_mul_hi_u32 v204, v203, s26
	v_lshrrev_b32_e32 v204, 5, v204
	v_mul_u32_u24_e32 v220, 48, v204
	v_sub_u32_e32 v220, v203, v220
	v_lshrrev_b32_e32 v221, 4, v220
	v_mul_u32_u24_e32 v221, 0x700, v221
	v_lshl_add_u32 v221, v220, 4, v221
	v_lshl_add_u32 v221, v204, 13, v221
	global_load_dwordx4 v[2:5], v221, s[34:35]
	v_add_u32_e32 v203, 2560, v202
	v_mul_hi_u32 v204, v203, s26
	v_lshrrev_b32_e32 v204, 5, v204
	v_mul_u32_u24_e32 v220, 48, v204
	v_sub_u32_e32 v220, v203, v220
	v_lshrrev_b32_e32 v221, 4, v220
	v_mul_u32_u24_e32 v221, 0x700, v221
	v_lshl_add_u32 v221, v220, 4, v221
	v_lshl_add_u32 v221, v204, 13, v221
	global_load_dwordx4 v[6:9], v221, s[34:35]
	v_add_u32_e32 v203, 2816, v202
	v_mul_hi_u32 v204, v203, s26
	v_lshrrev_b32_e32 v204, 5, v204
	v_mul_u32_u24_e32 v220, 48, v204
	v_sub_u32_e32 v220, v203, v220
	v_lshrrev_b32_e32 v221, 4, v220
	v_mul_u32_u24_e32 v221, 0x700, v221
	v_lshl_add_u32 v221, v220, 4, v221
	v_lshl_add_u32 v221, v204, 13, v221
	global_load_dwordx4 v[10:13], v221, s[34:35]
	s_mov_b64 s[28:29], exec
	v_cmp_gt_u32_e32 vcc, 0x90, v202
	s_and_b64 exec, s[28:29], vcc
	s_cbranch_execz .Lrl_l_no12
	v_add_u32_e32 v203, 3072, v202
	v_mul_hi_u32 v204, v203, s26
	v_lshrrev_b32_e32 v204, 5, v204
	v_mul_u32_u24_e32 v220, 48, v204
	v_sub_u32_e32 v220, v203, v220
	v_lshrrev_b32_e32 v221, 4, v220
	v_mul_u32_u24_e32 v221, 0x700, v221
	v_lshl_add_u32 v221, v220, 4, v221
	v_lshl_add_u32 v221, v204, 13, v221
	global_load_dwordx4 v[14:17], v221, s[34:35]

.LBB0_194:
	s_andn2_saveexec_b64 s[0:1], s[0:1]
	s_cbranch_execz .LBB0_42
	v_lshrrev_b32_e32 v47, 1, v49
	v_or_b32_e32 v174, v82, v47
	v_mov_b32_e32 v175, v83
	v_lshlrev_b64 v[174:175], 13, v[174:175]
	v_lshl_add_u64 v[174:175], s[74:75], 0, v[174:175]
	v_lshlrev_b32_e32 v176, 1, v84
	v_mov_b32_e32 v177, v1
	v_lshlrev_b32_e32 v47, 7, v49
	v_lshl_add_u64 v[174:175], v[174:175], 0, v[176:177]
	v_and_b32_e32 v176, 0x80, v47
	v_lshl_add_u64 v[178:179], v[174:175], 0, v[176:177]
	s_mov_b64 s[18:19], 0x1000
	v_lshl_add_u64 v[180:181], v[178:179], 0, s[18:19]
	s_movk_i32 s18, 0x1000
	v_cvt_pk_bf16_f32 v175, v4, v5
	v_add_co_u32_e32 v4, vcc, s18, v178
	v_cvt_pk_bf16_f32 v174, v0, v3
	v_cvt_pk_bf16_f32 v176, v6, v7
	v_cvt_pk_bf16_f32 v177, v8, v9
	v_addc_co_u32_e32 v5, vcc, 0, v179, vcc
	global_store_dwordx4 v[4:5], v[174:177], off
	v_cvt_pk_bf16_f32 v4, v10, v11
	v_cvt_pk_bf16_f32 v5, v12, v13
	v_cvt_pk_bf16_f32 v6, v14, v15
	v_cvt_pk_bf16_f32 v7, v16, v17
	global_store_dwordx4 v[180:181], v[4:7], off offset:16
	s_nop 1
	v_cvt_pk_bf16_f32 v4, v18, v19
	v_cvt_pk_bf16_f32 v5, v20, v21
	v_cvt_pk_bf16_f32 v6, v22, v23
	v_cvt_pk_bf16_f32 v7, v24, v25
	global_store_dwordx4 v[180:181], v[4:7], off offset:32
	s_nop 1
	v_cvt_pk_bf16_f32 v4, v26, v27
	v_cvt_pk_bf16_f32 v5, v28, v29
	v_cvt_pk_bf16_f32 v6, v30, v31
	v_cvt_pk_bf16_f32 v7, v32, v33
	global_store_dwordx4 v[180:181], v[4:7], off offset:48
	s_nop 1
	v_cvt_pk_bf16_f32 v4, v34, v35
	v_cvt_pk_bf16_f32 v5, v36, v37
	v_cvt_pk_bf16_f32 v6, v86, v87
	v_cvt_pk_bf16_f32 v7, v88, v89
	global_store_dwordx4 v[180:181], v[4:7], off offset:64
	s_nop 1
	v_cvt_pk_bf16_f32 v4, v90, v91
	v_cvt_pk_bf16_f32 v5, v92, v93
	v_cvt_pk_bf16_f32 v6, v94, v95
	v_cvt_pk_bf16_f32 v7, v96, v97
	global_store_dwordx4 v[180:181], v[4:7], off offset:80
	s_nop 1
	v_cvt_pk_bf16_f32 v4, v98, v99
	v_cvt_pk_bf16_f32 v5, v100, v101
	v_cvt_pk_bf16_f32 v6, v102, v103
	v_cvt_pk_bf16_f32 v7, v104, v105
	global_store_dwordx4 v[180:181], v[4:7], off offset:96
	s_nop 1
	v_cvt_pk_bf16_f32 v4, v106, v107
	v_cvt_pk_bf16_f32 v5, v108, v109
	v_cvt_pk_bf16_f32 v6, v110, v111
	v_cvt_pk_bf16_f32 v7, v112, v2
	global_store_dwordx4 v[180:181], v[4:7], off offset:112
	s_branch .LBB0_42

.LBB0_203:
	s_or_b64 exec, exec, s[6:7]
	v_mad_i32_i24 v9, v10, 3, v9
	v_mov_b64_e32 v[10:11], s[2:3]
	s_movk_i32 s6, 0x1800
	v_mad_i64_i32 v[10:11], s[6:7], v9, s6, v[10:11]
	v_add_u32_e32 v0, s8, v0
	s_mov_b32 s6, 0x8ffff
	v_cmp_lt_i32_e32 vcc, s6, v0
	v_lshl_add_u64 v[6:7], v[6:7], 1, v[10:11]
	s_or_b64 s[4:5], vcc, s[4:5]
	v_add_u32_e32 v8, s9, v8
	s_waitcnt vmcnt(0) lgkmcnt(0)
	global_store_dwordx4 v[6:7], v[2:5], off
	s_andn2_b64 exec, exec, s[4:5]
	s_cbranch_execz .LBB0_208
.LBB0_204:
	v_mul_hi_i32 v2, v0, s92
	s_waitcnt lgkmcnt(0)
	v_lshrrev_b32_e32 v3, 31, v2
	v_ashrrev_i32_e32 v2, 6, v2
	v_add_u32_e32 v2, v2, v3
	s_mov_b32 s6, 0x55555556
	v_mul_hi_i32 v4, v2, s6
	v_lshrrev_b32_e32 v5, 31, v4
	v_add_u32_e32 v4, v4, v5
	v_lshl_add_u32 v4, v4, 1, v4
	s_mov_b32 s6, 0x38e38e39
	v_mul_i32_i24_e32 v3, 0x180, v2
	v_sub_u32_e32 v9, v2, v4
	v_mul_hi_i32 v2, v0, s6
	v_lshrrev_b32_e32 v4, 31, v2
	v_ashrrev_i32_e32 v2, 8, v2
	v_add_u32_e32 v10, v2, v4
	v_and_b32_e32 v2, 63, v10
	v_cmp_ne_u32_e32 vcc, 0, v2
	v_lshlrev_b32_e32 v2, 3, v3
	v_sub_u32_e32 v6, v8, v2
	s_and_saveexec_b64 s[6:7], vcc
	s_xor_b64 s[6:7], exec, s[6:7]
	s_cbranch_execz .LBB0_206
	v_lshlrev_b32_e32 v2, 6, v10
	v_add3_u32 v2, v2, v9, -3
	v_ashrrev_i32_e32 v3, 31, v2
	v_lshlrev_b64 v[2:3], 13, v[2:3]
	v_lshl_add_u64 v[2:3], s[74:75], 0, v[2:3]
	v_ashrrev_i32_e32 v7, 31, v6
	v_lshl_add_u64 v[2:3], v[6:7], 1, v[2:3]
	global_load_dwordx4 v[2:5], v[2:3], off

.LBB0_214:
	v_mul_f32_e32 v0, 0xbfb8aa3b, v155
	v_exp_f32_e32 v0, v0
	s_waitcnt lgkmcnt(0)
	s_barrier
	v_add_f32_e32 v0, 1.0, v0
	v_div_scale_f32 v98, s[0:1], v0, v0, 1.0
	v_rcp_f32_e32 v99, v98
	s_add_i32 s90, s90, s63
	s_cmpk_gt_i32 s90, 0x7ff
	v_fma_f32 v100, -v98, v99, 1.0
	v_fmac_f32_e32 v99, v100, v99
	v_div_scale_f32 v100, vcc, 1.0, v0, 1.0
	v_mul_f32_e32 v101, v100, v99
	v_fma_f32 v102, -v98, v101, v100
	v_fmac_f32_e32 v101, v102, v99
	v_fma_f32 v98, -v98, v101, v100
	v_div_fmas_f32 v98, v98, v99, v101
	v_div_fixup_f32 v0, v98, v0, 1.0
	v_add_f32_e32 v98, v146, v148
	v_div_scale_f32 v99, s[0:1], v98, v98, v0
	v_rcp_f32_e32 v100, v99
	s_nop 0
	v_fma_f32 v101, -v99, v100, 1.0
	v_fmac_f32_e32 v100, v101, v100
	v_div_scale_f32 v101, vcc, v0, v98, v0
	v_mul_f32_e32 v102, v101, v100
	v_fma_f32 v103, -v99, v102, v101
	v_fmac_f32_e32 v102, v103, v100
	v_fma_f32 v99, -v99, v102, v101
	v_div_fmas_f32 v99, v99, v100, v102
	v_div_fixup_f32 v0, v99, v98, v0
	v_pk_mul_f32 v[34:35], v[34:35], v[0:1] op_sel_hi:[1,0]
	v_pk_mul_f32 v[50:51], v[50:51], v[0:1] op_sel_hi:[1,0]
	v_pk_mul_f32 v[36:37], v[36:37], v[0:1] op_sel_hi:[1,0]
	v_pk_mul_f32 v[52:53], v[52:53], v[0:1] op_sel_hi:[1,0]
	v_pk_mul_f32 v[38:39], v[38:39], v[0:1] op_sel_hi:[1,0]
	v_pk_mul_f32 v[54:55], v[54:55], v[0:1] op_sel_hi:[1,0]
	v_pk_mul_f32 v[40:41], v[40:41], v[0:1] op_sel_hi:[1,0]
	v_pk_mul_f32 v[56:57], v[56:57], v[0:1] op_sel_hi:[1,0]
	v_pk_mul_f32 v[42:43], v[42:43], v[0:1] op_sel_hi:[1,0]
	v_pk_mul_f32 v[58:59], v[58:59], v[0:1] op_sel_hi:[1,0]
	v_pk_mul_f32 v[44:45], v[44:45], v[0:1] op_sel_hi:[1,0]
	v_pk_mul_f32 v[60:61], v[60:61], v[0:1] op_sel_hi:[1,0]
	v_pk_mul_f32 v[46:47], v[46:47], v[0:1] op_sel_hi:[1,0]
	v_pk_mul_f32 v[62:63], v[62:63], v[0:1] op_sel_hi:[1,0]
	v_pk_mul_f32 v[48:49], v[48:49], v[0:1] op_sel_hi:[1,0]
	v_pk_mul_f32 v[64:65], v[64:65], v[0:1] op_sel_hi:[1,0]
	v_mul_f32_e32 v0, 0xbfb8aa3b, v156
	v_exp_f32_e32 v0, v0
	s_nop 0
	v_add_f32_e32 v0, 1.0, v0
	v_div_scale_f32 v98, s[0:1], v0, v0, 1.0
	v_rcp_f32_e32 v99, v98
	s_nop 0
	v_fma_f32 v100, -v98, v99, 1.0
	v_fmac_f32_e32 v99, v100, v99
	v_div_scale_f32 v100, vcc, 1.0, v0, 1.0
	v_mul_f32_e32 v101, v100, v99
	v_fma_f32 v102, -v98, v101, v100
	v_fmac_f32_e32 v101, v102, v99
	v_fma_f32 v98, -v98, v101, v100
	v_div_fmas_f32 v98, v98, v99, v101
	v_div_fixup_f32 v98, v98, v0, 1.0
	v_mul_f32_e32 v0, 0xbfb8aa3b, v154
	v_exp_f32_e32 v0, v0
	s_nop 0
	v_add_f32_e32 v0, 1.0, v0
	v_div_scale_f32 v99, s[0:1], v0, v0, 1.0
	v_rcp_f32_e32 v100, v99
	s_nop 0
	v_fma_f32 v101, -v99, v100, 1.0
	v_fmac_f32_e32 v100, v101, v100
	v_div_scale_f32 v101, vcc, 1.0, v0, 1.0
	v_mul_f32_e32 v102, v101, v100
	v_fma_f32 v103, -v99, v102, v101
	v_fmac_f32_e32 v102, v103, v100
	v_fma_f32 v99, -v99, v102, v101
	v_div_fmas_f32 v99, v99, v100, v102
	v_div_fixup_f32 v0, v99, v0, 1.0
	v_mul_f32_e32 v0, v0, v140
	v_pk_fma_f32 v[2:3], v[2:3], v[0:1], v[34:35] op_sel_hi:[1,0,1]
	v_pk_fma_f32 v[18:19], v[18:19], v[0:1], v[50:51] op_sel_hi:[1,0,1]
	v_pk_fma_f32 v[4:5], v[4:5], v[0:1], v[36:37] op_sel_hi:[1,0,1]
	v_pk_fma_f32 v[20:21], v[20:21], v[0:1], v[52:53] op_sel_hi:[1,0,1]
	v_pk_fma_f32 v[6:7], v[6:7], v[0:1], v[38:39] op_sel_hi:[1,0,1]
	v_pk_fma_f32 v[22:23], v[22:23], v[0:1], v[54:55] op_sel_hi:[1,0,1]
	v_pk_fma_f32 v[8:9], v[8:9], v[0:1], v[40:41] op_sel_hi:[1,0,1]
	v_pk_fma_f32 v[24:25], v[24:25], v[0:1], v[56:57] op_sel_hi:[1,0,1]
	v_pk_fma_f32 v[10:11], v[10:11], v[0:1], v[42:43] op_sel_hi:[1,0,1]
	v_pk_fma_f32 v[26:27], v[26:27], v[0:1], v[58:59] op_sel_hi:[1,0,1]
	v_pk_fma_f32 v[12:13], v[12:13], v[0:1], v[44:45] op_sel_hi:[1,0,1]
	v_pk_fma_f32 v[28:29], v[28:29], v[0:1], v[60:61] op_sel_hi:[1,0,1]
	v_pk_fma_f32 v[14:15], v[14:15], v[0:1], v[46:47] op_sel_hi:[1,0,1]
	v_pk_fma_f32 v[30:31], v[30:31], v[0:1], v[62:63] op_sel_hi:[1,0,1]
	v_pk_fma_f32 v[16:17], v[16:17], v[0:1], v[48:49] op_sel_hi:[1,0,1]
	v_pk_fma_f32 v[32:33], v[32:33], v[0:1], v[64:65] op_sel_hi:[1,0,1]
	v_mov_b32_e32 v0, v222
	s_nop 0
	v_lshlrev_b32_e32 v0, 2, v0
	v_xor_b32_e32 v0, 0x80, v0
	ds_bpermute_b32 v0, v0, v147
	s_waitcnt lgkmcnt(0)
	v_add_f32_e32 v0, v147, v0
	v_div_scale_f32 v34, s[0:1], v0, v0, v98
	v_rcp_f32_e32 v35, v34
	v_readlane_b32 s0, v254, 21
	v_readlane_b32 s1, v254, 22
	v_fma_f32 v36, -v34, v35, 1.0
	v_fmac_f32_e32 v35, v36, v35
	v_div_scale_f32 v36, vcc, v98, v0, v98
	v_mul_f32_e32 v37, v36, v35
	v_fma_f32 v38, -v34, v37, v36
	v_fmac_f32_e32 v37, v38, v35
	v_fma_f32 v34, -v34, v37, v36
	v_div_fmas_f32 v34, v34, v35, v37
	v_lshlrev_b64 v[36:37], 11, v[190:191]
	v_div_fixup_f32 v34, v34, v0, v98
	v_lshl_add_u64 v[36:37], s[0:1], 0, v[36:37]
	v_lshlrev_b32_e32 v0, 7, v189
	v_lshl_add_u64 v[36:37], v[36:37], 0, v[0:1]
	v_mov_b32_e32 v189, v1
	v_pk_fma_f32 v[2:3], v[82:83], v[34:35], v[2:3] op_sel_hi:[1,0,1]
	v_pk_fma_f32 v[4:5], v[84:85], v[34:35], v[4:5] op_sel_hi:[1,0,1]
	v_lshl_add_u64 v[36:37], v[36:37], 0, v[188:189]
	v_cvt_pk_bf16_f32 v2, v2, v3
	v_cvt_pk_bf16_f32 v3, v4, v5
	global_store_dwordx2 v[36:37], v[2:3], off
	v_pk_fma_f32 v[2:3], v[86:87], v[34:35], v[6:7] op_sel_hi:[1,0,1]
	v_pk_fma_f32 v[4:5], v[88:89], v[34:35], v[8:9] op_sel_hi:[1,0,1]
	v_cvt_pk_bf16_f32 v2, v2, v3
	v_cvt_pk_bf16_f32 v3, v4, v5
	global_store_dwordx2 v[36:37], v[2:3], off offset:16
	v_pk_fma_f32 v[2:3], v[90:91], v[34:35], v[10:11] op_sel_hi:[1,0,1]
	v_pk_fma_f32 v[4:5], v[92:93], v[34:35], v[12:13] op_sel_hi:[1,0,1]
	v_cvt_pk_bf16_f32 v2, v2, v3
	v_cvt_pk_bf16_f32 v3, v4, v5
	global_store_dwordx2 v[36:37], v[2:3], off offset:32
	v_pk_fma_f32 v[2:3], v[94:95], v[34:35], v[14:15] op_sel_hi:[1,0,1]
	v_pk_fma_f32 v[4:5], v[96:97], v[34:35], v[16:17] op_sel_hi:[1,0,1]
	v_cvt_pk_bf16_f32 v2, v2, v3
	v_cvt_pk_bf16_f32 v3, v4, v5
	global_store_dwordx2 v[36:37], v[2:3], off offset:48
	v_pk_fma_f32 v[2:3], v[66:67], v[34:35], v[18:19] op_sel_hi:[1,0,1]
	v_pk_fma_f32 v[4:5], v[68:69], v[34:35], v[20:21] op_sel_hi:[1,0,1]
	v_cvt_pk_bf16_f32 v2, v2, v3
	v_cvt_pk_bf16_f32 v3, v4, v5
	global_store_dwordx2 v[36:37], v[2:3], off offset:64
	v_pk_fma_f32 v[2:3], v[70:71], v[34:35], v[22:23] op_sel_hi:[1,0,1]
	v_pk_fma_f32 v[4:5], v[72:73], v[34:35], v[24:25] op_sel_hi:[1,0,1]
	v_cvt_pk_bf16_f32 v2, v2, v3
	v_cvt_pk_bf16_f32 v3, v4, v5
	global_store_dwordx2 v[36:37], v[2:3], off offset:80
	v_pk_fma_f32 v[2:3], v[74:75], v[34:35], v[26:27] op_sel_hi:[1,0,1]
	v_pk_fma_f32 v[4:5], v[76:77], v[34:35], v[28:29] op_sel_hi:[1,0,1]
	v_cvt_pk_bf16_f32 v2, v2, v3
	v_cvt_pk_bf16_f32 v3, v4, v5
	global_store_dwordx2 v[36:37], v[2:3], off offset:96
	v_pk_fma_f32 v[2:3], v[78:79], v[34:35], v[30:31] op_sel_hi:[1,0,1]
	v_pk_fma_f32 v[4:5], v[80:81], v[34:35], v[32:33] op_sel_hi:[1,0,1]
	v_cvt_pk_bf16_f32 v2, v2, v3
	v_cvt_pk_bf16_f32 v3, v4, v5
	global_store_dwordx2 v[36:37], v[2:3], off offset:112
	s_cbranch_scc1 .LBB0_404

.LBB0_217:
	s_or_b64 exec, exec, s[0:1]
	s_abs_i32 s1, s90
	s_mul_hi_u32 s8, s1, s89
	s_mul_i32 s9, s8, s88
	s_ashr_i32 s0, s90, 31
	s_sub_i32 s1, s1, s9
	s_xor_b32 s0, s0, s71
	s_add_i32 s9, s8, 1
	s_sub_i32 s10, s1, s88
	s_cmp_ge_u32 s1, s88
	s_cselect_b32 s8, s9, s8
	s_cselect_b32 s1, s10, s1
	s_add_i32 s9, s8, 1
	s_cmp_ge_u32 s1, s88
	s_cselect_b32 s1, s9, s8
	s_xor_b32 s1, s1, s0
	s_sub_i32 s0, s1, s0
	s_mul_i32 s1, s0, s63
	s_sub_i32 s8, s90, s1
	s_ashr_i32 s1, s8, 5
	s_not_b32 s10, s1
	s_mul_i32 s9, s0, s34
	s_and_b32 s0, s0, 1
	s_add_i32 s10, s34, s10
	s_cmp_eq_u32 s0, 0
	s_cselect_b32 s0, s1, s10
	s_add_i32 s9, s0, s9
	s_ashr_i32 s10, s90, 5
	s_and_b64 s[0:1], s[84:85], exec
	s_cselect_b32 s0, s8, s90
	s_cselect_b32 s67, s9, s10
	s_and_b32 s68, s0, 31
	s_bfe_u32 s1, s0, 0x30002
	s_lshl_b32 s0, s0, 2
	s_lshl_b32 s91, s67, 6
	s_lshl_b32 s94, s1, 12
	s_lshl_b32 s1, s1, 4
	s_and_b32 s8, s0, 12
	s_add_i32 s91, s91, s35
	s_or_b32 s0, s1, s8
	v_or_b32_e32 v192, s91, v195
	v_or_b32_e32 v0, s0, v201
	v_ashrrev_i32_e32 v193, 31, v192
	v_lshlrev_b32_e32 v0, 12, v0
	v_lshl_add_u64 v[2:3], v[192:193], 0, v[0:1]
	v_lshlrev_b64 v[2:3], 7, v[2:3]
	v_lshl_add_u64 v[190:191], v[192:193], 0, s[94:95]
	v_lshl_add_u64 v[2:3], v[172:173], 0, v[2:3]
	global_load_dwordx4 v[110:113], v[2:3], off
	global_load_dwordx4 v[82:85], v[2:3], off offset:32
	global_load_dwordx4 v[114:117], v[2:3], off offset:64
	global_load_dwordx4 v[86:89], v[2:3], off offset:96
	v_lshlrev_b64 v[2:3], 8, v[190:191]
	v_lshl_add_u64 v[2:3], v[174:175], 0, v[2:3]
	global_load_dwordx4 v[126:129], v[2:3], off
	global_load_dwordx4 v[122:125], v[2:3], off offset:16
	global_load_dwordx4 v[118:121], v[2:3], off offset:32
	global_load_dwordx4 v[106:109], v[2:3], off offset:48
	global_load_dwordx4 v[102:105], v[2:3], off offset:128
	global_load_dwordx4 v[98:101], v[2:3], off offset:144
	global_load_dwordx4 v[94:97], v[2:3], off offset:160
	global_load_dwordx4 v[90:93], v[2:3], off offset:176
	v_mov_b64_e32 v[2:3], s[82:83]
	s_movk_i32 s9, 0xc0
	v_mad_u64_u32 v[2:3], s[0:1], v190, s9, v[2:3]
	s_sub_i32 s0, s91, 24
	s_ashr_i32 s10, s0, 4
	s_lshl_b32 s0, s67, 2
	s_addk_i32 s0, 0x42
	v_or_b32_e32 v189, s8, v201
	s_ashr_i32 s8, s0, 6
	s_lshl_b64 s[0:1], -1, s8
	s_or_b32 s61, s91, 7
	s_not_b64 s[0:1], s[0:1]
	s_cmp_lt_i32 s8, 64
	v_mul_u32_u24_e32 v0, 3, v189
	s_cselect_b32 s1, s1, -1
	s_cselect_b32 s0, s0, -1
	s_lshl_b32 s94, s68, 15
	v_mad_i32_i24 v3, v191, s9, v3
	v_lshlrev_b32_e32 v0, 2, v0
	s_add_u32 s8, s38, s94
	v_lshl_add_u64 v[2:3], v[2:3], 0, v[0:1]
	s_addc_u32 s9, s39, 0
	s_ff1_i32_b64 s26, s[0:1]
	global_load_dwordx3 v[154:156], v[2:3], off
	s_cmp_gt_i32 s61, 30
	v_lshl_add_u32 v2, s26, 6, v176
	s_cselect_b32 s19, s10, -1
	s_sub_i32 s10, s91, 31
	v_ashrrev_i32_e32 v3, 31, v2
	s_ashr_i32 s10, s10, 4
	v_lshlrev_b64 v[2:3], 7, v[2:3]
	s_cmp_gt_i32 s91, 30
	v_lshl_add_u64 v[2:3], s[8:9], 0, v[2:3]
	v_mov_b32_e32 v187, v1
	s_cselect_b32 s24, s10, -1
	s_add_u32 s10, s0, -1
	v_lshl_add_u64 v[2:3], v[2:3], 0, v[186:187]
	s_addc_u32 s11, s1, -1
	s_waitcnt vmcnt(0)
	global_load_dwordx4 v[130:133], v[2:3], off
	v_lshl_add_u64 v[2:3], v[178:179], 0, s[94:95]
	s_lshl_b32 s94, s26, 7
	v_lshl_add_u64 v[4:5], v[2:3], 0, s[94:95]
	v_lshl_add_u64 v[4:5], v[4:5], 0, v[186:187]
	global_load_dwordx4 v[134:137], v[4:5], off
	v_subrev_u32_e32 v0, 31, v192
	v_ashrrev_i32_e32 v0, 4, v0
	v_cmp_lt_i32_e32 vcc, 30, v192
	v_add_u32_e32 v0, 1, v0
	v_lshl_add_u64 v[198:199], v[2:3], 0, v[186:187]
	v_mov_b32_e32 v2, v1
	v_mov_b32_e32 v3, v1
	v_mov_b32_e32 v4, v1
	v_mov_b32_e32 v5, v1
	v_mov_b32_e32 v6, v1
	v_mov_b32_e32 v7, v1
	v_mov_b32_e32 v8, v1
	v_mov_b32_e32 v9, v1
	v_mov_b32_e32 v10, v1
	v_mov_b32_e32 v11, v1
	v_mov_b32_e32 v12, v1
	v_mov_b32_e32 v13, v1
	v_mov_b32_e32 v14, v1
	v_mov_b32_e32 v15, v1
	v_mov_b32_e32 v16, v1
	v_mov_b32_e32 v17, v1
	v_mov_b32_e32 v18, v1
	v_mov_b32_e32 v19, v1
	v_mov_b32_e32 v20, v1
	v_mov_b32_e32 v21, v1
	v_mov_b32_e32 v22, v1
	v_mov_b32_e32 v23, v1
	v_mov_b32_e32 v24, v1
	v_mov_b32_e32 v25, v1
	v_mov_b32_e32 v26, v1
	v_mov_b32_e32 v27, v1
	v_mov_b32_e32 v28, v1
	v_mov_b32_e32 v29, v1
	v_mov_b32_e32 v30, v1
	v_mov_b32_e32 v31, v1
	v_mov_b32_e32 v48, v1
	v_mov_b32_e32 v49, v1
	v_cndmask_b32_e32 v194, 0, v0, vcc
	v_mov_b32_e32 v0, v1
	v_mov_b32_e32 v34, v1
	v_mov_b32_e32 v35, v1
	v_mov_b32_e32 v36, v1
	v_mov_b32_e32 v37, v1
	v_mov_b32_e32 v38, v1
	v_mov_b32_e32 v39, v1
	v_mov_b32_e32 v40, v1
	v_mov_b32_e32 v41, v1
	v_mov_b32_e32 v42, v1
	v_mov_b32_e32 v43, v1
	v_mov_b32_e32 v44, v1
	v_mov_b32_e32 v45, v1
	v_mov_b32_e32 v46, v1
	v_mov_b32_e32 v47, v1
	v_mov_b64_e32 v[64:65], v[48:49]
	v_mov_b64_e32 v[32:33], v[30:31]
	s_mov_b32 s18, 0
	s_and_b64 s[20:21], s[10:11], s[0:1]
	v_lshl_add_u64 v[196:197], s[8:9], 0, v[186:187]
	v_add_u32_e32 v157, -1, v194
	v_cmp_lt_i32_e64 s[8:9], 0, v194
	v_cmp_gt_i32_e64 s[10:11], 1, v194
	v_mov_b32_e32 v200, v194
	v_mov_b32_e32 v167, v194
	v_mov_b32_e32 v209, 0xf149f2ca
	v_mov_b32_e32 v187, 0
	v_mov_b64_e32 v[62:63], v[46:47]
	v_mov_b64_e32 v[60:61], v[44:45]
	v_mov_b64_e32 v[58:59], v[42:43]
	v_mov_b64_e32 v[56:57], v[40:41]
	v_mov_b64_e32 v[54:55], v[38:39]
	v_mov_b64_e32 v[52:53], v[36:37]
	v_mov_b64_e32 v[50:51], v[34:35]
	v_mov_b64_e32 v[30:31], v[28:29]
	v_mov_b64_e32 v[28:29], v[26:27]
	v_mov_b64_e32 v[26:27], v[24:25]
	v_mov_b64_e32 v[24:25], v[22:23]
	v_mov_b64_e32 v[22:23], v[20:21]
	v_mov_b64_e32 v[20:21], v[18:19]
	v_mov_b64_e32 v[18:19], v[16:17]
	v_mov_b64_e32 v[16:17], v[14:15]
	v_mov_b64_e32 v[14:15], v[12:13]
	v_mov_b64_e32 v[12:13], v[10:11]
	v_mov_b64_e32 v[10:11], v[8:9]
	v_mov_b64_e32 v[8:9], v[6:7]
	v_mov_b64_e32 v[6:7], v[4:5]
	v_mov_b64_e32 v[4:5], v[2:3]
	v_mov_b64_e32 v[2:3], v[0:1]
	s_waitcnt vmcnt(0) lgkmcnt(0)
	ds_write_b128 v203, v[130:133]
	ds_write_b128 v203, v[134:137] offset:9216
	s_branch .LBB0_221

.LBB0_221:
	s_waitcnt lgkmcnt(0)
	s_barrier
	s_cmp_lg_u64 s[20:21], 0
	s_mov_b64 s[0:1], 0
	s_cselect_b64 s[12:13], -1, 0
	s_cmp_eq_u64 s[20:21], 0
	s_mov_b32 s25, 0
	s_cbranch_scc1 .LBB0_223
	s_ff1_i32_b64 s25, s[20:21]
	v_lshl_add_u32 v66, s25, 6, v176
	v_ashrrev_i32_e32 v67, 31, v66
	s_add_u32 s0, s20, -1
	v_lshlrev_b64 v[66:67], 7, v[66:67]
	s_addc_u32 s1, s21, -1
	v_lshl_add_u64 v[66:67], v[196:197], 0, v[66:67]
	s_lshl_b32 s94, s25, 7
	v_lshl_add_u64 v[68:69], v[198:199], 0, s[94:95]
	s_waitcnt vmcnt(0) lgkmcnt(0)
	global_load_dwordx4 v[130:133], v[66:67], off
	global_load_dwordx4 v[134:137], v[68:69], off
	s_and_b64 s[0:1], s[0:1], s[20:21]
.LBB0_223:
	s_mul_i32 s20, s18, 0x4800
	s_add_i32 s20, s20, 0
	s_lshl_b32 s26, s26, 6
	v_add_u32_e32 v0, s20, v170
	v_add_u32_e32 v193, s20, v171
	s_cmp_gt_i32 s26, s19
	v_add_u32_e32 v211, v0, v204
	s_cbranch_scc1 .LBB0_231
	s_lshl_b32 s94, s26, 1
	v_lshl_add_u64 v[66:67], v[180:181], 0, s[94:95]
	global_load_dwordx4 v[146:149], v[66:67], off
	global_load_dwordx4 v[142:145], v[66:67], off offset:32
	v_add_co_u32_e32 v66, vcc, 0x4000, v66
	s_or_b32 s20, s26, 31
	s_nop 0
	v_addc_co_u32_e32 v67, vcc, 0, v67, vcc
	global_load_dwordx4 v[150:153], v[66:67], off
	global_load_dwordx4 v[138:141], v[66:67], off offset:32
	ds_read_b128 v[66:69], v211
	ds_read_b128 v[212:215], v211 offset:32
	s_cmp_le_i32 s20, s24
	s_mov_b64 s[20:21], -1
	s_waitcnt lgkmcnt(0)
	v_mfma_f32_32x32x16_bf16 v[66:81], v[66:69], v[110:113], 0
	v_mfma_f32_32x32x16_bf16 v[66:81], v[212:215], v[82:85], v[66:81]
	ds_read_b128 v[212:215], v211 offset:64
	s_waitcnt lgkmcnt(0)
	v_mfma_f32_32x32x16_bf16 v[66:81], v[212:215], v[114:117], v[66:81]
	ds_read_b128 v[212:215], v211 offset:96
	s_waitcnt lgkmcnt(0)
	v_mfma_f32_32x32x16_bf16 v[66:81], v[212:215], v[86:89], v[66:81]
	s_cbranch_scc0 .LBB0_240
	s_nop 10
	v_max3_f32 v0, v66, s72, v67
	v_max3_f32 v0, v0, v68, v69
	v_max3_f32 v0, v0, v70, v71
	v_max3_f32 v0, v0, v72, v73
	v_max3_f32 v0, v0, v74, v75
	v_max3_f32 v0, v0, v76, v77
	v_max3_f32 v0, v0, v78, v79
	v_mov_b32_e32 v210, v222
	v_max3_f32 v0, v0, v80, v81
	v_mul_f32_e32 v0, 0x3e38aa3b, v0
	v_lshlrev_b32_e32 v210, 2, v210
	v_cndmask_b32_e64 v0, v230, v0, s[8:9]
	v_xor_b32_e32 v210, 0x80, v210
	ds_bpermute_b32 v210, v210, v0
	s_waitcnt lgkmcnt(0)
	v_max3_f32 v210, v209, v0, v210
	v_fma_f32 v0, v66, s36, -v210
	v_exp_f32_e32 v213, v0
	v_fma_f32 v0, v67, s36, -v210
	v_exp_f32_e32 v212, v0
	v_fma_f32 v0, v68, s36, -v210
	v_exp_f32_e32 v215, v0
	v_fma_f32 v0, v69, s36, -v210
	v_exp_f32_e32 v214, v0
	v_fma_f32 v216, v70, s36, -v210
	v_add_f32_e32 v0, 0, v213
	v_exp_f32_e32 v217, v216
	v_fma_f32 v216, v71, s36, -v210
	v_add_f32_e32 v0, v212, v0
	v_exp_f32_e32 v216, v216
	v_fma_f32 v220, v72, s36, -v210
	v_add_f32_e32 v0, v215, v0
	v_exp_f32_e32 v239, v220
	v_fma_f32 v220, v73, s36, -v210
	v_add_f32_e32 v0, v214, v0
	v_exp_f32_e32 v238, v220
	v_fma_f32 v220, v74, s36, -v210
	v_add_f32_e32 v0, v217, v0
	v_exp_f32_e32 v241, v220
	v_fma_f32 v220, v75, s36, -v210
	v_add_f32_e32 v0, v216, v0
	v_exp_f32_e32 v240, v220
	v_fma_f32 v220, v76, s36, -v210
	v_add_f32_e32 v0, v239, v0
	v_exp_f32_e32 v244, v220
	v_fma_f32 v220, v77, s36, -v210
	v_add_f32_e32 v0, v238, v0
	v_exp_f32_e32 v243, v220
	v_fma_f32 v220, v78, s36, -v210
	v_add_f32_e32 v0, v241, v0
	v_exp_f32_e32 v246, v220
	v_fma_f32 v220, v79, s36, -v210
	v_add_f32_e32 v0, v240, v0
	v_exp_f32_e32 v245, v220
	v_fma_f32 v220, v80, s36, -v210
	v_add_f32_e32 v0, v244, v0
	v_exp_f32_e32 v248, v220
	v_fma_f32 v220, v81, s36, -v210
	v_add_f32_e32 v0, v243, v0
	v_exp_f32_e32 v247, v220
	v_add_f32_e32 v0, v246, v0
	v_add_f32_e32 v0, v245, v0
	v_add_f32_e32 v0, v248, v0
	v_add_f32_e32 v242, v247, v0
	s_and_saveexec_b64 s[20:21], s[10:11]
	s_cbranch_execz .LBB0_227
	v_mov_b32_e32 v247, 0
	v_mov_b32_e32 v248, 0
	v_mov_b32_e32 v245, 0
	v_mov_b32_e32 v246, 0
	v_mov_b32_e32 v243, 0
	v_mov_b32_e32 v244, 0
	v_mov_b32_e32 v240, 0
	v_mov_b32_e32 v241, 0
	v_mov_b32_e32 v238, 0
	v_mov_b32_e32 v239, 0
	v_mov_b32_e32 v216, 0
	v_mov_b32_e32 v217, 0
	v_mov_b32_e32 v214, 0
	v_mov_b32_e32 v215, 0
	v_mov_b32_e32 v212, 0
	v_mov_b32_e32 v213, 0
	v_mov_b32_e32 v242, 0

.LBB0_232:
	s_lshl_b32 s94, s26, 1
	v_lshl_add_u64 v[66:67], v[180:181], 0, s[94:95]
	global_load_dwordx4 v[146:149], v[66:67], off offset:64
	global_load_dwordx4 v[142:145], v[66:67], off offset:96
	v_add_co_u32_e32 v66, vcc, 0x4000, v66
	s_or_b32 s20, s26, 63
	s_nop 0
	v_addc_co_u32_e32 v67, vcc, 0, v67, vcc
	global_load_dwordx4 v[150:153], v[66:67], off offset:64
	global_load_dwordx4 v[138:141], v[66:67], off offset:96
	ds_read_b128 v[66:69], v211 offset:4608
	ds_read_b128 v[212:215], v211 offset:4640
	s_waitcnt lgkmcnt(0)
	v_mfma_f32_32x32x16_bf16 v[66:81], v[66:69], v[110:113], 0
	s_cmp_gt_i32 s20, s24
	s_mov_b64 s[20:21], -1
	v_mfma_f32_32x32x16_bf16 v[66:81], v[212:215], v[82:85], v[66:81]
	ds_read_b128 v[212:215], v211 offset:4672
	s_waitcnt lgkmcnt(0)
	v_mfma_f32_32x32x16_bf16 v[66:81], v[212:215], v[114:117], v[66:81]
	ds_read_b128 v[212:215], v211 offset:4704
	s_waitcnt lgkmcnt(0)
	v_mfma_f32_32x32x16_bf16 v[66:81], v[212:215], v[86:89], v[66:81]
	s_cbranch_scc1 .LBB0_242
	s_nop 10
	v_max3_f32 v0, v66, s72, v67
	v_max3_f32 v0, v0, v68, v69
	v_max3_f32 v0, v0, v70, v71
	v_max3_f32 v0, v0, v72, v73
	v_max3_f32 v0, v0, v74, v75
	v_max3_f32 v0, v0, v76, v77
	v_max3_f32 v0, v0, v78, v79
	v_mov_b32_e32 v209, v222
	v_max3_f32 v0, v0, v80, v81
	v_mul_f32_e32 v0, 0x3e38aa3b, v0
	v_lshlrev_b32_e32 v209, 2, v209
	v_cndmask_b32_e64 v0, v230, v0, s[8:9]
	v_xor_b32_e32 v209, 0x80, v209
	ds_bpermute_b32 v209, v209, v0
	s_waitcnt lgkmcnt(0)
	v_max3_f32 v209, v210, v0, v209
	v_fma_f32 v0, v66, s36, -v209
	v_exp_f32_e32 v212, v0
	v_fma_f32 v0, v67, s36, -v209
	v_exp_f32_e32 v211, v0
	v_fma_f32 v0, v68, s36, -v209
	v_exp_f32_e32 v214, v0
	v_fma_f32 v0, v69, s36, -v209
	v_exp_f32_e32 v213, v0
	v_fma_f32 v215, v70, s36, -v209
	v_add_f32_e32 v0, 0, v212
	v_exp_f32_e32 v216, v215
	v_fma_f32 v215, v71, s36, -v209
	v_add_f32_e32 v0, v211, v0
	v_exp_f32_e32 v215, v215
	v_fma_f32 v217, v72, s36, -v209
	v_add_f32_e32 v0, v214, v0
	v_exp_f32_e32 v238, v217
	v_fma_f32 v217, v73, s36, -v209
	v_add_f32_e32 v0, v213, v0
	v_exp_f32_e32 v217, v217
	v_fma_f32 v220, v74, s36, -v209
	v_add_f32_e32 v0, v216, v0
	v_exp_f32_e32 v240, v220
	v_fma_f32 v220, v75, s36, -v209
	v_add_f32_e32 v0, v215, v0
	v_exp_f32_e32 v239, v220
	v_fma_f32 v220, v76, s36, -v209
	v_add_f32_e32 v0, v238, v0
	v_exp_f32_e32 v243, v220
	v_fma_f32 v220, v77, s36, -v209
	v_add_f32_e32 v0, v217, v0
	v_exp_f32_e32 v242, v220
	v_fma_f32 v220, v78, s36, -v209
	v_add_f32_e32 v0, v240, v0
	v_exp_f32_e32 v245, v220
	v_fma_f32 v220, v79, s36, -v209
	v_add_f32_e32 v0, v239, v0
	v_exp_f32_e32 v244, v220
	v_fma_f32 v220, v80, s36, -v209
	v_add_f32_e32 v0, v243, v0
	v_exp_f32_e32 v247, v220
	v_fma_f32 v220, v81, s36, -v209
	v_add_f32_e32 v0, v242, v0
	v_exp_f32_e32 v246, v220
	v_add_f32_e32 v0, v245, v0
	v_add_f32_e32 v0, v244, v0
	v_add_f32_e32 v0, v247, v0
	v_add_f32_e32 v241, v246, v0
	s_and_saveexec_b64 s[20:21], s[10:11]
	s_cbranch_execz .LBB0_235
	v_mov_b32_e32 v246, 0
	v_mov_b32_e32 v247, 0
	v_mov_b32_e32 v244, 0
	v_mov_b32_e32 v245, 0
	v_mov_b32_e32 v242, 0
	v_mov_b32_e32 v243, 0
	v_mov_b32_e32 v239, 0
	v_mov_b32_e32 v240, 0
	v_mov_b32_e32 v217, 0
	v_mov_b32_e32 v238, 0
	v_mov_b32_e32 v215, 0
	v_mov_b32_e32 v216, 0
	v_mov_b32_e32 v213, 0
	v_mov_b32_e32 v214, 0
	v_mov_b32_e32 v211, 0
	v_mov_b32_e32 v212, 0
	v_mov_b32_e32 v241, 0

.LBB0_345:
	s_or_b64 exec, exec, s[0:1]
	v_lshlrev_b32_e32 v36, 16, v114
	v_and_b32_e32 v37, 0xffff0000, v114
	v_mov_b32_e32 v39, v128
	v_mov_b32_e32 v128, v127
	v_lshlrev_b32_e32 v34, 16, v110
	v_and_b32_e32 v35, 0xffff0000, v110
	v_mov_b32_e32 v38, v126
	v_pk_mul_f32 v[40:41], v[128:129], v[36:37]
	s_waitcnt lgkmcnt(0)
	v_pk_fma_f32 v[40:41], v[38:39], v[34:35], v[40:41] neg_lo:[0,0,1] neg_hi:[0,0,1]
	v_pk_mul_f32 v[34:35], v[128:129], v[34:35]
	v_cvt_pk_bf16_f32 v114, v40, v41
	v_pk_fma_f32 v[34:35], v[38:39], v[36:37], v[34:35]
	v_lshlrev_b32_e32 v36, 16, v115
	v_and_b32_e32 v37, 0xffff0000, v115
	v_mov_b32_e32 v39, v124
	v_mov_b32_e32 v124, v123
	v_cvt_pk_bf16_f32 v126, v34, v35
	v_lshlrev_b32_e32 v34, 16, v111
	v_and_b32_e32 v35, 0xffff0000, v111
	v_mov_b32_e32 v38, v122
	v_pk_mul_f32 v[40:41], v[124:125], v[36:37]
	s_barrier
	v_pk_fma_f32 v[40:41], v[38:39], v[34:35], v[40:41] neg_lo:[0,0,1] neg_hi:[0,0,1]
	v_pk_mul_f32 v[34:35], v[124:125], v[34:35]
	s_nop 0
	v_pk_fma_f32 v[34:35], v[38:39], v[36:37], v[34:35]
	ds_read_b64 v[110:111], v208 offset:53248
	ds_read_b64 v[36:37], v1 offset:53760
	s_lshl_b32 s18, s68, 18
	s_lshl_b32 s94, s68, 19
	v_readlane_b32 s0, v254, 39
	s_add_u32 s0, s0, s94
	s_waitcnt lgkmcnt(0)
	v_readfirstlane_b32 s8, v36
	v_readfirstlane_b32 s9, v37
	s_ff1_i32_b64 s24, s[8:9]
	v_readlane_b32 s1, v254, 41
	v_lshl_add_u32 v36, s24, 6, v176
	s_addc_u32 s1, s1, 0
	v_ashrrev_i32_e32 v37, 31, v36
	s_add_u32 s10, s8, -1
	v_lshlrev_b64 v[36:37], 7, v[36:37]
	s_addc_u32 s11, s9, -1
	v_lshl_add_u64 v[36:37], s[0:1], 0, v[36:37]
	v_mov_b32_e32 v187, v1
	v_lshl_add_u64 v[38:39], v[182:183], 0, s[94:95]
	s_lshl_b32 s94, s24, 7
	v_cvt_pk_bf16_f32 v115, v40, v41
	v_lshl_add_u64 v[36:37], v[36:37], 0, v[186:187]
	v_lshl_add_u64 v[40:41], v[38:39], 0, s[94:95]
	v_lshl_add_u64 v[40:41], v[40:41], 0, v[186:187]
	s_waitcnt vmcnt(0)
	global_load_dwordx4 v[130:133], v[36:37], off
	global_load_dwordx4 v[134:137], v[40:41], off
	v_lshlrev_b32_e32 v36, 16, v116
	v_and_b32_e32 v37, 0xffff0000, v116
	v_mov_b32_e32 v41, v120
	v_mov_b32_e32 v120, v119
	v_cvt_pk_bf16_f32 v127, v34, v35
	v_lshlrev_b32_e32 v34, 16, v112
	v_and_b32_e32 v35, 0xffff0000, v112
	v_mov_b32_e32 v40, v118
	v_pk_mul_f32 v[42:43], v[120:121], v[36:37]
	v_mov_b32_e32 v146, 0
	v_pk_fma_f32 v[42:43], v[40:41], v[34:35], v[42:43] neg_lo:[0,0,1] neg_hi:[0,0,1]
	v_pk_mul_f32 v[34:35], v[120:121], v[34:35]
	v_cvt_pk_bf16_f32 v116, v42, v43
	v_pk_fma_f32 v[34:35], v[40:41], v[36:37], v[34:35]
	v_lshlrev_b32_e32 v36, 16, v117
	v_and_b32_e32 v37, 0xffff0000, v117
	v_mov_b32_e32 v41, v108
	v_mov_b32_e32 v108, v107
	v_cvt_pk_bf16_f32 v128, v34, v35
	v_lshlrev_b32_e32 v34, 16, v113
	v_and_b32_e32 v35, 0xffff0000, v113
	v_mov_b32_e32 v40, v106
	v_pk_mul_f32 v[42:43], v[108:109], v[36:37]
	s_and_b64 s[8:9], s[10:11], s[8:9]
	v_pk_fma_f32 v[42:43], v[40:41], v[34:35], v[42:43] neg_lo:[0,0,1] neg_hi:[0,0,1]
	v_pk_mul_f32 v[34:35], v[108:109], v[34:35]
	v_cvt_pk_bf16_f32 v117, v42, v43
	v_pk_fma_f32 v[34:35], v[40:41], v[36:37], v[34:35]
	v_lshlrev_b32_e32 v36, 16, v86
	v_and_b32_e32 v37, 0xffff0000, v86
	v_mov_b32_e32 v41, v104
	v_mov_b32_e32 v104, v103
	v_cvt_pk_bf16_f32 v129, v34, v35
	v_lshlrev_b32_e32 v34, 16, v82
	v_and_b32_e32 v35, 0xffff0000, v82
	v_mov_b32_e32 v40, v102
	v_pk_mul_f32 v[42:43], v[104:105], v[36:37]
	s_mov_b32 s19, 0
	v_pk_fma_f32 v[42:43], v[40:41], v[34:35], v[42:43] neg_lo:[0,0,1] neg_hi:[0,0,1]
	v_pk_mul_f32 v[34:35], v[104:105], v[34:35]
	v_cvt_pk_bf16_f32 v118, v42, v43
	v_pk_fma_f32 v[34:35], v[40:41], v[36:37], v[34:35]
	v_lshlrev_b32_e32 v36, 16, v87
	v_and_b32_e32 v37, 0xffff0000, v87
	v_mov_b32_e32 v41, v100
	v_mov_b32_e32 v100, v99
	v_cvt_pk_bf16_f32 v122, v34, v35
	v_lshlrev_b32_e32 v34, 16, v83
	v_and_b32_e32 v35, 0xffff0000, v83
	v_mov_b32_e32 v40, v98
	v_pk_mul_f32 v[42:43], v[100:101], v[36:37]
	v_lshl_add_u64 v[82:83], s[0:1], 0, v[186:187]
	v_pk_fma_f32 v[42:43], v[40:41], v[34:35], v[42:43] neg_lo:[0,0,1] neg_hi:[0,0,1]
	v_pk_mul_f32 v[34:35], v[100:101], v[34:35]
	v_cvt_pk_bf16_f32 v119, v42, v43
	v_pk_fma_f32 v[34:35], v[40:41], v[36:37], v[34:35]
	v_lshlrev_b32_e32 v36, 16, v88
	v_and_b32_e32 v37, 0xffff0000, v88
	v_mov_b32_e32 v41, v96
	v_mov_b32_e32 v96, v95
	v_cvt_pk_bf16_f32 v123, v34, v35
	v_lshlrev_b32_e32 v34, 16, v84
	v_and_b32_e32 v35, 0xffff0000, v84
	v_mov_b32_e32 v40, v94
	v_pk_mul_f32 v[42:43], v[96:97], v[36:37]
	v_mov_b32_e32 v87, 0xf149f2ca
	v_pk_fma_f32 v[42:43], v[40:41], v[34:35], v[42:43] neg_lo:[0,0,1] neg_hi:[0,0,1]
	v_pk_mul_f32 v[34:35], v[96:97], v[34:35]
	v_cvt_pk_bf16_f32 v120, v42, v43
	v_pk_fma_f32 v[34:35], v[40:41], v[36:37], v[34:35]
	v_lshlrev_b32_e32 v36, 16, v89
	v_and_b32_e32 v37, 0xffff0000, v89
	v_mov_b32_e32 v41, v92
	v_mov_b32_e32 v92, v91
	v_cvt_pk_bf16_f32 v124, v34, v35
	v_lshlrev_b32_e32 v34, 16, v85
	v_and_b32_e32 v35, 0xffff0000, v85
	v_mov_b32_e32 v40, v90
	v_pk_mul_f32 v[42:43], v[92:93], v[36:37]
	v_lshl_add_u64 v[84:85], v[38:39], 0, v[186:187]
	v_pk_fma_f32 v[42:43], v[40:41], v[34:35], v[42:43] neg_lo:[0,0,1] neg_hi:[0,0,1]
	v_pk_mul_f32 v[34:35], v[92:93], v[34:35]
	v_cvt_pk_bf16_f32 v121, v42, v43
	v_pk_fma_f32 v[34:35], v[40:41], v[36:37], v[34:35]
	v_mov_b32_e32 v36, v146
	v_cvt_pk_bf16_f32 v125, v34, v35
	v_mov_b32_e32 v34, 0
	v_mov_b32_e32 v35, v146
	v_mov_b32_e32 v37, v146
	v_mov_b32_e32 v38, v146
	v_mov_b32_e32 v39, v146
	v_mov_b32_e32 v40, v146
	v_mov_b32_e32 v41, v146
	v_mov_b32_e32 v42, v146
	v_mov_b32_e32 v43, v146
	v_mov_b32_e32 v44, v146
	v_mov_b32_e32 v45, v146
	v_mov_b32_e32 v46, v146
	v_mov_b32_e32 v47, v146
	v_mov_b32_e32 v48, v146
	v_mov_b32_e32 v49, v146
	v_mov_b32_e32 v50, v146
	v_mov_b32_e32 v51, v146
	v_mov_b32_e32 v52, v146
	v_mov_b32_e32 v53, v146
	v_mov_b32_e32 v54, v146
	v_mov_b32_e32 v55, v146
	v_mov_b32_e32 v56, v146
	v_mov_b32_e32 v57, v146
	v_mov_b32_e32 v58, v146
	v_mov_b32_e32 v59, v146
	v_mov_b32_e32 v60, v146
	v_mov_b32_e32 v61, v146
	v_mov_b32_e32 v62, v146
	v_mov_b32_e32 v63, v146
	v_mov_b32_e32 v64, v146
	v_mov_b32_e32 v65, v146
	s_waitcnt vmcnt(0) lgkmcnt(0)
	ds_write_b128 v203, v[130:133]
	ds_write_b128 v203, v[134:137] offset:9216
	s_branch .LBB0_349

.LBB0_349:
	s_waitcnt lgkmcnt(0)
	s_barrier
	s_cmp_lg_u64 s[8:9], 0
	s_mov_b64 s[0:1], 0
	s_cselect_b64 s[12:13], -1, 0
	s_cmp_eq_u64 s[8:9], 0
	s_mov_b32 s26, 0
	s_cbranch_scc1 .LBB0_351
	s_ff1_i32_b64 s26, s[8:9]
	v_lshl_add_u32 v66, s26, 6, v176
	v_ashrrev_i32_e32 v67, 31, v66
	s_add_u32 s0, s8, -1
	v_lshlrev_b64 v[66:67], 7, v[66:67]
	s_addc_u32 s1, s9, -1
	v_lshl_add_u64 v[66:67], v[82:83], 0, v[66:67]
	s_lshl_b32 s94, s26, 7
	v_lshl_add_u64 v[68:69], v[84:85], 0, s[94:95]
	s_waitcnt vmcnt(0) lgkmcnt(0)
	global_load_dwordx4 v[130:133], v[66:67], off
	global_load_dwordx4 v[134:137], v[68:69], off
	s_and_b64 s[0:1], s[0:1], s[8:9]

.LBB0_373:
	s_max_i32 s0, s67, 8
	s_add_i32 s8, s0, -8
	s_add_i32 s0, s67, 1
	s_lshl_b64 s[0:1], -1, s0
	s_not_b64 s[0:1], s[0:1]
	s_cmp_lt_i32 s67, 63
	s_cselect_b32 s1, s1, -1
	s_cselect_b32 s0, s0, -1
	s_lshl_b64 s[8:9], -1, s8
	s_and_b64 s[0:1], s[0:1], s[8:9]
	s_lshl_b32 s94, s18, 1
	v_readlane_b32 s8, v254, 42
	s_add_u32 s10, s8, s94
	v_readlane_b32 s8, v254, 44
	s_addc_u32 s11, s8, 0
	s_ff1_i32_b64 s8, s[0:1]
	v_lshl_add_u32 v66, s8, 6, v176
	s_add_i32 s18, s91, 0xfffffe01
	s_add_i32 s19, s91, 0xfffffe08
	v_ashrrev_i32_e32 v67, 31, v66
	s_add_u32 s12, s0, -1
	v_lshlrev_b64 v[66:67], 7, v[66:67]
	s_addc_u32 s13, s1, -1
	v_lshl_add_u64 v[66:67], s[10:11], 0, v[66:67]
	v_mov_b32_e32 v187, v1
	v_lshl_add_u64 v[98:99], v[184:185], 0, s[94:95]
	s_lshl_b32 s94, s8, 7
	v_mov_b32_e32 v81, v222
	v_lshl_add_u64 v[66:67], v[66:67], 0, v[186:187]
	v_lshl_add_u64 v[68:69], v[98:99], 0, s[94:95]
	s_waitcnt lgkmcnt(0)
	s_barrier
	v_lshl_add_u64 v[68:69], v[68:69], 0, v[186:187]
	s_waitcnt vmcnt(0) lgkmcnt(0)
	global_load_dwordx4 v[130:133], v[66:67], off
	global_load_dwordx4 v[134:137], v[68:69], off
	v_lshlrev_b32_e32 v81, 2, v81
	v_xor_b32_e32 v81, 0x80, v81
	ds_bpermute_b32 v148, v81, v146
	s_and_b64 s[0:1], s[12:13], s[0:1]
	v_add_u32_e32 v0, 0xfffffe01, v192
	v_mov_b32_e32 v147, 0
	s_cmp_lt_i32 s91, 0
	s_mov_b32 s24, 0
	v_mov_b32_e32 v139, v192
	v_mov_b32_e32 v150, 0xf149f2ca
	v_mov_b32_e32 v82, 0
	v_mov_b32_e32 v141, v0
	v_mov_b32_e32 v83, v147
	v_mov_b32_e32 v84, v147
	v_mov_b32_e32 v85, v147
	v_mov_b32_e32 v86, v147
	v_mov_b32_e32 v87, v147
	v_mov_b32_e32 v88, v147
	v_mov_b32_e32 v89, v147
	v_mov_b32_e32 v90, v147
	v_mov_b32_e32 v91, v147
	v_mov_b32_e32 v92, v147
	v_mov_b32_e32 v93, v147
	v_mov_b32_e32 v94, v147
	v_mov_b32_e32 v95, v147
	v_mov_b32_e32 v96, v147
	v_mov_b32_e32 v97, v147
	v_mov_b32_e32 v66, v147
	v_mov_b32_e32 v67, v147
	v_mov_b32_e32 v68, v147
	v_mov_b32_e32 v69, v147
	v_mov_b32_e32 v70, v147
	v_mov_b32_e32 v71, v147
	v_mov_b32_e32 v72, v147
	v_mov_b32_e32 v73, v147
	v_mov_b32_e32 v74, v147
	v_mov_b32_e32 v75, v147
	v_mov_b32_e32 v76, v147
	v_mov_b32_e32 v77, v147
	v_mov_b32_e32 v78, v147
	v_mov_b32_e32 v79, v147
	v_mov_b32_e32 v80, v147
	v_lshl_add_u64 v[142:143], v[98:99], 0, v[186:187]
	v_lshl_add_u64 v[144:145], s[10:11], 0, v[186:187]
	s_cselect_b64 s[12:13], -1, 0
	v_mov_b32_e32 v81, v147
	s_waitcnt vmcnt(0) lgkmcnt(0)
	ds_write_b128 v203, v[130:133]
	ds_write_b128 v203, v[134:137] offset:9216
	s_branch .LBB0_376

.LBB0_376:
	s_waitcnt lgkmcnt(0)
	s_barrier
	s_cmp_lg_u64 s[0:1], 0
	s_mov_b64 s[86:87], 0
	s_cselect_b64 s[20:21], -1, 0
	s_cmp_eq_u64 s[0:1], 0
	s_mov_b32 s25, 0
	s_cbranch_scc1 .LBB0_378
	s_ff1_i32_b64 s25, s[0:1]
	v_lshl_add_u32 v98, s25, 6, v176
	v_ashrrev_i32_e32 v99, 31, v98
	s_add_u32 s10, s0, -1
	v_lshlrev_b64 v[98:99], 7, v[98:99]
	s_addc_u32 s11, s1, -1
	v_lshl_add_u64 v[98:99], v[144:145], 0, v[98:99]
	s_lshl_b32 s94, s25, 7
	v_lshl_add_u64 v[100:101], v[142:143], 0, s[94:95]
	s_waitcnt vmcnt(0) lgkmcnt(0)
	global_load_dwordx4 v[130:133], v[98:99], off
	global_load_dwordx4 v[134:137], v[100:101], off
	s_and_b64 s[86:87], s[10:11], s[0:1]

.LBB0_418:
	s_lshl_b64 s[0:1], s[0:1], 19
	s_add_u32 s0, s18, s0
	s_addc_u32 s1, s13, s1
	s_lshl_b32 s10, s20, 11
	s_add_u32 s0, s0, s10
	s_addc_u32 s1, s1, 0
	v_lshlrev_b32_e32 v0, 2, v168
	v_lshl_add_u64 v[20:21], s[0:1], 0, v[0:1]
	global_load_dword v0, v[20:21], off
	global_load_dword v22, v[20:21], off offset:3072
	global_load_dword v23, v[10:11], off
	s_waitcnt vmcnt(0) lgkmcnt(0)
	v_add_f32_e32 v0, v0, v22
	v_add_f32_e32 v0, v0, v23
	v_mul_f32_e32 v22, 0x3d372713, v0
	v_mul_f32_e32 v22, v0, v22
	v_fma_f32 v22, v0, v22, v0
	v_mul_f32_e32 v22, 0x3f4c422a, v22
	v_add_f32_e32 v22, v22, v22
	v_mul_f32_e32 v22, 0x3fb8aa3b, v22
	v_exp_f32_e32 v22, v22
	v_mul_f32_e32 v0, 0.5, v0
	v_add_f32_e32 v22, 1.0, v22
	v_div_scale_f32 v23, s[0:1], v22, v22, 2.0
	v_rcp_f32_e32 v31, v23
	v_div_scale_f32 v32, vcc, 2.0, v22, 2.0
	v_fma_f32 v33, -v23, v31, 1.0
	v_fmac_f32_e32 v31, v33, v31
	v_mul_f32_e32 v33, v32, v31
	v_fma_f32 v34, -v23, v33, v32
	v_fmac_f32_e32 v33, v34, v31
	v_fma_f32 v23, -v23, v33, v32
	v_div_fmas_f32 v23, v23, v31, v33
	v_div_fixup_f32 v22, v23, v22, 2.0
	v_sub_f32_e32 v22, 1.0, v22
	v_add_f32_e32 v22, 1.0, v22
	v_mul_f32_e32 v0, v0, v22
	ds_write_b32 v24, v0
	global_load_dword v0, v[20:21], off offset:256
	global_load_dword v22, v[20:21], off offset:3328
	global_load_dword v23, v[12:13], off
	s_waitcnt vmcnt(0) lgkmcnt(0)
	v_add_f32_e32 v0, v0, v22
	v_add_f32_e32 v0, v0, v23
	v_mul_f32_e32 v22, 0x3d372713, v0
	v_mul_f32_e32 v22, v0, v22
	v_fma_f32 v22, v0, v22, v0
	v_mul_f32_e32 v22, 0x3f4c422a, v22
	v_add_f32_e32 v22, v22, v22
	v_mul_f32_e32 v22, 0x3fb8aa3b, v22
	v_exp_f32_e32 v22, v22
	v_mul_f32_e32 v0, 0.5, v0
	v_add_f32_e32 v22, 1.0, v22
	v_div_scale_f32 v23, s[0:1], v22, v22, 2.0
	v_rcp_f32_e32 v31, v23
	v_div_scale_f32 v32, vcc, 2.0, v22, 2.0
	v_fma_f32 v33, -v23, v31, 1.0
	v_fmac_f32_e32 v31, v33, v31
	v_mul_f32_e32 v33, v32, v31
	v_fma_f32 v34, -v23, v33, v32
	v_fmac_f32_e32 v33, v34, v31
	v_fma_f32 v23, -v23, v33, v32
	v_div_fmas_f32 v23, v23, v31, v33
	v_div_fixup_f32 v22, v23, v22, 2.0
	v_sub_f32_e32 v22, 1.0, v22
	v_add_f32_e32 v22, 1.0, v22
	v_mul_f32_e32 v0, v0, v22
	ds_write_b32 v24, v0 offset:256
	global_load_dword v0, v[20:21], off offset:512
	global_load_dword v22, v[20:21], off offset:3584
	global_load_dword v23, v[14:15], off
	s_waitcnt vmcnt(0) lgkmcnt(0)
	v_add_f32_e32 v0, v0, v22
	v_add_f32_e32 v0, v0, v23
	v_mul_f32_e32 v22, 0x3d372713, v0
	v_mul_f32_e32 v22, v0, v22
	v_fma_f32 v22, v0, v22, v0
	v_mul_f32_e32 v22, 0x3f4c422a, v22
	v_add_f32_e32 v22, v22, v22
	v_mul_f32_e32 v22, 0x3fb8aa3b, v22
	v_exp_f32_e32 v22, v22
	v_mul_f32_e32 v0, 0.5, v0
	v_add_f32_e32 v22, 1.0, v22
	v_div_scale_f32 v23, s[0:1], v22, v22, 2.0
	v_rcp_f32_e32 v31, v23
	v_div_scale_f32 v32, vcc, 2.0, v22, 2.0
	v_fma_f32 v33, -v23, v31, 1.0
	v_fmac_f32_e32 v31, v33, v31
	v_mul_f32_e32 v33, v32, v31
	v_fma_f32 v34, -v23, v33, v32
	v_fmac_f32_e32 v33, v34, v31
	v_fma_f32 v23, -v23, v33, v32
	v_div_fmas_f32 v23, v23, v31, v33
	v_div_fixup_f32 v22, v23, v22, 2.0
	v_sub_f32_e32 v22, 1.0, v22
	v_add_f32_e32 v22, 1.0, v22
	v_mul_f32_e32 v0, v0, v22
	ds_write_b32 v24, v0 offset:512
	global_load_dword v0, v[20:21], off offset:768
	s_nop 0
	global_load_dword v20, v[20:21], off offset:3840
	s_nop 0
	global_load_dword v21, v[16:17], off
	s_waitcnt vmcnt(0) lgkmcnt(0)
	v_add_f32_e32 v0, v0, v20
	v_add_f32_e32 v0, v0, v21
	v_mul_f32_e32 v20, 0x3d372713, v0
	v_mul_f32_e32 v20, v0, v20
	v_fma_f32 v20, v0, v20, v0
	v_mul_f32_e32 v20, 0x3f4c422a, v20
	v_add_f32_e32 v20, v20, v20
	v_mul_f32_e32 v20, 0x3fb8aa3b, v20
	v_exp_f32_e32 v20, v20
	v_mul_f32_e32 v0, 0.5, v0
	v_add_f32_e32 v20, 1.0, v20
	v_div_scale_f32 v21, s[0:1], v20, v20, 2.0
	v_rcp_f32_e32 v22, v21
	v_div_scale_f32 v23, vcc, 2.0, v20, 2.0
	s_mov_b32 s0, -4
	v_fma_f32 v31, -v21, v22, 1.0
	v_fmac_f32_e32 v22, v31, v22
	v_mul_f32_e32 v31, v23, v22
	v_fma_f32 v32, -v21, v31, v23
	v_fmac_f32_e32 v31, v32, v22
	v_fma_f32 v21, -v21, v31, v23
	v_div_fmas_f32 v21, v21, v22, v31
	v_div_fixup_f32 v20, v21, v20, 2.0
	v_sub_f32_e32 v20, 1.0, v20
	v_add_f32_e32 v20, 1.0, v20
	v_mul_f32_e32 v0, v0, v20
	ds_write_b32 v24, v0 offset:768
	s_waitcnt lgkmcnt(0)
	global_load_dword v20, v[8:9], off
	v_mov_b32_e32 v21, 0
	s_mov_b32 s1, s12
	v_mov_b32_e32 v0, v30
	v_mov_b32_e32 v22, v21
	v_mov_b32_e32 v23, v21

.LBB0_422:
	v_bfe_u32 v0, v20, 16, 1
	v_add3_u32 v0, v20, v0, s33
	global_store_short_d16_hi v[18:19], v0, off
	s_waitcnt lgkmcnt(0)
	s_branch .LBB0_414

.LBB0_425:
	s_and_b64 vcc, exec, s[10:11]
	s_cbranch_vccz .LBB0_414
	global_store_short v[18:19], v1, off
	s_branch .LBB0_414

.LBB0_454:
	v_lshl_add_u32 v140, s6, 8, v136
	v_lshl_or_b32 v142, s7, 8, v138
	v_ashrrev_i32_e32 v141, 31, v140
	v_ashrrev_i32_e32 v143, 31, v142
	v_lshlrev_b64 v[144:145], 11, v[140:141]
	v_lshl_add_u64 v[144:145], s[16:17], 0, v[144:145]
	v_lshlrev_b64 v[142:143], 2, v[142:143]
	v_lshl_add_u64 v[144:145], v[144:145], 0, v[142:143]
	global_store_dwordx4 v[144:145], v[126:129], off
	global_store_dwordx4 v[144:145], v[122:125], off offset:64
	global_store_dwordx4 v[144:145], v[110:113], off offset:512
	global_store_dwordx4 v[144:145], v[102:105], off offset:576
	s_mov_b64 s[6:7], 0x40000
	s_mov_b32 s92, 0x2aaaaaab
	v_or_b32_e32 v102, 16, v140
	v_ashrrev_i32_e32 v103, 31, v102
	v_lshlrev_b64 v[102:103], 11, v[102:103]
	v_lshl_add_u64 v[102:103], s[16:17], 0, v[102:103]
	v_lshl_add_u64 v[102:103], v[102:103], 0, v[142:143]
	global_store_dwordx4 v[102:103], v[118:121], off
	global_store_dwordx4 v[102:103], v[114:117], off offset:64
	global_store_dwordx4 v[102:103], v[94:97], off offset:512
	global_store_dwordx4 v[102:103], v[86:89], off offset:576
	s_nop 1
	v_or_b32_e32 v86, 32, v140
	v_ashrrev_i32_e32 v87, 31, v86
	v_lshlrev_b64 v[86:87], 11, v[86:87]
	v_lshl_add_u64 v[86:87], s[16:17], 0, v[86:87]
	v_lshl_add_u64 v[86:87], v[86:87], 0, v[142:143]
	global_store_dwordx4 v[86:87], v[106:109], off
	global_store_dwordx4 v[86:87], v[98:101], off offset:64
	global_store_dwordx4 v[86:87], v[78:81], off offset:512
	global_store_dwordx4 v[86:87], v[74:77], off offset:576
	s_nop 1
	v_or_b32_e32 v74, 48, v140
	v_ashrrev_i32_e32 v75, 31, v74
	v_lshlrev_b64 v[74:75], 11, v[74:75]
	v_lshl_add_u64 v[74:75], s[16:17], 0, v[74:75]
	v_lshl_add_u64 v[74:75], v[74:75], 0, v[142:143]
	global_store_dwordx4 v[74:75], v[90:93], off
	global_store_dwordx4 v[74:75], v[82:85], off offset:64
	global_store_dwordx4 v[74:75], v[70:73], off offset:512
	global_store_dwordx4 v[74:75], v[66:69], off offset:576
	s_nop 1
	v_lshl_add_u64 v[66:67], v[144:145], 0, s[6:7]
	s_mov_b32 s6, 0x40000
	v_add_co_u32_e32 v68, vcc, s6, v144
	s_mov_b64 s[6:7], 0x48000
	s_nop 0
	v_addc_co_u32_e32 v69, vcc, 0, v145, vcc
	global_store_dwordx4 v[68:69], v[62:65], off
	global_store_dwordx4 v[66:67], v[58:61], off offset:64
	global_store_dwordx4 v[66:67], v[46:49], off offset:512
	global_store_dwordx4 v[66:67], v[42:45], off offset:576
	s_nop 1
	v_lshl_add_u64 v[42:43], v[144:145], 0, s[6:7]
	s_mov_b32 s6, 0x48000
	v_add_co_u32_e32 v44, vcc, s6, v144
	s_mov_b64 s[6:7], 0x50000
	s_nop 0
	v_addc_co_u32_e32 v45, vcc, 0, v145, vcc
	global_store_dwordx4 v[44:45], v[54:57], off
	global_store_dwordx4 v[42:43], v[50:53], off offset:64
	global_store_dwordx4 v[42:43], v[30:33], off offset:512
	global_store_dwordx4 v[42:43], v[26:29], off offset:576
	s_nop 1
	v_lshl_add_u64 v[26:27], v[144:145], 0, s[6:7]
	s_mov_b32 s6, 0x50000
	v_add_co_u32_e32 v28, vcc, s6, v144
	s_mov_b64 s[6:7], 0x58000
	s_nop 0
	v_addc_co_u32_e32 v29, vcc, 0, v145, vcc
	global_store_dwordx4 v[28:29], v[38:41], off
	global_store_dwordx4 v[26:27], v[34:37], off offset:64
	global_store_dwordx4 v[26:27], v[14:17], off offset:512
	global_store_dwordx4 v[26:27], v[10:13], off offset:576
	s_nop 1
	v_add_co_u32_e32 v12, vcc, 0x58000, v144
	v_lshl_add_u64 v[10:11], v[144:145], 0, s[6:7]
	s_nop 0
	v_addc_co_u32_e32 v13, vcc, 0, v145, vcc
	s_andn2_b64 vcc, exec, s[10:11]
	s_mov_b64 s[6:7], -1
	global_store_dwordx4 v[12:13], v[22:25], off
	global_store_dwordx4 v[10:11], v[18:21], off offset:64
	global_store_dwordx4 v[10:11], v[6:9], off offset:512
	global_store_dwordx4 v[10:11], v[2:5], off offset:576
	s_cbranch_vccnz .LBB0_443
	s_andn2_b64 vcc, exec, s[4:5]
	s_cbranch_vccnz .LBB0_442
	s_barrier
	s_branch .LBB0_442

.LBB0_464:
	s_lshl_b32 s5, s4, 4
	s_and_b32 s5, s5, 0x7000
	s_and_b32 s8, s2, 0xfc0
	s_or_b32 s5, s8, s5
	v_or_b32_e32 v0, s5, v104
	s_and_b32 s5, s4, 0xc0
	v_mul_u32_u24_e32 v0, 0xa00, v0
	s_lshl_b32 s6, s5, 1
	v_lshlrev_b32_e32 v0, 1, v0
	s_cmpk_lt_u32 s4, 0x800
	s_movk_i32 s5, 0xe00
	v_lshl_add_u64 v[22:23], s[74:75], 0, v[0:1]
	s_cselect_b32 s94, s5, 0x1200
	v_lshl_add_u64 v[22:23], v[22:23], 0, s[94:95]
	s_mov_b32 s7, s95
	v_lshl_add_u64 v[22:23], v[22:23], 0, s[6:7]
	v_mov_b32_e32 v5, v1
	v_lshl_add_u64 v[22:23], v[22:23], 0, v[4:5]
	s_mov_b32 s5, 0xa000
	v_add_co_u32_e32 v30, vcc, s5, v22
	s_mov_b32 s5, 0x14000
	s_nop 0
	v_addc_co_u32_e32 v31, vcc, 0, v23, vcc
	v_add_co_u32_e32 v34, vcc, s5, v22
	s_mov_b32 s5, 0x1e000
	s_nop 0
	v_addc_co_u32_e32 v35, vcc, 0, v23, vcc
	v_add_co_u32_e32 v38, vcc, s5, v22
	s_mov_b32 s5, 0x28000
	s_nop 0
	v_addc_co_u32_e32 v39, vcc, 0, v23, vcc
	v_add_co_u32_e32 v42, vcc, s5, v22
	global_load_dwordx4 v[26:29], v[22:23], off
	s_nop 0
	v_addc_co_u32_e32 v43, vcc, 0, v23, vcc
	s_mov_b32 s5, 0x32000
	global_load_dwordx4 v[30:33], v[30:31], off
	v_add_co_u32_e32 v46, vcc, s5, v22
	global_load_dwordx4 v[34:37], v[34:35], off
	s_nop 0
	v_addc_co_u32_e32 v47, vcc, 0, v23, vcc
	s_mov_b32 s5, 0x3c000
	global_load_dwordx4 v[38:41], v[38:39], off
	v_add_co_u32_e32 v50, vcc, s5, v22
	global_load_dwordx4 v[42:45], v[42:43], off
	s_nop 0
	v_addc_co_u32_e32 v51, vcc, 0, v23, vcc
	s_mov_b32 s5, 0x46000
	global_load_dwordx4 v[46:49], v[46:47], off
	v_add_co_u32_e32 v22, vcc, s5, v22
	global_load_dwordx4 v[50:53], v[50:51], off
	s_nop 0
	v_addc_co_u32_e32 v23, vcc, 0, v23, vcc
	global_load_dwordx4 v[54:57], v[22:23], off
	s_cselect_b32 s5, s11, s13
	s_cselect_b32 s6, s10, s12
	s_lshl_b32 s7, s4, 13
	s_and_b32 s7, s7, 0xf80000
	s_add_u32 s6, s6, s7
	s_addc_u32 s5, s5, 0
	s_lshl_b32 s7, s8, 1
	s_add_u32 s6, s6, s7
	s_addc_u32 s7, s5, 0
	v_lshl_add_u64 v[22:23], s[6:7], 0, v[4:5]
	v_mov_b32_e32 v7, v1
	v_mov_b32_e32 v9, v1
	v_mov_b32_e32 v11, v1
	v_mov_b32_e32 v13, v1
	v_mov_b32_e32 v15, v1
	v_mov_b32_e32 v17, v1
	v_mov_b32_e32 v19, v1
	v_mov_b32_e32 v21, v1
	s_add_i32 s4, s4, s56
	s_add_i32 s2, s2, s3
	s_cmpk_gt_i32 s4, 0xfff
	s_waitcnt vmcnt(0) lgkmcnt(0)
	ds_write_b128 v25, v[26:29]
	ds_write_b128 v25, v[30:33] offset:1152
	ds_write_b128 v25, v[34:37] offset:2304
	ds_write_b128 v25, v[38:41] offset:3456
	ds_write_b128 v25, v[42:45] offset:4608
	ds_write_b128 v25, v[46:49] offset:5760
	ds_write_b128 v25, v[50:53] offset:6912
	ds_write_b128 v25, v[54:57] offset:8064
	s_waitcnt lgkmcnt(0)
	ds_read_u16 v0, v3
	ds_read_u16 v5, v3 offset:144
	v_lshl_add_u64 v[30:31], v[22:23], 0, v[6:7]
	s_waitcnt lgkmcnt(0)
	v_lshl_or_b32 v26, v5, 16, v0
	ds_read_u16 v0, v3 offset:288
	ds_read_u16 v5, v3 offset:432
	s_waitcnt lgkmcnt(0)
	v_lshl_or_b32 v27, v5, 16, v0
	ds_read_u16 v0, v3 offset:576
	ds_read_u16 v5, v3 offset:720
	s_waitcnt lgkmcnt(0)
	v_lshl_or_b32 v28, v5, 16, v0
	ds_read_u16 v0, v3 offset:864
	ds_read_u16 v5, v3 offset:1008
	s_waitcnt lgkmcnt(0)
	v_lshl_or_b32 v29, v5, 16, v0
	global_store_dwordx4 v[30:31], v[26:29], off
	ds_read_u16 v0, v3 offset:16
	ds_read_u16 v5, v3 offset:160
	v_lshl_add_u64 v[30:31], v[22:23], 0, v[8:9]
	s_waitcnt lgkmcnt(0)
	v_lshl_or_b32 v26, v5, 16, v0
	ds_read_u16 v0, v3 offset:304
	ds_read_u16 v5, v3 offset:448
	s_waitcnt lgkmcnt(0)
	v_lshl_or_b32 v27, v5, 16, v0
	ds_read_u16 v0, v3 offset:592
	ds_read_u16 v5, v3 offset:736
	s_waitcnt lgkmcnt(0)
	v_lshl_or_b32 v28, v5, 16, v0
	ds_read_u16 v0, v3 offset:880
	ds_read_u16 v5, v3 offset:1024
	s_waitcnt lgkmcnt(0)
	v_lshl_or_b32 v29, v5, 16, v0
	global_store_dwordx4 v[30:31], v[26:29], off
	ds_read_u16 v0, v3 offset:32
	ds_read_u16 v5, v3 offset:176
	v_lshl_add_u64 v[30:31], v[22:23], 0, v[10:11]
	s_waitcnt lgkmcnt(0)
	v_lshl_or_b32 v26, v5, 16, v0
	ds_read_u16 v0, v3 offset:320
	ds_read_u16 v5, v3 offset:464
	s_waitcnt lgkmcnt(0)
	v_lshl_or_b32 v27, v5, 16, v0
	ds_read_u16 v0, v3 offset:608
	ds_read_u16 v5, v3 offset:752
	s_waitcnt lgkmcnt(0)
	v_lshl_or_b32 v28, v5, 16, v0
	ds_read_u16 v0, v3 offset:896
	ds_read_u16 v5, v3 offset:1040
	s_waitcnt lgkmcnt(0)
	v_lshl_or_b32 v29, v5, 16, v0
	global_store_dwordx4 v[30:31], v[26:29], off
	ds_read_u16 v0, v3 offset:48
	ds_read_u16 v5, v3 offset:192
	v_lshl_add_u64 v[30:31], v[22:23], 0, v[12:13]
	s_waitcnt lgkmcnt(0)
	v_lshl_or_b32 v26, v5, 16, v0
	ds_read_u16 v0, v3 offset:336
	ds_read_u16 v5, v3 offset:480
	s_waitcnt lgkmcnt(0)
	v_lshl_or_b32 v27, v5, 16, v0
	ds_read_u16 v0, v3 offset:624
	ds_read_u16 v5, v3 offset:768
	s_waitcnt lgkmcnt(0)
	v_lshl_or_b32 v28, v5, 16, v0
	ds_read_u16 v0, v3 offset:912
	ds_read_u16 v5, v3 offset:1056
	s_waitcnt lgkmcnt(0)
	v_lshl_or_b32 v29, v5, 16, v0
	global_store_dwordx4 v[30:31], v[26:29], off
	ds_read_u16 v0, v3 offset:64
	ds_read_u16 v5, v3 offset:208
	v_lshl_add_u64 v[30:31], v[22:23], 0, v[14:15]
	s_waitcnt lgkmcnt(0)
	v_lshl_or_b32 v26, v5, 16, v0
	ds_read_u16 v0, v3 offset:352
	ds_read_u16 v5, v3 offset:496
	s_waitcnt lgkmcnt(0)
	v_lshl_or_b32 v27, v5, 16, v0
	ds_read_u16 v0, v3 offset:640
	ds_read_u16 v5, v3 offset:784
	s_waitcnt lgkmcnt(0)
	v_lshl_or_b32 v28, v5, 16, v0
	ds_read_u16 v0, v3 offset:928
	ds_read_u16 v5, v3 offset:1072
	s_waitcnt lgkmcnt(0)
	v_lshl_or_b32 v29, v5, 16, v0
	global_store_dwordx4 v[30:31], v[26:29], off
	ds_read_u16 v0, v3 offset:80
	ds_read_u16 v5, v3 offset:224
	v_lshl_add_u64 v[30:31], v[22:23], 0, v[16:17]
	s_waitcnt lgkmcnt(0)
	v_lshl_or_b32 v26, v5, 16, v0
	ds_read_u16 v0, v3 offset:368
	ds_read_u16 v5, v3 offset:512
	s_waitcnt lgkmcnt(0)
	v_lshl_or_b32 v27, v5, 16, v0
	ds_read_u16 v0, v3 offset:656
	ds_read_u16 v5, v3 offset:800
	s_waitcnt lgkmcnt(0)
	v_lshl_or_b32 v28, v5, 16, v0
	ds_read_u16 v0, v3 offset:944
	ds_read_u16 v5, v3 offset:1088
	s_waitcnt lgkmcnt(0)
	v_lshl_or_b32 v29, v5, 16, v0
	global_store_dwordx4 v[30:31], v[26:29], off
	ds_read_u16 v0, v3 offset:96
	ds_read_u16 v5, v3 offset:240
	v_lshl_add_u64 v[30:31], v[22:23], 0, v[18:19]
	v_lshl_add_u64 v[22:23], v[22:23], 0, v[20:21]
	s_waitcnt lgkmcnt(0)
	v_lshl_or_b32 v26, v5, 16, v0
	ds_read_u16 v0, v3 offset:384
	ds_read_u16 v5, v3 offset:528
	s_waitcnt lgkmcnt(0)
	v_lshl_or_b32 v27, v5, 16, v0
	ds_read_u16 v0, v3 offset:672
	ds_read_u16 v5, v3 offset:816
	s_waitcnt lgkmcnt(0)
	v_lshl_or_b32 v28, v5, 16, v0
	ds_read_u16 v0, v3 offset:960
	ds_read_u16 v5, v3 offset:1104
	s_waitcnt lgkmcnt(0)
	v_lshl_or_b32 v29, v5, 16, v0
	global_store_dwordx4 v[30:31], v[26:29], off
	ds_read_u16 v0, v3 offset:112
	ds_read_u16 v5, v3 offset:256
	s_waitcnt lgkmcnt(0)
	v_lshl_or_b32 v26, v5, 16, v0
	ds_read_u16 v0, v3 offset:400
	ds_read_u16 v5, v3 offset:544
	s_waitcnt lgkmcnt(0)
	v_lshl_or_b32 v27, v5, 16, v0
	ds_read_u16 v0, v3 offset:688
	ds_read_u16 v5, v3 offset:832
	s_waitcnt lgkmcnt(0)
	v_lshl_or_b32 v28, v5, 16, v0
	ds_read_u16 v0, v3 offset:976
	ds_read_u16 v5, v3 offset:1120
	s_waitcnt lgkmcnt(0)
	v_lshl_or_b32 v29, v5, 16, v0
	global_store_dwordx4 v[22:23], v[26:29], off
	s_waitcnt lgkmcnt(0)
	s_cbranch_scc0 .LBB0_464
	v_mov_b32_e32 v0, v2

.LBB0_469:
	s_add_i32 s8, s56, s5
	s_cmp_lt_i32 s8, 0x8000
	s_cselect_b32 s0, s8, s5
	s_ashr_i32 s1, s0, 31
	s_mul_i32 s12, s0, 0x1400
	s_mul_hi_i32 s9, s0, 0x1400
	s_add_u32 s18, s74, s12
	s_addc_u32 s19, s75, s9
	s_lshl_b64 s[0:1], s[0:1], 8
	v_lshl_add_u64 v[22:23], v[84:85], 0, s[0:1]
	v_lshl_add_u64 v[50:51], s[58:59], 0, v[94:95]
	s_mov_b32 s0, 0xac00000
	v_add_co_u32_e32 v62, vcc, s0, v50
	v_lshl_add_u64 v[66:67], s[58:59], 0, v[92:93]
	s_nop 0
	v_addc_co_u32_e32 v63, vcc, 0, v51, vcc
	v_mov_b32_e32 v97, v1
	v_add_co_u32_e32 v78, vcc, s79, v66
	v_lshl_add_u64 v[18:19], s[18:19], 0, v[0:1]
	v_lshl_add_u64 v[20:21], s[18:19], 0, v[96:97]
	v_addc_co_u32_e32 v79, vcc, 0, v67, vcc
	v_lshl_add_u64 v[70:71], s[58:59], 0, v[90:91]
	global_load_dwordx4 v[46:49], v[18:19], off
	global_load_dwordx4 v[42:45], v[18:19], off offset:1024
	global_load_dwordx4 v[38:41], v[20:21], off
	s_nop 0
	global_load_dwordx4 v[18:21], v[18:19], off offset:2048
	s_nop 0
	global_load_dwordx4 v[34:37], v[22:23], off
	global_load_dwordx4 v[30:33], v[22:23], off offset:16
	global_load_dwordx4 v[26:29], v[22:23], off offset:32
	s_nop 0
	global_load_dwordx4 v[22:25], v[22:23], off offset:48
	s_nop 0
	global_load_dwordx4 v[50:53], v[62:63], off offset:48
	global_load_dwordx4 v[54:57], v[62:63], off offset:32
	global_load_dwordx4 v[58:61], v[62:63], off offset:16
	s_nop 0
	global_load_dwordx4 v[62:65], v[62:63], off
	v_mov_b32_e32 v97, v222
	global_load_dwordx4 v[66:69], v[78:79], off offset:2048
	s_nop 0
	global_load_dwordx4 v[70:73], v[70:71], off
	s_nop 0
	global_load_dwordx4 v[74:77], v[78:79], off offset:1024
	s_nop 0
	global_load_dwordx4 v[78:81], v[78:79], off
	v_mov_b32_e32 v98, v222
	s_ashr_i32 s12, s5, 12
	v_lshlrev_b32_e32 v98, 2, v98
	v_xor_b32_e32 v110, 8, v98
	v_mov_b32_e32 v98, v222
	v_lshlrev_b32_e32 v97, 2, v97
	v_lshlrev_b32_e32 v98, 2, v98
	v_xor_b32_e32 v111, 16, v98
	v_xor_b32_e32 v97, 4, v97
	s_and_b32 s9, s5, 0xfff
	s_lshl_b32 s94, s9, 7
	s_cmpk_gt_i32 s8, 0x7fff
	s_waitcnt vmcnt(0) lgkmcnt(0)
	v_and_b32_e32 v99, 0xffff0000, v81
	v_and_b32_e32 v101, 0xffff0000, v80
	v_lshlrev_b32_e32 v98, 16, v81
	v_lshlrev_b32_e32 v100, 16, v80
	v_mov_b32_e32 v102, v99
	v_mov_b32_e32 v103, v101
	v_mov_b32_e32 v80, v98
	v_mov_b32_e32 v81, v100
	v_pk_mul_f32 v[102:103], v[102:103], v[102:103]
	v_and_b32_e32 v107, 0xffff0000, v78
	v_pk_fma_f32 v[80:81], v[80:81], v[80:81], v[102:103]
	v_and_b32_e32 v103, 0xffff0000, v79
	v_lshlrev_b32_e32 v102, 16, v79
	v_lshlrev_b32_e32 v106, 16, v78
	v_mov_b32_e32 v108, v107
	v_mov_b32_e32 v109, v103
	v_mov_b32_e32 v78, v106
	v_mov_b32_e32 v79, v102
	v_pk_mul_f32 v[108:109], v[108:109], v[108:109]
	s_nop 0
	v_pk_fma_f32 v[78:79], v[78:79], v[78:79], v[108:109]
	s_nop 0
	v_add_f32_e32 v78, v78, v79
	v_add_f32_e32 v78, v81, v78
	v_add_f32_e32 v78, v80, v78
	ds_bpermute_b32 v79, v97, v78
	s_waitcnt lgkmcnt(0)
	v_add_f32_e32 v78, v78, v79
	ds_bpermute_b32 v79, v110, v78
	s_waitcnt lgkmcnt(0)
	v_add_f32_e32 v78, v78, v79
	ds_bpermute_b32 v79, v111, v78
	s_waitcnt lgkmcnt(0)
	v_add_f32_e32 v78, v78, v79
	v_fmamk_f32 v78, v78, 0x3c800000, v218
	v_cmp_gt_f32_e32 vcc, s79, v78
	v_mul_f32_e32 v79, 0x4f800000, v78
	s_nop 0
	v_cndmask_b32_e32 v78, v78, v79, vcc
	v_sqrt_f32_e32 v79, v78
	s_nop 0
	v_add_u32_e32 v80, -1, v79
	v_fma_f32 v81, -v80, v79, v78
	v_cmp_ge_f32_e64 s[0:1], 0, v81
	v_add_u32_e32 v81, 1, v79
	s_nop 0
	v_cndmask_b32_e64 v80, v79, v80, s[0:1]
	v_fma_f32 v79, -v81, v79, v78
	v_cmp_lt_f32_e64 s[0:1], 0, v79
	s_nop 1
	v_cndmask_b32_e64 v79, v80, v81, s[0:1]
	v_mul_f32_e32 v80, 0x37800000, v79
	v_cndmask_b32_e32 v79, v79, v80, vcc
	v_cmp_class_f32_e32 vcc, v78, v205
	s_nop 1
	v_cndmask_b32_e32 v78, v79, v78, vcc
	v_div_scale_f32 v79, s[0:1], v78, v78, 1.0
	v_rcp_f32_e32 v80, v79
	s_nop 0
	v_fma_f32 v81, -v79, v80, 1.0
	v_fmac_f32_e32 v80, v81, v80
	v_div_scale_f32 v81, vcc, 1.0, v78, 1.0
	v_mul_f32_e32 v97, v81, v80
	v_fma_f32 v108, -v79, v97, v81
	v_fmac_f32_e32 v97, v108, v80
	v_fma_f32 v79, -v79, v97, v81
	v_div_fmas_f32 v79, v79, v80, v97
	v_div_fixup_f32 v108, v79, v78, 1.0
	v_pk_mul_f32 v[78:79], v[108:109], v[106:107] op_sel_hi:[0,1]
	v_pk_mul_f32 v[80:81], v[108:109], v[102:103] op_sel_hi:[0,1]
	v_pk_mul_f32 v[78:79], v[6:7], v[78:79]
	v_pk_mul_f32 v[80:81], v[8:9], v[80:81]
	v_cvt_pk_bf16_f32 v78, v78, v79
	v_cvt_pk_bf16_f32 v79, v80, v81
	v_pk_mul_f32 v[80:81], v[108:109], v[100:101] op_sel_hi:[0,1]
	v_pk_mul_f32 v[98:99], v[108:109], v[98:99] op_sel_hi:[0,1]
	v_lshl_or_b32 v100, s12, 4, v104
	v_pk_mul_f32 v[80:81], v[2:3], v[80:81]
	v_pk_mul_f32 v[98:99], v[4:5], v[98:99]
	v_ashrrev_i32_e32 v101, 31, v100
	v_cvt_pk_bf16_f32 v80, v80, v81
	v_cvt_pk_bf16_f32 v81, v98, v99
	v_lshlrev_b64 v[98:99], 19, v[100:101]
	v_lshl_add_u64 v[98:99], s[96:97], 0, v[98:99]
	v_lshl_add_u64 v[102:103], v[98:99], 0, s[94:95]
	v_lshlrev_b64 v[98:99], 1, v[82:83]
	v_lshl_add_u64 v[102:103], v[102:103], 0, v[98:99]
	global_store_dwordx4 v[102:103], v[78:81], off
	v_and_b32_e32 v107, 0xffff0000, v74
	v_lshlrev_b32_e32 v106, 16, v74
	v_mov_b32_e32 v78, v222
	v_and_b32_e32 v79, 0xffff0000, v77
	v_lshlrev_b32_e32 v78, 2, v78
	v_xor_b32_e32 v97, 4, v78
	v_mov_b32_e32 v78, v222
	v_and_b32_e32 v81, 0xffff0000, v76
	v_lshlrev_b32_e32 v78, 2, v78
	v_xor_b32_e32 v101, 8, v78
	v_mov_b32_e32 v78, v222
	v_lshlrev_b32_e32 v80, 16, v76
	v_lshlrev_b32_e32 v78, 2, v78
	v_xor_b32_e32 v110, 16, v78
	v_lshlrev_b32_e32 v78, 16, v77
	v_mov_b32_e32 v102, v79
	v_mov_b32_e32 v103, v81
	v_mov_b32_e32 v76, v78
	v_mov_b32_e32 v77, v80
	v_pk_mul_f32 v[102:103], v[102:103], v[102:103]
	v_mov_b32_e32 v108, v107
	v_pk_fma_f32 v[76:77], v[76:77], v[76:77], v[102:103]
	v_and_b32_e32 v103, 0xffff0000, v75
	v_lshlrev_b32_e32 v102, 16, v75
	v_mov_b32_e32 v109, v103
	v_mov_b32_e32 v74, v106
	v_mov_b32_e32 v75, v102
	v_pk_mul_f32 v[108:109], v[108:109], v[108:109]
	s_nop 0
	v_pk_fma_f32 v[74:75], v[74:75], v[74:75], v[108:109]
	s_nop 0
	v_add_f32_e32 v74, v74, v75
	v_add_f32_e32 v74, v77, v74
	v_add_f32_e32 v74, v76, v74
	ds_bpermute_b32 v75, v97, v74
	s_waitcnt lgkmcnt(0)
	v_add_f32_e32 v74, v74, v75
	ds_bpermute_b32 v75, v101, v74
	s_waitcnt lgkmcnt(0)
	v_add_f32_e32 v74, v74, v75
	ds_bpermute_b32 v75, v110, v74
	s_waitcnt lgkmcnt(0)
	v_add_f32_e32 v74, v74, v75
	v_fmamk_f32 v74, v74, 0x3c800000, v218
	v_cmp_gt_f32_e32 vcc, s79, v74
	v_mul_f32_e32 v75, 0x4f800000, v74
	s_nop 0
	v_cndmask_b32_e32 v74, v74, v75, vcc
	v_sqrt_f32_e32 v75, v74
	s_nop 0
	v_add_u32_e32 v76, -1, v75
	v_fma_f32 v77, -v76, v75, v74
	v_cmp_ge_f32_e64 s[0:1], 0, v77
	v_add_u32_e32 v77, 1, v75
	s_nop 0
	v_cndmask_b32_e64 v76, v75, v76, s[0:1]
	v_fma_f32 v75, -v77, v75, v74
	v_cmp_lt_f32_e64 s[0:1], 0, v75
	s_nop 1
	v_cndmask_b32_e64 v75, v76, v77, s[0:1]
	v_mul_f32_e32 v76, 0x37800000, v75
	v_cndmask_b32_e32 v75, v75, v76, vcc
	v_cmp_class_f32_e32 vcc, v74, v205
	s_nop 1
	v_cndmask_b32_e32 v74, v75, v74, vcc
	v_div_scale_f32 v75, s[0:1], v74, v74, 1.0
	v_rcp_f32_e32 v76, v75
	s_nop 0
	v_fma_f32 v77, -v75, v76, 1.0
	v_fmac_f32_e32 v76, v77, v76
	v_div_scale_f32 v77, vcc, 1.0, v74, 1.0
	v_mul_f32_e32 v97, v77, v76
	v_fma_f32 v101, -v75, v97, v77
	v_fmac_f32_e32 v97, v101, v76
	v_fma_f32 v75, -v75, v97, v77
	v_div_fmas_f32 v75, v75, v76, v97
	v_div_fixup_f32 v108, v75, v74, 1.0
	v_pk_mul_f32 v[74:75], v[108:109], v[106:107] op_sel_hi:[0,1]
	v_pk_mul_f32 v[76:77], v[108:109], v[102:103] op_sel_hi:[0,1]
	v_pk_mul_f32 v[74:75], v[6:7], v[74:75]
	v_pk_mul_f32 v[76:77], v[8:9], v[76:77]
	v_cvt_pk_bf16_f32 v74, v74, v75
	v_cvt_pk_bf16_f32 v75, v76, v77
	v_pk_mul_f32 v[76:77], v[108:109], v[80:81] op_sel_hi:[0,1]
	v_pk_mul_f32 v[78:79], v[108:109], v[78:79] op_sel_hi:[0,1]
	v_pk_mul_f32 v[76:77], v[2:3], v[76:77]
	v_pk_mul_f32 v[78:79], v[4:5], v[78:79]
	v_cvt_pk_bf16_f32 v76, v76, v77
	v_cvt_pk_bf16_f32 v77, v78, v79
	v_or_b32_e32 v78, 8, v100
	v_ashrrev_i32_e32 v79, 31, v78
	v_lshlrev_b64 v[78:79], 19, v[78:79]
	v_lshl_add_u64 v[78:79], s[96:97], 0, v[78:79]
	v_lshl_add_u64 v[78:79], v[78:79], 0, s[94:95]
	v_lshl_add_u64 v[78:79], v[78:79], 0, v[98:99]
	global_store_dwordx4 v[78:79], v[74:77], off
	v_and_b32_e32 v79, 0xffff0000, v72
	v_lshlrev_b32_e32 v78, 16, v72
	v_mov_b32_e32 v76, v222
	v_and_b32_e32 v77, 0xffff0000, v73
	v_lshlrev_b32_e32 v76, 2, v76
	v_xor_b32_e32 v97, 4, v76
	v_mov_b32_e32 v76, v222
	v_mov_b32_e32 v80, v77
	v_lshlrev_b32_e32 v76, 2, v76
	v_xor_b32_e32 v106, 8, v76
	v_mov_b32_e32 v76, v222
	v_mov_b32_e32 v81, v79
	v_lshlrev_b32_e32 v76, 2, v76
	v_xor_b32_e32 v107, 16, v76
	v_mov_b32_e32 v76, v222
	v_pk_mul_f32 v[80:81], v[80:81], v[80:81]
	v_lshlrev_b32_e32 v76, 2, v76
	v_xor_b32_e32 v108, 16, v76
	v_mov_b32_e32 v76, v222
	v_and_b32_e32 v101, 0xffff0000, v70
	v_lshlrev_b32_e32 v76, 2, v76
	v_xor_b32_e32 v109, 16, v76
	v_mov_b32_e32 v76, v222
	v_lshlrev_b32_e32 v100, 16, v70
	v_lshlrev_b32_e32 v76, 2, v76
	v_xor_b32_e32 v110, 16, v76
	v_mov_b32_e32 v76, v222
	v_mov_b32_e32 v102, v101
	v_lshlrev_b32_e32 v76, 2, v76
	v_xor_b32_e32 v111, 16, v76
	v_mov_b32_e32 v76, v222
	v_mov_b32_e32 v70, v100
	v_lshlrev_b32_e32 v76, 2, v76
	v_xor_b32_e32 v112, 16, v76
	v_mov_b32_e32 v76, v222
	v_lshl_or_b32 v74, s12, 2, v105
	v_lshlrev_b32_e32 v76, 2, v76
	v_xor_b32_e32 v113, 16, v76
	v_mov_b32_e32 v76, v222
	v_ashrrev_i32_e32 v75, 31, v74
	v_lshlrev_b32_e32 v76, 2, v76
	v_xor_b32_e32 v114, 16, v76
	v_mov_b32_e32 v76, v222
	v_lshlrev_b64 v[74:75], 18, v[74:75]
	v_lshlrev_b32_e32 v76, 2, v76
	v_xor_b32_e32 v115, 16, v76
	v_lshlrev_b32_e32 v76, 16, v73
	v_mov_b32_e32 v72, v76
	v_mov_b32_e32 v73, v78
	v_pk_fma_f32 v[72:73], v[72:73], v[72:73], v[80:81]
	v_and_b32_e32 v81, 0xffff0000, v71
	v_lshlrev_b32_e32 v80, 16, v71
	v_mov_b32_e32 v103, v81
	v_mov_b32_e32 v71, v80
	v_pk_mul_f32 v[102:103], v[102:103], v[102:103]
	v_lshl_or_b32 v74, s9, 6, v74
	v_pk_fma_f32 v[70:71], v[70:71], v[70:71], v[102:103]
	s_nop 0
	v_add_f32_e32 v70, v70, v71
	v_add_f32_e32 v70, v73, v70
	v_add_f32_e32 v70, v72, v70
	ds_bpermute_b32 v71, v97, v70
	s_waitcnt lgkmcnt(0)
	v_add_f32_e32 v70, v70, v71
	ds_bpermute_b32 v71, v106, v70
	s_waitcnt lgkmcnt(0)
	v_add_f32_e32 v70, v70, v71
	ds_bpermute_b32 v71, v107, v70
	s_waitcnt lgkmcnt(0)
	v_add_f32_e32 v70, v70, v71
	v_fmamk_f32 v70, v70, 0x3c800000, v218
	v_cmp_gt_f32_e32 vcc, s79, v70
	v_mul_f32_e32 v71, 0x4f800000, v70
	s_nop 0
	v_cndmask_b32_e32 v70, v70, v71, vcc
	v_sqrt_f32_e32 v71, v70
	s_nop 0
	v_add_u32_e32 v72, -1, v71
	v_fma_f32 v73, -v72, v71, v70
	v_cmp_ge_f32_e64 s[0:1], 0, v73
	v_add_u32_e32 v73, 1, v71
	s_nop 0
	v_cndmask_b32_e64 v72, v71, v72, s[0:1]
	v_fma_f32 v71, -v73, v71, v70
	v_cmp_lt_f32_e64 s[0:1], 0, v71
	s_nop 1
	v_cndmask_b32_e64 v71, v72, v73, s[0:1]
	v_mul_f32_e32 v72, 0x37800000, v71
	v_cndmask_b32_e32 v71, v71, v72, vcc
	v_cmp_class_f32_e32 vcc, v70, v205
	s_nop 1
	v_cndmask_b32_e32 v70, v71, v70, vcc
	v_div_scale_f32 v71, s[0:1], v70, v70, 1.0
	v_rcp_f32_e32 v72, v71
	s_nop 0
	v_fma_f32 v73, -v71, v72, 1.0
	v_fmac_f32_e32 v72, v73, v72
	v_div_scale_f32 v73, vcc, 1.0, v70, 1.0
	v_mul_f32_e32 v97, v73, v72
	v_fma_f32 v102, -v71, v97, v73
	v_fmac_f32_e32 v97, v102, v72
	v_fma_f32 v71, -v71, v97, v73
	v_div_fmas_f32 v71, v71, v72, v97
	v_div_fixup_f32 v70, v71, v70, 1.0
	v_pk_mul_f32 v[72:73], v[70:71], v[100:101] op_sel_hi:[0,1]
	v_pk_mul_f32 v[72:73], v[14:15], v[72:73]
	ds_bpermute_b32 v71, v108, v72
	ds_bpermute_b32 v97, v109, v73
	v_mov_b32_e32 v100, v62
	v_mov_b32_e32 v101, v64
	v_pk_mul_f32 v[72:73], v[100:101], v[72:73]
	s_waitcnt lgkmcnt(0)
	v_cndmask_b32_e64 v100, v71, -v71, s[2:3]
	v_cndmask_b32_e64 v101, v97, -v97, s[2:3]
	v_mov_b32_e32 v64, v63
	v_pk_fma_f32 v[62:63], v[64:65], v[100:101], v[72:73]
	v_pk_mul_f32 v[64:65], v[70:71], v[80:81] op_sel_hi:[0,1]
	v_pk_mul_f32 v[64:65], v[16:17], v[64:65]
	ds_bpermute_b32 v71, v110, v64
	ds_bpermute_b32 v80, v111, v65
	v_mov_b32_e32 v73, v60
	v_mov_b32_e32 v60, v59
	v_mov_b32_e32 v72, v58
	s_waitcnt lgkmcnt(0)
	v_cndmask_b32_e64 v81, v80, -v80, s[2:3]
	v_cndmask_b32_e64 v80, v71, -v71, s[2:3]
	v_pk_mul_f32 v[58:59], v[60:61], v[80:81]
	v_pk_mul_f32 v[60:61], v[70:71], v[78:79] op_sel_hi:[0,1]
	v_pk_mul_f32 v[60:61], v[10:11], v[60:61]
	v_pk_fma_f32 v[58:59], v[72:73], v[64:65], v[58:59]
	ds_bpermute_b32 v71, v112, v60
	ds_bpermute_b32 v72, v113, v61
	v_mov_b32_e32 v65, v56
	v_mov_b32_e32 v56, v55
	v_mov_b32_e32 v64, v54
	s_waitcnt lgkmcnt(0)
	v_cndmask_b32_e64 v73, v72, -v72, s[2:3]
	v_cndmask_b32_e64 v72, v71, -v71, s[2:3]
	v_pk_mul_f32 v[54:55], v[56:57], v[72:73]
	v_pk_mul_f32 v[56:57], v[70:71], v[76:77] op_sel_hi:[0,1]
	v_pk_mul_f32 v[56:57], v[12:13], v[56:57]
	v_pk_fma_f32 v[54:55], v[64:65], v[60:61], v[54:55]
	ds_bpermute_b32 v64, v114, v56
	ds_bpermute_b32 v65, v115, v57
	v_mov_b32_e32 v61, v52
	v_mov_b32_e32 v52, v51
	v_mov_b32_e32 v60, v50
	s_waitcnt lgkmcnt(0)
	v_cndmask_b32_e64 v64, v64, -v64, s[2:3]
	v_cndmask_b32_e64 v65, v65, -v65, s[2:3]
	v_pk_mul_f32 v[50:51], v[52:53], v[64:65]
	v_cvt_pk_bf16_f32 v52, v54, v55
	v_pk_fma_f32 v[56:57], v[60:61], v[56:57], v[50:51]
	v_lshl_add_u64 v[60:61], v[74:75], 0, v[82:83]
	v_lshlrev_b64 v[54:55], 1, v[60:61]
	v_cvt_pk_bf16_f32 v50, v62, v63
	v_cvt_pk_bf16_f32 v51, v58, v59
	v_cvt_pk_bf16_f32 v53, v56, v57
	v_lshl_add_u64 v[56:57], v[86:87], 0, v[54:55]
	global_store_dwordx4 v[56:57], v[50:53], off
	s_nop 1
	v_lshl_add_u64 v[50:51], v[88:89], 0, v[54:55]
	global_store_dwordx4 v[50:51], v[66:69], off
	s_cbranch_scc1 .LBB0_468
	v_mov_b32_e32 v50, v222
	v_and_b32_e32 v51, 0xffff0000, v49
	v_lshlrev_b32_e32 v50, 2, v50
	v_and_b32_e32 v53, 0xffff0000, v48
	v_xor_b32_e32 v60, 4, v50
	v_lshlrev_b32_e32 v50, 16, v49
	v_lshlrev_b32_e32 v52, 16, v48
	v_mov_b32_e32 v54, v51
	v_mov_b32_e32 v55, v53
	v_mov_b32_e32 v48, v50
	v_mov_b32_e32 v49, v52
	v_pk_mul_f32 v[54:55], v[54:55], v[54:55]
	v_and_b32_e32 v57, 0xffff0000, v46
	v_pk_fma_f32 v[48:49], v[48:49], v[48:49], v[54:55]
	v_and_b32_e32 v55, 0xffff0000, v47
	v_lshlrev_b32_e32 v54, 16, v47
	v_lshlrev_b32_e32 v56, 16, v46
	v_mov_b32_e32 v58, v57
	v_mov_b32_e32 v59, v55
	v_mov_b32_e32 v46, v56
	v_mov_b32_e32 v47, v54
	v_pk_mul_f32 v[58:59], v[58:59], v[58:59]
	s_ashr_i32 s9, s8, 12
	v_pk_fma_f32 v[46:47], v[46:47], v[46:47], v[58:59]
	s_and_b32 s8, s8, 0xfff
	v_add_f32_e32 v46, v46, v47
	v_add_f32_e32 v46, v49, v46
	v_add_f32_e32 v46, v48, v46
	ds_bpermute_b32 v47, v60, v46
	v_mov_b32_e32 v48, v222
	s_lshl_b32 s94, s8, 7
	v_lshlrev_b32_e32 v48, 2, v48
	v_xor_b32_e32 v48, 8, v48
	s_waitcnt lgkmcnt(0)
	v_add_f32_e32 v46, v46, v47
	ds_bpermute_b32 v47, v48, v46
	v_mov_b32_e32 v48, v222
	v_mov_b32_e32 v60, v222
	v_lshlrev_b32_e32 v48, 2, v48
	v_xor_b32_e32 v48, 16, v48
	s_waitcnt lgkmcnt(0)
	v_add_f32_e32 v46, v46, v47
	ds_bpermute_b32 v47, v48, v46
	s_waitcnt lgkmcnt(0)
	v_add_f32_e32 v46, v46, v47
	v_fmamk_f32 v46, v46, 0x3c800000, v218
	v_mul_f32_e32 v47, 0x4f800000, v46
	v_cmp_gt_f32_e32 vcc, s79, v46
	s_nop 1
	v_cndmask_b32_e32 v46, v46, v47, vcc
	v_sqrt_f32_e32 v47, v46
	s_nop 0
	v_add_u32_e32 v48, -1, v47
	v_fma_f32 v49, -v48, v47, v46
	v_cmp_ge_f32_e64 s[0:1], 0, v49
	v_add_u32_e32 v49, 1, v47
	s_nop 0
	v_cndmask_b32_e64 v48, v47, v48, s[0:1]
	v_fma_f32 v47, -v49, v47, v46
	v_cmp_lt_f32_e64 s[0:1], 0, v47
	s_nop 1
	v_cndmask_b32_e64 v47, v48, v49, s[0:1]
	v_mul_f32_e32 v48, 0x37800000, v47
	v_cndmask_b32_e32 v47, v47, v48, vcc
	v_cmp_class_f32_e32 vcc, v46, v205
	s_nop 1
	v_cndmask_b32_e32 v46, v47, v46, vcc
	v_div_scale_f32 v47, s[0:1], v46, v46, 1.0
	v_rcp_f32_e32 v48, v47
	s_nop 0
	v_fma_f32 v49, -v47, v48, 1.0
	v_fmac_f32_e32 v48, v49, v48
	v_div_scale_f32 v49, vcc, 1.0, v46, 1.0
	v_mul_f32_e32 v58, v49, v48
	v_fma_f32 v59, -v47, v58, v49
	v_fmac_f32_e32 v58, v59, v48
	v_fma_f32 v47, -v47, v58, v49
	v_div_fmas_f32 v47, v47, v48, v58
	v_div_fixup_f32 v58, v47, v46, 1.0
	v_pk_mul_f32 v[46:47], v[58:59], v[56:57] op_sel_hi:[0,1]
	v_pk_mul_f32 v[48:49], v[58:59], v[54:55] op_sel_hi:[0,1]
	v_pk_mul_f32 v[46:47], v[6:7], v[46:47]
	v_pk_mul_f32 v[48:49], v[8:9], v[48:49]
	v_cvt_pk_bf16_f32 v46, v46, v47
	v_cvt_pk_bf16_f32 v47, v48, v49
	v_pk_mul_f32 v[48:49], v[58:59], v[52:53] op_sel_hi:[0,1]
	v_pk_mul_f32 v[50:51], v[58:59], v[50:51] op_sel_hi:[0,1]
	v_pk_mul_f32 v[48:49], v[2:3], v[48:49]
	v_pk_mul_f32 v[50:51], v[4:5], v[50:51]
	v_cvt_pk_bf16_f32 v48, v48, v49
	v_cvt_pk_bf16_f32 v49, v50, v51
	v_lshl_or_b32 v50, s9, 4, v104
	v_ashrrev_i32_e32 v51, 31, v50
	v_lshlrev_b64 v[52:53], 19, v[50:51]
	v_lshl_add_u64 v[52:53], s[96:97], 0, v[52:53]
	v_lshl_add_u64 v[52:53], v[52:53], 0, s[94:95]
	v_lshl_add_u64 v[52:53], v[52:53], 0, v[98:99]
	global_store_dwordx4 v[52:53], v[46:49], off
	v_and_b32_e32 v55, 0xffff0000, v42
	v_lshlrev_b32_e32 v54, 16, v42
	v_mov_b32_e32 v46, v222
	v_and_b32_e32 v47, 0xffff0000, v45
	v_lshlrev_b32_e32 v46, 2, v46
	v_and_b32_e32 v49, 0xffff0000, v44
	v_xor_b32_e32 v51, 4, v46
	v_lshlrev_b32_e32 v46, 16, v45
	v_lshlrev_b32_e32 v48, 16, v44
	v_mov_b32_e32 v52, v47
	v_mov_b32_e32 v53, v49
	v_mov_b32_e32 v44, v46
	v_mov_b32_e32 v45, v48
	v_pk_mul_f32 v[52:53], v[52:53], v[52:53]
	v_mov_b32_e32 v56, v55
	v_pk_fma_f32 v[44:45], v[44:45], v[44:45], v[52:53]
	v_and_b32_e32 v53, 0xffff0000, v43
	v_lshlrev_b32_e32 v52, 16, v43
	v_mov_b32_e32 v57, v53
	v_mov_b32_e32 v42, v54
	v_mov_b32_e32 v43, v52
	v_pk_mul_f32 v[56:57], v[56:57], v[56:57]
	s_nop 0
	v_pk_fma_f32 v[42:43], v[42:43], v[42:43], v[56:57]
	s_nop 0
	v_add_f32_e32 v42, v42, v43
	v_add_f32_e32 v42, v45, v42
	v_add_f32_e32 v42, v44, v42
	ds_bpermute_b32 v43, v51, v42
	v_mov_b32_e32 v44, v222
	s_waitcnt lgkmcnt(0)
	v_add_f32_e32 v42, v42, v43
	v_lshlrev_b32_e32 v44, 2, v44
	v_xor_b32_e32 v44, 8, v44
	ds_bpermute_b32 v43, v44, v42
	v_mov_b32_e32 v44, v222
	s_waitcnt lgkmcnt(0)
	v_add_f32_e32 v42, v42, v43
	v_lshlrev_b32_e32 v44, 2, v44
	v_xor_b32_e32 v44, 16, v44
	ds_bpermute_b32 v43, v44, v42
	s_waitcnt lgkmcnt(0)
	v_add_f32_e32 v42, v42, v43
	v_fmamk_f32 v42, v42, 0x3c800000, v218
	v_mul_f32_e32 v43, 0x4f800000, v42
	v_cmp_gt_f32_e32 vcc, s79, v42
	s_nop 1
	v_cndmask_b32_e32 v42, v42, v43, vcc
	v_sqrt_f32_e32 v43, v42
	s_nop 0
	v_add_u32_e32 v44, -1, v43
	v_fma_f32 v45, -v44, v43, v42
	v_cmp_ge_f32_e64 s[0:1], 0, v45
	v_add_u32_e32 v45, 1, v43
	s_nop 0
	v_cndmask_b32_e64 v44, v43, v44, s[0:1]
	v_fma_f32 v43, -v45, v43, v42
	v_cmp_lt_f32_e64 s[0:1], 0, v43
	s_nop 1
	v_cndmask_b32_e64 v43, v44, v45, s[0:1]
	v_mul_f32_e32 v44, 0x37800000, v43
	v_cndmask_b32_e32 v43, v43, v44, vcc
	v_cmp_class_f32_e32 vcc, v42, v205
	s_nop 1
	v_cndmask_b32_e32 v42, v43, v42, vcc
	v_div_scale_f32 v43, s[0:1], v42, v42, 1.0
	v_rcp_f32_e32 v44, v43
	s_nop 0
	v_fma_f32 v45, -v43, v44, 1.0
	v_fmac_f32_e32 v44, v45, v44
	v_div_scale_f32 v45, vcc, 1.0, v42, 1.0
	v_mul_f32_e32 v51, v45, v44
	v_fma_f32 v56, -v43, v51, v45
	v_fmac_f32_e32 v51, v56, v44
	v_fma_f32 v43, -v43, v51, v45
	v_div_fmas_f32 v43, v43, v44, v51
	v_div_fixup_f32 v56, v43, v42, 1.0
	v_pk_mul_f32 v[42:43], v[56:57], v[54:55] op_sel_hi:[0,1]
	v_pk_mul_f32 v[44:45], v[56:57], v[52:53] op_sel_hi:[0,1]
	v_pk_mul_f32 v[42:43], v[6:7], v[42:43]
	v_pk_mul_f32 v[44:45], v[8:9], v[44:45]
	v_cvt_pk_bf16_f32 v42, v42, v43
	v_cvt_pk_bf16_f32 v43, v44, v45
	v_pk_mul_f32 v[44:45], v[56:57], v[48:49] op_sel_hi:[0,1]
	v_pk_mul_f32 v[46:47], v[56:57], v[46:47] op_sel_hi:[0,1]
	v_pk_mul_f32 v[44:45], v[2:3], v[44:45]
	v_pk_mul_f32 v[46:47], v[4:5], v[46:47]
	v_cvt_pk_bf16_f32 v44, v44, v45
	v_cvt_pk_bf16_f32 v45, v46, v47
	v_or_b32_e32 v46, 8, v50
	v_ashrrev_i32_e32 v47, 31, v46
	v_lshlrev_b64 v[46:47], 19, v[46:47]
	v_lshl_add_u64 v[46:47], s[96:97], 0, v[46:47]
	v_lshl_add_u64 v[46:47], v[46:47], 0, s[94:95]
	v_lshl_add_u64 v[46:47], v[46:47], 0, v[98:99]
	global_store_dwordx4 v[46:47], v[42:45], off
	v_and_b32_e32 v47, 0xffff0000, v40
	v_lshlrev_b32_e32 v46, 16, v40
	v_mov_b32_e32 v44, v222
	v_and_b32_e32 v45, 0xffff0000, v41
	v_lshlrev_b32_e32 v44, 2, v44
	v_xor_b32_e32 v54, 4, v44
	v_mov_b32_e32 v44, v222
	v_mov_b32_e32 v48, v45
	v_lshlrev_b32_e32 v44, 2, v44
	v_xor_b32_e32 v55, 8, v44
	v_mov_b32_e32 v44, v222
	v_mov_b32_e32 v49, v47
	v_lshlrev_b32_e32 v44, 2, v44
	v_xor_b32_e32 v56, 16, v44
	v_mov_b32_e32 v44, v222
	v_pk_mul_f32 v[48:49], v[48:49], v[48:49]
	v_lshlrev_b32_e32 v44, 2, v44
	v_xor_b32_e32 v57, 16, v44
	v_mov_b32_e32 v44, v222
	v_and_b32_e32 v51, 0xffff0000, v38
	v_lshlrev_b32_e32 v44, 2, v44
	v_xor_b32_e32 v58, 16, v44
	v_mov_b32_e32 v44, v222
	v_lshlrev_b32_e32 v50, 16, v38
	v_lshlrev_b32_e32 v44, 2, v44
	v_xor_b32_e32 v59, 16, v44
	v_lshlrev_b32_e32 v44, 16, v41
	v_mov_b32_e32 v40, v44
	v_mov_b32_e32 v41, v46
	v_pk_fma_f32 v[40:41], v[40:41], v[40:41], v[48:49]
	v_and_b32_e32 v49, 0xffff0000, v39
	v_lshlrev_b32_e32 v48, 16, v39
	v_mov_b32_e32 v52, v51
	v_mov_b32_e32 v53, v49
	v_mov_b32_e32 v38, v50
	v_mov_b32_e32 v39, v48
	v_pk_mul_f32 v[52:53], v[52:53], v[52:53]
	v_lshl_or_b32 v42, s9, 2, v105
	v_pk_fma_f32 v[38:39], v[38:39], v[38:39], v[52:53]
	v_ashrrev_i32_e32 v43, 31, v42
	v_add_f32_e32 v38, v38, v39
	v_add_f32_e32 v38, v41, v38
	v_add_f32_e32 v38, v40, v38
	ds_bpermute_b32 v39, v54, v38
	v_lshlrev_b32_e32 v40, 2, v60
	v_xor_b32_e32 v52, 16, v40
	v_mov_b32_e32 v40, v222
	s_waitcnt lgkmcnt(0)
	v_add_f32_e32 v38, v38, v39
	ds_bpermute_b32 v39, v55, v38
	v_lshlrev_b32_e32 v40, 2, v40
	v_xor_b32_e32 v53, 16, v40
	v_mov_b32_e32 v40, v222
	s_waitcnt lgkmcnt(0)
	v_add_f32_e32 v38, v38, v39
	ds_bpermute_b32 v39, v56, v38
	v_lshlrev_b32_e32 v40, 2, v40
	v_xor_b32_e32 v54, 16, v40
	v_mov_b32_e32 v40, v222
	s_waitcnt lgkmcnt(0)
	v_add_f32_e32 v38, v38, v39
	v_fmamk_f32 v38, v38, 0x3c800000, v218
	v_mul_f32_e32 v39, 0x4f800000, v38
	v_cmp_gt_f32_e32 vcc, s79, v38
	v_lshlrev_b32_e32 v40, 2, v40
	v_xor_b32_e32 v55, 16, v40
	v_cndmask_b32_e32 v38, v38, v39, vcc
	v_sqrt_f32_e32 v39, v38
	v_mov_b32_e32 v40, v222
	v_lshlrev_b64 v[42:43], 18, v[42:43]
	v_add_u32_e32 v41, -1, v39
	v_fma_f32 v56, -v41, v39, v38
	v_cmp_ge_f32_e64 s[0:1], 0, v56
	v_add_u32_e32 v56, 1, v39
	v_lshlrev_b32_e32 v40, 2, v40
	v_cndmask_b32_e64 v41, v39, v41, s[0:1]
	v_fma_f32 v39, -v56, v39, v38
	v_cmp_lt_f32_e64 s[0:1], 0, v39
	v_lshl_or_b32 v42, s8, 6, v42
	s_nop 0
	v_cndmask_b32_e64 v39, v41, v56, s[0:1]
	v_mul_f32_e32 v41, 0x37800000, v39
	v_cndmask_b32_e32 v39, v39, v41, vcc
	v_cmp_class_f32_e32 vcc, v38, v205
	v_xor_b32_e32 v56, 16, v40
	s_nop 0
	v_cndmask_b32_e32 v38, v39, v38, vcc
	v_div_scale_f32 v39, s[0:1], v38, v38, 1.0
	v_rcp_f32_e32 v41, v39
	s_nop 0
	v_fma_f32 v40, -v39, v41, 1.0
	v_fmac_f32_e32 v41, v40, v41
	v_div_scale_f32 v40, vcc, 1.0, v38, 1.0
	v_mul_f32_e32 v60, v40, v41
	v_fma_f32 v61, -v39, v60, v40
	v_fmac_f32_e32 v60, v61, v41
	v_fma_f32 v39, -v39, v60, v40
	v_div_fmas_f32 v39, v39, v41, v60
	v_div_fixup_f32 v38, v39, v38, 1.0
	v_pk_mul_f32 v[40:41], v[38:39], v[50:51] op_sel_hi:[0,1]
	v_pk_mul_f32 v[40:41], v[14:15], v[40:41]
	ds_bpermute_b32 v39, v58, v41
	v_mov_b32_e32 v50, v34
	v_mov_b32_e32 v51, v36
	v_mov_b32_e32 v36, v35
	ds_bpermute_b32 v57, v57, v40
	s_waitcnt lgkmcnt(0)
	v_pk_mul_f32 v[34:35], v[38:39], v[48:49] op_sel_hi:[0,1]
	v_pk_mul_f32 v[34:35], v[16:17], v[34:35]
	v_pk_mul_f32 v[40:41], v[50:51], v[40:41]
	v_cndmask_b32_e64 v51, v39, -v39, s[2:3]
	ds_bpermute_b32 v39, v52, v35
	ds_bpermute_b32 v48, v59, v34
	v_cndmask_b32_e64 v50, v57, -v57, s[2:3]
	v_pk_fma_f32 v[36:37], v[36:37], v[50:51], v[40:41]
	v_mov_b32_e32 v41, v32
	s_waitcnt lgkmcnt(0)
	v_cndmask_b32_e64 v49, v39, -v39, s[2:3]
	v_cndmask_b32_e64 v48, v48, -v48, s[2:3]
	v_mov_b32_e32 v32, v31
	v_mov_b32_e32 v40, v30
	v_pk_mul_f32 v[30:31], v[32:33], v[48:49]
	v_pk_mul_f32 v[32:33], v[38:39], v[46:47] op_sel_hi:[0,1]
	v_pk_mul_f32 v[32:33], v[10:11], v[32:33]
	ds_bpermute_b32 v39, v54, v33
	ds_bpermute_b32 v46, v53, v32
	v_pk_fma_f32 v[30:31], v[40:41], v[34:35], v[30:31]
	v_mov_b32_e32 v35, v28
	v_mov_b32_e32 v28, v27
	s_waitcnt lgkmcnt(0)
	v_cndmask_b32_e64 v41, v39, -v39, s[2:3]
	v_cndmask_b32_e64 v40, v46, -v46, s[2:3]
	v_mov_b32_e32 v34, v26
	v_pk_mul_f32 v[26:27], v[28:29], v[40:41]
	v_pk_mul_f32 v[28:29], v[38:39], v[44:45] op_sel_hi:[0,1]
	v_pk_mul_f32 v[28:29], v[12:13], v[28:29]
	ds_bpermute_b32 v38, v56, v29
	ds_bpermute_b32 v39, v55, v28
	v_pk_fma_f32 v[26:27], v[34:35], v[32:33], v[26:27]
	v_mov_b32_e32 v33, v24
	v_mov_b32_e32 v24, v23
	s_waitcnt lgkmcnt(0)
	v_cndmask_b32_e64 v35, v38, -v38, s[2:3]
	v_cndmask_b32_e64 v34, v39, -v39, s[2:3]
	v_mov_b32_e32 v32, v22
	v_pk_mul_f32 v[22:23], v[24:25], v[34:35]
	v_cvt_pk_bf16_f32 v24, v26, v27
	v_pk_fma_f32 v[28:29], v[32:33], v[28:29], v[22:23]
	v_lshl_add_u64 v[32:33], v[42:43], 0, v[82:83]
	v_lshlrev_b64 v[26:27], 1, v[32:33]
	v_cvt_pk_bf16_f32 v22, v36, v37
	v_cvt_pk_bf16_f32 v23, v30, v31
	v_cvt_pk_bf16_f32 v25, v28, v29
	v_lshl_add_u64 v[28:29], v[86:87], 0, v[26:27]
	global_store_dwordx4 v[28:29], v[22:25], off
	s_nop 1
	v_lshl_add_u64 v[22:23], v[88:89], 0, v[26:27]
	global_store_dwordx4 v[22:23], v[18:21], off
	s_branch .LBB0_468

.LBB0_476:
	v_ashrrev_i32_e32 v90, 7, v26
	v_and_b32_e32 v27, 0xfff, v90
	v_cmp_lt_u32_e32 vcc, 1, v27
	v_mov_b32_e32 v38, 0
	v_lshlrev_b32_e32 v0, 1, v82
	v_mov_b32_e32 v42, 0
	v_mov_b32_e32 v43, 0
	v_mov_b32_e32 v44, 0
	v_mov_b32_e32 v45, 0
	v_mov_b32_e32 v46, 0
	v_mov_b32_e32 v47, 0
	v_mov_b32_e32 v48, 0
	v_mov_b32_e32 v49, 0
	s_and_saveexec_b64 s[0:1], vcc
	s_cbranch_execz .LBB0_478
	v_add_u32_e32 v30, -2, v90
	v_mov_b64_e32 v[28:29], s[74:75]
	v_mad_i64_i32 v[28:29], s[6:7], v30, s9, v[28:29]
	v_lshl_add_u64 v[28:29], v[28:29], 0, v[0:1]
	v_add_co_u32_e32 v30, vcc, 0x1000, v28
	s_nop 1
	v_addc_co_u32_e32 v31, vcc, 0, v29, vcc
	global_load_dwordx4 v[42:45], v[28:29], off offset:2048
	global_load_dwordx4 v[46:49], v[30:31], off
.LBB0_478:
	s_or_b64 exec, exec, s[0:1]
	v_cmp_ne_u32_e32 vcc, 0, v27
	v_mov_b32_e32 v39, 0
	v_mov_b32_e32 v40, 0
	v_mov_b32_e32 v41, 0
	v_mov_b32_e32 v58, 0
	v_mov_b32_e32 v59, 0
	v_mov_b32_e32 v60, 0
	v_mov_b32_e32 v61, 0
	s_and_saveexec_b64 s[0:1], vcc
	s_cbranch_execz .LBB0_480
	v_add_u32_e32 v27, -1, v90
	v_mov_b64_e32 v[28:29], s[74:75]
	v_mad_i64_i32 v[28:29], s[6:7], v27, s9, v[28:29]
	v_lshl_add_u64 v[28:29], v[28:29], 0, v[0:1]
	v_add_co_u32_e32 v30, vcc, 0x1000, v28
	s_nop 1
	v_addc_co_u32_e32 v31, vcc, 0, v29, vcc
	global_load_dwordx4 v[38:41], v[28:29], off offset:2048
	global_load_dwordx4 v[58:61], v[30:31], off
.LBB0_480:
	s_or_b64 exec, exec, s[0:1]
	v_mov_b64_e32 v[28:29], s[74:75]
	v_mad_i64_i32 v[28:29], s[0:1], v90, s9, v[28:29]
	v_lshl_add_u64 v[28:29], v[28:29], 0, v[0:1]
	v_add_co_u32_e32 v30, vcc, s12, v28
	v_add_u32_e32 v83, s8, v26
	s_nop 0
	v_addc_co_u32_e32 v31, vcc, 0, v29, vcc
	global_load_dwordx4 v[78:81], v[28:29], off offset:2048
	global_load_dwordx4 v[74:77], v[30:31], off
	v_mad_i64_i32 v[28:29], s[0:1], v90, s9, v[84:85]
	global_load_dwordx4 v[70:73], v[28:29], off
	v_ashrrev_i32_e32 v88, 7, v83
	v_and_b32_e32 v27, 0xfff, v88
	v_cmp_gt_i32_e64 s[0:1], s13, v83
	v_cmp_lt_u32_e32 vcc, 1, v27
	s_and_b64 s[10:11], s[0:1], vcc
	v_mov_b32_e32 v26, 0
	v_mov_b32_e32 v30, 0
	v_mov_b32_e32 v31, 0
	v_mov_b32_e32 v32, 0
	v_mov_b32_e32 v33, 0
	v_mov_b32_e32 v34, 0
	v_mov_b32_e32 v35, 0
	v_mov_b32_e32 v36, 0
	v_mov_b32_e32 v37, 0
	s_and_saveexec_b64 s[6:7], s[10:11]
	s_cbranch_execz .LBB0_482
	v_add_u32_e32 v30, -2, v88
	v_mov_b64_e32 v[28:29], s[74:75]
	v_mad_i64_i32 v[28:29], s[10:11], v30, s9, v[28:29]
	v_lshl_add_u64 v[28:29], v[28:29], 0, v[0:1]
	v_add_co_u32_e32 v34, vcc, 0x1000, v28
	s_nop 1
	v_addc_co_u32_e32 v35, vcc, 0, v29, vcc
	global_load_dwordx4 v[30:33], v[28:29], off offset:2048
	s_nop 0
	global_load_dwordx4 v[34:37], v[34:35], off
.LBB0_482:
	s_or_b64 exec, exec, s[6:7]
	v_cmp_ne_u32_e32 vcc, 0, v27
	s_and_b64 s[10:11], s[0:1], vcc
	v_mov_b32_e32 v27, 0
	v_mov_b32_e32 v28, 0
	v_mov_b32_e32 v29, 0
	v_mov_b32_e32 v50, 0
	v_mov_b32_e32 v51, 0
	v_mov_b32_e32 v52, 0
	v_mov_b32_e32 v53, 0
	s_and_saveexec_b64 s[6:7], s[10:11]
	s_cbranch_execz .LBB0_484
	v_add_u32_e32 v28, -1, v88
	v_mov_b64_e32 v[26:27], s[74:75]
	v_mad_i64_i32 v[26:27], s[10:11], v28, s9, v[26:27]
	v_lshl_add_u64 v[26:27], v[26:27], 0, v[0:1]
	v_add_co_u32_e32 v50, vcc, 0x1000, v26
	s_nop 1
	v_addc_co_u32_e32 v51, vcc, 0, v27, vcc
	global_load_dwordx4 v[26:29], v[26:27], off offset:2048
	s_nop 0
	global_load_dwordx4 v[50:53], v[50:51], off
.LBB0_484:
	s_or_b64 exec, exec, s[6:7]
	v_mov_b32_e32 v54, 0
	v_mov_b32_e32 v62, 0
	v_mov_b32_e32 v63, 0
	v_mov_b32_e32 v64, 0
	v_mov_b32_e32 v65, 0
	v_mov_b32_e32 v66, 0
	v_mov_b32_e32 v67, 0
	v_mov_b32_e32 v68, 0
	v_mov_b32_e32 v69, 0
	s_and_saveexec_b64 s[6:7], s[0:1]
	s_cbranch_execz .LBB0_486
	v_mov_b64_e32 v[56:57], s[74:75]
	v_mad_i64_i32 v[56:57], s[10:11], v88, s9, v[56:57]
	v_lshl_add_u64 v[56:57], v[56:57], 0, v[0:1]
	v_add_co_u32_e32 v66, vcc, 0x1000, v56
	s_nop 1
	v_addc_co_u32_e32 v67, vcc, 0, v57, vcc
	global_load_dwordx4 v[62:65], v[56:57], off offset:2048
	s_nop 0
	global_load_dwordx4 v[66:69], v[66:67], off
.LBB0_486:
	s_or_b64 exec, exec, s[6:7]
	v_mov_b32_e32 v55, 0
	v_mov_b32_e32 v56, 0
	v_mov_b32_e32 v57, 0
	s_and_saveexec_b64 s[6:7], s[0:1]
	s_cbranch_execz .LBB0_488
	v_mad_i64_i32 v[54:55], s[10:11], v88, s9, v[84:85]
	global_load_dwordx4 v[54:57], v[54:55], off
.LBB0_488:
	s_or_b64 exec, exec, s[6:7]
	s_waitcnt vmcnt(0) lgkmcnt(0)
	v_lshlrev_b32_e32 v92, 16, v42
	v_and_b32_e32 v93, 0xffff0000, v42
	v_lshlrev_b32_e32 v42, 16, v43
	v_and_b32_e32 v43, 0xffff0000, v43
	v_lshlrev_b32_e32 v94, 16, v46
	v_and_b32_e32 v95, 0xffff0000, v46
	v_pk_mul_f32 v[42:43], v[20:21], v[42:43]
	v_lshlrev_b32_e32 v46, 16, v47
	v_and_b32_e32 v47, 0xffff0000, v47
	v_pk_fma_f32 v[42:43], v[42:43], v[46:47], 0 op_sel_hi:[1,1,0]
	v_lshlrev_b32_e32 v46, 16, v39
	v_and_b32_e32 v47, 0xffff0000, v39
	v_lshlrev_b32_e32 v96, 16, v58
	v_and_b32_e32 v97, 0xffff0000, v58
	v_pk_mul_f32 v[46:47], v[12:13], v[46:47]
	v_lshlrev_b32_e32 v58, 16, v59
	v_and_b32_e32 v59, 0xffff0000, v59
	v_pk_fma_f32 v[42:43], v[46:47], v[58:59], v[42:43]
	v_lshlrev_b32_e32 v46, 16, v79
	v_and_b32_e32 v47, 0xffff0000, v79
	v_pk_mul_f32 v[46:47], v[4:5], v[46:47]
	v_lshlrev_b32_e32 v58, 16, v75
	v_and_b32_e32 v59, 0xffff0000, v75
	v_pk_fma_f32 v[42:43], v[46:47], v[58:59], v[42:43]
	v_lshlrev_b32_e32 v46, 16, v71
	v_and_b32_e32 v47, 0xffff0000, v71
	v_pk_mul_f32 v[42:43], v[42:43], v[46:47]
	v_lshlrev_b32_e32 v46, 16, v48
	v_cvt_pk_bf16_f32 v39, v42, v43
	v_lshlrev_b32_e32 v42, 16, v44
	v_and_b32_e32 v43, 0xffff0000, v44
	v_pk_mul_f32 v[42:43], v[22:23], v[42:43]
	v_and_b32_e32 v47, 0xffff0000, v48
	v_pk_fma_f32 v[42:43], v[42:43], v[46:47], 0 op_sel_hi:[1,1,0]
	v_lshlrev_b32_e32 v46, 16, v40
	v_and_b32_e32 v47, 0xffff0000, v40
	v_pk_mul_f32 v[46:47], v[14:15], v[46:47]
	v_lshlrev_b32_e32 v58, 16, v60
	v_and_b32_e32 v59, 0xffff0000, v60
	v_pk_fma_f32 v[42:43], v[46:47], v[58:59], v[42:43]
	v_lshlrev_b32_e32 v46, 16, v80
	v_and_b32_e32 v47, 0xffff0000, v80
	v_pk_mul_f32 v[46:47], v[6:7], v[46:47]
	v_lshlrev_b32_e32 v58, 16, v76
	v_and_b32_e32 v59, 0xffff0000, v76
	v_pk_fma_f32 v[42:43], v[46:47], v[58:59], v[42:43]
	v_lshlrev_b32_e32 v46, 16, v72
	v_and_b32_e32 v47, 0xffff0000, v72
	v_pk_mul_f32 v[42:43], v[42:43], v[46:47]
	v_lshlrev_b32_e32 v44, 16, v49
	v_cvt_pk_bf16_f32 v40, v42, v43
	v_lshlrev_b32_e32 v42, 16, v45
	v_and_b32_e32 v43, 0xffff0000, v45
	v_pk_mul_f32 v[42:43], v[24:25], v[42:43]
	v_and_b32_e32 v45, 0xffff0000, v49
	v_pk_mul_f32 v[92:93], v[18:19], v[92:93]
	v_pk_fma_f32 v[42:43], v[42:43], v[44:45], 0 op_sel_hi:[1,1,0]
	v_lshlrev_b32_e32 v44, 16, v41
	v_and_b32_e32 v45, 0xffff0000, v41
	v_pk_fma_f32 v[92:93], v[92:93], v[94:95], 0 op_sel_hi:[1,1,0]
	v_lshlrev_b32_e32 v94, 16, v38
	v_and_b32_e32 v95, 0xffff0000, v38
	v_pk_mul_f32 v[44:45], v[16:17], v[44:45]
	v_lshlrev_b32_e32 v46, 16, v61
	v_and_b32_e32 v47, 0xffff0000, v61
	v_pk_mul_f32 v[94:95], v[10:11], v[94:95]
	v_pk_fma_f32 v[42:43], v[44:45], v[46:47], v[42:43]
	v_lshlrev_b32_e32 v44, 16, v81
	v_and_b32_e32 v45, 0xffff0000, v81
	v_pk_fma_f32 v[92:93], v[94:95], v[96:97], v[92:93]
	v_lshlrev_b32_e32 v94, 16, v78
	v_and_b32_e32 v95, 0xffff0000, v78
	v_pk_mul_f32 v[44:45], v[8:9], v[44:45]
	v_lshlrev_b32_e32 v46, 16, v77
	v_and_b32_e32 v47, 0xffff0000, v77
	v_pk_mul_f32 v[94:95], v[2:3], v[94:95]
	v_lshlrev_b32_e32 v96, 16, v74
	v_and_b32_e32 v97, 0xffff0000, v74
	v_pk_fma_f32 v[42:43], v[44:45], v[46:47], v[42:43]
	v_lshlrev_b32_e32 v44, 16, v73
	v_and_b32_e32 v45, 0xffff0000, v73
	v_ashrrev_i32_e32 v91, 31, v90
	v_pk_fma_f32 v[92:93], v[94:95], v[96:97], v[92:93]
	v_lshlrev_b32_e32 v94, 16, v70
	v_and_b32_e32 v95, 0xffff0000, v70
	v_pk_mul_f32 v[42:43], v[42:43], v[44:45]
	v_pk_mul_f32 v[92:93], v[92:93], v[94:95]
	v_cvt_pk_bf16_f32 v41, v42, v43
	v_lshlrev_b64 v[42:43], 11, v[90:91]
	v_cvt_pk_bf16_f32 v38, v92, v93
	v_lshl_add_u64 v[42:43], v[86:87], 0, v[42:43]
	global_store_dwordx4 v[42:43], v[38:41], off
	s_and_saveexec_b64 s[6:7], s[0:1]
	s_cbranch_execz .LBB0_475
	v_lshlrev_b32_e32 v38, 16, v30
	v_and_b32_e32 v39, 0xffff0000, v30
	v_pk_mul_f32 v[38:39], v[18:19], v[38:39]
	v_lshlrev_b32_e32 v40, 16, v34
	v_and_b32_e32 v41, 0xffff0000, v34
	v_pk_fma_f32 v[38:39], v[38:39], v[40:41], 0 op_sel_hi:[1,1,0]
	v_lshlrev_b32_e32 v40, 16, v26
	v_and_b32_e32 v41, 0xffff0000, v26
	v_pk_mul_f32 v[40:41], v[10:11], v[40:41]
	v_lshlrev_b32_e32 v42, 16, v50
	v_and_b32_e32 v43, 0xffff0000, v50
	v_pk_fma_f32 v[38:39], v[40:41], v[42:43], v[38:39]
	v_lshlrev_b32_e32 v40, 16, v62
	v_and_b32_e32 v41, 0xffff0000, v62
	v_pk_mul_f32 v[40:41], v[2:3], v[40:41]
	v_lshlrev_b32_e32 v42, 16, v66
	v_and_b32_e32 v43, 0xffff0000, v66
	v_lshlrev_b32_e32 v30, 16, v31
	v_and_b32_e32 v31, 0xffff0000, v31
	v_pk_fma_f32 v[38:39], v[40:41], v[42:43], v[38:39]
	v_lshlrev_b32_e32 v40, 16, v54
	v_and_b32_e32 v41, 0xffff0000, v54
	v_pk_mul_f32 v[30:31], v[20:21], v[30:31]
	v_lshlrev_b32_e32 v34, 16, v35
	v_and_b32_e32 v35, 0xffff0000, v35
	v_pk_mul_f32 v[38:39], v[38:39], v[40:41]
	v_pk_fma_f32 v[30:31], v[30:31], v[34:35], 0 op_sel_hi:[1,1,0]
	v_lshlrev_b32_e32 v34, 16, v27
	v_and_b32_e32 v35, 0xffff0000, v27
	v_cvt_pk_bf16_f32 v26, v38, v39
	v_pk_mul_f32 v[34:35], v[12:13], v[34:35]
	v_lshlrev_b32_e32 v38, 16, v51
	v_and_b32_e32 v39, 0xffff0000, v51
	v_pk_fma_f32 v[30:31], v[34:35], v[38:39], v[30:31]
	v_lshlrev_b32_e32 v34, 16, v63
	v_and_b32_e32 v35, 0xffff0000, v63
	v_pk_mul_f32 v[34:35], v[4:5], v[34:35]
	v_lshlrev_b32_e32 v38, 16, v67
	v_and_b32_e32 v39, 0xffff0000, v67
	v_pk_fma_f32 v[30:31], v[34:35], v[38:39], v[30:31]
	v_lshlrev_b32_e32 v34, 16, v55
	v_and_b32_e32 v35, 0xffff0000, v55
	v_pk_mul_f32 v[30:31], v[30:31], v[34:35]
	v_lshlrev_b32_e32 v34, 16, v36
	v_cvt_pk_bf16_f32 v27, v30, v31
	v_lshlrev_b32_e32 v30, 16, v32
	v_and_b32_e32 v31, 0xffff0000, v32
	v_pk_mul_f32 v[30:31], v[22:23], v[30:31]
	v_and_b32_e32 v35, 0xffff0000, v36
	v_pk_fma_f32 v[30:31], v[30:31], v[34:35], 0 op_sel_hi:[1,1,0]
	v_lshlrev_b32_e32 v34, 16, v28
	v_and_b32_e32 v35, 0xffff0000, v28
	v_pk_mul_f32 v[34:35], v[14:15], v[34:35]
	v_lshlrev_b32_e32 v38, 16, v52
	v_and_b32_e32 v39, 0xffff0000, v52
	v_pk_fma_f32 v[30:31], v[34:35], v[38:39], v[30:31]
	v_lshlrev_b32_e32 v34, 16, v64
	v_and_b32_e32 v35, 0xffff0000, v64
	v_pk_mul_f32 v[34:35], v[6:7], v[34:35]
	v_lshlrev_b32_e32 v38, 16, v68
	v_and_b32_e32 v39, 0xffff0000, v68
	v_pk_fma_f32 v[30:31], v[34:35], v[38:39], v[30:31]
	v_lshlrev_b32_e32 v34, 16, v56
	v_and_b32_e32 v35, 0xffff0000, v56
	v_pk_mul_f32 v[30:31], v[30:31], v[34:35]
	v_lshlrev_b32_e32 v32, 16, v37
	v_cvt_pk_bf16_f32 v28, v30, v31
	v_lshlrev_b32_e32 v30, 16, v33
	v_and_b32_e32 v31, 0xffff0000, v33
	v_pk_mul_f32 v[30:31], v[24:25], v[30:31]
	v_and_b32_e32 v33, 0xffff0000, v37
	v_pk_fma_f32 v[30:31], v[30:31], v[32:33], 0 op_sel_hi:[1,1,0]
	v_lshlrev_b32_e32 v32, 16, v29
	v_and_b32_e32 v33, 0xffff0000, v29
	v_pk_mul_f32 v[32:33], v[16:17], v[32:33]
	v_lshlrev_b32_e32 v34, 16, v53
	v_and_b32_e32 v35, 0xffff0000, v53
	v_pk_fma_f32 v[30:31], v[32:33], v[34:35], v[30:31]
	v_lshlrev_b32_e32 v32, 16, v65
	v_and_b32_e32 v33, 0xffff0000, v65
	v_pk_mul_f32 v[32:33], v[8:9], v[32:33]
	v_lshlrev_b32_e32 v34, 16, v69
	v_and_b32_e32 v35, 0xffff0000, v69
	v_pk_fma_f32 v[30:31], v[32:33], v[34:35], v[30:31]
	v_lshlrev_b32_e32 v32, 16, v57
	v_and_b32_e32 v33, 0xffff0000, v57
	v_pk_mul_f32 v[30:31], v[30:31], v[32:33]
	v_ashrrev_i32_e32 v89, 31, v88
	v_cvt_pk_bf16_f32 v29, v30, v31
	v_lshlrev_b64 v[30:31], 11, v[88:89]
	v_lshl_add_u64 v[30:31], v[86:87], 0, v[30:31]
	global_store_dwordx4 v[30:31], v[26:29], off
	s_branch .LBB0_475

.LBB0_498:
	v_lshl_add_u64 v[34:35], s[12:13], 0, v[0:1]
	v_add_co_u32_e32 v12, vcc, 0x1f800000, v34
	v_lshl_add_u64 v[10:11], s[6:7], 0, v[0:1]
	s_nop 0
	v_addc_co_u32_e32 v13, vcc, 0, v35, vcc
	global_load_dwordx4 v[36:39], v[12:13], off
	v_add_co_u32_e32 v14, vcc, 0xf801000, v10
	s_mov_b32 s0, 0xf803000
	s_nop 0
	v_addc_co_u32_e32 v15, vcc, 0, v11, vcc
	global_load_dwordx4 v[40:43], v[14:15], off offset:2048
	global_load_dwordx4 v[30:33], v[12:13], off offset:1024
	global_load_dwordx4 v[26:29], v[14:15], off offset:3072
	global_load_dwordx4 v[18:21], v[12:13], off offset:2048
	v_add_co_u32_e32 v10, vcc, s0, v10
	s_add_i32 s2, s2, s4
	s_nop 0
	v_addc_co_u32_e32 v11, vcc, 0, v11, vcc
	global_load_dwordx4 v[22:25], v[10:11], off offset:2048
	global_load_dwordx4 v[14:17], v[12:13], off offset:3072
	s_nop 0
	global_load_dwordx4 v[10:13], v[10:11], off offset:3072
	s_add_u32 s6, s6, s10
	s_addc_u32 s7, s7, s11
	s_add_u32 s12, s12, s16
	s_addc_u32 s13, s13, s17
	s_cmpk_gt_i32 s2, 0x7fff
	s_waitcnt vmcnt(0) lgkmcnt(0)
	v_lshlrev_b32_e32 v44, 16, v39
	v_and_b32_e32 v45, 0xffff0000, v39
	v_lshlrev_b32_e32 v48, 16, v38
	v_and_b32_e32 v49, 0xffff0000, v38
	v_lshlrev_b32_e32 v38, 16, v42
	v_and_b32_e32 v39, 0xffff0000, v42
	v_lshlrev_b32_e32 v46, 16, v43
	v_and_b32_e32 v47, 0xffff0000, v43
	v_mul_f32_e32 v42, 0xbfb8aa3b, v38
	v_mul_f32_e32 v43, 0xbfb8aa3b, v39
	v_exp_f32_e32 v42, v42
	v_exp_f32_e32 v43, v43
	v_lshlrev_b32_e32 v50, 16, v41
	v_and_b32_e32 v51, 0xffff0000, v41
	v_add_f32_e32 v42, 1.0, v42
	v_add_f32_e32 v43, 1.0, v43
	v_rcp_f32_e32 v42, v42
	v_rcp_f32_e32 v43, v43
	v_mov_b32_e32 v55, v45
	v_mov_b32_e32 v57, v49
	v_pk_mul_f32 v[38:39], v[42:43], v[38:39]
	v_lshlrev_b32_e32 v42, 16, v37
	v_and_b32_e32 v43, 0xffff0000, v37
	v_mul_f32_e32 v37, 0xbfb8aa3b, v50
	v_exp_f32_e32 v37, v37
	v_mov_b32_e32 v54, v43
	v_pk_mul_f32 v[54:55], v[54:55], v[54:55]
	v_add_f32_e32 v37, 1.0, v37
	v_rcp_f32_e32 v52, v37
	v_mul_f32_e32 v37, 0xbfb8aa3b, v51
	v_exp_f32_e32 v37, v37
	s_nop 0
	v_add_f32_e32 v37, 1.0, v37
	v_rcp_f32_e32 v53, v37
	v_and_b32_e32 v37, 0xffff0000, v40
	v_mul_f32_e32 v41, 0xbfb8aa3b, v37
	v_exp_f32_e32 v41, v41
	v_pk_mul_f32 v[50:51], v[52:53], v[50:51]
	v_lshlrev_b32_e32 v52, 16, v36
	v_and_b32_e32 v53, 0xffff0000, v36
	v_lshlrev_b32_e32 v36, 16, v40
	v_mul_f32_e32 v40, 0xbfb8aa3b, v36
	v_exp_f32_e32 v40, v40
	v_add_f32_e32 v41, 1.0, v41
	v_rcp_f32_e32 v41, v41
	v_mov_b32_e32 v56, v53
	v_add_f32_e32 v40, 1.0, v40
	v_rcp_f32_e32 v40, v40
	v_pk_mul_f32 v[56:57], v[56:57], v[56:57]
	v_pk_mul_f32 v[36:37], v[40:41], v[36:37]
	v_mov_b32_e32 v40, v42
	v_mov_b32_e32 v41, v44
	v_pk_fma_f32 v[40:41], v[40:41], v[40:41], v[54:55]
	v_mov_b32_e32 v54, v52
	v_mov_b32_e32 v55, v48
	v_pk_fma_f32 v[54:55], v[54:55], v[54:55], v[56:57]
	s_nop 0
	v_pk_add_f32 v[40:41], v[54:55], v[40:41]
	s_nop 0
	v_add_f32_e32 v40, v40, v41
	s_nop 1
	v_add_f32_dpp v40, v40, v40 row_ror:8 row_mask:0xf bank_mask:0xf bound_ctrl:1
	s_nop 1
	v_add_f32_dpp v40, v40, v40 row_ror:4 row_mask:0xf bank_mask:0xf bound_ctrl:1
	s_nop 1
	v_add_f32_dpp v40, v40, v40 row_ror:2 row_mask:0xf bank_mask:0xf bound_ctrl:1
	s_nop 1
	v_add_f32_dpp v40, v40, v40 row_ror:1 row_mask:0xf bank_mask:0xf bound_ctrl:1
	v_fmamk_f32 v40, v40, 0x3c000000, v218
	v_cmp_gt_f32_e32 vcc, s79, v40
	v_mul_f32_e32 v41, 0x4f800000, v40
	s_nop 0
	v_cndmask_b32_e32 v40, v40, v41, vcc
	v_sqrt_f32_e32 v41, v40
	s_nop 0
	v_add_u32_e32 v54, -1, v41
	v_fma_f32 v55, -v54, v41, v40
	v_cmp_ge_f32_e64 s[0:1], 0, v55
	v_add_u32_e32 v55, 1, v41
	s_nop 0
	v_cndmask_b32_e64 v54, v41, v54, s[0:1]
	v_fma_f32 v41, -v55, v41, v40
	v_cmp_lt_f32_e64 s[0:1], 0, v41
	s_nop 1
	v_cndmask_b32_e64 v41, v54, v55, s[0:1]
	v_mul_f32_e32 v54, 0x37800000, v41
	v_cndmask_b32_e32 v41, v41, v54, vcc
	v_cmp_class_f32_e32 vcc, v40, v205
	s_nop 1
	v_cndmask_b32_e32 v40, v41, v40, vcc
	v_div_scale_f32 v41, s[0:1], v40, v40, 1.0
	v_rcp_f32_e32 v54, v41
	s_mov_b32 s0, 0xb800000
	v_fma_f32 v55, -v41, v54, 1.0
	v_fmac_f32_e32 v54, v55, v54
	v_div_scale_f32 v55, vcc, 1.0, v40, 1.0
	v_mul_f32_e32 v56, v55, v54
	v_fma_f32 v57, -v41, v56, v55
	v_fmac_f32_e32 v56, v57, v54
	v_fma_f32 v41, -v41, v56, v55
	v_div_fmas_f32 v41, v41, v54, v56
	v_div_fixup_f32 v40, v41, v40, 1.0
	v_pk_mul_f32 v[52:53], v[40:41], v[52:53] op_sel_hi:[0,1]
	v_pk_mul_f32 v[42:43], v[40:41], v[42:43] op_sel_hi:[0,1]
	v_pk_mul_f32 v[48:49], v[40:41], v[48:49] op_sel_hi:[0,1]
	v_mul_f32_e32 v41, 0xbfb8aa3b, v46
	v_exp_f32_e32 v41, v41
	v_pk_mul_f32 v[48:49], v[2:3], v[48:49]
	v_pk_mul_f32 v[52:53], v[6:7], v[52:53]
	v_pk_mul_f32 v[38:39], v[38:39], v[48:49]
	v_add_f32_e32 v41, 1.0, v41
	v_rcp_f32_e32 v48, v41
	v_pk_mul_f32 v[40:41], v[40:41], v[44:45] op_sel_hi:[0,1]
	v_mul_f32_e32 v44, 0xbfb8aa3b, v47
	v_exp_f32_e32 v44, v44
	v_pk_mul_f32 v[42:43], v[8:9], v[42:43]
	v_pk_mul_f32 v[36:37], v[36:37], v[52:53]
	v_pk_mul_f32 v[42:43], v[50:51], v[42:43]
	v_add_f32_e32 v44, 1.0, v44
	v_rcp_f32_e32 v49, v44
	v_cvt_pk_bf16_f32 v36, v36, v37
	v_cvt_pk_bf16_f32 v37, v42, v43
	v_lshlrev_b32_e32 v42, 16, v27
	v_and_b32_e32 v43, 0xffff0000, v27
	v_mul_f32_e32 v27, 0xbfb8aa3b, v42
	v_exp_f32_e32 v27, v27
	v_pk_mul_f32 v[40:41], v[4:5], v[40:41]
	v_pk_mul_f32 v[44:45], v[48:49], v[46:47]
	v_add_co_u32_e32 v34, vcc, s0, v34
	v_pk_mul_f32 v[40:41], v[44:45], v[40:41]
	v_cvt_pk_bf16_f32 v38, v38, v39
	v_cvt_pk_bf16_f32 v39, v40, v41
	v_addc_co_u32_e32 v35, vcc, 0, v35, vcc
	global_store_dwordx4 v[34:35], v[36:39], off
	v_lshlrev_b32_e32 v40, 16, v32
	v_and_b32_e32 v41, 0xffff0000, v32
	v_lshlrev_b32_e32 v36, 16, v33
	v_and_b32_e32 v37, 0xffff0000, v33
	v_lshlrev_b32_e32 v32, 16, v28
	v_and_b32_e32 v33, 0xffff0000, v28
	v_add_f32_e32 v27, 1.0, v27
	v_lshlrev_b32_e32 v38, 16, v29
	v_and_b32_e32 v39, 0xffff0000, v29
	v_mul_f32_e32 v28, 0xbfb8aa3b, v32
	v_mul_f32_e32 v29, 0xbfb8aa3b, v33
	v_rcp_f32_e32 v44, v27
	v_mul_f32_e32 v27, 0xbfb8aa3b, v43
	v_exp_f32_e32 v28, v28
	v_exp_f32_e32 v29, v29
	v_exp_f32_e32 v27, v27
	v_mov_b32_e32 v47, v37
	v_add_f32_e32 v28, 1.0, v28
	v_add_f32_e32 v29, 1.0, v29
	v_add_f32_e32 v27, 1.0, v27
	v_rcp_f32_e32 v28, v28
	v_rcp_f32_e32 v29, v29
	v_rcp_f32_e32 v45, v27
	v_mov_b32_e32 v49, v41
	v_pk_mul_f32 v[28:29], v[28:29], v[32:33]
	v_lshlrev_b32_e32 v32, 16, v31
	v_and_b32_e32 v33, 0xffff0000, v31
	v_pk_mul_f32 v[42:43], v[44:45], v[42:43]
	v_lshlrev_b32_e32 v44, 16, v30
	v_and_b32_e32 v45, 0xffff0000, v30
	v_lshlrev_b32_e32 v30, 16, v26
	v_and_b32_e32 v31, 0xffff0000, v26
	v_mul_f32_e32 v26, 0xbfb8aa3b, v30
	v_mul_f32_e32 v27, 0xbfb8aa3b, v31
	v_exp_f32_e32 v26, v26
	v_exp_f32_e32 v27, v27
	v_mov_b32_e32 v46, v33
	v_pk_mul_f32 v[46:47], v[46:47], v[46:47]
	v_add_f32_e32 v26, 1.0, v26
	v_add_f32_e32 v27, 1.0, v27
	v_rcp_f32_e32 v26, v26
	v_rcp_f32_e32 v27, v27
	v_mov_b32_e32 v48, v45
	v_pk_mul_f32 v[48:49], v[48:49], v[48:49]
	v_pk_mul_f32 v[26:27], v[26:27], v[30:31]
	v_mov_b32_e32 v30, v32
	v_mov_b32_e32 v31, v36
	v_pk_fma_f32 v[30:31], v[30:31], v[30:31], v[46:47]
	v_mov_b32_e32 v46, v44
	v_mov_b32_e32 v47, v40
	v_pk_fma_f32 v[46:47], v[46:47], v[46:47], v[48:49]
	s_nop 0
	v_pk_add_f32 v[30:31], v[46:47], v[30:31]
	s_nop 0
	v_add_f32_e32 v30, v30, v31
	s_nop 1
	v_add_f32_dpp v30, v30, v30 row_ror:8 row_mask:0xf bank_mask:0xf bound_ctrl:1
	s_nop 1
	v_add_f32_dpp v30, v30, v30 row_ror:4 row_mask:0xf bank_mask:0xf bound_ctrl:1
	s_nop 1
	v_add_f32_dpp v30, v30, v30 row_ror:2 row_mask:0xf bank_mask:0xf bound_ctrl:1
	s_nop 1
	v_add_f32_dpp v30, v30, v30 row_ror:1 row_mask:0xf bank_mask:0xf bound_ctrl:1
	v_fmamk_f32 v30, v30, 0x3c000000, v218
	v_cmp_gt_f32_e32 vcc, s79, v30
	v_mul_f32_e32 v31, 0x4f800000, v30
	s_nop 0
	v_cndmask_b32_e32 v30, v30, v31, vcc
	v_sqrt_f32_e32 v31, v30
	s_nop 0
	v_add_u32_e32 v46, -1, v31
	v_fma_f32 v47, -v46, v31, v30
	v_cmp_ge_f32_e64 s[0:1], 0, v47
	v_add_u32_e32 v47, 1, v31
	s_nop 0
	v_cndmask_b32_e64 v46, v31, v46, s[0:1]
	v_fma_f32 v31, -v47, v31, v30
	v_cmp_lt_f32_e64 s[0:1], 0, v31
	s_nop 1
	v_cndmask_b32_e64 v31, v46, v47, s[0:1]
	v_mul_f32_e32 v46, 0x37800000, v31
	v_cndmask_b32_e32 v31, v31, v46, vcc
	v_cmp_class_f32_e32 vcc, v30, v205
	s_nop 1
	v_cndmask_b32_e32 v30, v31, v30, vcc
	v_div_scale_f32 v31, s[0:1], v30, v30, 1.0
	v_rcp_f32_e32 v46, v31
	s_nop 0
	v_fma_f32 v47, -v31, v46, 1.0
	v_fmac_f32_e32 v46, v47, v46
	v_div_scale_f32 v47, vcc, 1.0, v30, 1.0
	v_mul_f32_e32 v48, v47, v46
	v_fma_f32 v49, -v31, v48, v47
	v_fmac_f32_e32 v48, v49, v46
	v_fma_f32 v31, -v31, v48, v47
	v_div_fmas_f32 v31, v31, v46, v48
	v_div_fixup_f32 v30, v31, v30, 1.0
	v_pk_mul_f32 v[44:45], v[30:31], v[44:45] op_sel_hi:[0,1]
	v_pk_mul_f32 v[32:33], v[30:31], v[32:33] op_sel_hi:[0,1]
	v_pk_mul_f32 v[40:41], v[30:31], v[40:41] op_sel_hi:[0,1]
	v_mul_f32_e32 v31, 0xbfb8aa3b, v38
	v_exp_f32_e32 v31, v31
	v_pk_mul_f32 v[40:41], v[2:3], v[40:41]
	v_pk_mul_f32 v[44:45], v[6:7], v[44:45]
	v_pk_mul_f32 v[28:29], v[28:29], v[40:41]
	v_add_f32_e32 v31, 1.0, v31
	v_rcp_f32_e32 v40, v31
	v_pk_mul_f32 v[30:31], v[30:31], v[36:37] op_sel_hi:[0,1]
	v_mul_f32_e32 v36, 0xbfb8aa3b, v39
	v_exp_f32_e32 v36, v36
	v_pk_mul_f32 v[32:33], v[8:9], v[32:33]
	v_pk_mul_f32 v[30:31], v[4:5], v[30:31]
	v_pk_mul_f32 v[26:27], v[26:27], v[44:45]
	v_add_f32_e32 v36, 1.0, v36
	v_rcp_f32_e32 v41, v36
	v_pk_mul_f32 v[32:33], v[42:43], v[32:33]
	v_cvt_pk_bf16_f32 v26, v26, v27
	v_cvt_pk_bf16_f32 v27, v32, v33
	v_pk_mul_f32 v[36:37], v[40:41], v[38:39]
	v_cvt_pk_bf16_f32 v28, v28, v29
	v_pk_mul_f32 v[30:31], v[36:37], v[30:31]
	v_lshlrev_b32_e32 v32, 16, v23
	v_cvt_pk_bf16_f32 v29, v30, v31
	global_store_dwordx4 v[34:35], v[26:29], off offset:1024
	v_lshlrev_b32_e32 v30, 16, v20
	v_and_b32_e32 v31, 0xffff0000, v20
	v_lshlrev_b32_e32 v26, 16, v21
	v_and_b32_e32 v27, 0xffff0000, v21
	v_lshlrev_b32_e32 v20, 16, v24
	v_and_b32_e32 v21, 0xffff0000, v24
	v_lshlrev_b32_e32 v28, 16, v25
	v_and_b32_e32 v29, 0xffff0000, v25
	v_mul_f32_e32 v24, 0xbfb8aa3b, v20
	v_mul_f32_e32 v25, 0xbfb8aa3b, v21
	v_exp_f32_e32 v24, v24
	v_exp_f32_e32 v25, v25
	v_and_b32_e32 v33, 0xffff0000, v23
	v_mov_b32_e32 v39, v27
	v_add_f32_e32 v24, 1.0, v24
	v_add_f32_e32 v25, 1.0, v25
	v_rcp_f32_e32 v24, v24
	v_rcp_f32_e32 v25, v25
	v_mov_b32_e32 v41, v31
	v_pk_mul_f32 v[20:21], v[24:25], v[20:21]
	v_lshlrev_b32_e32 v24, 16, v19
	v_and_b32_e32 v25, 0xffff0000, v19
	v_mul_f32_e32 v19, 0xbfb8aa3b, v32
	v_exp_f32_e32 v19, v19
	v_mov_b32_e32 v38, v25
	v_pk_mul_f32 v[38:39], v[38:39], v[38:39]
	v_add_f32_e32 v19, 1.0, v19
	v_rcp_f32_e32 v36, v19
	v_mul_f32_e32 v19, 0xbfb8aa3b, v33
	v_exp_f32_e32 v19, v19
	s_nop 0
	v_add_f32_e32 v19, 1.0, v19
	v_rcp_f32_e32 v37, v19
	v_and_b32_e32 v19, 0xffff0000, v22
	v_mul_f32_e32 v23, 0xbfb8aa3b, v19
	v_exp_f32_e32 v23, v23
	v_pk_mul_f32 v[32:33], v[36:37], v[32:33]
	v_lshlrev_b32_e32 v36, 16, v18
	v_and_b32_e32 v37, 0xffff0000, v18
	v_lshlrev_b32_e32 v18, 16, v22
	v_mul_f32_e32 v22, 0xbfb8aa3b, v18
	v_exp_f32_e32 v22, v22
	v_add_f32_e32 v23, 1.0, v23
	v_rcp_f32_e32 v23, v23
	v_mov_b32_e32 v40, v37
	v_add_f32_e32 v22, 1.0, v22
	v_rcp_f32_e32 v22, v22
	v_pk_mul_f32 v[40:41], v[40:41], v[40:41]
	v_pk_mul_f32 v[18:19], v[22:23], v[18:19]
	v_mov_b32_e32 v22, v24
	v_mov_b32_e32 v23, v26
	v_pk_fma_f32 v[22:23], v[22:23], v[22:23], v[38:39]
	v_mov_b32_e32 v38, v36
	v_mov_b32_e32 v39, v30
	v_pk_fma_f32 v[38:39], v[38:39], v[38:39], v[40:41]
	s_nop 0
	v_pk_add_f32 v[22:23], v[38:39], v[22:23]
	s_nop 0
	v_add_f32_e32 v22, v22, v23
	s_nop 1
	v_add_f32_dpp v22, v22, v22 row_ror:8 row_mask:0xf bank_mask:0xf bound_ctrl:1
	s_nop 1
	v_add_f32_dpp v22, v22, v22 row_ror:4 row_mask:0xf bank_mask:0xf bound_ctrl:1
	s_nop 1
	v_add_f32_dpp v22, v22, v22 row_ror:2 row_mask:0xf bank_mask:0xf bound_ctrl:1
	s_nop 1
	v_add_f32_dpp v22, v22, v22 row_ror:1 row_mask:0xf bank_mask:0xf bound_ctrl:1
	v_fmamk_f32 v22, v22, 0x3c000000, v218
	v_cmp_gt_f32_e32 vcc, s79, v22
	v_mul_f32_e32 v23, 0x4f800000, v22
	s_nop 0
	v_cndmask_b32_e32 v22, v22, v23, vcc
	v_sqrt_f32_e32 v23, v22
	s_nop 0
	v_add_u32_e32 v38, -1, v23
	v_fma_f32 v39, -v38, v23, v22
	v_cmp_ge_f32_e64 s[0:1], 0, v39
	v_add_u32_e32 v39, 1, v23
	s_nop 0
	v_cndmask_b32_e64 v38, v23, v38, s[0:1]
	v_fma_f32 v23, -v39, v23, v22
	v_cmp_lt_f32_e64 s[0:1], 0, v23
	s_nop 1
	v_cndmask_b32_e64 v23, v38, v39, s[0:1]
	v_mul_f32_e32 v38, 0x37800000, v23
	v_cndmask_b32_e32 v23, v23, v38, vcc
	v_cmp_class_f32_e32 vcc, v22, v205
	s_nop 1
	v_cndmask_b32_e32 v22, v23, v22, vcc
	v_div_scale_f32 v23, s[0:1], v22, v22, 1.0
	v_rcp_f32_e32 v38, v23
	s_nop 0
	v_fma_f32 v39, -v23, v38, 1.0
	v_fmac_f32_e32 v38, v39, v38
	v_div_scale_f32 v39, vcc, 1.0, v22, 1.0
	v_mul_f32_e32 v40, v39, v38
	v_fma_f32 v41, -v23, v40, v39
	v_fmac_f32_e32 v40, v41, v38
	v_fma_f32 v23, -v23, v40, v39
	v_div_fmas_f32 v23, v23, v38, v40
	v_div_fixup_f32 v22, v23, v22, 1.0
	v_pk_mul_f32 v[36:37], v[22:23], v[36:37] op_sel_hi:[0,1]
	v_pk_mul_f32 v[24:25], v[22:23], v[24:25] op_sel_hi:[0,1]
	v_pk_mul_f32 v[30:31], v[22:23], v[30:31] op_sel_hi:[0,1]
	v_mul_f32_e32 v23, 0xbfb8aa3b, v28
	v_exp_f32_e32 v23, v23
	v_pk_mul_f32 v[30:31], v[2:3], v[30:31]
	v_pk_mul_f32 v[36:37], v[6:7], v[36:37]
	v_pk_mul_f32 v[20:21], v[20:21], v[30:31]
	v_add_f32_e32 v23, 1.0, v23
	v_rcp_f32_e32 v30, v23
	v_pk_mul_f32 v[22:23], v[22:23], v[26:27] op_sel_hi:[0,1]
	v_mul_f32_e32 v26, 0xbfb8aa3b, v29
	v_exp_f32_e32 v26, v26
	v_pk_mul_f32 v[24:25], v[8:9], v[24:25]
	v_pk_mul_f32 v[18:19], v[18:19], v[36:37]
	v_pk_mul_f32 v[24:25], v[32:33], v[24:25]
	v_add_f32_e32 v26, 1.0, v26
	v_rcp_f32_e32 v31, v26
	v_cvt_pk_bf16_f32 v18, v18, v19
	v_cvt_pk_bf16_f32 v19, v24, v25
	v_lshlrev_b32_e32 v24, 16, v11
	v_and_b32_e32 v25, 0xffff0000, v11
	v_mul_f32_e32 v11, 0xbfb8aa3b, v24
	v_exp_f32_e32 v11, v11
	v_pk_mul_f32 v[22:23], v[4:5], v[22:23]
	v_pk_mul_f32 v[26:27], v[30:31], v[28:29]
	v_cvt_pk_bf16_f32 v20, v20, v21
	v_pk_mul_f32 v[22:23], v[26:27], v[22:23]
	v_add_f32_e32 v11, 1.0, v11
	v_cvt_pk_bf16_f32 v21, v22, v23
	global_store_dwordx4 v[34:35], v[18:21], off offset:2048
	v_lshlrev_b32_e32 v22, 16, v16
	v_and_b32_e32 v23, 0xffff0000, v16
	v_lshlrev_b32_e32 v18, 16, v17
	v_and_b32_e32 v19, 0xffff0000, v17
	v_lshlrev_b32_e32 v16, 16, v12
	v_and_b32_e32 v17, 0xffff0000, v12
	v_lshlrev_b32_e32 v20, 16, v13
	v_and_b32_e32 v21, 0xffff0000, v13
	v_mul_f32_e32 v12, 0xbfb8aa3b, v16
	v_mul_f32_e32 v13, 0xbfb8aa3b, v17
	v_rcp_f32_e32 v26, v11
	v_mul_f32_e32 v11, 0xbfb8aa3b, v25
	v_exp_f32_e32 v12, v12
	v_exp_f32_e32 v13, v13
	v_exp_f32_e32 v11, v11
	v_mov_b32_e32 v29, v19
	v_add_f32_e32 v12, 1.0, v12
	v_add_f32_e32 v13, 1.0, v13
	v_add_f32_e32 v11, 1.0, v11
	v_rcp_f32_e32 v12, v12
	v_rcp_f32_e32 v13, v13
	v_rcp_f32_e32 v27, v11
	v_mov_b32_e32 v31, v23
	v_pk_mul_f32 v[12:13], v[12:13], v[16:17]
	v_lshlrev_b32_e32 v16, 16, v15
	v_and_b32_e32 v17, 0xffff0000, v15
	v_pk_mul_f32 v[24:25], v[26:27], v[24:25]
	v_lshlrev_b32_e32 v26, 16, v14
	v_and_b32_e32 v27, 0xffff0000, v14
	v_lshlrev_b32_e32 v14, 16, v10
	v_and_b32_e32 v15, 0xffff0000, v10
	v_mul_f32_e32 v10, 0xbfb8aa3b, v14
	v_mul_f32_e32 v11, 0xbfb8aa3b, v15
	v_exp_f32_e32 v10, v10
	v_exp_f32_e32 v11, v11
	v_mov_b32_e32 v28, v17
	v_pk_mul_f32 v[28:29], v[28:29], v[28:29]
	v_add_f32_e32 v10, 1.0, v10
	v_add_f32_e32 v11, 1.0, v11
	v_rcp_f32_e32 v10, v10
	v_rcp_f32_e32 v11, v11
	v_mov_b32_e32 v30, v27
	v_pk_mul_f32 v[30:31], v[30:31], v[30:31]
	v_pk_mul_f32 v[10:11], v[10:11], v[14:15]
	v_mov_b32_e32 v14, v16
	v_mov_b32_e32 v15, v18
	v_pk_fma_f32 v[14:15], v[14:15], v[14:15], v[28:29]
	v_mov_b32_e32 v28, v26
	v_mov_b32_e32 v29, v22
	v_pk_fma_f32 v[28:29], v[28:29], v[28:29], v[30:31]
	s_nop 0
	v_pk_add_f32 v[14:15], v[28:29], v[14:15]
	s_nop 0
	v_add_f32_e32 v14, v14, v15
	s_nop 1
	v_add_f32_dpp v14, v14, v14 row_ror:8 row_mask:0xf bank_mask:0xf bound_ctrl:1
	s_nop 1
	v_add_f32_dpp v14, v14, v14 row_ror:4 row_mask:0xf bank_mask:0xf bound_ctrl:1
	s_nop 1
	v_add_f32_dpp v14, v14, v14 row_ror:2 row_mask:0xf bank_mask:0xf bound_ctrl:1
	s_nop 1
	v_add_f32_dpp v14, v14, v14 row_ror:1 row_mask:0xf bank_mask:0xf bound_ctrl:1
	v_fmamk_f32 v14, v14, 0x3c000000, v218
	v_cmp_gt_f32_e32 vcc, s79, v14
	v_mul_f32_e32 v15, 0x4f800000, v14
	s_nop 0
	v_cndmask_b32_e32 v14, v14, v15, vcc
	v_sqrt_f32_e32 v15, v14
	s_nop 0
	v_add_u32_e32 v28, -1, v15
	v_fma_f32 v29, -v28, v15, v14
	v_cmp_ge_f32_e64 s[0:1], 0, v29
	v_add_u32_e32 v29, 1, v15
	s_nop 0
	v_cndmask_b32_e64 v28, v15, v28, s[0:1]
	v_fma_f32 v15, -v29, v15, v14
	v_cmp_lt_f32_e64 s[0:1], 0, v15
	s_nop 1
	v_cndmask_b32_e64 v15, v28, v29, s[0:1]
	v_mul_f32_e32 v28, 0x37800000, v15
	v_cndmask_b32_e32 v15, v15, v28, vcc
	v_cmp_class_f32_e32 vcc, v14, v205
	s_nop 1
	v_cndmask_b32_e32 v14, v15, v14, vcc
	v_div_scale_f32 v15, s[0:1], v14, v14, 1.0
	v_rcp_f32_e32 v28, v15
	s_nop 0
	v_fma_f32 v29, -v15, v28, 1.0
	v_fmac_f32_e32 v28, v29, v28
	v_div_scale_f32 v29, vcc, 1.0, v14, 1.0
	v_mul_f32_e32 v30, v29, v28
	v_fma_f32 v31, -v15, v30, v29
	v_fmac_f32_e32 v30, v31, v28
	v_fma_f32 v15, -v15, v30, v29
	v_div_fmas_f32 v15, v15, v28, v30
	v_div_fixup_f32 v14, v15, v14, 1.0
	v_pk_mul_f32 v[26:27], v[14:15], v[26:27] op_sel_hi:[0,1]
	v_pk_mul_f32 v[16:17], v[14:15], v[16:17] op_sel_hi:[0,1]
	v_pk_mul_f32 v[22:23], v[14:15], v[22:23] op_sel_hi:[0,1]
	v_mul_f32_e32 v15, 0xbfb8aa3b, v20
	v_exp_f32_e32 v15, v15
	v_pk_mul_f32 v[22:23], v[2:3], v[22:23]
	v_pk_mul_f32 v[26:27], v[6:7], v[26:27]
	v_pk_mul_f32 v[12:13], v[12:13], v[22:23]
	v_add_f32_e32 v15, 1.0, v15
	v_rcp_f32_e32 v22, v15
	v_pk_mul_f32 v[14:15], v[14:15], v[18:19] op_sel_hi:[0,1]
	v_mul_f32_e32 v18, 0xbfb8aa3b, v21
	v_exp_f32_e32 v18, v18
	v_pk_mul_f32 v[16:17], v[8:9], v[16:17]
	v_pk_mul_f32 v[14:15], v[4:5], v[14:15]
	v_pk_mul_f32 v[10:11], v[10:11], v[26:27]
	v_add_f32_e32 v18, 1.0, v18
	v_rcp_f32_e32 v23, v18
	v_pk_mul_f32 v[16:17], v[24:25], v[16:17]
	v_cvt_pk_bf16_f32 v10, v10, v11
	v_cvt_pk_bf16_f32 v11, v16, v17
	v_pk_mul_f32 v[18:19], v[22:23], v[20:21]
	v_cvt_pk_bf16_f32 v12, v12, v13
	v_pk_mul_f32 v[14:15], v[18:19], v[14:15]
	s_nop 0
	v_cvt_pk_bf16_f32 v13, v14, v15
	global_store_dwordx4 v[34:35], v[10:13], off offset:3072
	s_cbranch_scc0 .LBB0_498

.LBB0_507:
	s_or_b64 exec, exec, s[0:1]
	s_ashr_i32 s0, s27, 5
	s_ashr_i32 s1, s0, 31
	s_and_b32 s29, s27, 7
	s_ashr_i32 s28, s27, 2
	s_lshl_b64 s[72:73], s[0:1], 12
	s_mov_b64 s[8:9], -1
	s_and_b64 vcc, exec, s[6:7]
	s_cbranch_vccz .LBB0_513
	s_and_b32 s8, s28, 0x3fffff8
	s_or_b32 s8, s8, s29
	s_lshl_b32 s8, s8, 6
	s_mov_b64 s[24:25], -1
	s_and_b64 vcc, exec, s[10:11]
	s_cbranch_vccz .LBB0_510
	s_ashr_i32 s9, s8, 31
	s_lshl_b64 s[24:25], s[8:9], 14
	v_lshl_add_u64 v[2:3], v[150:151], 0, s[24:25]
	s_lshl_b64 s[24:25], s[8:9], 2
	global_load_dwordx4 v[110:113], v[2:3], off
	global_load_dwordx4 v[106:109], v[2:3], off offset:32
	global_load_dwordx4 v[102:105], v[2:3], off offset:64
	global_load_dwordx4 v[98:101], v[2:3], off offset:96
	s_add_u32 s24, s18, s24
	s_addc_u32 s25, s19, s25
	v_mov_b64_e32 v[2:3], s[24:25]
	global_load_dword v204, v[2:3], off
	s_lshl_b32 s94, s29, 7
	s_mov_b64 s[24:25], 0
.LBB0_510:
	s_andn2_b64 vcc, exec, s[24:25]
	s_cbranch_vccnz .LBB0_512
	v_mov_b32_e32 v3, s73
	v_or_b32_e32 v2, s72, v152
	v_lshlrev_b64 v[2:3], 13, v[2:3]
	v_lshl_add_u64 v[2:3], s[74:75], 0, v[2:3]
	s_lshl_b32 s24, s29, 8
	s_mov_b32 s25, s95
	v_lshl_add_u64 v[2:3], v[2:3], 0, s[24:25]
	v_lshlrev_b32_e32 v4, 1, v146
	v_mov_b32_e32 v5, v1
	v_lshl_add_u64 v[2:3], v[2:3], 0, v[4:5]
	global_load_dwordx4 v[50:53], v[2:3], off
	global_load_dwordx4 v[54:57], v[2:3], off offset:32
	global_load_dwordx4 v[58:61], v[2:3], off offset:64
	global_load_dwordx4 v[62:65], v[2:3], off offset:96
	global_load_dwordx4 v[66:69], v[2:3], off offset:128
	global_load_dwordx4 v[70:73], v[2:3], off offset:160
	global_load_dwordx4 v[74:77], v[2:3], off offset:192
	global_load_dwordx4 v[78:81], v[2:3], off offset:224
	s_ashr_i32 s9, s8, 31
	s_lshl_b64 s[8:9], s[8:9], 13
	v_lshl_add_u64 v[2:3], v[154:155], 0, s[8:9]
	s_waitcnt vmcnt(0) lgkmcnt(0)
	global_load_dwordx4 v[110:113], v[2:3], off
	global_load_dwordx4 v[106:109], v[2:3], off offset:32
	global_load_dwordx4 v[102:105], v[2:3], off offset:64
	global_load_dwordx4 v[98:101], v[2:3], off offset:96
	s_lshl_b32 s94, s29, 7
	v_mov_b32_e32 v204, 1.0

.LBB0_513:
	s_andn2_b64 vcc, exec, s[8:9]
	s_bfe_u32 s8, s27, 0x20003
	s_cbranch_vccnz .LBB0_515
	v_mov_b32_e32 v3, s73
	v_or_b32_e32 v2, s72, v152
	v_lshlrev_b64 v[2:3], 13, v[2:3]
	v_lshl_add_u64 v[2:3], s[74:75], 0, v[2:3]
	s_lshl_b32 s24, s29, 8
	s_mov_b32 s25, s95
	v_lshl_add_u64 v[2:3], v[2:3], 0, s[24:25]
	v_lshlrev_b32_e32 v4, 1, v146
	v_mov_b32_e32 v5, v1
	v_lshl_add_u64 v[2:3], v[2:3], 0, v[4:5]
	global_load_dwordx4 v[50:53], v[2:3], off offset:2048
	global_load_dwordx4 v[54:57], v[2:3], off offset:2080
	global_load_dwordx4 v[58:61], v[2:3], off offset:2112
	global_load_dwordx4 v[62:65], v[2:3], off offset:2144
	global_load_dwordx4 v[66:69], v[2:3], off offset:2176
	global_load_dwordx4 v[70:73], v[2:3], off offset:2208
	global_load_dwordx4 v[74:77], v[2:3], off offset:2240
	global_load_dwordx4 v[78:81], v[2:3], off offset:2272
	v_lshl_or_b32 v2, s8, 5, v147
	v_lshrrev_b32_e32 v2, 1, v2
	v_or_b32_e32 v2, s72, v2
	v_mov_b32_e32 v3, s73
	v_lshlrev_b64 v[2:3], 13, v[2:3]
	v_lshl_add_u64 v[2:3], s[74:75], 0, v[2:3]
	v_lshl_add_u64 v[2:3], v[2:3], 0, s[24:25]
	v_mov_b32_e32 v185, v1
	v_lshl_add_u64 v[2:3], v[2:3], 0, v[184:185]
	s_mov_b32 s39, s95
	v_lshl_add_u64 v[2:3], v[2:3], 0, s[38:39]
	v_mov_b32_e32 v187, v1
	v_lshl_add_u64 v[2:3], v[2:3], 0, v[186:187]
	v_lshl_add_u64 v[4:5], v[2:3], 0, s[34:35]
	v_add_co_u32_e32 v2, vcc, 0x1000, v2
	s_waitcnt vmcnt(0) lgkmcnt(0)
	v_mov_b64_e32 v[100:101], v[96:97]
	v_addc_co_u32_e32 v3, vcc, 0, v3, vcc
	global_load_dwordx2 v[188:189], v[2:3], off
	global_load_dwordx2 v[190:191], v[4:5], off offset:16
	global_load_dwordx2 v[192:193], v[4:5], off offset:32
	global_load_dwordx2 v[194:195], v[4:5], off offset:48
	v_mov_b64_e32 v[104:105], v[92:93]
	v_mov_b64_e32 v[108:109], v[88:89]
	v_mov_b64_e32 v[112:113], v[84:85]
	s_lshl_b32 s94, s29, 7
	v_mov_b32_e32 v204, 1.0
	v_mov_b64_e32 v[98:99], v[94:95]
	v_mov_b64_e32 v[102:103], v[90:91]
	v_mov_b64_e32 v[106:107], v[86:87]
	v_mov_b64_e32 v[110:111], v[82:83]

.LBB0_517:
	s_and_b64 vcc, exec, s[10:11]
	s_cbranch_vccz .LBB0_519
	v_lshl_add_u64 v[18:19], s[58:59], 0, v[202:203]
	v_add_co_u32_e32 v18, vcc, 0xb804000, v18
	s_add_u32 s0, s58, s28
	s_nop 0
	v_addc_co_u32_e32 v19, vcc, 0, v19, vcc
	global_load_dwordx4 v[82:85], v[18:19], off
	global_load_dwordx4 v[86:89], v[18:19], off offset:32
	global_load_dwordx4 v[90:93], v[18:19], off offset:64
	global_load_dwordx4 v[94:97], v[18:19], off offset:96
	s_addc_u32 s1, s59, s29
	v_mov_b64_e32 v[18:19], s[0:1]
	global_load_dword v198, v[18:19], off
	s_mov_b64 s[0:1], 0
.LBB0_519:
	v_mov_b64_e32 v[50:51], v[142:143]
	v_mov_b64_e32 v[54:55], v[138:139]
	v_mov_b64_e32 v[58:59], v[134:135]
	v_mov_b64_e32 v[62:63], v[130:131]
	v_mov_b64_e32 v[66:67], v[126:127]
	v_mov_b64_e32 v[70:71], v[122:123]
	v_mov_b64_e32 v[74:75], v[118:119]
	v_mov_b64_e32 v[78:79], v[114:115]
	s_andn2_b64 vcc, exec, s[0:1]
	v_mov_b64_e32 v[52:53], v[144:145]
	v_mov_b64_e32 v[56:57], v[140:141]
	v_mov_b64_e32 v[60:61], v[136:137]
	v_mov_b64_e32 v[64:65], v[132:133]
	v_mov_b64_e32 v[68:69], v[128:129]
	v_mov_b64_e32 v[72:73], v[124:125]
	v_mov_b64_e32 v[76:77], v[120:121]
	v_mov_b64_e32 v[80:81], v[116:117]
	s_cbranch_vccnz .LBB0_521
	v_lshl_add_u64 v[18:19], s[58:59], 0, v[206:207]
	v_add_co_u32_e32 v18, vcc, 0xf880000, v18
	s_waitcnt vmcnt(0) lgkmcnt(0)
	v_mov_b32_e32 v198, v204
	v_addc_co_u32_e32 v19, vcc, 0, v19, vcc
	global_load_dwordx4 v[50:53], v[18:19], off
	global_load_dwordx4 v[54:57], v[18:19], off offset:32
	global_load_dwordx4 v[58:61], v[18:19], off offset:64
	global_load_dwordx4 v[62:65], v[18:19], off offset:96
	global_load_dwordx4 v[66:69], v[18:19], off offset:128
	global_load_dwordx4 v[70:73], v[18:19], off offset:160
	global_load_dwordx4 v[74:77], v[18:19], off offset:192
	global_load_dwordx4 v[78:81], v[18:19], off offset:224
	v_lshl_add_u64 v[18:19], s[58:59], 0, v[200:201]
	v_add_co_u32_e32 v18, vcc, 0x23802000, v18
	s_nop 1
	v_addc_co_u32_e32 v19, vcc, 0, v19, vcc
	global_load_dwordx4 v[82:85], v[18:19], off
	global_load_dwordx4 v[86:89], v[18:19], off offset:32
	global_load_dwordx4 v[90:93], v[18:19], off offset:64
	global_load_dwordx4 v[94:97], v[18:19], off offset:96

.LBB0_522:
	s_andn2_b64 vcc, exec, s[0:1]
	v_mov_b64_e32 v[194:195], v[210:211]
	v_mov_b64_e32 v[192:193], v[212:213]
	v_mov_b64_e32 v[190:191], v[214:215]
	v_mov_b64_e32 v[188:189], v[216:217]
	s_cbranch_vccnz .LBB0_524
	v_lshl_add_u64 v[18:19], s[58:59], 0, v[206:207]
	v_add_co_u32_e32 v18, vcc, 0xf880000, v18
	s_waitcnt vmcnt(0) lgkmcnt(0)
	v_mov_b64_e32 v[94:95], v[98:99]
	v_addc_co_u32_e32 v19, vcc, 0, v19, vcc
	global_load_dwordx4 v[50:53], v[18:19], off offset:2048
	global_load_dwordx4 v[54:57], v[18:19], off offset:2080
	global_load_dwordx4 v[58:61], v[18:19], off offset:2112
	global_load_dwordx4 v[62:65], v[18:19], off offset:2144
	global_load_dwordx4 v[66:69], v[18:19], off offset:2176
	global_load_dwordx4 v[70:73], v[18:19], off offset:2208
	global_load_dwordx4 v[74:77], v[18:19], off offset:2240
	global_load_dwordx4 v[78:81], v[18:19], off offset:2272
	v_lshl_add_u64 v[18:19], s[58:59], 0, v[208:209]
	v_add_co_u32_e32 v18, vcc, 0xf881000, v18
	v_mov_b64_e32 v[90:91], v[102:103]
	s_nop 0
	v_addc_co_u32_e32 v19, vcc, 0, v19, vcc
	global_load_dwordx2 v[188:189], v[18:19], off
	global_load_dwordx2 v[190:191], v[18:19], off offset:16
	global_load_dwordx2 v[192:193], v[18:19], off offset:32
	global_load_dwordx2 v[194:195], v[18:19], off offset:48
	v_mov_b64_e32 v[86:87], v[106:107]
	v_mov_b64_e32 v[82:83], v[110:111]
	v_mov_b64_e32 v[96:97], v[100:101]
	v_mov_b64_e32 v[92:93], v[104:105]
	v_mov_b64_e32 v[88:89], v[108:109]
	v_mov_b64_e32 v[84:85], v[112:113]
	v_mov_b32_e32 v198, v204

.LBB0_531:
	s_andn2_b64 vcc, exec, s[24:25]
	s_cbranch_vccnz .LBB0_533
	v_add_u32_e32 v38, v153, v148
	ds_read_b128 v[34:37], v38 offset:8704
	s_waitcnt lgkmcnt(0)
	v_mfma_f32_32x32x16_bf16 v[18:33], v[110:113], v[34:37], v[18:33]
	ds_read_b128 v[34:37], v38 offset:8736
	s_waitcnt lgkmcnt(0)
	v_mfma_f32_32x32x16_bf16 v[18:33], v[106:109], v[34:37], v[18:33]
	ds_read_b128 v[34:37], v38 offset:8768
	s_waitcnt lgkmcnt(0)
	v_mfma_f32_32x32x16_bf16 v[18:33], v[102:105], v[34:37], v[18:33]
	ds_read_b128 v[34:37], v38 offset:8800
	v_add_u32_e32 v38, v173, v179
	s_waitcnt lgkmcnt(0)
	v_mfma_f32_32x32x16_bf16 v[18:33], v[98:101], v[34:37], v[18:33]
	s_nop 11
	v_bfe_u32 v34, v18, 16, 1
	v_bfe_u32 v35, v19, 16, 1
	v_bfe_u32 v36, v20, 16, 1
	v_bfe_u32 v37, v21, 16, 1
	v_bfe_u32 v39, v22, 16, 1
	v_bfe_u32 v40, v23, 16, 1
	v_bfe_u32 v41, v24, 16, 1
	v_bfe_u32 v42, v25, 16, 1
	v_bfe_u32 v43, v26, 16, 1
	v_bfe_u32 v44, v27, 16, 1
	v_bfe_u32 v45, v28, 16, 1
	v_add3_u32 v18, v18, v34, s33
	v_add3_u32 v19, v19, v35, s33
	v_add3_u32 v20, v20, v36, s33
	v_add3_u32 v21, v21, v37, s33
	v_add3_u32 v22, v22, v39, s33
	v_add3_u32 v23, v23, v40, s33
	v_add3_u32 v24, v24, v41, s33
	v_add3_u32 v25, v25, v42, s33
	v_add3_u32 v26, v26, v43, s33
	v_add3_u32 v27, v27, v44, s33
	ds_write_b16_d16_hi v38, v18 offset:8192
	ds_write_b16_d16_hi v38, v19 offset:8272
	ds_write_b16_d16_hi v38, v20 offset:8352
	ds_write_b16_d16_hi v38, v21 offset:8432
	ds_write_b16_d16_hi v38, v22 offset:8832
	ds_write_b16_d16_hi v38, v23 offset:8912
	ds_write_b16_d16_hi v38, v24 offset:8992
	ds_write_b16_d16_hi v38, v25 offset:9072
	ds_write_b16_d16_hi v38, v26 offset:9472
	ds_write_b16_d16_hi v38, v27 offset:9552
	v_add3_u32 v18, v28, v45, s33
	ds_write_b16_d16_hi v38, v18 offset:9632
	v_bfe_u32 v18, v29, 16, 1
	v_add3_u32 v18, v29, v18, s33
	ds_write_b16_d16_hi v38, v18 offset:9712
	v_bfe_u32 v18, v30, 16, 1
	v_add3_u32 v18, v30, v18, s33
	ds_write_b16_d16_hi v38, v18 offset:10112
	v_bfe_u32 v18, v31, 16, 1
	v_add3_u32 v18, v31, v18, s33
	ds_write_b16_d16_hi v38, v18 offset:10192
	v_bfe_u32 v18, v32, 16, 1
	v_add3_u32 v18, v32, v18, s33
	ds_write_b16_d16_hi v38, v18 offset:10272
	v_bfe_u32 v18, v33, 16, 1
	v_add3_u32 v18, v33, v18, s33
	ds_write_b16_d16_hi v38, v18 offset:10352
	v_add_u32_e32 v24, v175, v183
	s_waitcnt lgkmcnt(0)
	ds_read_b128 v[18:21], v24 offset:8192
	v_lshl_add_u64 v[22:23], v[156:157], 0, s[8:9]
	v_or_b32_e32 v23, s73, v23
	v_or_b32_e32 v22, s72, v22
	v_lshlrev_b64 v[22:23], 11, v[22:23]
	v_lshl_add_u64 v[22:23], v[196:197], 0, v[22:23]
	s_waitcnt lgkmcnt(0)
	global_store_dwordx4 v[22:23], v[18:21], off
	ds_read_b128 v[18:21], v24 offset:9472
	v_lshl_add_u64 v[22:23], v[176:177], 0, s[8:9]
	v_or_b32_e32 v23, s73, v23
	v_or_b32_e32 v22, s72, v22
	v_lshlrev_b64 v[22:23], 11, v[22:23]
	v_lshl_add_u64 v[22:23], v[196:197], 0, v[22:23]
	s_waitcnt lgkmcnt(0)
	global_store_dwordx4 v[22:23], v[18:21], off
	s_waitcnt lgkmcnt(0)
	v_mov_b64_e32 v[48:49], v[16:17]
	v_mov_b64_e32 v[46:47], v[14:15]
	v_mov_b64_e32 v[44:45], v[12:13]
	v_mov_b64_e32 v[42:43], v[10:11]
	v_mov_b64_e32 v[40:41], v[8:9]
	v_mov_b64_e32 v[38:39], v[6:7]
	v_mov_b64_e32 v[36:37], v[4:5]
	v_mov_b64_e32 v[34:35], v[2:3]

.LBB0_542:
	v_add_u32_e32 v22, v153, v148
	ds_read_b128 v[18:21], v22 offset:8704
	s_waitcnt vmcnt(0) lgkmcnt(0)
	v_mfma_f32_32x32x16_bf16 v[2:17], v[82:85], v[18:21], v[2:17]
	ds_read_b128 v[18:21], v22 offset:8736
	s_waitcnt lgkmcnt(0)
	v_mfma_f32_32x32x16_bf16 v[2:17], v[86:89], v[18:21], v[2:17]
	ds_read_b128 v[18:21], v22 offset:8768
	s_waitcnt lgkmcnt(0)
	v_mfma_f32_32x32x16_bf16 v[2:17], v[90:93], v[18:21], v[2:17]
	ds_read_b128 v[18:21], v22 offset:8800
	v_add_u32_e32 v22, v173, v179
	s_waitcnt lgkmcnt(0)
	v_mfma_f32_32x32x16_bf16 v[2:17], v[94:97], v[18:21], v[2:17]
	s_nop 11
	v_bfe_u32 v18, v2, 16, 1
	v_bfe_u32 v19, v3, 16, 1
	v_bfe_u32 v20, v4, 16, 1
	v_bfe_u32 v21, v5, 16, 1
	v_bfe_u32 v23, v6, 16, 1
	v_bfe_u32 v24, v7, 16, 1
	v_bfe_u32 v25, v8, 16, 1
	v_bfe_u32 v26, v9, 16, 1
	v_bfe_u32 v27, v10, 16, 1
	v_bfe_u32 v28, v11, 16, 1
	v_bfe_u32 v29, v12, 16, 1
	v_add3_u32 v2, v2, v18, s33
	v_add3_u32 v3, v3, v19, s33
	v_add3_u32 v4, v4, v20, s33
	v_add3_u32 v5, v5, v21, s33
	v_add3_u32 v6, v6, v23, s33
	v_add3_u32 v7, v7, v24, s33
	v_add3_u32 v8, v8, v25, s33
	v_add3_u32 v9, v9, v26, s33
	v_add3_u32 v10, v10, v27, s33
	v_add3_u32 v11, v11, v28, s33
	ds_write_b16_d16_hi v22, v2 offset:8192
	ds_write_b16_d16_hi v22, v3 offset:8272
	ds_write_b16_d16_hi v22, v4 offset:8352
	ds_write_b16_d16_hi v22, v5 offset:8432
	ds_write_b16_d16_hi v22, v6 offset:8832
	ds_write_b16_d16_hi v22, v7 offset:8912
	ds_write_b16_d16_hi v22, v8 offset:8992
	ds_write_b16_d16_hi v22, v9 offset:9072
	ds_write_b16_d16_hi v22, v10 offset:9472
	ds_write_b16_d16_hi v22, v11 offset:9552
	v_add3_u32 v2, v12, v29, s33
	ds_write_b16_d16_hi v22, v2 offset:9632
	v_bfe_u32 v2, v13, 16, 1
	v_add3_u32 v2, v13, v2, s33
	ds_write_b16_d16_hi v22, v2 offset:9712
	v_bfe_u32 v2, v14, 16, 1
	v_add3_u32 v2, v14, v2, s33
	ds_write_b16_d16_hi v22, v2 offset:10112
	v_bfe_u32 v2, v15, 16, 1
	v_add3_u32 v2, v15, v2, s33
	ds_write_b16_d16_hi v22, v2 offset:10192
	v_bfe_u32 v2, v16, 16, 1
	v_add3_u32 v2, v16, v2, s33
	ds_write_b16_d16_hi v22, v2 offset:10272
	v_bfe_u32 v2, v17, 16, 1
	v_add3_u32 v2, v17, v2, s33
	ds_write_b16_d16_hi v22, v2 offset:10352
	v_add_u32_e32 v8, v175, v183
	s_waitcnt lgkmcnt(0)
	ds_read_b128 v[2:5], v8 offset:8192
	v_mov_b32_e32 v7, s73
	v_or_b32_e32 v6, s72, v170
	v_lshlrev_b64 v[6:7], 11, v[6:7]
	v_lshl_add_u64 v[6:7], v[196:197], 0, v[6:7]
	s_waitcnt lgkmcnt(0)
	global_store_dwordx4 v[6:7], v[2:5], off
	ds_read_b128 v[2:5], v8 offset:9472
	v_mov_b32_e32 v7, s73
	v_or_b32_e32 v6, s72, v172
	v_lshlrev_b64 v[6:7], 11, v[6:7]
	v_lshl_add_u64 v[6:7], v[196:197], 0, v[6:7]
	s_waitcnt lgkmcnt(0)
	global_store_dwordx4 v[6:7], v[2:5], off
	s_waitcnt lgkmcnt(0)
	s_branch .LBB0_503

.LBB0_566:
	s_or_b64 exec, exec, s[0:1]
	v_ashrrev_i32_e32 v7, 31, v6
	v_lshlrev_b64 v[2:3], 14, v[6:7]
	v_lshl_add_u64 v[2:3], v[4:5], 0, v[2:3]
	global_load_dwordx4 v[12:15], v[2:3], off
	global_load_dwordx4 v[16:19], v[2:3], off offset:16
	global_load_dwordx4 v[20:23], v[2:3], off offset:32
	global_load_dwordx4 v[24:27], v[2:3], off offset:48
	s_waitcnt vmcnt(0) lgkmcnt(0)
	v_mov_b32_e32 v2, v13
	v_mov_b32_e32 v3, v14
	v_mov_b32_e32 v13, v15
	v_pk_add_f32 v[2:3], v[2:3], v[12:13]
	v_mov_b32_e32 v12, v17
	v_mov_b32_e32 v13, v18
	v_mov_b32_e32 v17, v19
	v_pk_add_f32 v[12:13], v[12:13], v[16:17]
	v_pk_add_f32 v[2:3], v[2:3], v[2:3] op_sel:[0,1] op_sel_hi:[1,0]
	v_pk_add_f32 v[12:13], v[12:13], v[12:13] op_sel:[0,1] op_sel_hi:[1,0]
	v_add_f32_e32 v14, v20, v21
	v_add_f32_e32 v16, v22, v23
	v_mov_b32_e32 v3, v24
	v_mov_b32_e32 v13, v25
	v_mov_b32_e32 v15, v26
	v_mov_b32_e32 v17, v27
	v_pk_add_f32 v[2:3], v[2:3], v[12:13]
	v_pk_add_f32 v[12:13], v[14:15], v[16:17]
	s_nop 0
	v_pk_add_f32 v[2:3], v[2:3], v[12:13]
	s_nop 0
	v_add_f32_e32 v0, v2, v3
	v_fmamk_f32 v0, v0, 0x3a800000, v218
	v_cmp_gt_f32_e32 vcc, s79, v0
	v_mul_f32_e32 v2, 0x4f800000, v0
	s_nop 0
	v_cndmask_b32_e32 v0, v0, v2, vcc
	v_sqrt_f32_e32 v2, v0
	s_nop 0
	v_add_u32_e32 v3, -1, v2
	v_fma_f32 v7, -v3, v2, v0
	v_cmp_ge_f32_e64 s[0:1], 0, v7
	v_add_u32_e32 v7, 1, v2
	s_nop 0
	v_cndmask_b32_e64 v3, v2, v3, s[0:1]
	v_fma_f32 v2, -v7, v2, v0
	v_cmp_lt_f32_e64 s[0:1], 0, v2
	s_nop 1
	v_cndmask_b32_e64 v2, v3, v7, s[0:1]
	v_mul_f32_e32 v3, 0x37800000, v2
	v_cndmask_b32_e32 v2, v2, v3, vcc
	v_cmp_class_f32_e32 vcc, v0, v205
	s_nop 1
	v_cndmask_b32_e32 v0, v2, v0, vcc
	v_div_scale_f32 v2, s[0:1], v0, v0, 1.0
	v_rcp_f32_e32 v3, v2
	s_nop 0
	v_fma_f32 v7, -v2, v3, 1.0
	v_fmac_f32_e32 v3, v7, v3
	v_div_scale_f32 v7, vcc, 1.0, v0, 1.0
	v_mul_f32_e32 v9, v7, v3
	v_fma_f32 v11, -v2, v9, v7
	v_fmac_f32_e32 v9, v11, v3
	v_fma_f32 v2, -v2, v9, v7
	v_div_fmas_f32 v2, v2, v3, v9
	v_div_fixup_f32 v0, v2, v0, 1.0

.LBB0_570:
	s_or_b64 exec, exec, s[0:1]
	v_ashrrev_i32_e32 v7, 31, v6
	v_lshlrev_b64 v[2:3], 14, v[6:7]
	v_lshl_add_u64 v[2:3], v[4:5], 0, v[2:3]
	global_load_dwordx4 v[12:15], v[2:3], off
	global_load_dwordx4 v[16:19], v[2:3], off offset:16
	global_load_dwordx4 v[20:23], v[2:3], off offset:32
	global_load_dwordx4 v[24:27], v[2:3], off offset:48
	s_waitcnt vmcnt(0) lgkmcnt(0)
	v_mov_b32_e32 v2, v13
	v_mov_b32_e32 v3, v14
	v_mov_b32_e32 v13, v15
	v_pk_add_f32 v[2:3], v[2:3], v[12:13]
	v_mov_b32_e32 v12, v17
	v_mov_b32_e32 v13, v18
	v_mov_b32_e32 v17, v19
	v_pk_add_f32 v[12:13], v[12:13], v[16:17]
	v_pk_add_f32 v[2:3], v[2:3], v[2:3] op_sel:[0,1] op_sel_hi:[1,0]
	v_pk_add_f32 v[12:13], v[12:13], v[12:13] op_sel:[0,1] op_sel_hi:[1,0]
	v_add_f32_e32 v14, v20, v21
	v_add_f32_e32 v16, v22, v23
	v_mov_b32_e32 v3, v24
	v_mov_b32_e32 v13, v25
	v_mov_b32_e32 v15, v26
	v_mov_b32_e32 v17, v27
	v_pk_add_f32 v[2:3], v[2:3], v[12:13]
	v_pk_add_f32 v[12:13], v[14:15], v[16:17]
	s_nop 0
	v_pk_add_f32 v[2:3], v[2:3], v[12:13]
	s_nop 0
	v_add_f32_e32 v2, v2, v3
	v_fmamk_f32 v2, v2, 0x3a800000, v218
	v_cmp_gt_f32_e32 vcc, s79, v2
	v_mul_f32_e32 v3, 0x4f800000, v2
	s_nop 0
	v_cndmask_b32_e32 v2, v2, v3, vcc
	v_sqrt_f32_e32 v3, v2
	s_nop 0
	v_add_u32_e32 v7, -1, v3
	v_fma_f32 v9, -v7, v3, v2
	v_cmp_ge_f32_e64 s[0:1], 0, v9
	v_add_u32_e32 v9, 1, v3
	s_nop 0
	v_cndmask_b32_e64 v7, v3, v7, s[0:1]
	v_fma_f32 v3, -v9, v3, v2
	v_cmp_lt_f32_e64 s[0:1], 0, v3
	s_nop 1
	v_cndmask_b32_e64 v3, v7, v9, s[0:1]
	v_mul_f32_e32 v7, 0x37800000, v3
	v_cndmask_b32_e32 v3, v3, v7, vcc
	v_cmp_class_f32_e32 vcc, v2, v205
	s_nop 1
	v_cndmask_b32_e32 v2, v3, v2, vcc
	v_div_scale_f32 v3, s[0:1], v2, v2, 1.0
	v_rcp_f32_e32 v7, v3
	s_nop 0
	v_fma_f32 v9, -v3, v7, 1.0
	v_fmac_f32_e32 v7, v9, v7
	v_div_scale_f32 v9, vcc, 1.0, v2, 1.0
	v_mul_f32_e32 v11, v9, v7
	v_fma_f32 v12, -v3, v11, v9
	v_fmac_f32_e32 v11, v12, v7
	v_fma_f32 v3, -v3, v11, v9
	v_div_fmas_f32 v3, v3, v7, v11
	v_div_fixup_f32 v3, v3, v2, 1.0

.LBB0_574:
	s_or_b64 exec, exec, s[6:7]
	v_ashrrev_i32_e32 v7, 31, v6
	v_lshlrev_b64 v[8:9], 14, v[6:7]
	v_lshl_add_u64 v[8:9], v[4:5], 0, v[8:9]
	global_load_dwordx4 v[12:15], v[8:9], off
	global_load_dwordx4 v[16:19], v[8:9], off offset:16
	global_load_dwordx4 v[20:23], v[8:9], off offset:32
	global_load_dwordx4 v[24:27], v[8:9], off offset:48
	s_waitcnt vmcnt(0) lgkmcnt(0)
	v_mov_b32_e32 v8, v13
	v_mov_b32_e32 v9, v14
	v_mov_b32_e32 v13, v15
	v_pk_add_f32 v[8:9], v[8:9], v[12:13]
	v_mov_b32_e32 v12, v17
	v_mov_b32_e32 v13, v18
	v_mov_b32_e32 v17, v19
	v_pk_add_f32 v[12:13], v[12:13], v[16:17]
	v_pk_add_f32 v[8:9], v[8:9], v[8:9] op_sel:[0,1] op_sel_hi:[1,0]
	v_pk_add_f32 v[12:13], v[12:13], v[12:13] op_sel:[0,1] op_sel_hi:[1,0]
	v_add_f32_e32 v14, v20, v21
	v_add_f32_e32 v16, v22, v23
	v_mov_b32_e32 v9, v24
	v_mov_b32_e32 v13, v25
	v_mov_b32_e32 v15, v26
	v_mov_b32_e32 v17, v27
	v_pk_add_f32 v[8:9], v[8:9], v[12:13]
	v_pk_add_f32 v[12:13], v[14:15], v[16:17]
	s_nop 0
	v_pk_add_f32 v[8:9], v[8:9], v[12:13]
	s_nop 0
	v_add_f32_e32 v2, v8, v9
	v_fmamk_f32 v2, v2, 0x3a800000, v218
	v_cmp_gt_f32_e32 vcc, s79, v2
	v_mul_f32_e32 v7, 0x4f800000, v2
	s_nop 0
	v_cndmask_b32_e32 v2, v2, v7, vcc
	v_sqrt_f32_e32 v7, v2
	s_nop 0
	v_add_u32_e32 v8, -1, v7
	v_fma_f32 v9, -v8, v7, v2
	v_cmp_ge_f32_e64 s[6:7], 0, v9
	v_add_u32_e32 v9, 1, v7
	s_nop 0
	v_cndmask_b32_e64 v8, v7, v8, s[6:7]
	v_fma_f32 v7, -v9, v7, v2
	v_cmp_lt_f32_e64 s[6:7], 0, v7
	s_nop 1
	v_cndmask_b32_e64 v7, v8, v9, s[6:7]
	v_mul_f32_e32 v8, 0x37800000, v7
	v_cndmask_b32_e32 v7, v7, v8, vcc
	v_cmp_class_f32_e32 vcc, v2, v205
	s_nop 1
	v_cndmask_b32_e32 v2, v7, v2, vcc
	v_div_scale_f32 v7, s[6:7], v2, v2, 1.0
	v_rcp_f32_e32 v8, v7
	s_nop 0
	v_fma_f32 v9, -v7, v8, 1.0
	v_fmac_f32_e32 v8, v9, v8
	v_div_scale_f32 v9, vcc, 1.0, v2, 1.0
	v_mul_f32_e32 v11, v9, v8
	v_fma_f32 v12, -v7, v11, v9
	v_fmac_f32_e32 v11, v12, v8
	v_fma_f32 v7, -v7, v11, v9
	v_div_fmas_f32 v7, v7, v8, v11
	v_div_fixup_f32 v2, v7, v2, 1.0
	s_or_b64 exec, exec, s[16:17]
	s_and_saveexec_b64 s[6:7], s[2:3]
	s_cbranch_execnz .LBB0_578

.LBB0_595:
	s_lshl_b32 s75, s0, 8
	v_readlane_b32 s0, v254, 41
	s_add_i32 s75, s75, s0
	s_lshl_b32 s0, s72, 8
	v_or_b32_e32 v194, s75, v167
	v_or_b32_e32 v142, s0, v190
	s_cmp_ge_i32 s0, s30
	s_mov_b64 s[0:1], -1
	s_cbranch_scc0 .LBB0_644
	v_lshl_add_u32 v0, s19, 8, v188
	v_lshl_add_u32 v0, v0, 2, 0
	v_add_u32_e32 v143, 0x20000, v0
	ds_read_b32 v195, v143
	v_mad_i64_i32 v[144:145], s[0:1], s12, v194, 0
	v_cmp_le_i32_e32 vcc, s30, v142
	v_cmp_gt_i32_e64 s[0:1], s31, v142
	v_lshl_add_u64 v[186:187], v[144:145], 2, s[16:17]
	s_and_b64 s[82:83], vcc, s[0:1]
	v_subrev_u32_e32 v0, s30, v142
	s_and_saveexec_b64 s[0:1], s[82:83]
	s_cbranch_execz .LBB0_598
	v_lshl_add_u64 v[144:145], v[0:1], 2, v[186:187]
	s_waitcnt lgkmcnt(0)
	v_mul_f32_e32 v146, v126, v195
	global_store_dword v[144:145], v146, off
.LBB0_598:
	s_or_b64 exec, exec, s[0:1]
	v_or_b32_e32 v144, 1, v142
	v_cmp_le_i32_e32 vcc, s30, v144
	v_cmp_gt_i32_e64 s[0:1], s31, v144
	s_and_b64 s[84:85], vcc, s[0:1]
	v_subrev_u32_e32 v144, s30, v144
	s_and_saveexec_b64 s[0:1], s[84:85]
	s_cbranch_execz .LBB0_600
	v_mov_b32_e32 v145, v1
	v_lshl_add_u64 v[146:147], v[144:145], 2, v[186:187]
	s_waitcnt lgkmcnt(0)
	v_mul_f32_e32 v145, v127, v195
	global_store_dword v[146:147], v145, off
.LBB0_600:
	s_or_b64 exec, exec, s[0:1]
	v_or_b32_e32 v145, 2, v142
	v_cmp_le_i32_e32 vcc, s30, v145
	v_cmp_gt_i32_e64 s[0:1], s31, v145
	s_and_b64 s[86:87], vcc, s[0:1]
	v_subrev_u32_e32 v146, s30, v145
	s_and_saveexec_b64 s[0:1], s[86:87]
	s_cbranch_execz .LBB0_602
	v_mov_b32_e32 v147, v1
	v_lshl_add_u64 v[148:149], v[146:147], 2, v[186:187]
	s_waitcnt lgkmcnt(0)
	v_mul_f32_e32 v145, v128, v195
	global_store_dword v[148:149], v145, off
.LBB0_602:
	s_or_b64 exec, exec, s[0:1]
	v_or_b32_e32 v145, 3, v142
	v_cmp_le_i32_e32 vcc, s30, v145
	v_cmp_gt_i32_e64 s[0:1], s31, v145
	s_and_b64 s[96:97], vcc, s[0:1]
	v_subrev_u32_e32 v148, s30, v145
	s_and_saveexec_b64 s[0:1], s[96:97]
	s_cbranch_execz .LBB0_604
	v_mov_b32_e32 v149, v1
	v_lshl_add_u64 v[150:151], v[148:149], 2, v[186:187]
	s_waitcnt lgkmcnt(0)
	v_mul_f32_e32 v145, v129, v195
	global_store_dword v[150:151], v145, off
.LBB0_604:
	s_or_b64 exec, exec, s[0:1]
	v_or_b32_e32 v145, 4, v142
	v_cmp_le_i32_e32 vcc, s30, v145
	v_cmp_gt_i32_e64 s[0:1], s31, v145
	s_and_b64 s[70:71], vcc, s[0:1]
	v_subrev_u32_e32 v150, s30, v145
	s_and_saveexec_b64 s[0:1], s[70:71]
	s_cbranch_execz .LBB0_606
	v_mov_b32_e32 v151, v1
	v_lshl_add_u64 v[152:153], v[150:151], 2, v[186:187]
	s_waitcnt lgkmcnt(0)
	v_mul_f32_e32 v145, v122, v195
	global_store_dword v[152:153], v145, off
.LBB0_606:
	s_or_b64 exec, exec, s[0:1]
	v_or_b32_e32 v145, 5, v142
	v_cmp_le_i32_e32 vcc, s30, v145
	v_cmp_gt_i32_e64 s[0:1], s31, v145
	s_and_b64 s[8:9], vcc, s[0:1]
	v_subrev_u32_e32 v152, s30, v145
	s_and_saveexec_b64 s[0:1], s[8:9]
	s_cbranch_execz .LBB0_608
	v_mov_b32_e32 v153, v1
	v_lshl_add_u64 v[154:155], v[152:153], 2, v[186:187]
	s_waitcnt lgkmcnt(0)
	v_mul_f32_e32 v145, v123, v195
	global_store_dword v[154:155], v145, off
.LBB0_608:
	s_or_b64 exec, exec, s[0:1]
	v_or_b32_e32 v145, 6, v142
	v_cmp_le_i32_e32 vcc, s30, v145
	v_cmp_gt_i32_e64 s[0:1], s31, v145
	s_and_b64 s[64:65], vcc, s[0:1]
	v_subrev_u32_e32 v154, s30, v145
	s_and_saveexec_b64 s[0:1], s[64:65]
	s_cbranch_execz .LBB0_610
	v_mov_b32_e32 v155, v1
	v_lshl_add_u64 v[156:157], v[154:155], 2, v[186:187]
	s_waitcnt lgkmcnt(0)
	v_mul_f32_e32 v145, v124, v195
	global_store_dword v[156:157], v145, off
.LBB0_610:
	s_or_b64 exec, exec, s[0:1]
	v_or_b32_e32 v145, 7, v142
	v_cmp_le_i32_e32 vcc, s30, v145
	v_cmp_gt_i32_e64 s[0:1], s31, v145
	s_and_b64 s[90:91], vcc, s[0:1]
	v_subrev_u32_e32 v156, s30, v145
	s_and_saveexec_b64 s[0:1], s[90:91]
	s_cbranch_execz .LBB0_612
	v_mov_b32_e32 v157, v1
	v_lshl_add_u64 v[170:171], v[156:157], 2, v[186:187]
	s_waitcnt lgkmcnt(0)
	v_mul_f32_e32 v145, v125, v195
	global_store_dword v[170:171], v145, off
.LBB0_612:
	s_or_b64 exec, exec, s[0:1]
	v_or_b32_e32 v145, 0x80, v142
	v_cmp_le_i32_e32 vcc, s30, v145
	v_cmp_gt_i32_e64 s[0:1], s31, v145
	s_and_b64 s[34:35], vcc, s[0:1]
	v_subrev_u32_e32 v170, s30, v145
	s_and_saveexec_b64 s[0:1], s[34:35]
	s_cbranch_execz .LBB0_614
	v_mov_b32_e32 v171, v1
	v_lshl_add_u64 v[172:173], v[170:171], 2, v[186:187]
	s_waitcnt lgkmcnt(0)
	v_mul_f32_e32 v145, v118, v195
	global_store_dword v[172:173], v145, off
.LBB0_614:
	s_or_b64 exec, exec, s[0:1]
	v_or_b32_e32 v145, 0x81, v142
	v_cmp_le_i32_e32 vcc, s30, v145
	v_cmp_gt_i32_e64 s[0:1], s31, v145
	s_and_b64 s[4:5], vcc, s[0:1]
	v_subrev_u32_e32 v172, s30, v145
	s_and_saveexec_b64 s[0:1], s[4:5]
	s_cbranch_execz .LBB0_616
	v_mov_b32_e32 v173, v1
	v_lshl_add_u64 v[174:175], v[172:173], 2, v[186:187]
	s_waitcnt lgkmcnt(0)
	v_mul_f32_e32 v145, v119, v195
	global_store_dword v[174:175], v145, off
.LBB0_616:
	s_or_b64 exec, exec, s[0:1]
	v_or_b32_e32 v145, 0x82, v142
	v_cmp_le_i32_e32 vcc, s30, v145
	v_cmp_gt_i32_e64 s[0:1], s31, v145
	s_and_b64 s[38:39], vcc, s[0:1]
	v_subrev_u32_e32 v174, s30, v145
	s_and_saveexec_b64 s[0:1], s[38:39]
	s_cbranch_execz .LBB0_618
	v_mov_b32_e32 v175, v1
	v_lshl_add_u64 v[176:177], v[174:175], 2, v[186:187]
	s_waitcnt lgkmcnt(0)
	v_mul_f32_e32 v145, v120, v195
	global_store_dword v[176:177], v145, off
.LBB0_618:
	s_or_b64 exec, exec, s[0:1]
	v_or_b32_e32 v145, 0x83, v142
	v_cmp_le_i32_e32 vcc, s30, v145
	v_cmp_gt_i32_e64 s[0:1], s31, v145
	s_and_b64 s[68:69], vcc, s[0:1]
	v_subrev_u32_e32 v176, s30, v145
	s_and_saveexec_b64 s[0:1], s[68:69]
	s_cbranch_execz .LBB0_620
	v_mov_b32_e32 v177, v1
	v_lshl_add_u64 v[178:179], v[176:177], 2, v[186:187]
	s_waitcnt lgkmcnt(0)
	v_mul_f32_e32 v145, v121, v195
	global_store_dword v[178:179], v145, off
.LBB0_620:
	s_or_b64 exec, exec, s[0:1]
	v_or_b32_e32 v145, 0x84, v142
	v_cmp_le_i32_e32 vcc, s30, v145
	v_cmp_gt_i32_e64 s[0:1], s31, v145
	s_and_b64 s[88:89], vcc, s[0:1]
	v_subrev_u32_e32 v178, s30, v145
	s_and_saveexec_b64 s[0:1], s[88:89]
	s_cbranch_execz .LBB0_622
	v_mov_b32_e32 v179, v1
	v_lshl_add_u64 v[180:181], v[178:179], 2, v[186:187]
	s_waitcnt lgkmcnt(0)
	v_mul_f32_e32 v145, v114, v195
	global_store_dword v[180:181], v145, off
.LBB0_622:
	s_or_b64 exec, exec, s[0:1]
	v_or_b32_e32 v145, 0x85, v142
	v_cmp_le_i32_e32 vcc, s30, v145
	v_cmp_gt_i32_e64 s[0:1], s31, v145
	s_and_b64 s[24:25], vcc, s[0:1]
	v_subrev_u32_e32 v180, s30, v145
	s_and_saveexec_b64 s[0:1], s[24:25]
	s_cbranch_execz .LBB0_624
	v_mov_b32_e32 v181, v1
	v_lshl_add_u64 v[182:183], v[180:181], 2, v[186:187]
	s_waitcnt lgkmcnt(0)
	v_mul_f32_e32 v145, v115, v195
	global_store_dword v[182:183], v145, off
.LBB0_624:
	s_or_b64 exec, exec, s[0:1]
	v_or_b32_e32 v145, 0x86, v142
	v_cmp_le_i32_e32 vcc, s30, v145
	v_cmp_gt_i32_e64 s[0:1], s31, v145
	s_and_b64 s[26:27], vcc, s[0:1]
	v_subrev_u32_e32 v182, s30, v145
	s_and_saveexec_b64 s[0:1], s[26:27]
	s_cbranch_execz .LBB0_626
	v_mov_b32_e32 v183, v1
	v_lshl_add_u64 v[184:185], v[182:183], 2, v[186:187]
	s_waitcnt lgkmcnt(0)
	v_mul_f32_e32 v145, v116, v195
	global_store_dword v[184:185], v145, off
.LBB0_626:
	s_or_b64 exec, exec, s[0:1]
	v_or_b32_e32 v145, 0x87, v142
	v_cmp_le_i32_e32 vcc, s30, v145
	v_cmp_gt_i32_e64 s[0:1], s31, v145
	s_and_b64 s[0:1], vcc, s[0:1]
	v_subrev_u32_e32 v184, s30, v145
	s_and_saveexec_b64 s[28:29], s[0:1]
	s_cbranch_execz .LBB0_628
	v_mov_b32_e32 v185, v1
	v_lshl_add_u64 v[186:187], v[184:185], 2, v[186:187]
	s_waitcnt lgkmcnt(0)
	v_mul_f32_e32 v145, v117, v195
	global_store_dword v[186:187], v145, off
.LBB0_628:
	s_or_b64 exec, exec, s[28:29]
	s_waitcnt lgkmcnt(0)
	ds_read_b32 v195, v143 offset:64
	v_or_b32_e32 v145, 16, v194
	v_mad_i64_i32 v[186:187], s[28:29], s12, v145, 0
	v_lshl_add_u64 v[186:187], v[186:187], 2, s[16:17]
	s_and_saveexec_b64 s[28:29], s[82:83]
	s_cbranch_execz .LBB0_654
	v_lshl_add_u64 v[196:197], v[0:1], 2, v[186:187]
	s_waitcnt lgkmcnt(0)
	v_mul_f32_e32 v145, v110, v195
	global_store_dword v[196:197], v145, off
	s_or_b64 exec, exec, s[28:29]
	s_and_saveexec_b64 s[28:29], s[84:85]
	s_cbranch_execnz .LBB0_655

.LBB0_631:
	v_mov_b32_e32 v147, v1
	v_lshl_add_u64 v[196:197], v[146:147], 2, v[186:187]
	s_waitcnt lgkmcnt(0)
	v_mul_f32_e32 v145, v112, v195
	global_store_dword v[196:197], v145, off
	s_or_b64 exec, exec, s[28:29]
	s_and_saveexec_b64 s[28:29], s[96:97]
	s_cbranch_execnz .LBB0_657

.LBB0_633:
	v_mov_b32_e32 v151, v1
	v_lshl_add_u64 v[196:197], v[150:151], 2, v[186:187]
	s_waitcnt lgkmcnt(0)
	v_mul_f32_e32 v145, v106, v195
	global_store_dword v[196:197], v145, off
	s_or_b64 exec, exec, s[28:29]
	s_and_saveexec_b64 s[28:29], s[8:9]
	s_cbranch_execnz .LBB0_659

.LBB0_635:
	v_mov_b32_e32 v155, v1
	v_lshl_add_u64 v[196:197], v[154:155], 2, v[186:187]
	s_waitcnt lgkmcnt(0)
	v_mul_f32_e32 v145, v108, v195
	global_store_dword v[196:197], v145, off
	s_or_b64 exec, exec, s[28:29]
	s_and_saveexec_b64 s[28:29], s[90:91]
	s_cbranch_execnz .LBB0_661

.LBB0_637:
	v_mov_b32_e32 v171, v1
	v_lshl_add_u64 v[196:197], v[170:171], 2, v[186:187]
	s_waitcnt lgkmcnt(0)
	v_mul_f32_e32 v145, v102, v195
	global_store_dword v[196:197], v145, off
	s_or_b64 exec, exec, s[28:29]
	s_and_saveexec_b64 s[28:29], s[4:5]
	s_cbranch_execnz .LBB0_663

.LBB0_639:
	v_mov_b32_e32 v175, v1
	v_lshl_add_u64 v[196:197], v[174:175], 2, v[186:187]
	s_waitcnt lgkmcnt(0)
	v_mul_f32_e32 v145, v104, v195
	global_store_dword v[196:197], v145, off
	s_or_b64 exec, exec, s[28:29]
	s_and_saveexec_b64 s[28:29], s[68:69]
	s_cbranch_execnz .LBB0_665

.LBB0_641:
	v_mov_b32_e32 v179, v1
	v_lshl_add_u64 v[196:197], v[178:179], 2, v[186:187]
	s_waitcnt lgkmcnt(0)
	v_mul_f32_e32 v145, v98, v195
	global_store_dword v[196:197], v145, off
	s_or_b64 exec, exec, s[28:29]
	s_and_saveexec_b64 s[28:29], s[24:25]
	s_cbranch_execnz .LBB0_667

.LBB0_643:
	v_mov_b32_e32 v183, v1
	v_lshl_add_u64 v[196:197], v[182:183], 2, v[186:187]
	s_waitcnt lgkmcnt(0)
	v_mul_f32_e32 v145, v100, v195
	global_store_dword v[196:197], v145, off
	s_or_b64 exec, exec, s[28:29]
	s_and_saveexec_b64 s[28:29], s[0:1]
	s_cbranch_execnz .LBB0_669
	s_branch .LBB0_670
.LBB0_644:
	s_and_b64 vcc, exec, s[0:1]
	s_cbranch_vccz .LBB0_863
	s_lshr_b32 s0, s75, 6
	s_and_b32 s0, s0, 63
	s_cmp_lg_u32 s0, 63
	s_cselect_b64 s[4:5], -1, 0
	s_ashr_i32 s1, s75, 6
	s_andn2_b32 s1, s1, 63
	s_or_b32 s0, s0, s1
	s_mul_i32 s0, s0, 3
	v_add3_u32 v0, s0, 3, v191
	s_movk_i32 s0, 0x1800
	v_mad_i64_i32 v[146:147], s[0:1], v0, s0, 0
	v_lshl_add_u32 v0, s19, 10, v192
	ds_read_b32 v148, v0
	v_readlane_b32 s8, v254, 35
	s_waitcnt lgkmcnt(0)
	v_ashrrev_i32_e32 v143, 31, v142
	v_mad_i64_i32 v[144:145], s[0:1], v194, s30, 0
	v_readlane_b32 s9, v254, 36
	v_pk_mul_f32 v[128:129], v[128:129], v[148:149] op_sel_hi:[1,0]
	v_pk_mul_f32 v[126:127], v[126:127], v[148:149] op_sel_hi:[1,0]
	v_lshl_add_u64 v[150:151], v[144:145], 1, s[8:9]
	v_lshlrev_b64 v[144:145], 1, v[142:143]
	v_lshl_add_u64 v[150:151], v[150:151], 0, v[144:145]
	v_pk_mul_f32 v[152:153], v[124:125], v[148:149] op_sel_hi:[1,0]
	v_pk_mul_f32 v[124:125], v[122:123], v[148:149] op_sel_hi:[1,0]
	v_cvt_pk_bf16_f32 v122, v126, v127
	v_cvt_pk_bf16_f32 v123, v128, v129
	v_pk_mul_f32 v[120:121], v[120:121], v[148:149] op_sel_hi:[1,0]
	v_cvt_pk_bf16_f32 v124, v124, v125
	v_cvt_pk_bf16_f32 v125, v152, v153
	global_store_dwordx4 v[150:151], v[122:125], off
	v_pk_mul_f32 v[118:119], v[118:119], v[148:149] op_sel_hi:[1,0]
	s_cmp_gt_i32 s72, 11
	v_pk_mul_f32 v[122:123], v[116:117], v[148:149] op_sel_hi:[1,0]
	v_pk_mul_f32 v[116:117], v[114:115], v[148:149] op_sel_hi:[1,0]
	v_cvt_pk_bf16_f32 v114, v118, v119
	v_cvt_pk_bf16_f32 v115, v120, v121
	s_nop 0
	v_cvt_pk_bf16_f32 v116, v116, v117
	v_cvt_pk_bf16_f32 v117, v122, v123
	global_store_dwordx4 v[150:151], v[114:117], off offset:256
	ds_read_b32 v114, v0 offset:64
	s_nop 0
	v_or_b32_e32 v115, 16, v194
	v_mad_i64_i32 v[116:117], s[0:1], v115, s30, 0
	v_lshl_add_u64 v[116:117], v[116:117], 1, s[8:9]
	v_lshl_add_u64 v[116:117], v[116:117], 0, v[144:145]
	s_waitcnt lgkmcnt(0)
	v_pk_mul_f32 v[112:113], v[112:113], v[114:115] op_sel_hi:[1,0]
	v_pk_mul_f32 v[110:111], v[110:111], v[114:115] op_sel_hi:[1,0]
	v_pk_mul_f32 v[118:119], v[108:109], v[114:115] op_sel_hi:[1,0]
	v_pk_mul_f32 v[108:109], v[106:107], v[114:115] op_sel_hi:[1,0]
	v_cvt_pk_bf16_f32 v106, v110, v111
	v_cvt_pk_bf16_f32 v107, v112, v113
	v_pk_mul_f32 v[104:105], v[104:105], v[114:115] op_sel_hi:[1,0]
	v_cvt_pk_bf16_f32 v108, v108, v109
	v_cvt_pk_bf16_f32 v109, v118, v119
	global_store_dwordx4 v[116:117], v[106:109], off
	v_pk_mul_f32 v[102:103], v[102:103], v[114:115] op_sel_hi:[1,0]
	s_nop 0
	v_pk_mul_f32 v[106:107], v[100:101], v[114:115] op_sel_hi:[1,0]
	v_pk_mul_f32 v[100:101], v[98:99], v[114:115] op_sel_hi:[1,0]
	v_cvt_pk_bf16_f32 v98, v102, v103
	v_cvt_pk_bf16_f32 v99, v104, v105
	s_nop 0
	v_cvt_pk_bf16_f32 v100, v100, v101
	v_cvt_pk_bf16_f32 v101, v106, v107
	global_store_dwordx4 v[116:117], v[98:101], off offset:256
	ds_read_b32 v98, v0 offset:128
	s_nop 0
	v_or_b32_e32 v99, 32, v194
	v_mad_i64_i32 v[100:101], s[0:1], v99, s30, 0
	v_lshl_add_u64 v[100:101], v[100:101], 1, s[8:9]
	v_lshl_add_u64 v[100:101], v[100:101], 0, v[144:145]
	s_waitcnt lgkmcnt(0)
	v_pk_mul_f32 v[96:97], v[96:97], v[98:99] op_sel_hi:[1,0]
	v_pk_mul_f32 v[94:95], v[94:95], v[98:99] op_sel_hi:[1,0]
	v_pk_mul_f32 v[102:103], v[92:93], v[98:99] op_sel_hi:[1,0]
	v_pk_mul_f32 v[92:93], v[90:91], v[98:99] op_sel_hi:[1,0]
	v_cvt_pk_bf16_f32 v90, v94, v95
	v_cvt_pk_bf16_f32 v91, v96, v97
	v_pk_mul_f32 v[88:89], v[88:89], v[98:99] op_sel_hi:[1,0]
	v_cvt_pk_bf16_f32 v92, v92, v93
	v_cvt_pk_bf16_f32 v93, v102, v103
	global_store_dwordx4 v[100:101], v[90:93], off
	v_pk_mul_f32 v[86:87], v[86:87], v[98:99] op_sel_hi:[1,0]
	s_nop 0
	v_pk_mul_f32 v[90:91], v[84:85], v[98:99] op_sel_hi:[1,0]
	v_pk_mul_f32 v[84:85], v[82:83], v[98:99] op_sel_hi:[1,0]
	v_cvt_pk_bf16_f32 v82, v86, v87
	v_cvt_pk_bf16_f32 v83, v88, v89
	s_nop 0
	v_cvt_pk_bf16_f32 v84, v84, v85
	v_cvt_pk_bf16_f32 v85, v90, v91
	global_store_dwordx4 v[100:101], v[82:85], off offset:256
	ds_read_b32 v84, v0 offset:192
	s_waitcnt lgkmcnt(0)
	v_pk_mul_f32 v[78:79], v[78:79], v[84:85] op_sel_hi:[1,0]
	v_or_b32_e32 v82, 48, v194
	v_mad_i64_i32 v[82:83], s[0:1], v82, s30, 0
	v_lshl_add_u64 v[82:83], v[82:83], 1, s[8:9]
	v_readlane_b32 s8, v254, 46
	s_cselect_b64 s[0:1], -1, 0
	v_readlane_b32 s9, v254, 47
	s_or_b64 s[0:1], s[8:9], s[0:1]
	v_readlane_b32 s8, v254, 42
	v_readlane_b32 s9, v254, 43
	v_pk_mul_f32 v[86:87], v[76:77], v[84:85] op_sel_hi:[1,0]
	v_pk_mul_f32 v[76:77], v[74:75], v[84:85] op_sel_hi:[1,0]
	v_cvt_pk_bf16_f32 v74, v78, v79
	s_xor_b64 s[0:1], s[0:1], -1
	v_lshl_add_u64 v[78:79], s[8:9], 0, v[146:147]
	v_lshl_add_u64 v[82:83], v[82:83], 0, v[144:145]
	s_and_b64 s[4:5], s[0:1], s[4:5]
	v_lshl_add_u64 v[78:79], v[142:143], 1, v[78:79]
	v_pk_mul_f32 v[80:81], v[80:81], v[84:85] op_sel_hi:[1,0]
	s_nop 0
	v_cvt_pk_bf16_f32 v75, v80, v81
	v_cvt_pk_bf16_f32 v76, v76, v77
	v_cvt_pk_bf16_f32 v77, v86, v87
	global_store_dwordx4 v[82:83], v[74:77], off
	s_and_saveexec_b64 s[8:9], s[4:5]
	s_cbranch_execz .LBB0_647
	global_store_dwordx4 v[78:79], v[74:77], off
.LBB0_647:
	s_or_b64 exec, exec, s[8:9]
	v_mov_b32_e32 v85, v84
	v_mov_b32_e32 v74, v84
	v_mov_b32_e32 v75, v84
	v_pk_mul_f32 v[72:73], v[72:73], v[74:75]
	v_pk_mul_f32 v[74:75], v[68:69], v[74:75]
	v_pk_mul_f32 v[68:69], v[66:67], v[84:85]
	v_pk_mul_f32 v[70:71], v[70:71], v[84:85]
	s_nop 0
	v_cvt_pk_bf16_f32 v66, v70, v71
	v_cvt_pk_bf16_f32 v67, v72, v73
	v_cvt_pk_bf16_f32 v68, v68, v69
	v_cvt_pk_bf16_f32 v69, v74, v75
	global_store_dwordx4 v[82:83], v[66:69], off offset:256
	s_and_saveexec_b64 s[8:9], s[4:5]
	s_cbranch_execz .LBB0_649
	global_store_dwordx4 v[78:79], v[66:69], off offset:256
.LBB0_649:
	s_or_b64 exec, exec, s[8:9]
	s_nop 0
	v_add_u32_e32 v69, 0x80, v194
	v_lshrrev_b32_e32 v66, 6, v69
	v_and_b32_e32 v67, 63, v66
	v_cmp_ne_u32_e32 vcc, 63, v67
	v_ashrrev_i32_e32 v67, 6, v69
	v_bfi_b32 v66, 63, v66, v67
	ds_read_b32 v68, v0 offset:512
	v_lshl_add_u32 v66, v66, 1, v66
	v_add3_u32 v66, v66, v191, 3
	s_movk_i32 s4, 0x1800
	v_readlane_b32 s8, v254, 35
	v_mad_i64_i32 v[66:67], s[4:5], v66, s4, 0
	v_mad_i64_i32 v[70:71], s[4:5], v69, s30, 0
	v_readlane_b32 s9, v254, 36
	s_waitcnt lgkmcnt(0)
	v_pk_mul_f32 v[64:65], v[64:65], v[68:69] op_sel_hi:[1,0]
	v_pk_mul_f32 v[62:63], v[62:63], v[68:69] op_sel_hi:[1,0]
	v_lshl_add_u64 v[70:71], v[70:71], 1, s[8:9]
	v_lshl_add_u64 v[70:71], v[70:71], 0, v[144:145]
	v_pk_mul_f32 v[72:73], v[60:61], v[68:69] op_sel_hi:[1,0]
	v_pk_mul_f32 v[60:61], v[58:59], v[68:69] op_sel_hi:[1,0]
	v_cvt_pk_bf16_f32 v58, v62, v63
	v_cvt_pk_bf16_f32 v59, v64, v65
	v_pk_mul_f32 v[56:57], v[56:57], v[68:69] op_sel_hi:[1,0]
	v_cvt_pk_bf16_f32 v60, v60, v61
	v_cvt_pk_bf16_f32 v61, v72, v73
	global_store_dwordx4 v[70:71], v[58:61], off
	v_pk_mul_f32 v[54:55], v[54:55], v[68:69] op_sel_hi:[1,0]
	s_and_b64 s[0:1], s[0:1], vcc
	v_pk_mul_f32 v[58:59], v[52:53], v[68:69] op_sel_hi:[1,0]
	v_pk_mul_f32 v[52:53], v[50:51], v[68:69] op_sel_hi:[1,0]
	v_cvt_pk_bf16_f32 v50, v54, v55
	v_cvt_pk_bf16_f32 v51, v56, v57
	s_nop 0
	v_cvt_pk_bf16_f32 v52, v52, v53
	v_cvt_pk_bf16_f32 v53, v58, v59
	global_store_dwordx4 v[70:71], v[50:53], off offset:256
	ds_read_b32 v50, v0 offset:576
	s_nop 0
	v_add_u32_e32 v51, 0x90, v194
	v_mad_i64_i32 v[52:53], s[4:5], v51, s30, 0
	v_lshl_add_u64 v[52:53], v[52:53], 1, s[8:9]
	v_lshl_add_u64 v[52:53], v[52:53], 0, v[144:145]
	s_waitcnt lgkmcnt(0)
	v_pk_mul_f32 v[48:49], v[48:49], v[50:51] op_sel_hi:[1,0]
	v_pk_mul_f32 v[46:47], v[46:47], v[50:51] op_sel_hi:[1,0]
	v_pk_mul_f32 v[54:55], v[44:45], v[50:51] op_sel_hi:[1,0]
	v_pk_mul_f32 v[44:45], v[42:43], v[50:51] op_sel_hi:[1,0]
	v_cvt_pk_bf16_f32 v42, v46, v47
	v_cvt_pk_bf16_f32 v43, v48, v49
	v_pk_mul_f32 v[40:41], v[40:41], v[50:51] op_sel_hi:[1,0]
	v_cvt_pk_bf16_f32 v44, v44, v45
	v_cvt_pk_bf16_f32 v45, v54, v55
	global_store_dwordx4 v[52:53], v[42:45], off
	v_pk_mul_f32 v[38:39], v[38:39], v[50:51] op_sel_hi:[1,0]
	s_nop 0
	v_pk_mul_f32 v[42:43], v[36:37], v[50:51] op_sel_hi:[1,0]
	v_pk_mul_f32 v[36:37], v[34:35], v[50:51] op_sel_hi:[1,0]
	v_cvt_pk_bf16_f32 v34, v38, v39
	v_cvt_pk_bf16_f32 v35, v40, v41
	s_nop 0
	v_cvt_pk_bf16_f32 v36, v36, v37
	v_cvt_pk_bf16_f32 v37, v42, v43
	global_store_dwordx4 v[52:53], v[34:37], off offset:256
	ds_read_b32 v34, v0 offset:640
	s_nop 0
	v_add_u32_e32 v35, 0xa0, v194
	v_mad_i64_i32 v[36:37], s[4:5], v35, s30, 0
	v_lshl_add_u64 v[36:37], v[36:37], 1, s[8:9]
	v_lshl_add_u64 v[36:37], v[36:37], 0, v[144:145]
	s_waitcnt lgkmcnt(0)
	v_pk_mul_f32 v[32:33], v[32:33], v[34:35] op_sel_hi:[1,0]
	v_pk_mul_f32 v[30:31], v[30:31], v[34:35] op_sel_hi:[1,0]
	v_pk_mul_f32 v[38:39], v[28:29], v[34:35] op_sel_hi:[1,0]
	v_pk_mul_f32 v[28:29], v[26:27], v[34:35] op_sel_hi:[1,0]
	v_cvt_pk_bf16_f32 v26, v30, v31
	v_cvt_pk_bf16_f32 v27, v32, v33
	v_pk_mul_f32 v[24:25], v[24:25], v[34:35] op_sel_hi:[1,0]
	v_cvt_pk_bf16_f32 v28, v28, v29
	v_cvt_pk_bf16_f32 v29, v38, v39
	global_store_dwordx4 v[36:37], v[26:29], off
	v_pk_mul_f32 v[22:23], v[22:23], v[34:35] op_sel_hi:[1,0]
	s_nop 0
	v_pk_mul_f32 v[26:27], v[20:21], v[34:35] op_sel_hi:[1,0]
	v_pk_mul_f32 v[20:21], v[18:19], v[34:35] op_sel_hi:[1,0]
	v_cvt_pk_bf16_f32 v18, v22, v23
	v_cvt_pk_bf16_f32 v19, v24, v25
	s_nop 0
	v_cvt_pk_bf16_f32 v20, v20, v21
	v_cvt_pk_bf16_f32 v21, v26, v27
	global_store_dwordx4 v[36:37], v[18:21], off offset:256
	ds_read_b32 v20, v0 offset:704
	s_waitcnt lgkmcnt(0)
	v_pk_mul_f32 v[14:15], v[14:15], v[20:21] op_sel_hi:[1,0]
	v_add_u32_e32 v18, 0xb0, v194
	v_mad_i64_i32 v[18:19], s[4:5], v18, s30, 0
	v_readlane_b32 s4, v254, 42
	v_readlane_b32 s5, v254, 43
	v_lshl_add_u64 v[18:19], v[18:19], 1, s[8:9]
	v_pk_mul_f32 v[22:23], v[12:13], v[20:21] op_sel_hi:[1,0]
	v_pk_mul_f32 v[12:13], v[10:11], v[20:21] op_sel_hi:[1,0]
	v_cvt_pk_bf16_f32 v10, v14, v15
	v_lshl_add_u64 v[14:15], s[4:5], 0, v[66:67]
	v_lshl_add_u64 v[18:19], v[18:19], 0, v[144:145]
	v_lshl_add_u64 v[14:15], v[142:143], 1, v[14:15]
	v_pk_mul_f32 v[16:17], v[16:17], v[20:21] op_sel_hi:[1,0]
	s_nop 0
	v_cvt_pk_bf16_f32 v11, v16, v17
	v_cvt_pk_bf16_f32 v12, v12, v13
	v_cvt_pk_bf16_f32 v13, v22, v23
	global_store_dwordx4 v[18:19], v[10:13], off
	s_and_saveexec_b64 s[4:5], s[0:1]
	s_cbranch_execz .LBB0_651
	global_store_dwordx4 v[14:15], v[10:13], off
.LBB0_651:
	s_or_b64 exec, exec, s[4:5]
	v_mov_b32_e32 v21, v20
	v_mov_b32_e32 v10, v20
	v_mov_b32_e32 v11, v20
	v_pk_mul_f32 v[8:9], v[8:9], v[10:11]
	v_pk_mul_f32 v[10:11], v[4:5], v[10:11]
	v_pk_mul_f32 v[4:5], v[2:3], v[20:21]
	v_pk_mul_f32 v[6:7], v[6:7], v[20:21]
	s_nop 0
	v_cvt_pk_bf16_f32 v2, v6, v7
	v_cvt_pk_bf16_f32 v3, v8, v9
	v_cvt_pk_bf16_f32 v4, v4, v5
	v_cvt_pk_bf16_f32 v5, v10, v11
	global_store_dwordx4 v[18:19], v[2:5], off offset:256
	s_and_saveexec_b64 s[4:5], s[0:1]
	s_cbranch_execz .LBB0_653
	global_store_dwordx4 v[14:15], v[2:5], off offset:256

.LBB0_655:
	v_mov_b32_e32 v145, v1
	v_lshl_add_u64 v[196:197], v[144:145], 2, v[186:187]
	s_waitcnt lgkmcnt(0)
	v_mul_f32_e32 v145, v111, v195
	global_store_dword v[196:197], v145, off
	s_or_b64 exec, exec, s[28:29]
	s_and_saveexec_b64 s[28:29], s[86:87]
	s_cbranch_execnz .LBB0_631

.LBB0_657:
	v_mov_b32_e32 v149, v1
	v_lshl_add_u64 v[196:197], v[148:149], 2, v[186:187]
	s_waitcnt lgkmcnt(0)
	v_mul_f32_e32 v145, v113, v195
	global_store_dword v[196:197], v145, off
	s_or_b64 exec, exec, s[28:29]
	s_and_saveexec_b64 s[28:29], s[70:71]
	s_cbranch_execnz .LBB0_633

.LBB0_659:
	v_mov_b32_e32 v153, v1
	v_lshl_add_u64 v[196:197], v[152:153], 2, v[186:187]
	s_waitcnt lgkmcnt(0)
	v_mul_f32_e32 v145, v107, v195
	global_store_dword v[196:197], v145, off
	s_or_b64 exec, exec, s[28:29]
	s_and_saveexec_b64 s[28:29], s[64:65]
	s_cbranch_execnz .LBB0_635

.LBB0_661:
	v_mov_b32_e32 v157, v1
	v_lshl_add_u64 v[196:197], v[156:157], 2, v[186:187]
	s_waitcnt lgkmcnt(0)
	v_mul_f32_e32 v145, v109, v195
	global_store_dword v[196:197], v145, off
	s_or_b64 exec, exec, s[28:29]
	s_and_saveexec_b64 s[28:29], s[34:35]
	s_cbranch_execnz .LBB0_637

.LBB0_663:
	v_mov_b32_e32 v173, v1
	v_lshl_add_u64 v[196:197], v[172:173], 2, v[186:187]
	s_waitcnt lgkmcnt(0)
	v_mul_f32_e32 v145, v103, v195
	global_store_dword v[196:197], v145, off
	s_or_b64 exec, exec, s[28:29]
	s_and_saveexec_b64 s[28:29], s[38:39]
	s_cbranch_execnz .LBB0_639

.LBB0_665:
	v_mov_b32_e32 v177, v1
	v_lshl_add_u64 v[196:197], v[176:177], 2, v[186:187]
	s_waitcnt lgkmcnt(0)
	v_mul_f32_e32 v145, v105, v195
	global_store_dword v[196:197], v145, off
	s_or_b64 exec, exec, s[28:29]
	s_and_saveexec_b64 s[28:29], s[88:89]
	s_cbranch_execnz .LBB0_641

.LBB0_667:
	v_mov_b32_e32 v181, v1
	v_lshl_add_u64 v[196:197], v[180:181], 2, v[186:187]
	s_waitcnt lgkmcnt(0)
	v_mul_f32_e32 v145, v99, v195
	global_store_dword v[196:197], v145, off
	s_or_b64 exec, exec, s[28:29]
	s_and_saveexec_b64 s[28:29], s[26:27]
	s_cbranch_execnz .LBB0_643

.LBB0_669:
	v_mov_b32_e32 v185, v1
	v_lshl_add_u64 v[186:187], v[184:185], 2, v[186:187]
	s_waitcnt lgkmcnt(0)
	v_mul_f32_e32 v145, v101, v195
	global_store_dword v[186:187], v145, off
.LBB0_670:
	s_or_b64 exec, exec, s[28:29]
	s_waitcnt lgkmcnt(0)
	ds_read_b32 v195, v143 offset:128
	v_or_b32_e32 v145, 32, v194
	v_mad_i64_i32 v[186:187], s[28:29], s12, v145, 0
	v_lshl_add_u64 v[186:187], v[186:187], 2, s[16:17]
	s_and_saveexec_b64 s[28:29], s[82:83]
	s_cbranch_execz .LBB0_686
	v_lshl_add_u64 v[196:197], v[0:1], 2, v[186:187]
	s_waitcnt lgkmcnt(0)
	v_mul_f32_e32 v145, v94, v195
	global_store_dword v[196:197], v145, off
	s_or_b64 exec, exec, s[28:29]
	s_and_saveexec_b64 s[28:29], s[84:85]
	s_cbranch_execnz .LBB0_687

.LBB0_673:
	v_mov_b32_e32 v147, v1
	v_lshl_add_u64 v[196:197], v[146:147], 2, v[186:187]
	s_waitcnt lgkmcnt(0)
	v_mul_f32_e32 v145, v96, v195
	global_store_dword v[196:197], v145, off
	s_or_b64 exec, exec, s[28:29]
	s_and_saveexec_b64 s[28:29], s[96:97]
	s_cbranch_execnz .LBB0_689

.LBB0_675:
	v_mov_b32_e32 v151, v1
	v_lshl_add_u64 v[196:197], v[150:151], 2, v[186:187]
	s_waitcnt lgkmcnt(0)
	v_mul_f32_e32 v145, v90, v195
	global_store_dword v[196:197], v145, off
	s_or_b64 exec, exec, s[28:29]
	s_and_saveexec_b64 s[28:29], s[8:9]
	s_cbranch_execnz .LBB0_691

.LBB0_677:
	v_mov_b32_e32 v155, v1
	v_lshl_add_u64 v[196:197], v[154:155], 2, v[186:187]
	s_waitcnt lgkmcnt(0)
	v_mul_f32_e32 v145, v92, v195
	global_store_dword v[196:197], v145, off
	s_or_b64 exec, exec, s[28:29]
	s_and_saveexec_b64 s[28:29], s[90:91]
	s_cbranch_execnz .LBB0_693

.LBB0_679:
	v_mov_b32_e32 v171, v1
	v_lshl_add_u64 v[196:197], v[170:171], 2, v[186:187]
	s_waitcnt lgkmcnt(0)
	v_mul_f32_e32 v145, v86, v195
	global_store_dword v[196:197], v145, off
	s_or_b64 exec, exec, s[28:29]
	s_and_saveexec_b64 s[28:29], s[4:5]
	s_cbranch_execnz .LBB0_695

.LBB0_681:
	v_mov_b32_e32 v175, v1
	v_lshl_add_u64 v[196:197], v[174:175], 2, v[186:187]
	s_waitcnt lgkmcnt(0)
	v_mul_f32_e32 v145, v88, v195
	global_store_dword v[196:197], v145, off
	s_or_b64 exec, exec, s[28:29]
	s_and_saveexec_b64 s[28:29], s[68:69]
	s_cbranch_execnz .LBB0_697

.LBB0_683:
	v_mov_b32_e32 v179, v1
	v_lshl_add_u64 v[196:197], v[178:179], 2, v[186:187]
	s_waitcnt lgkmcnt(0)
	v_mul_f32_e32 v145, v82, v195
	global_store_dword v[196:197], v145, off
	s_or_b64 exec, exec, s[28:29]
	s_and_saveexec_b64 s[28:29], s[24:25]
	s_cbranch_execnz .LBB0_699

.LBB0_685:
	v_mov_b32_e32 v183, v1
	v_lshl_add_u64 v[196:197], v[182:183], 2, v[186:187]
	s_waitcnt lgkmcnt(0)
	v_mul_f32_e32 v145, v84, v195
	global_store_dword v[196:197], v145, off
	s_or_b64 exec, exec, s[28:29]
	s_and_saveexec_b64 s[28:29], s[0:1]
	s_cbranch_execnz .LBB0_701
	s_branch .LBB0_702

.LBB0_687:
	v_mov_b32_e32 v145, v1
	v_lshl_add_u64 v[196:197], v[144:145], 2, v[186:187]
	s_waitcnt lgkmcnt(0)
	v_mul_f32_e32 v145, v95, v195
	global_store_dword v[196:197], v145, off
	s_or_b64 exec, exec, s[28:29]
	s_and_saveexec_b64 s[28:29], s[86:87]
	s_cbranch_execnz .LBB0_673

.LBB0_689:
	v_mov_b32_e32 v149, v1
	v_lshl_add_u64 v[196:197], v[148:149], 2, v[186:187]
	s_waitcnt lgkmcnt(0)
	v_mul_f32_e32 v145, v97, v195
	global_store_dword v[196:197], v145, off
	s_or_b64 exec, exec, s[28:29]
	s_and_saveexec_b64 s[28:29], s[70:71]
	s_cbranch_execnz .LBB0_675

.LBB0_691:
	v_mov_b32_e32 v153, v1
	v_lshl_add_u64 v[196:197], v[152:153], 2, v[186:187]
	s_waitcnt lgkmcnt(0)
	v_mul_f32_e32 v145, v91, v195
	global_store_dword v[196:197], v145, off
	s_or_b64 exec, exec, s[28:29]
	s_and_saveexec_b64 s[28:29], s[64:65]
	s_cbranch_execnz .LBB0_677

.LBB0_693:
	v_mov_b32_e32 v157, v1
	v_lshl_add_u64 v[196:197], v[156:157], 2, v[186:187]
	s_waitcnt lgkmcnt(0)
	v_mul_f32_e32 v145, v93, v195
	global_store_dword v[196:197], v145, off
	s_or_b64 exec, exec, s[28:29]
	s_and_saveexec_b64 s[28:29], s[34:35]
	s_cbranch_execnz .LBB0_679

.LBB0_695:
	v_mov_b32_e32 v173, v1
	v_lshl_add_u64 v[196:197], v[172:173], 2, v[186:187]
	s_waitcnt lgkmcnt(0)
	v_mul_f32_e32 v145, v87, v195
	global_store_dword v[196:197], v145, off
	s_or_b64 exec, exec, s[28:29]
	s_and_saveexec_b64 s[28:29], s[38:39]
	s_cbranch_execnz .LBB0_681

.LBB0_697:
	v_mov_b32_e32 v177, v1
	v_lshl_add_u64 v[196:197], v[176:177], 2, v[186:187]
	s_waitcnt lgkmcnt(0)
	v_mul_f32_e32 v145, v89, v195
	global_store_dword v[196:197], v145, off
	s_or_b64 exec, exec, s[28:29]
	s_and_saveexec_b64 s[28:29], s[88:89]
	s_cbranch_execnz .LBB0_683

.LBB0_699:
	v_mov_b32_e32 v181, v1
	v_lshl_add_u64 v[196:197], v[180:181], 2, v[186:187]
	s_waitcnt lgkmcnt(0)
	v_mul_f32_e32 v145, v83, v195
	global_store_dword v[196:197], v145, off
	s_or_b64 exec, exec, s[28:29]
	s_and_saveexec_b64 s[28:29], s[26:27]
	s_cbranch_execnz .LBB0_685

.LBB0_701:
	v_mov_b32_e32 v185, v1
	v_lshl_add_u64 v[186:187], v[184:185], 2, v[186:187]
	s_waitcnt lgkmcnt(0)
	v_mul_f32_e32 v145, v85, v195
	global_store_dword v[186:187], v145, off
.LBB0_702:
	s_or_b64 exec, exec, s[28:29]
	s_waitcnt lgkmcnt(0)
	ds_read_b32 v195, v143 offset:192
	v_or_b32_e32 v145, 48, v194
	v_mad_i64_i32 v[186:187], s[28:29], s12, v145, 0
	v_lshl_add_u64 v[186:187], v[186:187], 2, s[16:17]
	s_and_saveexec_b64 s[28:29], s[82:83]
	s_cbranch_execz .LBB0_718
	v_lshl_add_u64 v[196:197], v[0:1], 2, v[186:187]
	s_waitcnt lgkmcnt(0)
	v_mul_f32_e32 v145, v78, v195
	global_store_dword v[196:197], v145, off
	s_or_b64 exec, exec, s[28:29]
	s_and_saveexec_b64 s[28:29], s[84:85]
	s_cbranch_execnz .LBB0_719

.LBB0_705:
	v_mov_b32_e32 v147, v1
	v_lshl_add_u64 v[196:197], v[146:147], 2, v[186:187]
	s_waitcnt lgkmcnt(0)
	v_mul_f32_e32 v145, v80, v195
	global_store_dword v[196:197], v145, off
	s_or_b64 exec, exec, s[28:29]
	s_and_saveexec_b64 s[28:29], s[96:97]
	s_cbranch_execnz .LBB0_721

.LBB0_707:
	v_mov_b32_e32 v151, v1
	v_lshl_add_u64 v[196:197], v[150:151], 2, v[186:187]
	s_waitcnt lgkmcnt(0)
	v_mul_f32_e32 v145, v74, v195
	global_store_dword v[196:197], v145, off
	s_or_b64 exec, exec, s[28:29]
	s_and_saveexec_b64 s[28:29], s[8:9]
	s_cbranch_execnz .LBB0_723

.LBB0_709:
	v_mov_b32_e32 v155, v1
	v_lshl_add_u64 v[196:197], v[154:155], 2, v[186:187]
	s_waitcnt lgkmcnt(0)
	v_mul_f32_e32 v145, v76, v195
	global_store_dword v[196:197], v145, off
	s_or_b64 exec, exec, s[28:29]
	s_and_saveexec_b64 s[28:29], s[90:91]
	s_cbranch_execnz .LBB0_725

.LBB0_711:
	v_mov_b32_e32 v171, v1
	v_lshl_add_u64 v[196:197], v[170:171], 2, v[186:187]
	s_waitcnt lgkmcnt(0)
	v_mul_f32_e32 v145, v70, v195
	global_store_dword v[196:197], v145, off
	s_or_b64 exec, exec, s[28:29]
	s_and_saveexec_b64 s[28:29], s[4:5]
	s_cbranch_execnz .LBB0_727

.LBB0_713:
	v_mov_b32_e32 v175, v1
	v_lshl_add_u64 v[196:197], v[174:175], 2, v[186:187]
	s_waitcnt lgkmcnt(0)
	v_mul_f32_e32 v145, v72, v195
	global_store_dword v[196:197], v145, off
	s_or_b64 exec, exec, s[28:29]
	s_and_saveexec_b64 s[28:29], s[68:69]
	s_cbranch_execnz .LBB0_729

.LBB0_715:
	v_mov_b32_e32 v179, v1
	v_lshl_add_u64 v[196:197], v[178:179], 2, v[186:187]
	s_waitcnt lgkmcnt(0)
	v_mul_f32_e32 v145, v66, v195
	global_store_dword v[196:197], v145, off
	s_or_b64 exec, exec, s[28:29]
	s_and_saveexec_b64 s[28:29], s[24:25]
	s_cbranch_execnz .LBB0_731

.LBB0_717:
	v_mov_b32_e32 v183, v1
	v_lshl_add_u64 v[196:197], v[182:183], 2, v[186:187]
	s_waitcnt lgkmcnt(0)
	v_mul_f32_e32 v145, v68, v195
	global_store_dword v[196:197], v145, off
	s_or_b64 exec, exec, s[28:29]
	s_and_saveexec_b64 s[28:29], s[0:1]
	s_cbranch_execnz .LBB0_733
	s_branch .LBB0_734

.LBB0_719:
	v_mov_b32_e32 v145, v1
	v_lshl_add_u64 v[196:197], v[144:145], 2, v[186:187]
	s_waitcnt lgkmcnt(0)
	v_mul_f32_e32 v145, v79, v195
	global_store_dword v[196:197], v145, off
	s_or_b64 exec, exec, s[28:29]
	s_and_saveexec_b64 s[28:29], s[86:87]
	s_cbranch_execnz .LBB0_705

.LBB0_721:
	v_mov_b32_e32 v149, v1
	v_lshl_add_u64 v[196:197], v[148:149], 2, v[186:187]
	s_waitcnt lgkmcnt(0)
	v_mul_f32_e32 v145, v81, v195
	global_store_dword v[196:197], v145, off
	s_or_b64 exec, exec, s[28:29]
	s_and_saveexec_b64 s[28:29], s[70:71]
	s_cbranch_execnz .LBB0_707

.LBB0_723:
	v_mov_b32_e32 v153, v1
	v_lshl_add_u64 v[196:197], v[152:153], 2, v[186:187]
	s_waitcnt lgkmcnt(0)
	v_mul_f32_e32 v145, v75, v195
	global_store_dword v[196:197], v145, off
	s_or_b64 exec, exec, s[28:29]
	s_and_saveexec_b64 s[28:29], s[64:65]
	s_cbranch_execnz .LBB0_709

.LBB0_725:
	v_mov_b32_e32 v157, v1
	v_lshl_add_u64 v[196:197], v[156:157], 2, v[186:187]
	s_waitcnt lgkmcnt(0)
	v_mul_f32_e32 v145, v77, v195
	global_store_dword v[196:197], v145, off
	s_or_b64 exec, exec, s[28:29]
	s_and_saveexec_b64 s[28:29], s[34:35]
	s_cbranch_execnz .LBB0_711

.LBB0_727:
	v_mov_b32_e32 v173, v1
	v_lshl_add_u64 v[196:197], v[172:173], 2, v[186:187]
	s_waitcnt lgkmcnt(0)
	v_mul_f32_e32 v145, v71, v195
	global_store_dword v[196:197], v145, off
	s_or_b64 exec, exec, s[28:29]
	s_and_saveexec_b64 s[28:29], s[38:39]
	s_cbranch_execnz .LBB0_713

.LBB0_729:
	v_mov_b32_e32 v177, v1
	v_lshl_add_u64 v[196:197], v[176:177], 2, v[186:187]
	s_waitcnt lgkmcnt(0)
	v_mul_f32_e32 v145, v73, v195
	global_store_dword v[196:197], v145, off
	s_or_b64 exec, exec, s[28:29]
	s_and_saveexec_b64 s[28:29], s[88:89]
	s_cbranch_execnz .LBB0_715

.LBB0_731:
	v_mov_b32_e32 v181, v1
	v_lshl_add_u64 v[196:197], v[180:181], 2, v[186:187]
	s_waitcnt lgkmcnt(0)
	v_mul_f32_e32 v145, v67, v195
	global_store_dword v[196:197], v145, off
	s_or_b64 exec, exec, s[28:29]
	s_and_saveexec_b64 s[28:29], s[26:27]
	s_cbranch_execnz .LBB0_717

.LBB0_733:
	v_mov_b32_e32 v185, v1
	v_lshl_add_u64 v[186:187], v[184:185], 2, v[186:187]
	s_waitcnt lgkmcnt(0)
	v_mul_f32_e32 v145, v69, v195
	global_store_dword v[186:187], v145, off
.LBB0_734:
	s_or_b64 exec, exec, s[28:29]
	s_waitcnt lgkmcnt(0)
	ds_read_b32 v195, v143 offset:512
	v_add_u32_e32 v145, 0x80, v194
	v_mad_i64_i32 v[186:187], s[28:29], s12, v145, 0
	v_lshl_add_u64 v[186:187], v[186:187], 2, s[16:17]
	s_and_saveexec_b64 s[28:29], s[82:83]
	s_cbranch_execz .LBB0_750
	v_lshl_add_u64 v[196:197], v[0:1], 2, v[186:187]
	s_waitcnt lgkmcnt(0)
	v_mul_f32_e32 v145, v62, v195
	global_store_dword v[196:197], v145, off
	s_or_b64 exec, exec, s[28:29]
	s_and_saveexec_b64 s[28:29], s[84:85]
	s_cbranch_execnz .LBB0_751

.LBB0_737:
	v_mov_b32_e32 v147, v1
	v_lshl_add_u64 v[196:197], v[146:147], 2, v[186:187]
	s_waitcnt lgkmcnt(0)
	v_mul_f32_e32 v145, v64, v195
	global_store_dword v[196:197], v145, off
	s_or_b64 exec, exec, s[28:29]
	s_and_saveexec_b64 s[28:29], s[96:97]
	s_cbranch_execnz .LBB0_753

.LBB0_739:
	v_mov_b32_e32 v151, v1
	v_lshl_add_u64 v[196:197], v[150:151], 2, v[186:187]
	s_waitcnt lgkmcnt(0)
	v_mul_f32_e32 v145, v58, v195
	global_store_dword v[196:197], v145, off
	s_or_b64 exec, exec, s[28:29]
	s_and_saveexec_b64 s[28:29], s[8:9]
	s_cbranch_execnz .LBB0_755

.LBB0_741:
	v_mov_b32_e32 v155, v1
	v_lshl_add_u64 v[196:197], v[154:155], 2, v[186:187]
	s_waitcnt lgkmcnt(0)
	v_mul_f32_e32 v145, v60, v195
	global_store_dword v[196:197], v145, off
	s_or_b64 exec, exec, s[28:29]
	s_and_saveexec_b64 s[28:29], s[90:91]
	s_cbranch_execnz .LBB0_757

.LBB0_743:
	v_mov_b32_e32 v171, v1
	v_lshl_add_u64 v[196:197], v[170:171], 2, v[186:187]
	s_waitcnt lgkmcnt(0)
	v_mul_f32_e32 v145, v54, v195
	global_store_dword v[196:197], v145, off
	s_or_b64 exec, exec, s[28:29]
	s_and_saveexec_b64 s[28:29], s[4:5]
	s_cbranch_execnz .LBB0_759

.LBB0_745:
	v_mov_b32_e32 v175, v1
	v_lshl_add_u64 v[196:197], v[174:175], 2, v[186:187]
	s_waitcnt lgkmcnt(0)
	v_mul_f32_e32 v145, v56, v195
	global_store_dword v[196:197], v145, off
	s_or_b64 exec, exec, s[28:29]
	s_and_saveexec_b64 s[28:29], s[68:69]
	s_cbranch_execnz .LBB0_761

.LBB0_747:
	v_mov_b32_e32 v179, v1
	v_lshl_add_u64 v[196:197], v[178:179], 2, v[186:187]
	s_waitcnt lgkmcnt(0)
	v_mul_f32_e32 v145, v50, v195
	global_store_dword v[196:197], v145, off
	s_or_b64 exec, exec, s[28:29]
	s_and_saveexec_b64 s[28:29], s[24:25]
	s_cbranch_execnz .LBB0_763

.LBB0_749:
	v_mov_b32_e32 v183, v1
	v_lshl_add_u64 v[196:197], v[182:183], 2, v[186:187]
	s_waitcnt lgkmcnt(0)
	v_mul_f32_e32 v145, v52, v195
	global_store_dword v[196:197], v145, off
	s_or_b64 exec, exec, s[28:29]
	s_and_saveexec_b64 s[28:29], s[0:1]
	s_cbranch_execnz .LBB0_765
	s_branch .LBB0_766

.LBB0_751:
	v_mov_b32_e32 v145, v1
	v_lshl_add_u64 v[196:197], v[144:145], 2, v[186:187]
	s_waitcnt lgkmcnt(0)
	v_mul_f32_e32 v145, v63, v195
	global_store_dword v[196:197], v145, off
	s_or_b64 exec, exec, s[28:29]
	s_and_saveexec_b64 s[28:29], s[86:87]
	s_cbranch_execnz .LBB0_737

.LBB0_753:
	v_mov_b32_e32 v149, v1
	v_lshl_add_u64 v[196:197], v[148:149], 2, v[186:187]
	s_waitcnt lgkmcnt(0)
	v_mul_f32_e32 v145, v65, v195
	global_store_dword v[196:197], v145, off
	s_or_b64 exec, exec, s[28:29]
	s_and_saveexec_b64 s[28:29], s[70:71]
	s_cbranch_execnz .LBB0_739

.LBB0_755:
	v_mov_b32_e32 v153, v1
	v_lshl_add_u64 v[196:197], v[152:153], 2, v[186:187]
	s_waitcnt lgkmcnt(0)
	v_mul_f32_e32 v145, v59, v195
	global_store_dword v[196:197], v145, off
	s_or_b64 exec, exec, s[28:29]
	s_and_saveexec_b64 s[28:29], s[64:65]
	s_cbranch_execnz .LBB0_741

.LBB0_757:
	v_mov_b32_e32 v157, v1
	v_lshl_add_u64 v[196:197], v[156:157], 2, v[186:187]
	s_waitcnt lgkmcnt(0)
	v_mul_f32_e32 v145, v61, v195
	global_store_dword v[196:197], v145, off
	s_or_b64 exec, exec, s[28:29]
	s_and_saveexec_b64 s[28:29], s[34:35]
	s_cbranch_execnz .LBB0_743

.LBB0_759:
	v_mov_b32_e32 v173, v1
	v_lshl_add_u64 v[196:197], v[172:173], 2, v[186:187]
	s_waitcnt lgkmcnt(0)
	v_mul_f32_e32 v145, v55, v195
	global_store_dword v[196:197], v145, off
	s_or_b64 exec, exec, s[28:29]
	s_and_saveexec_b64 s[28:29], s[38:39]
	s_cbranch_execnz .LBB0_745

.LBB0_761:
	v_mov_b32_e32 v177, v1
	v_lshl_add_u64 v[196:197], v[176:177], 2, v[186:187]
	s_waitcnt lgkmcnt(0)
	v_mul_f32_e32 v145, v57, v195
	global_store_dword v[196:197], v145, off
	s_or_b64 exec, exec, s[28:29]
	s_and_saveexec_b64 s[28:29], s[88:89]
	s_cbranch_execnz .LBB0_747

.LBB0_763:
	v_mov_b32_e32 v181, v1
	v_lshl_add_u64 v[196:197], v[180:181], 2, v[186:187]
	s_waitcnt lgkmcnt(0)
	v_mul_f32_e32 v145, v51, v195
	global_store_dword v[196:197], v145, off
	s_or_b64 exec, exec, s[28:29]
	s_and_saveexec_b64 s[28:29], s[26:27]
	s_cbranch_execnz .LBB0_749

.LBB0_765:
	v_mov_b32_e32 v185, v1
	v_lshl_add_u64 v[186:187], v[184:185], 2, v[186:187]
	s_waitcnt lgkmcnt(0)
	v_mul_f32_e32 v145, v53, v195
	global_store_dword v[186:187], v145, off
.LBB0_766:
	s_or_b64 exec, exec, s[28:29]
	s_waitcnt lgkmcnt(0)
	ds_read_b32 v195, v143 offset:576
	v_add_u32_e32 v145, 0x90, v194
	v_mad_i64_i32 v[186:187], s[28:29], s12, v145, 0
	v_lshl_add_u64 v[186:187], v[186:187], 2, s[16:17]
	s_and_saveexec_b64 s[28:29], s[82:83]
	s_cbranch_execz .LBB0_782
	v_lshl_add_u64 v[196:197], v[0:1], 2, v[186:187]
	s_waitcnt lgkmcnt(0)
	v_mul_f32_e32 v145, v46, v195
	global_store_dword v[196:197], v145, off
	s_or_b64 exec, exec, s[28:29]
	s_and_saveexec_b64 s[28:29], s[84:85]
	s_cbranch_execnz .LBB0_783

.LBB0_769:
	v_mov_b32_e32 v147, v1
	v_lshl_add_u64 v[196:197], v[146:147], 2, v[186:187]
	s_waitcnt lgkmcnt(0)
	v_mul_f32_e32 v145, v48, v195
	global_store_dword v[196:197], v145, off
	s_or_b64 exec, exec, s[28:29]
	s_and_saveexec_b64 s[28:29], s[96:97]
	s_cbranch_execnz .LBB0_785

.LBB0_771:
	v_mov_b32_e32 v151, v1
	v_lshl_add_u64 v[196:197], v[150:151], 2, v[186:187]
	s_waitcnt lgkmcnt(0)
	v_mul_f32_e32 v145, v42, v195
	global_store_dword v[196:197], v145, off
	s_or_b64 exec, exec, s[28:29]
	s_and_saveexec_b64 s[28:29], s[8:9]
	s_cbranch_execnz .LBB0_787

.LBB0_773:
	v_mov_b32_e32 v155, v1
	v_lshl_add_u64 v[196:197], v[154:155], 2, v[186:187]
	s_waitcnt lgkmcnt(0)
	v_mul_f32_e32 v145, v44, v195
	global_store_dword v[196:197], v145, off
	s_or_b64 exec, exec, s[28:29]
	s_and_saveexec_b64 s[28:29], s[90:91]
	s_cbranch_execnz .LBB0_789

.LBB0_775:
	v_mov_b32_e32 v171, v1
	v_lshl_add_u64 v[196:197], v[170:171], 2, v[186:187]
	s_waitcnt lgkmcnt(0)
	v_mul_f32_e32 v145, v38, v195
	global_store_dword v[196:197], v145, off
	s_or_b64 exec, exec, s[28:29]
	s_and_saveexec_b64 s[28:29], s[4:5]
	s_cbranch_execnz .LBB0_791

.LBB0_777:
	v_mov_b32_e32 v175, v1
	v_lshl_add_u64 v[196:197], v[174:175], 2, v[186:187]
	s_waitcnt lgkmcnt(0)
	v_mul_f32_e32 v145, v40, v195
	global_store_dword v[196:197], v145, off
	s_or_b64 exec, exec, s[28:29]
	s_and_saveexec_b64 s[28:29], s[68:69]
	s_cbranch_execnz .LBB0_793

.LBB0_779:
	v_mov_b32_e32 v179, v1
	v_lshl_add_u64 v[196:197], v[178:179], 2, v[186:187]
	s_waitcnt lgkmcnt(0)
	v_mul_f32_e32 v145, v34, v195
	global_store_dword v[196:197], v145, off
	s_or_b64 exec, exec, s[28:29]
	s_and_saveexec_b64 s[28:29], s[24:25]
	s_cbranch_execnz .LBB0_795

.LBB0_781:
	v_mov_b32_e32 v183, v1
	v_lshl_add_u64 v[196:197], v[182:183], 2, v[186:187]
	s_waitcnt lgkmcnt(0)
	v_mul_f32_e32 v145, v36, v195
	global_store_dword v[196:197], v145, off
	s_or_b64 exec, exec, s[28:29]
	s_and_saveexec_b64 s[28:29], s[0:1]
	s_cbranch_execnz .LBB0_797
	s_branch .LBB0_798

.LBB0_783:
	v_mov_b32_e32 v145, v1
	v_lshl_add_u64 v[196:197], v[144:145], 2, v[186:187]
	s_waitcnt lgkmcnt(0)
	v_mul_f32_e32 v145, v47, v195
	global_store_dword v[196:197], v145, off
	s_or_b64 exec, exec, s[28:29]
	s_and_saveexec_b64 s[28:29], s[86:87]
	s_cbranch_execnz .LBB0_769

.LBB0_785:
	v_mov_b32_e32 v149, v1
	v_lshl_add_u64 v[196:197], v[148:149], 2, v[186:187]
	s_waitcnt lgkmcnt(0)
	v_mul_f32_e32 v145, v49, v195
	global_store_dword v[196:197], v145, off
	s_or_b64 exec, exec, s[28:29]
	s_and_saveexec_b64 s[28:29], s[70:71]
	s_cbranch_execnz .LBB0_771

.LBB0_787:
	v_mov_b32_e32 v153, v1
	v_lshl_add_u64 v[196:197], v[152:153], 2, v[186:187]
	s_waitcnt lgkmcnt(0)
	v_mul_f32_e32 v145, v43, v195
	global_store_dword v[196:197], v145, off
	s_or_b64 exec, exec, s[28:29]
	s_and_saveexec_b64 s[28:29], s[64:65]
	s_cbranch_execnz .LBB0_773

.LBB0_789:
	v_mov_b32_e32 v157, v1
	v_lshl_add_u64 v[196:197], v[156:157], 2, v[186:187]
	s_waitcnt lgkmcnt(0)
	v_mul_f32_e32 v145, v45, v195
	global_store_dword v[196:197], v145, off
	s_or_b64 exec, exec, s[28:29]
	s_and_saveexec_b64 s[28:29], s[34:35]
	s_cbranch_execnz .LBB0_775

.LBB0_791:
	v_mov_b32_e32 v173, v1
	v_lshl_add_u64 v[196:197], v[172:173], 2, v[186:187]
	s_waitcnt lgkmcnt(0)
	v_mul_f32_e32 v145, v39, v195
	global_store_dword v[196:197], v145, off
	s_or_b64 exec, exec, s[28:29]
	s_and_saveexec_b64 s[28:29], s[38:39]
	s_cbranch_execnz .LBB0_777

.LBB0_793:
	v_mov_b32_e32 v177, v1
	v_lshl_add_u64 v[196:197], v[176:177], 2, v[186:187]
	s_waitcnt lgkmcnt(0)
	v_mul_f32_e32 v145, v41, v195
	global_store_dword v[196:197], v145, off
	s_or_b64 exec, exec, s[28:29]
	s_and_saveexec_b64 s[28:29], s[88:89]
	s_cbranch_execnz .LBB0_779

.LBB0_795:
	v_mov_b32_e32 v181, v1
	v_lshl_add_u64 v[196:197], v[180:181], 2, v[186:187]
	s_waitcnt lgkmcnt(0)
	v_mul_f32_e32 v145, v35, v195
	global_store_dword v[196:197], v145, off
	s_or_b64 exec, exec, s[28:29]
	s_and_saveexec_b64 s[28:29], s[26:27]
	s_cbranch_execnz .LBB0_781

.LBB0_797:
	v_mov_b32_e32 v185, v1
	v_lshl_add_u64 v[186:187], v[184:185], 2, v[186:187]
	s_waitcnt lgkmcnt(0)
	v_mul_f32_e32 v145, v37, v195
	global_store_dword v[186:187], v145, off
.LBB0_798:
	s_or_b64 exec, exec, s[28:29]
	s_waitcnt lgkmcnt(0)
	ds_read_b32 v195, v143 offset:640
	v_add_u32_e32 v145, 0xa0, v194
	v_mad_i64_i32 v[186:187], s[28:29], s12, v145, 0
	v_lshl_add_u64 v[186:187], v[186:187], 2, s[16:17]
	s_and_saveexec_b64 s[28:29], s[82:83]
	s_cbranch_execz .LBB0_814
	v_lshl_add_u64 v[196:197], v[0:1], 2, v[186:187]
	s_waitcnt lgkmcnt(0)
	v_mul_f32_e32 v145, v30, v195
	global_store_dword v[196:197], v145, off
	s_or_b64 exec, exec, s[28:29]
	s_and_saveexec_b64 s[28:29], s[84:85]
	s_cbranch_execnz .LBB0_815

.LBB0_801:
	v_mov_b32_e32 v147, v1
	v_lshl_add_u64 v[196:197], v[146:147], 2, v[186:187]
	s_waitcnt lgkmcnt(0)
	v_mul_f32_e32 v145, v32, v195
	global_store_dword v[196:197], v145, off
	s_or_b64 exec, exec, s[28:29]
	s_and_saveexec_b64 s[28:29], s[96:97]
	s_cbranch_execnz .LBB0_817

.LBB0_803:
	v_mov_b32_e32 v151, v1
	v_lshl_add_u64 v[196:197], v[150:151], 2, v[186:187]
	s_waitcnt lgkmcnt(0)
	v_mul_f32_e32 v145, v26, v195
	global_store_dword v[196:197], v145, off
	s_or_b64 exec, exec, s[28:29]
	s_and_saveexec_b64 s[28:29], s[8:9]
	s_cbranch_execnz .LBB0_819

.LBB0_805:
	v_mov_b32_e32 v155, v1
	v_lshl_add_u64 v[196:197], v[154:155], 2, v[186:187]
	s_waitcnt lgkmcnt(0)
	v_mul_f32_e32 v145, v28, v195
	global_store_dword v[196:197], v145, off
	s_or_b64 exec, exec, s[28:29]
	s_and_saveexec_b64 s[28:29], s[90:91]
	s_cbranch_execnz .LBB0_821

.LBB0_807:
	v_mov_b32_e32 v171, v1
	v_lshl_add_u64 v[196:197], v[170:171], 2, v[186:187]
	s_waitcnt lgkmcnt(0)
	v_mul_f32_e32 v145, v22, v195
	global_store_dword v[196:197], v145, off
	s_or_b64 exec, exec, s[28:29]
	s_and_saveexec_b64 s[28:29], s[4:5]
	s_cbranch_execnz .LBB0_823

.LBB0_809:
	v_mov_b32_e32 v175, v1
	v_lshl_add_u64 v[196:197], v[174:175], 2, v[186:187]
	s_waitcnt lgkmcnt(0)
	v_mul_f32_e32 v145, v24, v195
	global_store_dword v[196:197], v145, off
	s_or_b64 exec, exec, s[28:29]
	s_and_saveexec_b64 s[28:29], s[68:69]
	s_cbranch_execnz .LBB0_825

.LBB0_811:
	v_mov_b32_e32 v179, v1
	v_lshl_add_u64 v[196:197], v[178:179], 2, v[186:187]
	s_waitcnt lgkmcnt(0)
	v_mul_f32_e32 v145, v18, v195
	global_store_dword v[196:197], v145, off
	s_or_b64 exec, exec, s[28:29]
	s_and_saveexec_b64 s[28:29], s[24:25]
	s_cbranch_execnz .LBB0_827

.LBB0_813:
	v_mov_b32_e32 v183, v1
	v_lshl_add_u64 v[196:197], v[182:183], 2, v[186:187]
	s_waitcnt lgkmcnt(0)
	v_mul_f32_e32 v145, v20, v195
	global_store_dword v[196:197], v145, off
	s_or_b64 exec, exec, s[28:29]
	s_and_saveexec_b64 s[28:29], s[0:1]
	s_cbranch_execnz .LBB0_829
	s_branch .LBB0_830

.LBB0_815:
	v_mov_b32_e32 v145, v1
	v_lshl_add_u64 v[196:197], v[144:145], 2, v[186:187]
	s_waitcnt lgkmcnt(0)
	v_mul_f32_e32 v145, v31, v195
	global_store_dword v[196:197], v145, off
	s_or_b64 exec, exec, s[28:29]
	s_and_saveexec_b64 s[28:29], s[86:87]
	s_cbranch_execnz .LBB0_801

.LBB0_817:
	v_mov_b32_e32 v149, v1
	s_waitcnt lgkmcnt(0)
	v_mul_f32_e32 v145, v33, v195
	v_lshl_add_u64 v[196:197], v[148:149], 2, v[186:187]
	global_store_dword v[196:197], v145, off
	s_or_b64 exec, exec, s[28:29]
	s_and_saveexec_b64 s[28:29], s[70:71]
	s_cbranch_execnz .LBB0_803

.LBB0_819:
	v_mov_b32_e32 v153, v1
	v_lshl_add_u64 v[196:197], v[152:153], 2, v[186:187]
	s_waitcnt lgkmcnt(0)
	v_mul_f32_e32 v145, v27, v195
	global_store_dword v[196:197], v145, off
	s_or_b64 exec, exec, s[28:29]
	s_and_saveexec_b64 s[28:29], s[64:65]
	s_cbranch_execnz .LBB0_805

.LBB0_821:
	v_mov_b32_e32 v157, v1
	v_lshl_add_u64 v[196:197], v[156:157], 2, v[186:187]
	s_waitcnt lgkmcnt(0)
	v_mul_f32_e32 v145, v29, v195
	global_store_dword v[196:197], v145, off
	s_or_b64 exec, exec, s[28:29]
	s_and_saveexec_b64 s[28:29], s[34:35]
	s_cbranch_execnz .LBB0_807

.LBB0_823:
	v_mov_b32_e32 v173, v1
	v_lshl_add_u64 v[196:197], v[172:173], 2, v[186:187]
	s_waitcnt lgkmcnt(0)
	v_mul_f32_e32 v145, v23, v195
	global_store_dword v[196:197], v145, off
	s_or_b64 exec, exec, s[28:29]
	s_and_saveexec_b64 s[28:29], s[38:39]
	s_cbranch_execnz .LBB0_809

.LBB0_825:
	v_mov_b32_e32 v177, v1
	v_lshl_add_u64 v[196:197], v[176:177], 2, v[186:187]
	s_waitcnt lgkmcnt(0)
	v_mul_f32_e32 v145, v25, v195
	global_store_dword v[196:197], v145, off
	s_or_b64 exec, exec, s[28:29]
	s_and_saveexec_b64 s[28:29], s[88:89]
	s_cbranch_execnz .LBB0_811

.LBB0_827:
	v_mov_b32_e32 v181, v1
	v_lshl_add_u64 v[196:197], v[180:181], 2, v[186:187]
	s_waitcnt lgkmcnt(0)
	v_mul_f32_e32 v145, v19, v195
	global_store_dword v[196:197], v145, off
	s_or_b64 exec, exec, s[28:29]
	s_and_saveexec_b64 s[28:29], s[26:27]
	s_cbranch_execnz .LBB0_813

.LBB0_829:
	v_mov_b32_e32 v185, v1
	v_lshl_add_u64 v[186:187], v[184:185], 2, v[186:187]
	s_waitcnt lgkmcnt(0)
	v_mul_f32_e32 v145, v21, v195
	global_store_dword v[186:187], v145, off
.LBB0_830:
	s_or_b64 exec, exec, s[28:29]
	ds_read_b32 v143, v143 offset:704
	v_add_u32_e32 v145, 0xb0, v194
	v_mad_i64_i32 v[186:187], s[28:29], s12, v145, 0
	v_lshl_add_u64 v[186:187], v[186:187], 2, s[16:17]
	s_and_saveexec_b64 s[28:29], s[82:83]
	s_cbranch_execz .LBB0_846
	v_lshl_add_u64 v[196:197], v[0:1], 2, v[186:187]
	s_waitcnt lgkmcnt(0)
	v_mul_f32_e32 v0, v14, v143
	global_store_dword v[196:197], v0, off
	s_or_b64 exec, exec, s[28:29]
	s_and_saveexec_b64 s[28:29], s[84:85]
	s_cbranch_execnz .LBB0_847

.LBB0_833:
	v_mov_b32_e32 v147, v1
	v_lshl_add_u64 v[144:145], v[146:147], 2, v[186:187]
	s_waitcnt lgkmcnt(0)
	v_mul_f32_e32 v0, v16, v143
	global_store_dword v[144:145], v0, off
	s_or_b64 exec, exec, s[28:29]
	s_and_saveexec_b64 s[28:29], s[96:97]
	s_cbranch_execnz .LBB0_849

.LBB0_835:
	v_mov_b32_e32 v151, v1
	v_lshl_add_u64 v[144:145], v[150:151], 2, v[186:187]
	s_waitcnt lgkmcnt(0)
	v_mul_f32_e32 v0, v10, v143
	global_store_dword v[144:145], v0, off
	s_or_b64 exec, exec, s[28:29]
	s_and_saveexec_b64 s[28:29], s[8:9]
	s_cbranch_execnz .LBB0_851

.LBB0_837:
	v_mov_b32_e32 v155, v1
	v_lshl_add_u64 v[144:145], v[154:155], 2, v[186:187]
	s_waitcnt lgkmcnt(0)
	v_mul_f32_e32 v0, v12, v143
	global_store_dword v[144:145], v0, off
	s_or_b64 exec, exec, s[8:9]
	s_and_saveexec_b64 s[8:9], s[90:91]
	s_cbranch_execnz .LBB0_853

.LBB0_839:
	v_mov_b32_e32 v171, v1
	v_lshl_add_u64 v[144:145], v[170:171], 2, v[186:187]
	s_waitcnt lgkmcnt(0)
	v_mul_f32_e32 v0, v6, v143
	global_store_dword v[144:145], v0, off
	s_or_b64 exec, exec, s[8:9]
	s_and_saveexec_b64 s[8:9], s[4:5]
	s_cbranch_execnz .LBB0_855

.LBB0_841:
	v_mov_b32_e32 v175, v1
	v_lshl_add_u64 v[144:145], v[174:175], 2, v[186:187]
	s_waitcnt lgkmcnt(0)
	v_mul_f32_e32 v0, v8, v143
	global_store_dword v[144:145], v0, off
	s_or_b64 exec, exec, s[4:5]
	s_and_saveexec_b64 s[4:5], s[68:69]
	s_cbranch_execnz .LBB0_857

.LBB0_843:
	v_mov_b32_e32 v179, v1
	v_lshl_add_u64 v[144:145], v[178:179], 2, v[186:187]
	s_waitcnt lgkmcnt(0)
	v_mul_f32_e32 v0, v2, v143
	global_store_dword v[144:145], v0, off
	s_or_b64 exec, exec, s[4:5]
	s_and_saveexec_b64 s[4:5], s[24:25]
	s_cbranch_execnz .LBB0_859

.LBB0_845:
	v_mov_b32_e32 v183, v1
	v_lshl_add_u64 v[144:145], v[182:183], 2, v[186:187]
	s_waitcnt lgkmcnt(0)
	v_mul_f32_e32 v0, v4, v143
	global_store_dword v[144:145], v0, off
	s_or_b64 exec, exec, s[4:5]
	s_and_saveexec_b64 s[4:5], s[0:1]
	s_cbranch_execnz .LBB0_861
	s_branch .LBB0_862

.LBB0_847:
	v_mov_b32_e32 v145, v1
	v_lshl_add_u64 v[144:145], v[144:145], 2, v[186:187]
	s_waitcnt lgkmcnt(0)
	v_mul_f32_e32 v0, v15, v143
	global_store_dword v[144:145], v0, off
	s_or_b64 exec, exec, s[28:29]
	s_and_saveexec_b64 s[28:29], s[86:87]
	s_cbranch_execnz .LBB0_833

.LBB0_849:
	v_mov_b32_e32 v149, v1
	v_lshl_add_u64 v[144:145], v[148:149], 2, v[186:187]
	s_waitcnt lgkmcnt(0)
	v_mul_f32_e32 v0, v17, v143
	global_store_dword v[144:145], v0, off
	s_or_b64 exec, exec, s[28:29]
	s_and_saveexec_b64 s[28:29], s[70:71]
	s_cbranch_execnz .LBB0_835

.LBB0_851:
	v_mov_b32_e32 v153, v1
	v_lshl_add_u64 v[144:145], v[152:153], 2, v[186:187]
	s_waitcnt lgkmcnt(0)
	v_mul_f32_e32 v0, v11, v143
	global_store_dword v[144:145], v0, off
	s_or_b64 exec, exec, s[28:29]
	s_and_saveexec_b64 s[8:9], s[64:65]
	s_cbranch_execnz .LBB0_837

.LBB0_853:
	v_mov_b32_e32 v157, v1
	v_lshl_add_u64 v[144:145], v[156:157], 2, v[186:187]
	s_waitcnt lgkmcnt(0)
	v_mul_f32_e32 v0, v13, v143
	global_store_dword v[144:145], v0, off
	s_or_b64 exec, exec, s[8:9]
	s_and_saveexec_b64 s[8:9], s[34:35]
	s_cbranch_execnz .LBB0_839

.LBB0_855:
	v_mov_b32_e32 v173, v1
	v_lshl_add_u64 v[144:145], v[172:173], 2, v[186:187]
	s_waitcnt lgkmcnt(0)
	v_mul_f32_e32 v0, v7, v143
	global_store_dword v[144:145], v0, off
	s_or_b64 exec, exec, s[8:9]
	s_and_saveexec_b64 s[4:5], s[38:39]
	s_cbranch_execnz .LBB0_841

.LBB0_857:
	v_mov_b32_e32 v177, v1
	v_lshl_add_u64 v[144:145], v[176:177], 2, v[186:187]
	s_waitcnt lgkmcnt(0)
	v_mul_f32_e32 v0, v9, v143
	global_store_dword v[144:145], v0, off
	s_or_b64 exec, exec, s[4:5]
	s_and_saveexec_b64 s[4:5], s[88:89]
	s_cbranch_execnz .LBB0_843

.LBB0_859:
	v_mov_b32_e32 v181, v1
	v_lshl_add_u64 v[144:145], v[180:181], 2, v[186:187]
	s_waitcnt lgkmcnt(0)
	v_mul_f32_e32 v0, v3, v143
	global_store_dword v[144:145], v0, off
	s_or_b64 exec, exec, s[4:5]
	s_and_saveexec_b64 s[4:5], s[26:27]
	s_cbranch_execnz .LBB0_845

.LBB0_861:
	v_mov_b32_e32 v185, v1
	s_waitcnt lgkmcnt(0)
	v_mul_f32_e32 v0, v5, v143
	v_lshl_add_u64 v[144:145], v[184:185], 2, v[186:187]
	global_store_dword v[144:145], v0, off

.LBB0_903:
	v_lshl_add_u32 v142, s70, 8, v144
	v_lshl_or_b32 v140, s69, 8, v146
	v_readlane_b32 s20, v254, 21
	v_readlane_b32 s21, v254, 22
	s_lshl_b32 s94, s69, 4
	s_lshl_b32 s24, s57, 2
	s_add_i32 s94, s94, s24
	v_lshlrev_b32_e32 v141, 12, v142
	v_lshl_add_u32 v141, v140, 2, v141
	v_add_u32_e32 v143, 0x10000, v141
	v_add_u32_e32 v156, 0x20000, v141
	v_add_u32_e32 v157, 0x30000, v141
	v_add_u32_e32 v202, 0x80000, v141
	v_add_u32_e32 v203, 0x90000, v141
	v_add_u32_e32 v220, 0xa0000, v141
	v_add_u32_e32 v221, 0xb0000, v141
	global_load_dwordx4 v[148:151], v141, s[8:9]
	global_load_dwordx4 v[152:155], v141, s[8:9] offset:16
	global_load_dwordx4 v[170:173], v141, s[8:9] offset:512
	global_load_dwordx4 v[174:177], v141, s[8:9] offset:528
	global_load_dwordx4 v[178:181], v143, s[8:9]
	global_load_dwordx4 v[182:185], v143, s[8:9] offset:16
	global_load_dwordx4 v[186:189], v143, s[8:9] offset:512
	global_load_dwordx4 v[190:193], v143, s[8:9] offset:528
	global_load_dwordx4 v[194:197], v156, s[8:9]
	global_load_dwordx4 v[198:201], v156, s[8:9] offset:16
	global_load_dwordx4 v[206:209], v156, s[8:9] offset:512
	global_load_dwordx4 v[210:213], v156, s[8:9] offset:528
	global_load_dwordx4 v[214:217], v157, s[8:9]
	global_load_dwordx4 v[238:241], v157, s[8:9] offset:16
	global_load_dwordx4 v[242:245], v157, s[8:9] offset:512
	global_load_dwordx4 v[246:249], v157, s[8:9] offset:528
	s_waitcnt vmcnt(14)
	v_pk_fma_f32 v[128:129], v[128:129], 0.5, v[150:151] op_sel_hi:[1,0,1]
	v_pk_fma_f32 v[126:127], v[126:127], 0.5, v[148:149] op_sel_hi:[1,0,1]
	v_pk_fma_f32 v[124:125], v[124:125], 0.5, v[154:155] op_sel_hi:[1,0,1]
	v_pk_fma_f32 v[122:123], v[122:123], 0.5, v[152:153] op_sel_hi:[1,0,1]
	global_store_dwordx4 v141, v[126:129], s[14:15]
	global_store_dwordx4 v141, v[122:125], s[14:15] offset:16
	v_cvt_pk_bf16_f32 v148, v126, v127
	v_cvt_pk_bf16_f32 v149, v128, v129
	v_cvt_pk_bf16_f32 v150, v122, v123
	v_cvt_pk_bf16_f32 v151, v124, v125
	v_lshrrev_b32_e32 v167, 1, v141
	global_store_dwordx4 v167, v[148:151], s[20:21]
	v_mul_f32_e32 v127, v127, v127
	v_mul_f32_e32 v129, v129, v129
	v_mul_f32_e32 v123, v123, v123
	v_mul_f32_e32 v125, v125, v125
	v_fmac_f32_e32 v127, v126, v126
	v_fmac_f32_e32 v129, v128, v128
	v_fmac_f32_e32 v123, v122, v122
	v_fmac_f32_e32 v125, v124, v124
	v_add_f32_e32 v122, v127, v129
	v_add_f32_e32 v123, v123, v125
	v_add_f32_e32 v126, v122, v123
	global_load_dwordx4 v[148:151], v202, s[8:9]
	global_load_dwordx4 v[152:155], v202, s[8:9] offset:16
	s_waitcnt vmcnt(17)
	v_pk_fma_f32 v[120:121], v[120:121], 0.5, v[172:173] op_sel_hi:[1,0,1]
	v_pk_fma_f32 v[118:119], v[118:119], 0.5, v[170:171] op_sel_hi:[1,0,1]
	v_pk_fma_f32 v[116:117], v[116:117], 0.5, v[176:177] op_sel_hi:[1,0,1]
	v_pk_fma_f32 v[114:115], v[114:115], 0.5, v[174:175] op_sel_hi:[1,0,1]
	global_store_dwordx4 v141, v[118:121], s[14:15] offset:512
	global_store_dwordx4 v141, v[114:117], s[14:15] offset:528
	v_cvt_pk_bf16_f32 v170, v118, v119
	v_cvt_pk_bf16_f32 v171, v120, v121
	v_cvt_pk_bf16_f32 v172, v114, v115
	v_cvt_pk_bf16_f32 v173, v116, v117
	global_store_dwordx4 v167, v[170:173], s[20:21] offset:256
	v_mul_f32_e32 v119, v119, v119
	v_mul_f32_e32 v121, v121, v121
	v_mul_f32_e32 v115, v115, v115
	v_mul_f32_e32 v117, v117, v117
	v_fmac_f32_e32 v119, v118, v118
	v_fmac_f32_e32 v121, v120, v120
	v_fmac_f32_e32 v115, v114, v114
	v_fmac_f32_e32 v117, v116, v116
	v_add_f32_e32 v114, v119, v121
	v_add_f32_e32 v115, v115, v117
	v_add_f32_e32 v114, v114, v115
	v_add_f32_e32 v114, v126, v114
	v_lshlrev_b32_e32 v116, 2, v222
	v_xor_b32_e32 v115, 64, v116
	ds_bpermute_b32 v115, v115, v114
	global_load_dwordx4 v[170:173], v202, s[8:9] offset:512
	global_load_dwordx4 v[174:177], v202, s[8:9] offset:528
	v_add_u32_e32 v167, 0, v142
	v_lshl_add_u32 v167, v167, 6, s94
	s_waitcnt lgkmcnt(0)
	v_add_f32_e32 v114, v114, v115
	v_xor_b32_e32 v115, 0x80, v116
	ds_bpermute_b32 v115, v115, v114
	s_and_saveexec_b64 s[24:25], s[2:3]
	s_waitcnt lgkmcnt(0)
	v_add_f32_e32 v114, v114, v115
	global_store_dword v167, v114, s[10:11]
	s_or_b64 exec, exec, s[24:25]
	s_waitcnt vmcnt(21)
	v_pk_fma_f32 v[112:113], v[112:113], 0.5, v[180:181] op_sel_hi:[1,0,1]
	v_pk_fma_f32 v[110:111], v[110:111], 0.5, v[178:179] op_sel_hi:[1,0,1]
	v_pk_fma_f32 v[108:109], v[108:109], 0.5, v[184:185] op_sel_hi:[1,0,1]
	v_pk_fma_f32 v[106:107], v[106:107], 0.5, v[182:183] op_sel_hi:[1,0,1]
	global_store_dwordx4 v143, v[110:113], s[14:15]
	global_store_dwordx4 v143, v[106:109], s[14:15] offset:16
	v_cvt_pk_bf16_f32 v178, v110, v111
	v_cvt_pk_bf16_f32 v179, v112, v113
	v_cvt_pk_bf16_f32 v180, v106, v107
	v_cvt_pk_bf16_f32 v181, v108, v109
	v_lshrrev_b32_e32 v167, 1, v143
	global_store_dwordx4 v167, v[178:181], s[20:21]
	v_mul_f32_e32 v111, v111, v111
	v_mul_f32_e32 v113, v113, v113
	v_mul_f32_e32 v107, v107, v107
	v_mul_f32_e32 v109, v109, v109
	v_fmac_f32_e32 v111, v110, v110
	v_fmac_f32_e32 v113, v112, v112
	v_fmac_f32_e32 v107, v106, v106
	v_fmac_f32_e32 v109, v108, v108
	v_add_f32_e32 v106, v111, v113
	v_add_f32_e32 v107, v107, v109
	v_add_f32_e32 v110, v106, v107
	global_load_dwordx4 v[178:181], v203, s[8:9]
	global_load_dwordx4 v[182:185], v203, s[8:9] offset:16
	s_waitcnt vmcnt(24)
	v_pk_fma_f32 v[104:105], v[104:105], 0.5, v[188:189] op_sel_hi:[1,0,1]
	v_pk_fma_f32 v[102:103], v[102:103], 0.5, v[186:187] op_sel_hi:[1,0,1]
	v_pk_fma_f32 v[100:101], v[100:101], 0.5, v[192:193] op_sel_hi:[1,0,1]
	v_pk_fma_f32 v[98:99], v[98:99], 0.5, v[190:191] op_sel_hi:[1,0,1]
	global_store_dwordx4 v143, v[102:105], s[14:15] offset:512
	global_store_dwordx4 v143, v[98:101], s[14:15] offset:528
	v_cvt_pk_bf16_f32 v186, v102, v103
	v_cvt_pk_bf16_f32 v187, v104, v105
	v_cvt_pk_bf16_f32 v188, v98, v99
	v_cvt_pk_bf16_f32 v189, v100, v101
	global_store_dwordx4 v167, v[186:189], s[20:21] offset:256
	v_mul_f32_e32 v103, v103, v103
	v_mul_f32_e32 v105, v105, v105
	v_mul_f32_e32 v99, v99, v99
	v_mul_f32_e32 v101, v101, v101
	v_fmac_f32_e32 v103, v102, v102
	v_fmac_f32_e32 v105, v104, v104
	v_fmac_f32_e32 v99, v98, v98
	v_fmac_f32_e32 v101, v100, v100
	v_add_f32_e32 v98, v103, v105
	v_add_f32_e32 v99, v99, v101
	v_add_f32_e32 v98, v98, v99
	v_add_f32_e32 v98, v110, v98
	v_lshlrev_b32_e32 v100, 2, v222
	v_xor_b32_e32 v99, 64, v100
	ds_bpermute_b32 v99, v99, v98
	global_load_dwordx4 v[186:189], v203, s[8:9] offset:512
	global_load_dwordx4 v[190:193], v203, s[8:9] offset:528
	v_add_u32_e32 v167, 16, v142
	v_lshl_add_u32 v167, v167, 6, s94
	s_waitcnt lgkmcnt(0)
	v_add_f32_e32 v98, v98, v99
	v_xor_b32_e32 v99, 0x80, v100
	ds_bpermute_b32 v99, v99, v98
	s_and_saveexec_b64 s[24:25], s[2:3]
	s_waitcnt lgkmcnt(0)
	v_add_f32_e32 v98, v98, v99
	global_store_dword v167, v98, s[10:11]
	s_or_b64 exec, exec, s[24:25]
	s_waitcnt vmcnt(28)
	v_pk_fma_f32 v[96:97], v[96:97], 0.5, v[196:197] op_sel_hi:[1,0,1]
	v_pk_fma_f32 v[94:95], v[94:95], 0.5, v[194:195] op_sel_hi:[1,0,1]
	v_pk_fma_f32 v[92:93], v[92:93], 0.5, v[200:201] op_sel_hi:[1,0,1]
	v_pk_fma_f32 v[90:91], v[90:91], 0.5, v[198:199] op_sel_hi:[1,0,1]
	global_store_dwordx4 v156, v[94:97], s[14:15]
	global_store_dwordx4 v156, v[90:93], s[14:15] offset:16
	v_cvt_pk_bf16_f32 v194, v94, v95
	v_cvt_pk_bf16_f32 v195, v96, v97
	v_cvt_pk_bf16_f32 v196, v90, v91
	v_cvt_pk_bf16_f32 v197, v92, v93
	v_lshrrev_b32_e32 v167, 1, v156
	global_store_dwordx4 v167, v[194:197], s[20:21]
	v_mul_f32_e32 v95, v95, v95
	v_mul_f32_e32 v97, v97, v97
	v_mul_f32_e32 v91, v91, v91
	v_mul_f32_e32 v93, v93, v93
	v_fmac_f32_e32 v95, v94, v94
	v_fmac_f32_e32 v97, v96, v96
	v_fmac_f32_e32 v91, v90, v90
	v_fmac_f32_e32 v93, v92, v92
	v_add_f32_e32 v90, v95, v97
	v_add_f32_e32 v91, v91, v93
	v_add_f32_e32 v94, v90, v91
	global_load_dwordx4 v[194:197], v220, s[8:9]
	global_load_dwordx4 v[198:201], v220, s[8:9] offset:16
	s_waitcnt vmcnt(31)
	v_pk_fma_f32 v[88:89], v[88:89], 0.5, v[208:209] op_sel_hi:[1,0,1]
	v_pk_fma_f32 v[86:87], v[86:87], 0.5, v[206:207] op_sel_hi:[1,0,1]
	v_pk_fma_f32 v[84:85], v[84:85], 0.5, v[212:213] op_sel_hi:[1,0,1]
	v_pk_fma_f32 v[82:83], v[82:83], 0.5, v[210:211] op_sel_hi:[1,0,1]
	global_store_dwordx4 v156, v[86:89], s[14:15] offset:512
	global_store_dwordx4 v156, v[82:85], s[14:15] offset:528
	v_cvt_pk_bf16_f32 v206, v86, v87
	v_cvt_pk_bf16_f32 v207, v88, v89
	v_cvt_pk_bf16_f32 v208, v82, v83
	v_cvt_pk_bf16_f32 v209, v84, v85
	global_store_dwordx4 v167, v[206:209], s[20:21] offset:256
	v_mul_f32_e32 v87, v87, v87
	v_mul_f32_e32 v89, v89, v89
	v_mul_f32_e32 v83, v83, v83
	v_mul_f32_e32 v85, v85, v85
	v_fmac_f32_e32 v87, v86, v86
	v_fmac_f32_e32 v89, v88, v88
	v_fmac_f32_e32 v83, v82, v82
	v_fmac_f32_e32 v85, v84, v84
	v_add_f32_e32 v82, v87, v89
	v_add_f32_e32 v83, v83, v85
	v_add_f32_e32 v82, v82, v83
	v_add_f32_e32 v82, v94, v82
	v_lshlrev_b32_e32 v84, 2, v222
	v_xor_b32_e32 v83, 64, v84
	ds_bpermute_b32 v83, v83, v82
	global_load_dwordx4 v[206:209], v220, s[8:9] offset:512
	global_load_dwordx4 v[210:213], v220, s[8:9] offset:528
	v_add_u32_e32 v167, 32, v142
	v_lshl_add_u32 v167, v167, 6, s94
	s_waitcnt lgkmcnt(0)
	v_add_f32_e32 v82, v82, v83
	v_xor_b32_e32 v83, 0x80, v84
	ds_bpermute_b32 v83, v83, v82
	s_and_saveexec_b64 s[24:25], s[2:3]
	s_waitcnt lgkmcnt(0)
	v_add_f32_e32 v82, v82, v83
	global_store_dword v167, v82, s[10:11]
	s_or_b64 exec, exec, s[24:25]
	s_waitcnt vmcnt(35)
	v_pk_fma_f32 v[80:81], v[80:81], 0.5, v[216:217] op_sel_hi:[1,0,1]
	v_pk_fma_f32 v[78:79], v[78:79], 0.5, v[214:215] op_sel_hi:[1,0,1]
	v_pk_fma_f32 v[76:77], v[76:77], 0.5, v[240:241] op_sel_hi:[1,0,1]
	v_pk_fma_f32 v[74:75], v[74:75], 0.5, v[238:239] op_sel_hi:[1,0,1]
	global_store_dwordx4 v157, v[78:81], s[14:15]
	global_store_dwordx4 v157, v[74:77], s[14:15] offset:16
	v_cvt_pk_bf16_f32 v214, v78, v79
	v_cvt_pk_bf16_f32 v215, v80, v81
	v_cvt_pk_bf16_f32 v216, v74, v75
	v_cvt_pk_bf16_f32 v217, v76, v77
	v_lshrrev_b32_e32 v167, 1, v157
	global_store_dwordx4 v167, v[214:217], s[20:21]
	v_mul_f32_e32 v79, v79, v79
	v_mul_f32_e32 v81, v81, v81
	v_mul_f32_e32 v75, v75, v75
	v_mul_f32_e32 v77, v77, v77
	v_fmac_f32_e32 v79, v78, v78
	v_fmac_f32_e32 v81, v80, v80
	v_fmac_f32_e32 v75, v74, v74
	v_fmac_f32_e32 v77, v76, v76
	v_add_f32_e32 v74, v79, v81
	v_add_f32_e32 v75, v75, v77
	v_add_f32_e32 v78, v74, v75
	global_load_dwordx4 v[214:217], v221, s[8:9]
	global_load_dwordx4 v[238:241], v221, s[8:9] offset:16
	s_waitcnt vmcnt(38)
	v_pk_fma_f32 v[72:73], v[72:73], 0.5, v[244:245] op_sel_hi:[1,0,1]
	v_pk_fma_f32 v[70:71], v[70:71], 0.5, v[242:243] op_sel_hi:[1,0,1]
	v_pk_fma_f32 v[68:69], v[68:69], 0.5, v[248:249] op_sel_hi:[1,0,1]
	v_pk_fma_f32 v[66:67], v[66:67], 0.5, v[246:247] op_sel_hi:[1,0,1]
	global_store_dwordx4 v157, v[70:73], s[14:15] offset:512
	global_store_dwordx4 v157, v[66:69], s[14:15] offset:528
	v_cvt_pk_bf16_f32 v242, v70, v71
	v_cvt_pk_bf16_f32 v243, v72, v73
	v_cvt_pk_bf16_f32 v244, v66, v67
	v_cvt_pk_bf16_f32 v245, v68, v69
	global_store_dwordx4 v167, v[242:245], s[20:21] offset:256
	v_mul_f32_e32 v71, v71, v71
	v_mul_f32_e32 v73, v73, v73
	v_mul_f32_e32 v67, v67, v67
	v_mul_f32_e32 v69, v69, v69
	v_fmac_f32_e32 v71, v70, v70
	v_fmac_f32_e32 v73, v72, v72
	v_fmac_f32_e32 v67, v66, v66
	v_fmac_f32_e32 v69, v68, v68
	v_add_f32_e32 v66, v71, v73
	v_add_f32_e32 v67, v67, v69
	v_add_f32_e32 v66, v66, v67
	v_add_f32_e32 v66, v78, v66
	v_lshlrev_b32_e32 v68, 2, v222
	v_xor_b32_e32 v67, 64, v68
	ds_bpermute_b32 v67, v67, v66
	global_load_dwordx4 v[242:245], v221, s[8:9] offset:512
	global_load_dwordx4 v[246:249], v221, s[8:9] offset:528
	v_add_u32_e32 v167, 48, v142
	v_lshl_add_u32 v167, v167, 6, s94
	s_waitcnt lgkmcnt(0)
	v_add_f32_e32 v66, v66, v67
	v_xor_b32_e32 v67, 0x80, v68
	ds_bpermute_b32 v67, v67, v66
	s_and_saveexec_b64 s[24:25], s[2:3]
	s_waitcnt lgkmcnt(0)
	v_add_f32_e32 v66, v66, v67
	global_store_dword v167, v66, s[10:11]
	s_or_b64 exec, exec, s[24:25]
	s_waitcnt vmcnt(39)
	v_pk_fma_f32 v[64:65], v[64:65], 0.5, v[150:151] op_sel_hi:[1,0,1]
	v_pk_fma_f32 v[62:63], v[62:63], 0.5, v[148:149] op_sel_hi:[1,0,1]
	v_pk_fma_f32 v[60:61], v[60:61], 0.5, v[154:155] op_sel_hi:[1,0,1]
	v_pk_fma_f32 v[58:59], v[58:59], 0.5, v[152:153] op_sel_hi:[1,0,1]
	global_store_dwordx4 v202, v[62:65], s[14:15]
	global_store_dwordx4 v202, v[58:61], s[14:15] offset:16
	v_cvt_pk_bf16_f32 v148, v62, v63
	v_cvt_pk_bf16_f32 v149, v64, v65
	v_cvt_pk_bf16_f32 v150, v58, v59
	v_cvt_pk_bf16_f32 v151, v60, v61
	v_lshrrev_b32_e32 v167, 1, v202
	global_store_dwordx4 v167, v[148:151], s[20:21]
	v_mul_f32_e32 v63, v63, v63
	v_mul_f32_e32 v65, v65, v65
	v_mul_f32_e32 v59, v59, v59
	v_mul_f32_e32 v61, v61, v61
	v_fmac_f32_e32 v63, v62, v62
	v_fmac_f32_e32 v65, v64, v64
	v_fmac_f32_e32 v59, v58, v58
	v_fmac_f32_e32 v61, v60, v60
	v_add_f32_e32 v58, v63, v65
	v_add_f32_e32 v59, v59, v61
	v_add_f32_e32 v62, v58, v59
	s_waitcnt vmcnt(37)
	v_pk_fma_f32 v[56:57], v[56:57], 0.5, v[172:173] op_sel_hi:[1,0,1]
	v_pk_fma_f32 v[54:55], v[54:55], 0.5, v[170:171] op_sel_hi:[1,0,1]
	v_pk_fma_f32 v[52:53], v[52:53], 0.5, v[176:177] op_sel_hi:[1,0,1]
	v_pk_fma_f32 v[50:51], v[50:51], 0.5, v[174:175] op_sel_hi:[1,0,1]
	global_store_dwordx4 v202, v[54:57], s[14:15] offset:512
	global_store_dwordx4 v202, v[50:53], s[14:15] offset:528
	v_cvt_pk_bf16_f32 v170, v54, v55
	v_cvt_pk_bf16_f32 v171, v56, v57
	v_cvt_pk_bf16_f32 v172, v50, v51
	v_cvt_pk_bf16_f32 v173, v52, v53
	global_store_dwordx4 v167, v[170:173], s[20:21] offset:256
	v_mul_f32_e32 v55, v55, v55
	v_mul_f32_e32 v57, v57, v57
	v_mul_f32_e32 v51, v51, v51
	v_mul_f32_e32 v53, v53, v53
	v_fmac_f32_e32 v55, v54, v54
	v_fmac_f32_e32 v57, v56, v56
	v_fmac_f32_e32 v51, v50, v50
	v_fmac_f32_e32 v53, v52, v52
	v_add_f32_e32 v50, v55, v57
	v_add_f32_e32 v51, v51, v53
	v_add_f32_e32 v50, v50, v51
	v_add_f32_e32 v50, v62, v50
	v_lshlrev_b32_e32 v52, 2, v222
	v_xor_b32_e32 v51, 64, v52
	ds_bpermute_b32 v51, v51, v50
	v_add_u32_e32 v167, 128, v142
	v_lshl_add_u32 v167, v167, 6, s94
	s_waitcnt lgkmcnt(0)
	v_add_f32_e32 v50, v50, v51
	v_xor_b32_e32 v51, 0x80, v52
	ds_bpermute_b32 v51, v51, v50
	s_and_saveexec_b64 s[24:25], s[2:3]
	s_waitcnt lgkmcnt(0)
	v_add_f32_e32 v50, v50, v51
	global_store_dword v167, v50, s[10:11]
	s_or_b64 exec, exec, s[24:25]
	s_waitcnt vmcnt(35)
	v_pk_fma_f32 v[48:49], v[48:49], 0.5, v[180:181] op_sel_hi:[1,0,1]
	v_pk_fma_f32 v[46:47], v[46:47], 0.5, v[178:179] op_sel_hi:[1,0,1]
	v_pk_fma_f32 v[44:45], v[44:45], 0.5, v[184:185] op_sel_hi:[1,0,1]
	v_pk_fma_f32 v[42:43], v[42:43], 0.5, v[182:183] op_sel_hi:[1,0,1]
	global_store_dwordx4 v203, v[46:49], s[14:15]
	global_store_dwordx4 v203, v[42:45], s[14:15] offset:16
	v_cvt_pk_bf16_f32 v178, v46, v47
	v_cvt_pk_bf16_f32 v179, v48, v49
	v_cvt_pk_bf16_f32 v180, v42, v43
	v_cvt_pk_bf16_f32 v181, v44, v45
	v_lshrrev_b32_e32 v167, 1, v203
	global_store_dwordx4 v167, v[178:181], s[20:21]
	v_mul_f32_e32 v47, v47, v47
	v_mul_f32_e32 v49, v49, v49
	v_mul_f32_e32 v43, v43, v43
	v_mul_f32_e32 v45, v45, v45
	v_fmac_f32_e32 v47, v46, v46
	v_fmac_f32_e32 v49, v48, v48
	v_fmac_f32_e32 v43, v42, v42
	v_fmac_f32_e32 v45, v44, v44
	v_add_f32_e32 v42, v47, v49
	v_add_f32_e32 v43, v43, v45
	v_add_f32_e32 v46, v42, v43
	s_waitcnt vmcnt(33)
	v_pk_fma_f32 v[40:41], v[40:41], 0.5, v[188:189] op_sel_hi:[1,0,1]
	v_pk_fma_f32 v[38:39], v[38:39], 0.5, v[186:187] op_sel_hi:[1,0,1]
	v_pk_fma_f32 v[36:37], v[36:37], 0.5, v[192:193] op_sel_hi:[1,0,1]
	v_pk_fma_f32 v[34:35], v[34:35], 0.5, v[190:191] op_sel_hi:[1,0,1]
	global_store_dwordx4 v203, v[38:41], s[14:15] offset:512
	global_store_dwordx4 v203, v[34:37], s[14:15] offset:528
	v_cvt_pk_bf16_f32 v186, v38, v39
	v_cvt_pk_bf16_f32 v187, v40, v41
	v_cvt_pk_bf16_f32 v188, v34, v35
	v_cvt_pk_bf16_f32 v189, v36, v37
	global_store_dwordx4 v167, v[186:189], s[20:21] offset:256
	v_mul_f32_e32 v39, v39, v39
	v_mul_f32_e32 v41, v41, v41
	v_mul_f32_e32 v35, v35, v35
	v_mul_f32_e32 v37, v37, v37
	v_fmac_f32_e32 v39, v38, v38
	v_fmac_f32_e32 v41, v40, v40
	v_fmac_f32_e32 v35, v34, v34
	v_fmac_f32_e32 v37, v36, v36
	v_add_f32_e32 v34, v39, v41
	v_add_f32_e32 v35, v35, v37
	v_add_f32_e32 v34, v34, v35
	v_add_f32_e32 v34, v46, v34
	v_lshlrev_b32_e32 v36, 2, v222
	v_xor_b32_e32 v35, 64, v36
	ds_bpermute_b32 v35, v35, v34
	v_add_u32_e32 v167, 144, v142
	v_lshl_add_u32 v167, v167, 6, s94
	s_waitcnt lgkmcnt(0)
	v_add_f32_e32 v34, v34, v35
	v_xor_b32_e32 v35, 0x80, v36
	ds_bpermute_b32 v35, v35, v34
	s_and_saveexec_b64 s[24:25], s[2:3]
	s_waitcnt lgkmcnt(0)
	v_add_f32_e32 v34, v34, v35
	global_store_dword v167, v34, s[10:11]
	s_or_b64 exec, exec, s[24:25]
	s_waitcnt vmcnt(31)
	v_pk_fma_f32 v[32:33], v[32:33], 0.5, v[196:197] op_sel_hi:[1,0,1]
	v_pk_fma_f32 v[30:31], v[30:31], 0.5, v[194:195] op_sel_hi:[1,0,1]
	v_pk_fma_f32 v[28:29], v[28:29], 0.5, v[200:201] op_sel_hi:[1,0,1]
	v_pk_fma_f32 v[26:27], v[26:27], 0.5, v[198:199] op_sel_hi:[1,0,1]
	global_store_dwordx4 v220, v[30:33], s[14:15]
	global_store_dwordx4 v220, v[26:29], s[14:15] offset:16
	v_cvt_pk_bf16_f32 v194, v30, v31
	v_cvt_pk_bf16_f32 v195, v32, v33
	v_cvt_pk_bf16_f32 v196, v26, v27
	v_cvt_pk_bf16_f32 v197, v28, v29
	v_lshrrev_b32_e32 v167, 1, v220
	global_store_dwordx4 v167, v[194:197], s[20:21]
	v_mul_f32_e32 v31, v31, v31
	v_mul_f32_e32 v33, v33, v33
	v_mul_f32_e32 v27, v27, v27
	v_mul_f32_e32 v29, v29, v29
	v_fmac_f32_e32 v31, v30, v30
	v_fmac_f32_e32 v33, v32, v32
	v_fmac_f32_e32 v27, v26, v26
	v_fmac_f32_e32 v29, v28, v28
	v_add_f32_e32 v26, v31, v33
	v_add_f32_e32 v27, v27, v29
	v_add_f32_e32 v30, v26, v27
	s_waitcnt vmcnt(29)
	v_pk_fma_f32 v[24:25], v[24:25], 0.5, v[208:209] op_sel_hi:[1,0,1]
	v_pk_fma_f32 v[22:23], v[22:23], 0.5, v[206:207] op_sel_hi:[1,0,1]
	v_pk_fma_f32 v[20:21], v[20:21], 0.5, v[212:213] op_sel_hi:[1,0,1]
	v_pk_fma_f32 v[18:19], v[18:19], 0.5, v[210:211] op_sel_hi:[1,0,1]
	global_store_dwordx4 v220, v[22:25], s[14:15] offset:512
	global_store_dwordx4 v220, v[18:21], s[14:15] offset:528
	v_cvt_pk_bf16_f32 v206, v22, v23
	v_cvt_pk_bf16_f32 v207, v24, v25
	v_cvt_pk_bf16_f32 v208, v18, v19
	v_cvt_pk_bf16_f32 v209, v20, v21
	global_store_dwordx4 v167, v[206:209], s[20:21] offset:256
	v_mul_f32_e32 v23, v23, v23
	v_mul_f32_e32 v25, v25, v25
	v_mul_f32_e32 v19, v19, v19
	v_mul_f32_e32 v21, v21, v21
	v_fmac_f32_e32 v23, v22, v22
	v_fmac_f32_e32 v25, v24, v24
	v_fmac_f32_e32 v19, v18, v18
	v_fmac_f32_e32 v21, v20, v20
	v_add_f32_e32 v18, v23, v25
	v_add_f32_e32 v19, v19, v21
	v_add_f32_e32 v18, v18, v19
	v_add_f32_e32 v18, v30, v18
	v_lshlrev_b32_e32 v20, 2, v222
	v_xor_b32_e32 v19, 64, v20
	ds_bpermute_b32 v19, v19, v18
	v_add_u32_e32 v167, 160, v142
	v_lshl_add_u32 v167, v167, 6, s94
	s_waitcnt lgkmcnt(0)
	v_add_f32_e32 v18, v18, v19
	v_xor_b32_e32 v19, 0x80, v20
	ds_bpermute_b32 v19, v19, v18
	s_and_saveexec_b64 s[24:25], s[2:3]
	s_waitcnt lgkmcnt(0)
	v_add_f32_e32 v18, v18, v19
	global_store_dword v167, v18, s[10:11]
	s_or_b64 exec, exec, s[24:25]
	s_waitcnt vmcnt(27)
	v_pk_fma_f32 v[16:17], v[16:17], 0.5, v[216:217] op_sel_hi:[1,0,1]
	v_pk_fma_f32 v[14:15], v[14:15], 0.5, v[214:215] op_sel_hi:[1,0,1]
	v_pk_fma_f32 v[12:13], v[12:13], 0.5, v[240:241] op_sel_hi:[1,0,1]
	v_pk_fma_f32 v[10:11], v[10:11], 0.5, v[238:239] op_sel_hi:[1,0,1]
	global_store_dwordx4 v221, v[14:17], s[14:15]
	global_store_dwordx4 v221, v[10:13], s[14:15] offset:16
	v_cvt_pk_bf16_f32 v214, v14, v15
	v_cvt_pk_bf16_f32 v215, v16, v17
	v_cvt_pk_bf16_f32 v216, v10, v11
	v_cvt_pk_bf16_f32 v217, v12, v13
	v_lshrrev_b32_e32 v167, 1, v221
	global_store_dwordx4 v167, v[214:217], s[20:21]
	v_mul_f32_e32 v15, v15, v15
	v_mul_f32_e32 v17, v17, v17
	v_mul_f32_e32 v11, v11, v11
	v_mul_f32_e32 v13, v13, v13
	v_fmac_f32_e32 v15, v14, v14
	v_fmac_f32_e32 v17, v16, v16
	v_fmac_f32_e32 v11, v10, v10
	v_fmac_f32_e32 v13, v12, v12
	v_add_f32_e32 v10, v15, v17
	v_add_f32_e32 v11, v11, v13
	v_add_f32_e32 v14, v10, v11
	s_waitcnt vmcnt(25)
	v_pk_fma_f32 v[8:9], v[8:9], 0.5, v[244:245] op_sel_hi:[1,0,1]
	v_pk_fma_f32 v[6:7], v[6:7], 0.5, v[242:243] op_sel_hi:[1,0,1]
	v_pk_fma_f32 v[4:5], v[4:5], 0.5, v[248:249] op_sel_hi:[1,0,1]
	v_pk_fma_f32 v[2:3], v[2:3], 0.5, v[246:247] op_sel_hi:[1,0,1]
	global_store_dwordx4 v221, v[6:9], s[14:15] offset:512
	global_store_dwordx4 v221, v[2:5], s[14:15] offset:528
	v_cvt_pk_bf16_f32 v242, v6, v7
	v_cvt_pk_bf16_f32 v243, v8, v9
	v_cvt_pk_bf16_f32 v244, v2, v3
	v_cvt_pk_bf16_f32 v245, v4, v5
	global_store_dwordx4 v167, v[242:245], s[20:21] offset:256
	v_mul_f32_e32 v7, v7, v7
	v_mul_f32_e32 v9, v9, v9
	v_mul_f32_e32 v3, v3, v3
	v_mul_f32_e32 v5, v5, v5
	v_fmac_f32_e32 v7, v6, v6
	v_fmac_f32_e32 v9, v8, v8
	v_fmac_f32_e32 v3, v2, v2
	v_fmac_f32_e32 v5, v4, v4
	v_add_f32_e32 v2, v7, v9
	v_add_f32_e32 v3, v3, v5
	v_add_f32_e32 v2, v2, v3
	v_add_f32_e32 v2, v14, v2
	v_lshlrev_b32_e32 v4, 2, v222
	v_xor_b32_e32 v3, 64, v4
	ds_bpermute_b32 v3, v3, v2
	v_add_u32_e32 v167, 176, v142
	v_lshl_add_u32 v167, v167, 6, s94
	s_waitcnt lgkmcnt(0)
	v_add_f32_e32 v2, v2, v3
	v_xor_b32_e32 v3, 0x80, v4
	ds_bpermute_b32 v3, v3, v2
	s_and_saveexec_b64 s[24:25], s[2:3]
	s_waitcnt lgkmcnt(0)
	v_add_f32_e32 v2, v2, v3
	global_store_dword v167, v2, s[10:11]
	s_mov_b32 s72, 0xf149f2ca
	s_lshl_b32 s20, s69, 2
	s_ashr_i32 s21, s20, 31
	s_lshl_b32 s94, s57, 2

.LBB0_936:
	s_or_b64 exec, exec, s[0:1]
	v_ashrrev_i32_e32 v7, 31, v6
	v_lshlrev_b64 v[2:3], 14, v[6:7]
	v_lshl_add_u64 v[2:3], v[4:5], 0, v[2:3]
	global_load_dwordx4 v[12:15], v[2:3], off
	global_load_dwordx4 v[16:19], v[2:3], off offset:16
	global_load_dwordx4 v[20:23], v[2:3], off offset:32
	global_load_dwordx4 v[24:27], v[2:3], off offset:48
	s_waitcnt vmcnt(0) lgkmcnt(0)
	v_mov_b32_e32 v2, v13
	v_mov_b32_e32 v3, v14
	v_mov_b32_e32 v13, v15
	v_mov_b32_e32 v14, v17
	v_mov_b32_e32 v15, v18
	v_mov_b32_e32 v17, v19
	v_pk_add_f32 v[2:3], v[2:3], v[12:13]
	v_pk_add_f32 v[12:13], v[14:15], v[16:17]
	v_pk_add_f32 v[2:3], v[2:3], v[2:3] op_sel:[0,1] op_sel_hi:[1,0]
	v_pk_add_f32 v[12:13], v[12:13], v[12:13] op_sel:[0,1] op_sel_hi:[1,0]
	v_add_f32_e32 v18, v20, v21
	v_add_f32_e32 v20, v22, v23
	v_mov_b32_e32 v19, v26
	v_mov_b32_e32 v21, v27
	v_mov_b32_e32 v3, v24
	v_mov_b32_e32 v13, v25
	v_pk_add_f32 v[14:15], v[18:19], v[20:21]
	v_pk_add_f32 v[2:3], v[2:3], v[12:13]
	s_nop 0
	v_pk_add_f32 v[2:3], v[2:3], v[14:15]
	s_nop 0
	v_add_f32_e32 v0, v2, v3
	v_fmamk_f32 v0, v0, 0x3a800000, v218
	v_mul_f32_e32 v2, 0x4f800000, v0
	v_cmp_gt_f32_e32 vcc, s79, v0
	s_nop 1
	v_cndmask_b32_e32 v0, v0, v2, vcc
	v_sqrt_f32_e32 v2, v0
	s_nop 0
	v_add_u32_e32 v3, -1, v2
	v_add_u32_e32 v7, 1, v2
	v_fma_f32 v9, -v3, v2, v0
	v_fma_f32 v11, -v7, v2, v0
	v_cmp_ge_f32_e64 s[0:1], 0, v9
	s_nop 1
	v_cndmask_b32_e64 v2, v2, v3, s[0:1]
	v_cmp_lt_f32_e64 s[0:1], 0, v11
	s_nop 1
	v_cndmask_b32_e64 v2, v2, v7, s[0:1]
	v_mul_f32_e32 v3, 0x37800000, v2
	v_cndmask_b32_e32 v2, v2, v3, vcc
	v_cmp_class_f32_e32 vcc, v0, v205
	s_nop 1
	v_cndmask_b32_e32 v0, v2, v0, vcc
	v_div_scale_f32 v2, s[0:1], v0, v0, 1.0
	v_rcp_f32_e32 v3, v2
	v_div_scale_f32 v7, vcc, 1.0, v0, 1.0
	v_fma_f32 v9, -v2, v3, 1.0
	v_fmac_f32_e32 v3, v9, v3
	v_mul_f32_e32 v9, v7, v3
	v_fma_f32 v11, -v2, v9, v7
	v_fmac_f32_e32 v9, v11, v3
	v_fma_f32 v2, -v2, v9, v7
	v_div_fmas_f32 v2, v2, v3, v9
	v_div_fixup_f32 v0, v2, v0, 1.0

.LBB0_940:
	s_or_b64 exec, exec, s[4:5]
	v_ashrrev_i32_e32 v7, 31, v6
	v_lshlrev_b64 v[2:3], 14, v[6:7]
	v_lshl_add_u64 v[2:3], v[4:5], 0, v[2:3]
	global_load_dwordx4 v[12:15], v[2:3], off
	global_load_dwordx4 v[16:19], v[2:3], off offset:16
	global_load_dwordx4 v[20:23], v[2:3], off offset:32
	global_load_dwordx4 v[24:27], v[2:3], off offset:48
	s_waitcnt vmcnt(0) lgkmcnt(0)
	v_mov_b32_e32 v2, v13
	v_mov_b32_e32 v3, v14
	v_mov_b32_e32 v13, v15
	v_mov_b32_e32 v14, v17
	v_mov_b32_e32 v15, v18
	v_mov_b32_e32 v17, v19
	v_pk_add_f32 v[2:3], v[2:3], v[12:13]
	v_pk_add_f32 v[12:13], v[14:15], v[16:17]
	v_pk_add_f32 v[2:3], v[2:3], v[2:3] op_sel:[0,1] op_sel_hi:[1,0]
	v_pk_add_f32 v[12:13], v[12:13], v[12:13] op_sel:[0,1] op_sel_hi:[1,0]
	v_add_f32_e32 v18, v20, v21
	v_add_f32_e32 v20, v22, v23
	v_mov_b32_e32 v19, v26
	v_mov_b32_e32 v21, v27
	v_mov_b32_e32 v3, v24
	v_mov_b32_e32 v13, v25
	v_pk_add_f32 v[14:15], v[18:19], v[20:21]
	v_pk_add_f32 v[2:3], v[2:3], v[12:13]
	s_nop 0
	v_pk_add_f32 v[2:3], v[2:3], v[14:15]
	s_nop 0
	v_add_f32_e32 v2, v2, v3
	v_fmamk_f32 v2, v2, 0x3a800000, v218
	v_mul_f32_e32 v3, 0x4f800000, v2
	v_cmp_gt_f32_e32 vcc, s79, v2
	s_nop 1
	v_cndmask_b32_e32 v2, v2, v3, vcc
	v_sqrt_f32_e32 v3, v2
	s_nop 0
	v_add_u32_e32 v7, -1, v3
	v_add_u32_e32 v9, 1, v3
	v_fma_f32 v11, -v7, v3, v2
	v_fma_f32 v12, -v9, v3, v2
	v_cmp_ge_f32_e64 s[4:5], 0, v11
	s_nop 1
	v_cndmask_b32_e64 v3, v3, v7, s[4:5]
	v_cmp_lt_f32_e64 s[4:5], 0, v12
	s_nop 1
	v_cndmask_b32_e64 v3, v3, v9, s[4:5]
	v_mul_f32_e32 v7, 0x37800000, v3
	v_cndmask_b32_e32 v3, v3, v7, vcc
	v_cmp_class_f32_e32 vcc, v2, v205
	s_nop 1
	v_cndmask_b32_e32 v2, v3, v2, vcc
	v_div_scale_f32 v3, s[4:5], v2, v2, 1.0
	v_rcp_f32_e32 v7, v3
	v_div_scale_f32 v9, vcc, 1.0, v2, 1.0
	v_fma_f32 v11, -v3, v7, 1.0
	v_fmac_f32_e32 v7, v11, v7
	v_mul_f32_e32 v11, v9, v7
	v_fma_f32 v12, -v3, v11, v9
	v_fmac_f32_e32 v11, v12, v7
	v_fma_f32 v3, -v3, v11, v9
	v_div_fmas_f32 v3, v3, v7, v11
	v_div_fixup_f32 v3, v3, v2, 1.0

.LBB0_944:
	s_or_b64 exec, exec, s[6:7]
	v_ashrrev_i32_e32 v7, 31, v6
	v_lshlrev_b64 v[8:9], 14, v[6:7]
	v_lshl_add_u64 v[8:9], v[4:5], 0, v[8:9]
	global_load_dwordx4 v[12:15], v[8:9], off
	global_load_dwordx4 v[16:19], v[8:9], off offset:16
	global_load_dwordx4 v[20:23], v[8:9], off offset:32
	global_load_dwordx4 v[24:27], v[8:9], off offset:48
	s_waitcnt vmcnt(0) lgkmcnt(0)
	v_mov_b32_e32 v8, v13
	v_mov_b32_e32 v9, v14
	v_mov_b32_e32 v13, v15
	v_mov_b32_e32 v14, v17
	v_mov_b32_e32 v15, v18
	v_mov_b32_e32 v17, v19
	v_pk_add_f32 v[8:9], v[8:9], v[12:13]
	v_pk_add_f32 v[12:13], v[14:15], v[16:17]
	v_pk_add_f32 v[8:9], v[8:9], v[8:9] op_sel:[0,1] op_sel_hi:[1,0]
	v_pk_add_f32 v[12:13], v[12:13], v[12:13] op_sel:[0,1] op_sel_hi:[1,0]
	v_add_f32_e32 v18, v20, v21
	v_add_f32_e32 v20, v22, v23
	v_mov_b32_e32 v19, v26
	v_mov_b32_e32 v21, v27
	v_mov_b32_e32 v9, v24
	v_mov_b32_e32 v13, v25
	v_pk_add_f32 v[14:15], v[18:19], v[20:21]
	v_pk_add_f32 v[8:9], v[8:9], v[12:13]
	s_nop 0
	v_pk_add_f32 v[8:9], v[8:9], v[14:15]
	s_nop 0
	v_add_f32_e32 v2, v8, v9
	v_fmamk_f32 v2, v2, 0x3a800000, v218
	v_mul_f32_e32 v7, 0x4f800000, v2
	v_cmp_gt_f32_e32 vcc, s79, v2
	s_nop 1
	v_cndmask_b32_e32 v2, v2, v7, vcc
	v_sqrt_f32_e32 v7, v2
	s_nop 0
	v_add_u32_e32 v8, -1, v7
	v_add_u32_e32 v9, 1, v7
	v_fma_f32 v11, -v8, v7, v2
	v_fma_f32 v12, -v9, v7, v2
	v_cmp_ge_f32_e64 s[6:7], 0, v11
	s_nop 1
	v_cndmask_b32_e64 v7, v7, v8, s[6:7]
	v_cmp_lt_f32_e64 s[6:7], 0, v12
	s_nop 1
	v_cndmask_b32_e64 v7, v7, v9, s[6:7]
	v_mul_f32_e32 v8, 0x37800000, v7
	v_cndmask_b32_e32 v7, v7, v8, vcc
	v_cmp_class_f32_e32 vcc, v2, v205
	s_nop 1
	v_cndmask_b32_e32 v2, v7, v2, vcc
	v_div_scale_f32 v7, s[6:7], v2, v2, 1.0
	v_rcp_f32_e32 v8, v7
	v_div_scale_f32 v9, vcc, 1.0, v2, 1.0
	v_fma_f32 v11, -v7, v8, 1.0
	v_fmac_f32_e32 v8, v11, v8
	v_mul_f32_e32 v11, v9, v8
	v_fma_f32 v12, -v7, v11, v9
	v_fmac_f32_e32 v11, v12, v8
	v_fma_f32 v7, -v7, v11, v9
	v_div_fmas_f32 v7, v7, v8, v11
	v_div_fixup_f32 v2, v7, v2, 1.0
	s_or_b64 exec, exec, s[8:9]
	s_and_saveexec_b64 s[6:7], s[2:3]
	s_cbranch_execnz .LBB0_948

.LBB0_963:
	v_lshl_add_u32 v148, s66, 10, v145
	ds_read_b32 v154, v148
	s_mov_b32 s20, 0xbfb8aa3b
	v_lshl_or_b32 v150, s9, 7, v144
	v_lshl_add_u32 v147, s8, 8, v142
	v_readlane_b32 s8, v254, 35
	s_waitcnt lgkmcnt(0)
	v_pk_mul_f32 v[126:127], v[126:127], v[154:155] op_sel_hi:[1,0]
	v_pk_mul_f32 v[122:123], v[122:123], v[154:155] op_sel_hi:[1,0]
	v_pk_mul_f32 v[156:157], v[126:127], s[20:21] op_sel_hi:[1,0]
	v_pk_mul_f32 v[124:125], v[124:125], v[154:155] op_sel_hi:[1,0]
	v_exp_f32_e32 v156, v156
	v_exp_f32_e32 v157, v157
	v_pk_mul_f32 v[118:119], v[118:119], v[154:155] op_sel_hi:[1,0]
	v_pk_mul_f32 v[114:115], v[114:115], v[154:155] op_sel_hi:[1,0]
	v_readlane_b32 s9, v254, 36
	v_pk_add_f32 v[156:157], v[156:157], 1.0 op_sel_hi:[1,0]
	v_pk_mul_f32 v[116:117], v[116:117], v[154:155] op_sel_hi:[1,0]
	v_rcp_f32_e32 v156, v156
	v_rcp_f32_e32 v157, v157
	v_ashrrev_i32_e32 v151, 31, v150
	v_mov_b64_e32 v[140:141], s[8:9]
	s_movk_i32 s7, 0x1600
	v_pk_mul_f32 v[126:127], v[126:127], v[156:157]
	v_mad_i64_i32 v[152:153], s[8:9], v147, s7, v[140:141]
	v_pk_mul_f32 v[122:123], v[122:123], v[126:127]
	v_pk_mul_f32 v[126:127], v[128:129], v[154:155] op_sel_hi:[1,0]
	v_cvt_pk_bf16_f32 v122, v122, v123
	s_andn2_b64 vcc, exec, s[2:3]
	v_pk_mul_f32 v[128:129], v[126:127], s[20:21] op_sel_hi:[1,0]
	s_mov_b32 s72, 0xf149f2ca
	v_exp_f32_e32 v128, v128
	v_exp_f32_e32 v129, v129
	s_nop 0
	v_pk_add_f32 v[128:129], v[128:129], 1.0 op_sel_hi:[1,0]
	s_nop 0
	v_rcp_f32_e32 v128, v128
	v_rcp_f32_e32 v129, v129
	s_nop 0
	v_pk_mul_f32 v[126:127], v[126:127], v[128:129]
	s_nop 0
	v_pk_mul_f32 v[124:125], v[124:125], v[126:127]
	s_nop 0
	v_cvt_pk_bf16_f32 v123, v124, v125
	v_pk_mul_f32 v[124:125], v[118:119], s[20:21] op_sel_hi:[1,0]
	s_nop 0
	v_exp_f32_e32 v124, v124
	v_exp_f32_e32 v125, v125
	s_nop 0
	v_pk_add_f32 v[124:125], v[124:125], 1.0 op_sel_hi:[1,0]
	s_nop 0
	v_rcp_f32_e32 v124, v124
	v_rcp_f32_e32 v125, v125
	s_nop 0
	v_pk_mul_f32 v[118:119], v[118:119], v[124:125]
	s_nop 0
	v_pk_mul_f32 v[114:115], v[114:115], v[118:119]
	s_nop 0
	v_cvt_pk_bf16_f32 v124, v114, v115
	v_pk_mul_f32 v[114:115], v[120:121], v[154:155] op_sel_hi:[1,0]
	s_nop 0
	v_pk_mul_f32 v[118:119], v[114:115], s[20:21] op_sel_hi:[1,0]
	s_nop 0
	v_exp_f32_e32 v118, v118
	v_exp_f32_e32 v119, v119
	s_nop 0
	v_pk_add_f32 v[118:119], v[118:119], 1.0 op_sel_hi:[1,0]
	s_nop 0
	v_rcp_f32_e32 v118, v118
	v_rcp_f32_e32 v119, v119
	s_nop 0
	v_pk_mul_f32 v[114:115], v[114:115], v[118:119]
	s_nop 0
	v_pk_mul_f32 v[114:115], v[116:117], v[114:115]
	s_nop 0
	v_cvt_pk_bf16_f32 v125, v114, v115
	v_lshlrev_b64 v[114:115], 1, v[150:151]
	v_lshl_add_u64 v[116:117], v[152:153], 0, v[114:115]
	global_store_dwordx4 v[116:117], v[122:125], off
	ds_read_b32 v118, v148 offset:64
	v_or_b32_e32 v116, 16, v147
	v_mad_i64_i32 v[116:117], s[8:9], v116, s7, v[140:141]
	s_waitcnt lgkmcnt(0)
	v_pk_mul_f32 v[110:111], v[110:111], v[118:119] op_sel_hi:[1,0]
	s_nop 0
	v_pk_mul_f32 v[120:121], v[110:111], s[20:21] op_sel_hi:[1,0]
	v_pk_mul_f32 v[106:107], v[106:107], v[118:119] op_sel_hi:[1,0]
	v_exp_f32_e32 v120, v120
	v_exp_f32_e32 v121, v121
	v_pk_mul_f32 v[108:109], v[108:109], v[118:119] op_sel_hi:[1,0]
	v_pk_mul_f32 v[102:103], v[102:103], v[118:119] op_sel_hi:[1,0]
	v_pk_mul_f32 v[98:99], v[98:99], v[118:119] op_sel_hi:[1,0]
	v_pk_add_f32 v[120:121], v[120:121], 1.0 op_sel_hi:[1,0]
	v_pk_mul_f32 v[100:101], v[100:101], v[118:119] op_sel_hi:[1,0]
	v_rcp_f32_e32 v120, v120
	v_rcp_f32_e32 v121, v121
	s_nop 0
	v_pk_mul_f32 v[110:111], v[110:111], v[120:121]
	s_nop 0
	v_pk_mul_f32 v[106:107], v[106:107], v[110:111]
	v_pk_mul_f32 v[110:111], v[112:113], v[118:119] op_sel_hi:[1,0]
	v_cvt_pk_bf16_f32 v106, v106, v107
	s_nop 0
	v_pk_mul_f32 v[112:113], v[110:111], s[20:21] op_sel_hi:[1,0]
	s_nop 0
	v_exp_f32_e32 v112, v112
	v_exp_f32_e32 v113, v113
	s_nop 0
	v_pk_add_f32 v[112:113], v[112:113], 1.0 op_sel_hi:[1,0]
	s_nop 0
	v_rcp_f32_e32 v112, v112
	v_rcp_f32_e32 v113, v113
	s_nop 0
	v_pk_mul_f32 v[110:111], v[110:111], v[112:113]
	s_nop 0
	v_pk_mul_f32 v[108:109], v[108:109], v[110:111]
	s_nop 0
	v_cvt_pk_bf16_f32 v107, v108, v109
	v_pk_mul_f32 v[108:109], v[102:103], s[20:21] op_sel_hi:[1,0]
	s_nop 0
	v_exp_f32_e32 v108, v108
	v_exp_f32_e32 v109, v109
	s_nop 0
	v_pk_add_f32 v[108:109], v[108:109], 1.0 op_sel_hi:[1,0]
	s_nop 0
	v_rcp_f32_e32 v108, v108
	v_rcp_f32_e32 v109, v109
	s_nop 0
	v_pk_mul_f32 v[102:103], v[102:103], v[108:109]
	s_nop 0
	v_pk_mul_f32 v[98:99], v[98:99], v[102:103]
	s_nop 0
	v_cvt_pk_bf16_f32 v108, v98, v99
	v_pk_mul_f32 v[98:99], v[104:105], v[118:119] op_sel_hi:[1,0]
	s_nop 0
	v_pk_mul_f32 v[102:103], v[98:99], s[20:21] op_sel_hi:[1,0]
	s_nop 0
	v_exp_f32_e32 v102, v102
	v_exp_f32_e32 v103, v103
	s_nop 0
	v_pk_add_f32 v[102:103], v[102:103], 1.0 op_sel_hi:[1,0]
	s_nop 0
	v_rcp_f32_e32 v102, v102
	v_rcp_f32_e32 v103, v103
	s_nop 0
	v_pk_mul_f32 v[98:99], v[98:99], v[102:103]
	s_nop 0
	v_pk_mul_f32 v[98:99], v[100:101], v[98:99]
	s_nop 0
	v_cvt_pk_bf16_f32 v109, v98, v99
	v_lshl_add_u64 v[98:99], v[116:117], 0, v[114:115]
	global_store_dwordx4 v[98:99], v[106:109], off
	ds_read_b32 v100, v148 offset:128
	v_or_b32_e32 v98, 32, v147
	v_mad_i64_i32 v[98:99], s[8:9], v98, s7, v[140:141]
	s_waitcnt lgkmcnt(0)
	v_pk_mul_f32 v[94:95], v[94:95], v[100:101] op_sel_hi:[1,0]
	s_nop 0
	v_pk_mul_f32 v[102:103], v[94:95], s[20:21] op_sel_hi:[1,0]
	v_pk_mul_f32 v[90:91], v[90:91], v[100:101] op_sel_hi:[1,0]
	v_exp_f32_e32 v102, v102
	v_exp_f32_e32 v103, v103
	v_pk_mul_f32 v[92:93], v[92:93], v[100:101] op_sel_hi:[1,0]
	v_pk_mul_f32 v[86:87], v[86:87], v[100:101] op_sel_hi:[1,0]
	v_pk_mul_f32 v[82:83], v[82:83], v[100:101] op_sel_hi:[1,0]
	v_pk_add_f32 v[102:103], v[102:103], 1.0 op_sel_hi:[1,0]
	v_pk_mul_f32 v[84:85], v[84:85], v[100:101] op_sel_hi:[1,0]
	v_rcp_f32_e32 v102, v102
	v_rcp_f32_e32 v103, v103
	s_nop 0
	v_pk_mul_f32 v[94:95], v[94:95], v[102:103]
	s_nop 0
	v_pk_mul_f32 v[90:91], v[90:91], v[94:95]
	v_pk_mul_f32 v[94:95], v[96:97], v[100:101] op_sel_hi:[1,0]
	v_cvt_pk_bf16_f32 v90, v90, v91
	s_nop 0
	v_pk_mul_f32 v[96:97], v[94:95], s[20:21] op_sel_hi:[1,0]
	s_nop 0
	v_exp_f32_e32 v96, v96
	v_exp_f32_e32 v97, v97
	s_nop 0
	v_pk_add_f32 v[96:97], v[96:97], 1.0 op_sel_hi:[1,0]
	s_nop 0
	v_rcp_f32_e32 v96, v96
	v_rcp_f32_e32 v97, v97
	s_nop 0
	v_pk_mul_f32 v[94:95], v[94:95], v[96:97]
	s_nop 0
	v_pk_mul_f32 v[92:93], v[92:93], v[94:95]
	s_nop 0
	v_cvt_pk_bf16_f32 v91, v92, v93
	v_pk_mul_f32 v[92:93], v[86:87], s[20:21] op_sel_hi:[1,0]
	s_nop 0
	v_exp_f32_e32 v92, v92
	v_exp_f32_e32 v93, v93
	s_nop 0
	v_pk_add_f32 v[92:93], v[92:93], 1.0 op_sel_hi:[1,0]
	s_nop 0
	v_rcp_f32_e32 v92, v92
	v_rcp_f32_e32 v93, v93
	s_nop 0
	v_pk_mul_f32 v[86:87], v[86:87], v[92:93]
	s_nop 0
	v_pk_mul_f32 v[82:83], v[82:83], v[86:87]
	s_nop 0
	v_cvt_pk_bf16_f32 v92, v82, v83
	v_pk_mul_f32 v[82:83], v[88:89], v[100:101] op_sel_hi:[1,0]
	s_nop 0
	v_pk_mul_f32 v[86:87], v[82:83], s[20:21] op_sel_hi:[1,0]
	s_nop 0
	v_exp_f32_e32 v86, v86
	v_exp_f32_e32 v87, v87
	s_nop 0
	v_pk_add_f32 v[86:87], v[86:87], 1.0 op_sel_hi:[1,0]
	s_nop 0
	v_rcp_f32_e32 v86, v86
	v_rcp_f32_e32 v87, v87
	s_nop 0
	v_pk_mul_f32 v[82:83], v[82:83], v[86:87]
	s_nop 0
	v_pk_mul_f32 v[82:83], v[84:85], v[82:83]
	s_nop 0
	v_cvt_pk_bf16_f32 v93, v82, v83
	v_lshl_add_u64 v[82:83], v[98:99], 0, v[114:115]
	global_store_dwordx4 v[82:83], v[90:93], off
	ds_read_b32 v84, v148 offset:192
	v_or_b32_e32 v82, 48, v147
	v_mad_i64_i32 v[82:83], s[8:9], v82, s7, v[140:141]
	s_waitcnt lgkmcnt(0)
	v_pk_mul_f32 v[78:79], v[78:79], v[84:85] op_sel_hi:[1,0]
	s_nop 0
	v_pk_mul_f32 v[86:87], v[78:79], s[20:21] op_sel_hi:[1,0]
	v_pk_mul_f32 v[74:75], v[74:75], v[84:85] op_sel_hi:[1,0]
	v_exp_f32_e32 v86, v86
	v_exp_f32_e32 v87, v87
	v_pk_mul_f32 v[76:77], v[76:77], v[84:85] op_sel_hi:[1,0]
	v_pk_mul_f32 v[70:71], v[70:71], v[84:85] op_sel_hi:[1,0]
	v_pk_mul_f32 v[66:67], v[66:67], v[84:85] op_sel_hi:[1,0]
	v_pk_add_f32 v[86:87], v[86:87], 1.0 op_sel_hi:[1,0]
	v_pk_mul_f32 v[68:69], v[68:69], v[84:85] op_sel_hi:[1,0]
	v_rcp_f32_e32 v86, v86
	v_rcp_f32_e32 v87, v87
	s_nop 0
	v_pk_mul_f32 v[78:79], v[78:79], v[86:87]
	s_nop 0
	v_pk_mul_f32 v[74:75], v[74:75], v[78:79]
	v_pk_mul_f32 v[78:79], v[80:81], v[84:85] op_sel_hi:[1,0]
	v_cvt_pk_bf16_f32 v74, v74, v75
	s_nop 0
	v_pk_mul_f32 v[80:81], v[78:79], s[20:21] op_sel_hi:[1,0]
	s_nop 0
	v_exp_f32_e32 v80, v80
	v_exp_f32_e32 v81, v81
	s_nop 0
	v_pk_add_f32 v[80:81], v[80:81], 1.0 op_sel_hi:[1,0]
	s_nop 0
	v_rcp_f32_e32 v80, v80
	v_rcp_f32_e32 v81, v81
	s_nop 0
	v_pk_mul_f32 v[78:79], v[78:79], v[80:81]
	s_nop 0
	v_pk_mul_f32 v[76:77], v[76:77], v[78:79]
	s_nop 0
	v_cvt_pk_bf16_f32 v75, v76, v77
	v_pk_mul_f32 v[76:77], v[70:71], s[20:21] op_sel_hi:[1,0]
	s_nop 0
	v_exp_f32_e32 v76, v76
	v_exp_f32_e32 v77, v77
	s_nop 0
	v_pk_add_f32 v[76:77], v[76:77], 1.0 op_sel_hi:[1,0]
	s_nop 0
	v_rcp_f32_e32 v76, v76
	v_rcp_f32_e32 v77, v77
	s_nop 0
	v_pk_mul_f32 v[70:71], v[70:71], v[76:77]
	s_nop 0
	v_pk_mul_f32 v[66:67], v[66:67], v[70:71]
	s_nop 0
	v_cvt_pk_bf16_f32 v76, v66, v67
	v_pk_mul_f32 v[66:67], v[72:73], v[84:85] op_sel_hi:[1,0]
	s_nop 0
	v_pk_mul_f32 v[70:71], v[66:67], s[20:21] op_sel_hi:[1,0]
	s_nop 0
	v_exp_f32_e32 v70, v70
	v_exp_f32_e32 v71, v71
	s_nop 0
	v_pk_add_f32 v[70:71], v[70:71], 1.0 op_sel_hi:[1,0]
	s_nop 0
	v_rcp_f32_e32 v70, v70
	v_rcp_f32_e32 v71, v71
	s_nop 0
	v_pk_mul_f32 v[66:67], v[66:67], v[70:71]
	s_nop 0
	v_pk_mul_f32 v[66:67], v[68:69], v[66:67]
	s_nop 0
	v_cvt_pk_bf16_f32 v77, v66, v67
	v_lshl_add_u64 v[66:67], v[82:83], 0, v[114:115]
	global_store_dwordx4 v[66:67], v[74:77], off
	ds_read_b32 v68, v148 offset:512
	v_add_u32_e32 v66, 0x80, v147
	v_mad_i64_i32 v[66:67], s[8:9], v66, s7, v[140:141]
	s_waitcnt lgkmcnt(0)
	v_pk_mul_f32 v[62:63], v[62:63], v[68:69] op_sel_hi:[1,0]
	s_nop 0
	v_pk_mul_f32 v[70:71], v[62:63], s[20:21] op_sel_hi:[1,0]
	v_pk_mul_f32 v[58:59], v[58:59], v[68:69] op_sel_hi:[1,0]
	v_exp_f32_e32 v70, v70
	v_exp_f32_e32 v71, v71
	v_pk_mul_f32 v[60:61], v[60:61], v[68:69] op_sel_hi:[1,0]
	v_pk_mul_f32 v[54:55], v[54:55], v[68:69] op_sel_hi:[1,0]
	v_pk_mul_f32 v[50:51], v[50:51], v[68:69] op_sel_hi:[1,0]
	v_pk_add_f32 v[70:71], v[70:71], 1.0 op_sel_hi:[1,0]
	v_pk_mul_f32 v[52:53], v[52:53], v[68:69] op_sel_hi:[1,0]
	v_rcp_f32_e32 v70, v70
	v_rcp_f32_e32 v71, v71
	s_nop 0
	v_pk_mul_f32 v[62:63], v[62:63], v[70:71]
	s_nop 0
	v_pk_mul_f32 v[58:59], v[58:59], v[62:63]
	v_pk_mul_f32 v[62:63], v[64:65], v[68:69] op_sel_hi:[1,0]
	v_cvt_pk_bf16_f32 v58, v58, v59
	s_nop 0
	v_pk_mul_f32 v[64:65], v[62:63], s[20:21] op_sel_hi:[1,0]
	s_nop 0
	v_exp_f32_e32 v64, v64
	v_exp_f32_e32 v65, v65
	s_nop 0
	v_pk_add_f32 v[64:65], v[64:65], 1.0 op_sel_hi:[1,0]
	s_nop 0
	v_rcp_f32_e32 v64, v64
	v_rcp_f32_e32 v65, v65
	s_nop 0
	v_pk_mul_f32 v[62:63], v[62:63], v[64:65]
	s_nop 0
	v_pk_mul_f32 v[60:61], v[60:61], v[62:63]
	s_nop 0
	v_cvt_pk_bf16_f32 v59, v60, v61
	v_pk_mul_f32 v[60:61], v[54:55], s[20:21] op_sel_hi:[1,0]
	s_nop 0
	v_exp_f32_e32 v60, v60
	v_exp_f32_e32 v61, v61
	s_nop 0
	v_pk_add_f32 v[60:61], v[60:61], 1.0 op_sel_hi:[1,0]
	s_nop 0
	v_rcp_f32_e32 v60, v60
	v_rcp_f32_e32 v61, v61
	s_nop 0
	v_pk_mul_f32 v[54:55], v[54:55], v[60:61]
	s_nop 0
	v_pk_mul_f32 v[50:51], v[50:51], v[54:55]
	s_nop 0
	v_cvt_pk_bf16_f32 v60, v50, v51
	v_pk_mul_f32 v[50:51], v[56:57], v[68:69] op_sel_hi:[1,0]
	s_nop 0
	v_pk_mul_f32 v[54:55], v[50:51], s[20:21] op_sel_hi:[1,0]
	s_nop 0
	v_exp_f32_e32 v54, v54
	v_exp_f32_e32 v55, v55
	s_nop 0
	v_pk_add_f32 v[54:55], v[54:55], 1.0 op_sel_hi:[1,0]
	s_nop 0
	v_rcp_f32_e32 v54, v54
	v_rcp_f32_e32 v55, v55
	s_nop 0
	v_pk_mul_f32 v[50:51], v[50:51], v[54:55]
	s_nop 0
	v_pk_mul_f32 v[50:51], v[52:53], v[50:51]
	s_nop 0
	v_cvt_pk_bf16_f32 v61, v50, v51
	v_lshl_add_u64 v[50:51], v[66:67], 0, v[114:115]
	global_store_dwordx4 v[50:51], v[58:61], off
	ds_read_b32 v52, v148 offset:576
	v_add_u32_e32 v50, 0x90, v147
	v_mad_i64_i32 v[50:51], s[8:9], v50, s7, v[140:141]
	s_waitcnt lgkmcnt(0)
	v_pk_mul_f32 v[46:47], v[46:47], v[52:53] op_sel_hi:[1,0]
	s_nop 0
	v_pk_mul_f32 v[54:55], v[46:47], s[20:21] op_sel_hi:[1,0]
	v_pk_mul_f32 v[42:43], v[42:43], v[52:53] op_sel_hi:[1,0]
	v_exp_f32_e32 v54, v54
	v_exp_f32_e32 v55, v55
	v_pk_mul_f32 v[44:45], v[44:45], v[52:53] op_sel_hi:[1,0]
	v_pk_mul_f32 v[38:39], v[38:39], v[52:53] op_sel_hi:[1,0]
	v_pk_mul_f32 v[34:35], v[34:35], v[52:53] op_sel_hi:[1,0]
	v_pk_add_f32 v[54:55], v[54:55], 1.0 op_sel_hi:[1,0]
	v_pk_mul_f32 v[36:37], v[36:37], v[52:53] op_sel_hi:[1,0]
	v_rcp_f32_e32 v54, v54
	v_rcp_f32_e32 v55, v55
	s_nop 0
	v_pk_mul_f32 v[46:47], v[46:47], v[54:55]
	s_nop 0
	v_pk_mul_f32 v[42:43], v[42:43], v[46:47]
	v_pk_mul_f32 v[46:47], v[48:49], v[52:53] op_sel_hi:[1,0]
	v_cvt_pk_bf16_f32 v42, v42, v43
	s_nop 0
	v_pk_mul_f32 v[48:49], v[46:47], s[20:21] op_sel_hi:[1,0]
	s_nop 0
	v_exp_f32_e32 v48, v48
	v_exp_f32_e32 v49, v49
	s_nop 0
	v_pk_add_f32 v[48:49], v[48:49], 1.0 op_sel_hi:[1,0]
	s_nop 0
	v_rcp_f32_e32 v48, v48
	v_rcp_f32_e32 v49, v49
	s_nop 0
	v_pk_mul_f32 v[46:47], v[46:47], v[48:49]
	s_nop 0
	v_pk_mul_f32 v[44:45], v[44:45], v[46:47]
	s_nop 0
	v_cvt_pk_bf16_f32 v43, v44, v45
	v_pk_mul_f32 v[44:45], v[38:39], s[20:21] op_sel_hi:[1,0]
	s_nop 0
	v_exp_f32_e32 v44, v44
	v_exp_f32_e32 v45, v45
	s_nop 0
	v_pk_add_f32 v[44:45], v[44:45], 1.0 op_sel_hi:[1,0]
	s_nop 0
	v_rcp_f32_e32 v44, v44
	v_rcp_f32_e32 v45, v45
	s_nop 0
	v_pk_mul_f32 v[38:39], v[38:39], v[44:45]
	s_nop 0
	v_pk_mul_f32 v[34:35], v[34:35], v[38:39]
	s_nop 0
	v_cvt_pk_bf16_f32 v44, v34, v35
	v_pk_mul_f32 v[34:35], v[40:41], v[52:53] op_sel_hi:[1,0]
	s_nop 0
	v_pk_mul_f32 v[38:39], v[34:35], s[20:21] op_sel_hi:[1,0]
	s_nop 0
	v_exp_f32_e32 v38, v38
	v_exp_f32_e32 v39, v39
	s_nop 0
	v_pk_add_f32 v[38:39], v[38:39], 1.0 op_sel_hi:[1,0]
	s_nop 0
	v_rcp_f32_e32 v38, v38
	v_rcp_f32_e32 v39, v39
	s_nop 0
	v_pk_mul_f32 v[34:35], v[34:35], v[38:39]
	s_nop 0
	v_pk_mul_f32 v[34:35], v[36:37], v[34:35]
	s_nop 0
	v_cvt_pk_bf16_f32 v45, v34, v35
	v_lshl_add_u64 v[34:35], v[50:51], 0, v[114:115]
	global_store_dwordx4 v[34:35], v[42:45], off
	ds_read_b32 v36, v148 offset:640
	v_add_u32_e32 v34, 0xa0, v147
	v_mad_i64_i32 v[34:35], s[8:9], v34, s7, v[140:141]
	s_waitcnt lgkmcnt(0)
	v_pk_mul_f32 v[30:31], v[30:31], v[36:37] op_sel_hi:[1,0]
	s_nop 0
	v_pk_mul_f32 v[38:39], v[30:31], s[20:21] op_sel_hi:[1,0]
	v_pk_mul_f32 v[26:27], v[26:27], v[36:37] op_sel_hi:[1,0]
	v_exp_f32_e32 v38, v38
	v_exp_f32_e32 v39, v39
	v_pk_mul_f32 v[28:29], v[28:29], v[36:37] op_sel_hi:[1,0]
	v_pk_mul_f32 v[22:23], v[22:23], v[36:37] op_sel_hi:[1,0]
	v_pk_mul_f32 v[18:19], v[18:19], v[36:37] op_sel_hi:[1,0]
	v_pk_add_f32 v[38:39], v[38:39], 1.0 op_sel_hi:[1,0]
	v_pk_mul_f32 v[20:21], v[20:21], v[36:37] op_sel_hi:[1,0]
	v_rcp_f32_e32 v38, v38
	v_rcp_f32_e32 v39, v39
	s_nop 0
	v_pk_mul_f32 v[30:31], v[30:31], v[38:39]
	s_nop 0
	v_pk_mul_f32 v[26:27], v[26:27], v[30:31]
	v_pk_mul_f32 v[30:31], v[32:33], v[36:37] op_sel_hi:[1,0]
	v_cvt_pk_bf16_f32 v26, v26, v27
	s_nop 0
	v_pk_mul_f32 v[32:33], v[30:31], s[20:21] op_sel_hi:[1,0]
	s_nop 0
	v_exp_f32_e32 v32, v32
	v_exp_f32_e32 v33, v33
	s_nop 0
	v_pk_add_f32 v[32:33], v[32:33], 1.0 op_sel_hi:[1,0]
	s_nop 0
	v_rcp_f32_e32 v32, v32
	v_rcp_f32_e32 v33, v33
	s_nop 0
	v_pk_mul_f32 v[30:31], v[30:31], v[32:33]
	s_nop 0
	v_pk_mul_f32 v[28:29], v[28:29], v[30:31]
	s_nop 0
	v_cvt_pk_bf16_f32 v27, v28, v29
	v_pk_mul_f32 v[28:29], v[22:23], s[20:21] op_sel_hi:[1,0]
	s_nop 0
	v_exp_f32_e32 v28, v28
	v_exp_f32_e32 v29, v29
	s_nop 0
	v_pk_add_f32 v[28:29], v[28:29], 1.0 op_sel_hi:[1,0]
	s_nop 0
	v_rcp_f32_e32 v28, v28
	v_rcp_f32_e32 v29, v29
	s_nop 0
	v_pk_mul_f32 v[22:23], v[22:23], v[28:29]
	s_nop 0
	v_pk_mul_f32 v[18:19], v[18:19], v[22:23]
	s_nop 0
	v_cvt_pk_bf16_f32 v28, v18, v19
	v_pk_mul_f32 v[18:19], v[24:25], v[36:37] op_sel_hi:[1,0]
	s_nop 0
	v_pk_mul_f32 v[22:23], v[18:19], s[20:21] op_sel_hi:[1,0]
	s_nop 0
	v_exp_f32_e32 v22, v22
	v_exp_f32_e32 v23, v23
	s_nop 0
	v_pk_add_f32 v[22:23], v[22:23], 1.0 op_sel_hi:[1,0]
	s_nop 0
	v_rcp_f32_e32 v22, v22
	v_rcp_f32_e32 v23, v23
	s_nop 0
	v_pk_mul_f32 v[18:19], v[18:19], v[22:23]
	s_nop 0
	v_pk_mul_f32 v[18:19], v[20:21], v[18:19]
	s_nop 0
	v_cvt_pk_bf16_f32 v29, v18, v19
	v_lshl_add_u64 v[18:19], v[34:35], 0, v[114:115]
	global_store_dwordx4 v[18:19], v[26:29], off
	ds_read_b32 v20, v148 offset:704
	v_add_u32_e32 v18, 0xb0, v147
	v_mad_i64_i32 v[18:19], s[8:9], v18, s7, v[140:141]
	s_mov_b64 s[8:9], -1
	s_waitcnt lgkmcnt(0)
	v_pk_mul_f32 v[14:15], v[14:15], v[20:21] op_sel_hi:[1,0]
	v_pk_mul_f32 v[10:11], v[10:11], v[20:21] op_sel_hi:[1,0]
	v_pk_mul_f32 v[22:23], v[14:15], s[20:21] op_sel_hi:[1,0]
	v_pk_mul_f32 v[12:13], v[12:13], v[20:21] op_sel_hi:[1,0]
	v_exp_f32_e32 v22, v22
	v_exp_f32_e32 v23, v23
	v_pk_mul_f32 v[6:7], v[6:7], v[20:21] op_sel_hi:[1,0]
	v_pk_mul_f32 v[2:3], v[2:3], v[20:21] op_sel_hi:[1,0]
	v_pk_mul_f32 v[4:5], v[4:5], v[20:21] op_sel_hi:[1,0]
	v_pk_add_f32 v[22:23], v[22:23], 1.0 op_sel_hi:[1,0]
	s_nop 0
	v_rcp_f32_e32 v22, v22
	v_rcp_f32_e32 v23, v23
	s_nop 0
	v_pk_mul_f32 v[14:15], v[14:15], v[22:23]
	s_nop 0
	v_pk_mul_f32 v[10:11], v[10:11], v[14:15]
	v_pk_mul_f32 v[14:15], v[16:17], v[20:21] op_sel_hi:[1,0]
	v_cvt_pk_bf16_f32 v10, v10, v11
	s_nop 0
	v_pk_mul_f32 v[16:17], v[14:15], s[20:21] op_sel_hi:[1,0]
	s_nop 0
	v_exp_f32_e32 v16, v16
	v_exp_f32_e32 v17, v17
	s_nop 0
	v_pk_add_f32 v[16:17], v[16:17], 1.0 op_sel_hi:[1,0]
	s_nop 0
	v_rcp_f32_e32 v16, v16
	v_rcp_f32_e32 v17, v17
	s_nop 0
	v_pk_mul_f32 v[14:15], v[14:15], v[16:17]
	s_nop 0
	v_pk_mul_f32 v[12:13], v[12:13], v[14:15]
	s_nop 0
	v_cvt_pk_bf16_f32 v11, v12, v13
	v_pk_mul_f32 v[12:13], v[6:7], s[20:21] op_sel_hi:[1,0]
	s_nop 0
	v_exp_f32_e32 v12, v12
	v_exp_f32_e32 v13, v13
	s_nop 0
	v_pk_add_f32 v[12:13], v[12:13], 1.0 op_sel_hi:[1,0]
	s_nop 0
	v_rcp_f32_e32 v12, v12
	v_rcp_f32_e32 v13, v13
	s_nop 0
	v_pk_mul_f32 v[6:7], v[6:7], v[12:13]
	s_nop 0
	v_pk_mul_f32 v[2:3], v[2:3], v[6:7]
	s_nop 0
	v_cvt_pk_bf16_f32 v12, v2, v3
	v_pk_mul_f32 v[2:3], v[8:9], v[20:21] op_sel_hi:[1,0]
	s_nop 0
	v_pk_mul_f32 v[6:7], v[2:3], s[20:21] op_sel_hi:[1,0]
	s_nop 0
	v_exp_f32_e32 v6, v6
	v_exp_f32_e32 v7, v7
	s_nop 0
	v_pk_add_f32 v[6:7], v[6:7], 1.0 op_sel_hi:[1,0]
	s_nop 0
	v_rcp_f32_e32 v6, v6
	v_rcp_f32_e32 v7, v7
	s_nop 0
	v_pk_mul_f32 v[2:3], v[2:3], v[6:7]
	s_nop 0
	v_pk_mul_f32 v[2:3], v[4:5], v[2:3]
	s_nop 0
	v_cvt_pk_bf16_f32 v13, v2, v3
	v_lshl_add_u64 v[2:3], v[18:19], 0, v[114:115]
	global_store_dwordx4 v[2:3], v[10:13], off
	s_cbranch_vccnz .LBB0_956
	s_andn2_b64 vcc, exec, s[0:1]
	s_cbranch_vccnz .LBB0_955
	s_barrier
	s_branch .LBB0_955

.LBB0_996:
	v_lshl_add_u32 v142, s24, 8, v144
	v_lshl_or_b32 v140, s72, 8, v146
	s_lshl_b32 s94, s72, 4
	s_lshl_b32 s26, s65, 2
	s_add_i32 s94, s94, s26
	v_lshlrev_b32_e32 v141, 12, v142
	v_lshl_add_u32 v141, v140, 2, v141
	v_add_u32_e32 v143, 0x10000, v141
	v_add_u32_e32 v156, 0x20000, v141
	v_add_u32_e32 v157, 0x30000, v141
	v_add_u32_e32 v202, 0x80000, v141
	v_add_u32_e32 v203, 0x90000, v141
	v_add_u32_e32 v220, 0xa0000, v141
	v_add_u32_e32 v221, 0xb0000, v141
	global_load_dwordx4 v[148:151], v141, s[14:15]
	global_load_dwordx4 v[152:155], v141, s[14:15] offset:16
	global_load_dwordx4 v[170:173], v141, s[14:15] offset:512
	global_load_dwordx4 v[174:177], v141, s[14:15] offset:528
	global_load_dwordx4 v[178:181], v143, s[14:15]
	global_load_dwordx4 v[182:185], v143, s[14:15] offset:16
	global_load_dwordx4 v[186:189], v143, s[14:15] offset:512
	global_load_dwordx4 v[190:193], v143, s[14:15] offset:528
	global_load_dwordx4 v[194:197], v156, s[14:15]
	global_load_dwordx4 v[198:201], v156, s[14:15] offset:16
	global_load_dwordx4 v[206:209], v156, s[14:15] offset:512
	global_load_dwordx4 v[210:213], v156, s[14:15] offset:528
	global_load_dwordx4 v[214:217], v157, s[14:15]
	global_load_dwordx4 v[238:241], v157, s[14:15] offset:16
	global_load_dwordx4 v[242:245], v157, s[14:15] offset:512
	global_load_dwordx4 v[246:249], v157, s[14:15] offset:528
	s_waitcnt vmcnt(14)
	v_pk_add_f32 v[128:129], v[128:129], v[150:151]
	v_pk_add_f32 v[126:127], v[126:127], v[148:149]
	v_pk_add_f32 v[124:125], v[124:125], v[154:155]
	v_pk_add_f32 v[122:123], v[122:123], v[152:153]
	global_store_dwordx4 v141, v[126:129], s[14:15]
	global_store_dwordx4 v141, v[122:125], s[14:15] offset:16
	v_cvt_pk_bf16_f32 v148, v126, v127
	v_cvt_pk_bf16_f32 v149, v128, v129
	v_cvt_pk_bf16_f32 v150, v122, v123
	v_cvt_pk_bf16_f32 v151, v124, v125
	v_lshrrev_b32_e32 v167, 1, v141
	global_store_dwordx4 v167, v[148:151], s[8:9]
	v_mul_f32_e32 v127, v127, v127
	v_mul_f32_e32 v129, v129, v129
	v_mul_f32_e32 v123, v123, v123
	v_mul_f32_e32 v125, v125, v125
	v_fmac_f32_e32 v127, v126, v126
	v_fmac_f32_e32 v129, v128, v128
	v_fmac_f32_e32 v123, v122, v122
	v_fmac_f32_e32 v125, v124, v124
	v_add_f32_e32 v122, v127, v129
	v_add_f32_e32 v123, v123, v125
	v_add_f32_e32 v126, v122, v123
	global_load_dwordx4 v[148:151], v202, s[14:15]
	global_load_dwordx4 v[152:155], v202, s[14:15] offset:16
	s_waitcnt vmcnt(17)
	v_pk_add_f32 v[120:121], v[120:121], v[172:173]
	v_pk_add_f32 v[118:119], v[118:119], v[170:171]
	v_pk_add_f32 v[116:117], v[116:117], v[176:177]
	v_pk_add_f32 v[114:115], v[114:115], v[174:175]
	global_store_dwordx4 v141, v[118:121], s[14:15] offset:512
	global_store_dwordx4 v141, v[114:117], s[14:15] offset:528
	v_cvt_pk_bf16_f32 v170, v118, v119
	v_cvt_pk_bf16_f32 v171, v120, v121
	v_cvt_pk_bf16_f32 v172, v114, v115
	v_cvt_pk_bf16_f32 v173, v116, v117
	global_store_dwordx4 v167, v[170:173], s[8:9] offset:256
	v_mul_f32_e32 v119, v119, v119
	v_mul_f32_e32 v121, v121, v121
	v_mul_f32_e32 v115, v115, v115
	v_mul_f32_e32 v117, v117, v117
	v_fmac_f32_e32 v119, v118, v118
	v_fmac_f32_e32 v121, v120, v120
	v_fmac_f32_e32 v115, v114, v114
	v_fmac_f32_e32 v117, v116, v116
	v_add_f32_e32 v114, v119, v121
	v_add_f32_e32 v115, v115, v117
	v_add_f32_e32 v114, v114, v115
	v_add_f32_e32 v114, v126, v114
	v_lshlrev_b32_e32 v116, 2, v222
	v_xor_b32_e32 v115, 64, v116
	ds_bpermute_b32 v115, v115, v114
	global_load_dwordx4 v[170:173], v202, s[14:15] offset:512
	global_load_dwordx4 v[174:177], v202, s[14:15] offset:528
	v_add_u32_e32 v167, 0, v142
	v_lshl_add_u32 v167, v167, 6, s94
	s_waitcnt lgkmcnt(0)
	v_add_f32_e32 v114, v114, v115
	v_xor_b32_e32 v115, 0x80, v116
	ds_bpermute_b32 v115, v115, v114
	s_and_saveexec_b64 s[26:27], s[2:3]
	s_waitcnt lgkmcnt(0)
	v_add_f32_e32 v114, v114, v115
	global_store_dword v167, v114, s[10:11]
	s_or_b64 exec, exec, s[26:27]
	s_waitcnt vmcnt(21)
	v_pk_add_f32 v[112:113], v[112:113], v[180:181]
	v_pk_add_f32 v[110:111], v[110:111], v[178:179]
	v_pk_add_f32 v[108:109], v[108:109], v[184:185]
	v_pk_add_f32 v[106:107], v[106:107], v[182:183]
	global_store_dwordx4 v143, v[110:113], s[14:15]
	global_store_dwordx4 v143, v[106:109], s[14:15] offset:16
	v_cvt_pk_bf16_f32 v178, v110, v111
	v_cvt_pk_bf16_f32 v179, v112, v113
	v_cvt_pk_bf16_f32 v180, v106, v107
	v_cvt_pk_bf16_f32 v181, v108, v109
	v_lshrrev_b32_e32 v167, 1, v143
	global_store_dwordx4 v167, v[178:181], s[8:9]
	v_mul_f32_e32 v111, v111, v111
	v_mul_f32_e32 v113, v113, v113
	v_mul_f32_e32 v107, v107, v107
	v_mul_f32_e32 v109, v109, v109
	v_fmac_f32_e32 v111, v110, v110
	v_fmac_f32_e32 v113, v112, v112
	v_fmac_f32_e32 v107, v106, v106
	v_fmac_f32_e32 v109, v108, v108
	v_add_f32_e32 v106, v111, v113
	v_add_f32_e32 v107, v107, v109
	v_add_f32_e32 v110, v106, v107
	global_load_dwordx4 v[178:181], v203, s[14:15]
	global_load_dwordx4 v[182:185], v203, s[14:15] offset:16
	s_waitcnt vmcnt(24)
	v_pk_add_f32 v[104:105], v[104:105], v[188:189]
	v_pk_add_f32 v[102:103], v[102:103], v[186:187]
	v_pk_add_f32 v[100:101], v[100:101], v[192:193]
	v_pk_add_f32 v[98:99], v[98:99], v[190:191]
	global_store_dwordx4 v143, v[102:105], s[14:15] offset:512
	global_store_dwordx4 v143, v[98:101], s[14:15] offset:528
	v_cvt_pk_bf16_f32 v186, v102, v103
	v_cvt_pk_bf16_f32 v187, v104, v105
	v_cvt_pk_bf16_f32 v188, v98, v99
	v_cvt_pk_bf16_f32 v189, v100, v101
	global_store_dwordx4 v167, v[186:189], s[8:9] offset:256
	v_mul_f32_e32 v103, v103, v103
	v_mul_f32_e32 v105, v105, v105
	v_mul_f32_e32 v99, v99, v99
	v_mul_f32_e32 v101, v101, v101
	v_fmac_f32_e32 v103, v102, v102
	v_fmac_f32_e32 v105, v104, v104
	v_fmac_f32_e32 v99, v98, v98
	v_fmac_f32_e32 v101, v100, v100
	v_add_f32_e32 v98, v103, v105
	v_add_f32_e32 v99, v99, v101
	v_add_f32_e32 v98, v98, v99
	v_add_f32_e32 v98, v110, v98
	v_lshlrev_b32_e32 v100, 2, v222
	v_xor_b32_e32 v99, 64, v100
	ds_bpermute_b32 v99, v99, v98
	global_load_dwordx4 v[186:189], v203, s[14:15] offset:512
	global_load_dwordx4 v[190:193], v203, s[14:15] offset:528
	v_add_u32_e32 v167, 16, v142
	v_lshl_add_u32 v167, v167, 6, s94
	s_waitcnt lgkmcnt(0)
	v_add_f32_e32 v98, v98, v99
	v_xor_b32_e32 v99, 0x80, v100
	ds_bpermute_b32 v99, v99, v98
	s_and_saveexec_b64 s[26:27], s[2:3]
	s_waitcnt lgkmcnt(0)
	v_add_f32_e32 v98, v98, v99
	global_store_dword v167, v98, s[10:11]
	s_or_b64 exec, exec, s[26:27]
	s_waitcnt vmcnt(28)
	v_pk_add_f32 v[96:97], v[96:97], v[196:197]
	v_pk_add_f32 v[94:95], v[94:95], v[194:195]
	v_pk_add_f32 v[92:93], v[92:93], v[200:201]
	v_pk_add_f32 v[90:91], v[90:91], v[198:199]
	global_store_dwordx4 v156, v[94:97], s[14:15]
	global_store_dwordx4 v156, v[90:93], s[14:15] offset:16
	v_cvt_pk_bf16_f32 v194, v94, v95
	v_cvt_pk_bf16_f32 v195, v96, v97
	v_cvt_pk_bf16_f32 v196, v90, v91
	v_cvt_pk_bf16_f32 v197, v92, v93
	v_lshrrev_b32_e32 v167, 1, v156
	global_store_dwordx4 v167, v[194:197], s[8:9]
	v_mul_f32_e32 v95, v95, v95
	v_mul_f32_e32 v97, v97, v97
	v_mul_f32_e32 v91, v91, v91
	v_mul_f32_e32 v93, v93, v93
	v_fmac_f32_e32 v95, v94, v94
	v_fmac_f32_e32 v97, v96, v96
	v_fmac_f32_e32 v91, v90, v90
	v_fmac_f32_e32 v93, v92, v92
	v_add_f32_e32 v90, v95, v97
	v_add_f32_e32 v91, v91, v93
	v_add_f32_e32 v94, v90, v91
	global_load_dwordx4 v[194:197], v220, s[14:15]
	global_load_dwordx4 v[198:201], v220, s[14:15] offset:16
	s_waitcnt vmcnt(31)
	v_pk_add_f32 v[88:89], v[88:89], v[208:209]
	v_pk_add_f32 v[86:87], v[86:87], v[206:207]
	v_pk_add_f32 v[84:85], v[84:85], v[212:213]
	v_pk_add_f32 v[82:83], v[82:83], v[210:211]
	global_store_dwordx4 v156, v[86:89], s[14:15] offset:512
	global_store_dwordx4 v156, v[82:85], s[14:15] offset:528
	v_cvt_pk_bf16_f32 v206, v86, v87
	v_cvt_pk_bf16_f32 v207, v88, v89
	v_cvt_pk_bf16_f32 v208, v82, v83
	v_cvt_pk_bf16_f32 v209, v84, v85
	global_store_dwordx4 v167, v[206:209], s[8:9] offset:256
	v_mul_f32_e32 v87, v87, v87
	v_mul_f32_e32 v89, v89, v89
	v_mul_f32_e32 v83, v83, v83
	v_mul_f32_e32 v85, v85, v85
	v_fmac_f32_e32 v87, v86, v86
	v_fmac_f32_e32 v89, v88, v88
	v_fmac_f32_e32 v83, v82, v82
	v_fmac_f32_e32 v85, v84, v84
	v_add_f32_e32 v82, v87, v89
	v_add_f32_e32 v83, v83, v85
	v_add_f32_e32 v82, v82, v83
	v_add_f32_e32 v82, v94, v82
	v_lshlrev_b32_e32 v84, 2, v222
	v_xor_b32_e32 v83, 64, v84
	ds_bpermute_b32 v83, v83, v82
	global_load_dwordx4 v[206:209], v220, s[14:15] offset:512
	global_load_dwordx4 v[210:213], v220, s[14:15] offset:528
	v_add_u32_e32 v167, 32, v142
	v_lshl_add_u32 v167, v167, 6, s94
	s_waitcnt lgkmcnt(0)
	v_add_f32_e32 v82, v82, v83
	v_xor_b32_e32 v83, 0x80, v84
	ds_bpermute_b32 v83, v83, v82
	s_and_saveexec_b64 s[26:27], s[2:3]
	s_waitcnt lgkmcnt(0)
	v_add_f32_e32 v82, v82, v83
	global_store_dword v167, v82, s[10:11]
	s_or_b64 exec, exec, s[26:27]
	s_waitcnt vmcnt(35)
	v_pk_add_f32 v[80:81], v[80:81], v[216:217]
	v_pk_add_f32 v[78:79], v[78:79], v[214:215]
	v_pk_add_f32 v[76:77], v[76:77], v[240:241]
	v_pk_add_f32 v[74:75], v[74:75], v[238:239]
	global_store_dwordx4 v157, v[78:81], s[14:15]
	global_store_dwordx4 v157, v[74:77], s[14:15] offset:16
	v_cvt_pk_bf16_f32 v214, v78, v79
	v_cvt_pk_bf16_f32 v215, v80, v81
	v_cvt_pk_bf16_f32 v216, v74, v75
	v_cvt_pk_bf16_f32 v217, v76, v77
	v_lshrrev_b32_e32 v167, 1, v157
	global_store_dwordx4 v167, v[214:217], s[8:9]
	v_mul_f32_e32 v79, v79, v79
	v_mul_f32_e32 v81, v81, v81
	v_mul_f32_e32 v75, v75, v75
	v_mul_f32_e32 v77, v77, v77
	v_fmac_f32_e32 v79, v78, v78
	v_fmac_f32_e32 v81, v80, v80
	v_fmac_f32_e32 v75, v74, v74
	v_fmac_f32_e32 v77, v76, v76
	v_add_f32_e32 v74, v79, v81
	v_add_f32_e32 v75, v75, v77
	v_add_f32_e32 v78, v74, v75
	global_load_dwordx4 v[214:217], v221, s[14:15]
	global_load_dwordx4 v[238:241], v221, s[14:15] offset:16
	s_waitcnt vmcnt(38)
	v_pk_add_f32 v[72:73], v[72:73], v[244:245]
	v_pk_add_f32 v[70:71], v[70:71], v[242:243]
	v_pk_add_f32 v[68:69], v[68:69], v[248:249]
	v_pk_add_f32 v[66:67], v[66:67], v[246:247]
	global_store_dwordx4 v157, v[70:73], s[14:15] offset:512
	global_store_dwordx4 v157, v[66:69], s[14:15] offset:528
	v_cvt_pk_bf16_f32 v242, v70, v71
	v_cvt_pk_bf16_f32 v243, v72, v73
	v_cvt_pk_bf16_f32 v244, v66, v67
	v_cvt_pk_bf16_f32 v245, v68, v69
	global_store_dwordx4 v167, v[242:245], s[8:9] offset:256
	v_mul_f32_e32 v71, v71, v71
	v_mul_f32_e32 v73, v73, v73
	v_mul_f32_e32 v67, v67, v67
	v_mul_f32_e32 v69, v69, v69
	v_fmac_f32_e32 v71, v70, v70
	v_fmac_f32_e32 v73, v72, v72
	v_fmac_f32_e32 v67, v66, v66
	v_fmac_f32_e32 v69, v68, v68
	v_add_f32_e32 v66, v71, v73
	v_add_f32_e32 v67, v67, v69
	v_add_f32_e32 v66, v66, v67
	v_add_f32_e32 v66, v78, v66
	v_lshlrev_b32_e32 v68, 2, v222
	v_xor_b32_e32 v67, 64, v68
	ds_bpermute_b32 v67, v67, v66
	global_load_dwordx4 v[242:245], v221, s[14:15] offset:512
	global_load_dwordx4 v[246:249], v221, s[14:15] offset:528
	v_add_u32_e32 v167, 48, v142
	v_lshl_add_u32 v167, v167, 6, s94
	s_waitcnt lgkmcnt(0)
	v_add_f32_e32 v66, v66, v67
	v_xor_b32_e32 v67, 0x80, v68
	ds_bpermute_b32 v67, v67, v66
	s_and_saveexec_b64 s[26:27], s[2:3]
	s_waitcnt lgkmcnt(0)
	v_add_f32_e32 v66, v66, v67
	global_store_dword v167, v66, s[10:11]
	s_or_b64 exec, exec, s[26:27]
	s_waitcnt vmcnt(39)
	v_pk_add_f32 v[64:65], v[64:65], v[150:151]
	v_pk_add_f32 v[62:63], v[62:63], v[148:149]
	v_pk_add_f32 v[60:61], v[60:61], v[154:155]
	v_pk_add_f32 v[58:59], v[58:59], v[152:153]
	global_store_dwordx4 v202, v[62:65], s[14:15]
	global_store_dwordx4 v202, v[58:61], s[14:15] offset:16
	v_cvt_pk_bf16_f32 v148, v62, v63
	v_cvt_pk_bf16_f32 v149, v64, v65
	v_cvt_pk_bf16_f32 v150, v58, v59
	v_cvt_pk_bf16_f32 v151, v60, v61
	v_lshrrev_b32_e32 v167, 1, v202
	global_store_dwordx4 v167, v[148:151], s[8:9]
	v_mul_f32_e32 v63, v63, v63
	v_mul_f32_e32 v65, v65, v65
	v_mul_f32_e32 v59, v59, v59
	v_mul_f32_e32 v61, v61, v61
	v_fmac_f32_e32 v63, v62, v62
	v_fmac_f32_e32 v65, v64, v64
	v_fmac_f32_e32 v59, v58, v58
	v_fmac_f32_e32 v61, v60, v60
	v_add_f32_e32 v58, v63, v65
	v_add_f32_e32 v59, v59, v61
	v_add_f32_e32 v62, v58, v59
	s_waitcnt vmcnt(37)
	v_pk_add_f32 v[56:57], v[56:57], v[172:173]
	v_pk_add_f32 v[54:55], v[54:55], v[170:171]
	v_pk_add_f32 v[52:53], v[52:53], v[176:177]
	v_pk_add_f32 v[50:51], v[50:51], v[174:175]
	global_store_dwordx4 v202, v[54:57], s[14:15] offset:512
	global_store_dwordx4 v202, v[50:53], s[14:15] offset:528
	v_cvt_pk_bf16_f32 v170, v54, v55
	v_cvt_pk_bf16_f32 v171, v56, v57
	v_cvt_pk_bf16_f32 v172, v50, v51
	v_cvt_pk_bf16_f32 v173, v52, v53
	global_store_dwordx4 v167, v[170:173], s[8:9] offset:256
	v_mul_f32_e32 v55, v55, v55
	v_mul_f32_e32 v57, v57, v57
	v_mul_f32_e32 v51, v51, v51
	v_mul_f32_e32 v53, v53, v53
	v_fmac_f32_e32 v55, v54, v54
	v_fmac_f32_e32 v57, v56, v56
	v_fmac_f32_e32 v51, v50, v50
	v_fmac_f32_e32 v53, v52, v52
	v_add_f32_e32 v50, v55, v57
	v_add_f32_e32 v51, v51, v53
	v_add_f32_e32 v50, v50, v51
	v_add_f32_e32 v50, v62, v50
	v_lshlrev_b32_e32 v52, 2, v222
	v_xor_b32_e32 v51, 64, v52
	ds_bpermute_b32 v51, v51, v50
	v_add_u32_e32 v167, 128, v142
	v_lshl_add_u32 v167, v167, 6, s94
	s_waitcnt lgkmcnt(0)
	v_add_f32_e32 v50, v50, v51
	v_xor_b32_e32 v51, 0x80, v52
	ds_bpermute_b32 v51, v51, v50
	s_and_saveexec_b64 s[26:27], s[2:3]
	s_waitcnt lgkmcnt(0)
	v_add_f32_e32 v50, v50, v51
	global_store_dword v167, v50, s[10:11]
	s_or_b64 exec, exec, s[26:27]
	s_waitcnt vmcnt(35)
	v_pk_add_f32 v[48:49], v[48:49], v[180:181]
	v_pk_add_f32 v[46:47], v[46:47], v[178:179]
	v_pk_add_f32 v[44:45], v[44:45], v[184:185]
	v_pk_add_f32 v[42:43], v[42:43], v[182:183]
	global_store_dwordx4 v203, v[46:49], s[14:15]
	global_store_dwordx4 v203, v[42:45], s[14:15] offset:16
	v_cvt_pk_bf16_f32 v178, v46, v47
	v_cvt_pk_bf16_f32 v179, v48, v49
	v_cvt_pk_bf16_f32 v180, v42, v43
	v_cvt_pk_bf16_f32 v181, v44, v45
	v_lshrrev_b32_e32 v167, 1, v203
	global_store_dwordx4 v167, v[178:181], s[8:9]
	v_mul_f32_e32 v47, v47, v47
	v_mul_f32_e32 v49, v49, v49
	v_mul_f32_e32 v43, v43, v43
	v_mul_f32_e32 v45, v45, v45
	v_fmac_f32_e32 v47, v46, v46
	v_fmac_f32_e32 v49, v48, v48
	v_fmac_f32_e32 v43, v42, v42
	v_fmac_f32_e32 v45, v44, v44
	v_add_f32_e32 v42, v47, v49
	v_add_f32_e32 v43, v43, v45
	v_add_f32_e32 v46, v42, v43
	s_waitcnt vmcnt(33)
	v_pk_add_f32 v[40:41], v[40:41], v[188:189]
	v_pk_add_f32 v[38:39], v[38:39], v[186:187]
	v_pk_add_f32 v[36:37], v[36:37], v[192:193]
	v_pk_add_f32 v[34:35], v[34:35], v[190:191]
	global_store_dwordx4 v203, v[38:41], s[14:15] offset:512
	global_store_dwordx4 v203, v[34:37], s[14:15] offset:528
	v_cvt_pk_bf16_f32 v186, v38, v39
	v_cvt_pk_bf16_f32 v187, v40, v41
	v_cvt_pk_bf16_f32 v188, v34, v35
	v_cvt_pk_bf16_f32 v189, v36, v37
	global_store_dwordx4 v167, v[186:189], s[8:9] offset:256
	v_mul_f32_e32 v39, v39, v39
	v_mul_f32_e32 v41, v41, v41
	v_mul_f32_e32 v35, v35, v35
	v_mul_f32_e32 v37, v37, v37
	v_fmac_f32_e32 v39, v38, v38
	v_fmac_f32_e32 v41, v40, v40
	v_fmac_f32_e32 v35, v34, v34
	v_fmac_f32_e32 v37, v36, v36
	v_add_f32_e32 v34, v39, v41
	v_add_f32_e32 v35, v35, v37
	v_add_f32_e32 v34, v34, v35
	v_add_f32_e32 v34, v46, v34
	v_lshlrev_b32_e32 v36, 2, v222
	v_xor_b32_e32 v35, 64, v36
	ds_bpermute_b32 v35, v35, v34
	v_add_u32_e32 v167, 144, v142
	v_lshl_add_u32 v167, v167, 6, s94
	s_waitcnt lgkmcnt(0)
	v_add_f32_e32 v34, v34, v35
	v_xor_b32_e32 v35, 0x80, v36
	ds_bpermute_b32 v35, v35, v34
	s_and_saveexec_b64 s[26:27], s[2:3]
	s_waitcnt lgkmcnt(0)
	v_add_f32_e32 v34, v34, v35
	global_store_dword v167, v34, s[10:11]
	s_or_b64 exec, exec, s[26:27]
	s_waitcnt vmcnt(31)
	v_pk_add_f32 v[32:33], v[32:33], v[196:197]
	v_pk_add_f32 v[30:31], v[30:31], v[194:195]
	v_pk_add_f32 v[28:29], v[28:29], v[200:201]
	v_pk_add_f32 v[26:27], v[26:27], v[198:199]
	global_store_dwordx4 v220, v[30:33], s[14:15]
	global_store_dwordx4 v220, v[26:29], s[14:15] offset:16
	v_cvt_pk_bf16_f32 v194, v30, v31
	v_cvt_pk_bf16_f32 v195, v32, v33
	v_cvt_pk_bf16_f32 v196, v26, v27
	v_cvt_pk_bf16_f32 v197, v28, v29
	v_lshrrev_b32_e32 v167, 1, v220
	global_store_dwordx4 v167, v[194:197], s[8:9]
	v_mul_f32_e32 v31, v31, v31
	v_mul_f32_e32 v33, v33, v33
	v_mul_f32_e32 v27, v27, v27
	v_mul_f32_e32 v29, v29, v29
	v_fmac_f32_e32 v31, v30, v30
	v_fmac_f32_e32 v33, v32, v32
	v_fmac_f32_e32 v27, v26, v26
	v_fmac_f32_e32 v29, v28, v28
	v_add_f32_e32 v26, v31, v33
	v_add_f32_e32 v27, v27, v29
	v_add_f32_e32 v30, v26, v27
	s_waitcnt vmcnt(29)
	v_pk_add_f32 v[24:25], v[24:25], v[208:209]
	v_pk_add_f32 v[22:23], v[22:23], v[206:207]
	v_pk_add_f32 v[20:21], v[20:21], v[212:213]
	v_pk_add_f32 v[18:19], v[18:19], v[210:211]
	global_store_dwordx4 v220, v[22:25], s[14:15] offset:512
	global_store_dwordx4 v220, v[18:21], s[14:15] offset:528
	v_cvt_pk_bf16_f32 v206, v22, v23
	v_cvt_pk_bf16_f32 v207, v24, v25
	v_cvt_pk_bf16_f32 v208, v18, v19
	v_cvt_pk_bf16_f32 v209, v20, v21
	global_store_dwordx4 v167, v[206:209], s[8:9] offset:256
	v_mul_f32_e32 v23, v23, v23
	v_mul_f32_e32 v25, v25, v25
	v_mul_f32_e32 v19, v19, v19
	v_mul_f32_e32 v21, v21, v21
	v_fmac_f32_e32 v23, v22, v22
	v_fmac_f32_e32 v25, v24, v24
	v_fmac_f32_e32 v19, v18, v18
	v_fmac_f32_e32 v21, v20, v20
	v_add_f32_e32 v18, v23, v25
	v_add_f32_e32 v19, v19, v21
	v_add_f32_e32 v18, v18, v19
	v_add_f32_e32 v18, v30, v18
	v_lshlrev_b32_e32 v20, 2, v222
	v_xor_b32_e32 v19, 64, v20
	ds_bpermute_b32 v19, v19, v18
	v_add_u32_e32 v167, 160, v142
	v_lshl_add_u32 v167, v167, 6, s94
	s_waitcnt lgkmcnt(0)
	v_add_f32_e32 v18, v18, v19
	v_xor_b32_e32 v19, 0x80, v20
	ds_bpermute_b32 v19, v19, v18
	s_and_saveexec_b64 s[26:27], s[2:3]
	s_waitcnt lgkmcnt(0)
	v_add_f32_e32 v18, v18, v19
	global_store_dword v167, v18, s[10:11]
	s_or_b64 exec, exec, s[26:27]
	s_waitcnt vmcnt(27)
	v_pk_add_f32 v[16:17], v[16:17], v[216:217]
	v_pk_add_f32 v[14:15], v[14:15], v[214:215]
	v_pk_add_f32 v[12:13], v[12:13], v[240:241]
	v_pk_add_f32 v[10:11], v[10:11], v[238:239]
	global_store_dwordx4 v221, v[14:17], s[14:15]
	global_store_dwordx4 v221, v[10:13], s[14:15] offset:16
	v_cvt_pk_bf16_f32 v214, v14, v15
	v_cvt_pk_bf16_f32 v215, v16, v17
	v_cvt_pk_bf16_f32 v216, v10, v11
	v_cvt_pk_bf16_f32 v217, v12, v13
	v_lshrrev_b32_e32 v167, 1, v221
	global_store_dwordx4 v167, v[214:217], s[8:9]
	v_mul_f32_e32 v15, v15, v15
	v_mul_f32_e32 v17, v17, v17
	v_mul_f32_e32 v11, v11, v11
	v_mul_f32_e32 v13, v13, v13
	v_fmac_f32_e32 v15, v14, v14
	v_fmac_f32_e32 v17, v16, v16
	v_fmac_f32_e32 v11, v10, v10
	v_fmac_f32_e32 v13, v12, v12
	v_add_f32_e32 v10, v15, v17
	v_add_f32_e32 v11, v11, v13
	v_add_f32_e32 v14, v10, v11
	s_waitcnt vmcnt(25)
	v_pk_add_f32 v[8:9], v[8:9], v[244:245]
	v_pk_add_f32 v[6:7], v[6:7], v[242:243]
	v_pk_add_f32 v[4:5], v[4:5], v[248:249]
	v_pk_add_f32 v[2:3], v[2:3], v[246:247]
	global_store_dwordx4 v221, v[6:9], s[14:15] offset:512
	global_store_dwordx4 v221, v[2:5], s[14:15] offset:528
	v_cvt_pk_bf16_f32 v242, v6, v7
	v_cvt_pk_bf16_f32 v243, v8, v9
	v_cvt_pk_bf16_f32 v244, v2, v3
	v_cvt_pk_bf16_f32 v245, v4, v5
	global_store_dwordx4 v167, v[242:245], s[8:9] offset:256
	v_mul_f32_e32 v7, v7, v7
	v_mul_f32_e32 v9, v9, v9
	v_mul_f32_e32 v3, v3, v3
	v_mul_f32_e32 v5, v5, v5
	v_fmac_f32_e32 v7, v6, v6
	v_fmac_f32_e32 v9, v8, v8
	v_fmac_f32_e32 v3, v2, v2
	v_fmac_f32_e32 v5, v4, v4
	v_add_f32_e32 v2, v7, v9
	v_add_f32_e32 v3, v3, v5
	v_add_f32_e32 v2, v2, v3
	v_add_f32_e32 v2, v14, v2
	v_lshlrev_b32_e32 v4, 2, v222
	v_xor_b32_e32 v3, 64, v4
	ds_bpermute_b32 v3, v3, v2
	v_add_u32_e32 v167, 176, v142
	v_lshl_add_u32 v167, v167, 6, s94
	s_waitcnt lgkmcnt(0)
	v_add_f32_e32 v2, v2, v3
	v_xor_b32_e32 v3, 0x80, v4
	ds_bpermute_b32 v3, v3, v2
	s_and_saveexec_b64 s[26:27], s[2:3]
	s_waitcnt lgkmcnt(0)
	v_add_f32_e32 v2, v2, v3
	global_store_dword v167, v2, s[10:11]
	s_lshl_b32 s24, s72, 2
	s_ashr_i32 s25, s24, 31
	s_lshl_b32 s94, s65, 2

.LBB0_1055:
	ds_read_b32 v0, v91
	ds_read_b32 v6, v91 offset:132
	ds_read_b32 v7, v91 offset:264
	ds_read_b32 v8, v91 offset:396
	ds_read_b32 v9, v91 offset:528
	ds_read_b32 v10, v91 offset:660
	ds_read_b32 v11, v91 offset:792
	ds_read_b32 v12, v91 offset:924
	s_waitcnt lgkmcnt(0)
	v_bfe_u32 v13, v0, 16, 1
	v_add3_u32 v0, v0, v13, s33
	v_bfe_u32 v13, v6, 16, 1
	v_lshrrev_b32_e32 v0, 16, v0
	v_add3_u32 v6, v6, v13, s33
	v_and_or_b32 v6, v6, s37, v0
	v_bfe_u32 v0, v7, 16, 1
	v_add3_u32 v0, v7, v0, s33
	v_bfe_u32 v7, v8, 16, 1
	v_lshrrev_b32_e32 v0, 16, v0
	v_add3_u32 v7, v8, v7, s33
	v_and_or_b32 v7, v7, s37, v0
	v_bfe_u32 v0, v9, 16, 1
	v_add3_u32 v0, v9, v0, s33
	v_bfe_u32 v8, v10, 16, 1
	v_lshrrev_b32_e32 v0, 16, v0
	v_add3_u32 v8, v10, v8, s33
	v_and_or_b32 v8, v8, s37, v0
	v_bfe_u32 v0, v11, 16, 1
	v_add3_u32 v0, v11, v0, s33
	v_bfe_u32 v9, v12, 16, 1
	v_lshrrev_b32_e32 v0, 16, v0
	v_add3_u32 v9, v12, v9, s33
	s_ashr_i32 s1, s0, 31
	v_and_or_b32 v9, v9, s37, v0
	v_add_u32_e32 v0, s72, v71
	v_lshl_add_u64 v[4:5], s[0:1], 1, v[78:79]
	v_mad_i64_i32 v[10:11], s[0:1], v0, s75, 0
	v_lshl_add_u64 v[10:11], v[10:11], 1, v[4:5]
	global_store_dwordx4 v[10:11], v[6:9], off
	ds_read_b32 v0, v96
	ds_read_b32 v6, v96 offset:132
	ds_read_b32 v7, v96 offset:264
	ds_read_b32 v8, v96 offset:396
	ds_read_b32 v9, v96 offset:528
	ds_read_b32 v10, v96 offset:660
	ds_read_b32 v11, v96 offset:792
	ds_read_b32 v12, v96 offset:924
	s_waitcnt lgkmcnt(0)
	v_bfe_u32 v13, v0, 16, 1
	v_add3_u32 v0, v0, v13, s33
	v_bfe_u32 v13, v6, 16, 1
	v_lshrrev_b32_e32 v0, 16, v0
	v_add3_u32 v6, v6, v13, s33
	v_and_or_b32 v6, v6, s37, v0
	v_bfe_u32 v0, v7, 16, 1
	v_add3_u32 v0, v7, v0, s33
	v_bfe_u32 v7, v8, 16, 1
	v_lshrrev_b32_e32 v0, 16, v0
	v_add3_u32 v7, v8, v7, s33
	v_and_or_b32 v7, v7, s37, v0
	v_bfe_u32 v0, v9, 16, 1
	v_add3_u32 v0, v9, v0, s33
	v_bfe_u32 v8, v10, 16, 1
	v_lshrrev_b32_e32 v0, 16, v0
	v_add3_u32 v8, v10, v8, s33
	v_and_or_b32 v8, v8, s37, v0
	v_bfe_u32 v0, v11, 16, 1
	v_add3_u32 v0, v11, v0, s33
	v_bfe_u32 v9, v12, 16, 1
	v_lshrrev_b32_e32 v0, 16, v0
	v_add3_u32 v9, v12, v9, s33
	s_ashr_i32 s25, s24, 31
	v_and_or_b32 v9, v9, s37, v0
	v_add_u32_e32 v0, s38, v71
	v_lshl_add_u64 v[2:3], s[24:25], 1, v[78:79]
	v_mad_i64_i32 v[10:11], s[0:1], v0, s75, 0
	v_lshl_add_u64 v[10:11], v[10:11], 1, v[2:3]
	global_store_dwordx4 v[10:11], v[6:9], off
	ds_read_b32 v0, v91 offset:32
	ds_read_b32 v6, v91 offset:164
	ds_read_b32 v7, v91 offset:296
	ds_read_b32 v8, v91 offset:428
	ds_read_b32 v9, v91 offset:560
	ds_read_b32 v10, v91 offset:692
	ds_read_b32 v11, v91 offset:824
	ds_read_b32 v12, v91 offset:956
	s_waitcnt lgkmcnt(0)
	v_bfe_u32 v13, v0, 16, 1
	v_add3_u32 v0, v0, v13, s33
	v_bfe_u32 v13, v6, 16, 1
	v_lshrrev_b32_e32 v0, 16, v0
	v_add3_u32 v6, v6, v13, s33
	v_and_or_b32 v6, v6, s37, v0
	v_bfe_u32 v0, v7, 16, 1
	v_add3_u32 v0, v7, v0, s33
	v_bfe_u32 v7, v8, 16, 1
	v_lshrrev_b32_e32 v0, 16, v0
	v_add3_u32 v7, v8, v7, s33
	v_and_or_b32 v7, v7, s37, v0
	v_bfe_u32 v0, v9, 16, 1
	v_add3_u32 v0, v9, v0, s33
	v_bfe_u32 v8, v10, 16, 1
	v_lshrrev_b32_e32 v0, 16, v0
	v_add3_u32 v8, v10, v8, s33
	v_and_or_b32 v8, v8, s37, v0
	v_bfe_u32 v0, v11, 16, 1
	v_add3_u32 v0, v11, v0, s33
	v_bfe_u32 v9, v12, 16, 1
	v_lshrrev_b32_e32 v0, 16, v0
	v_add3_u32 v9, v12, v9, s33
	v_and_or_b32 v9, v9, s37, v0
	v_add_u32_e32 v0, s72, v84
	v_mad_i64_i32 v[10:11], s[0:1], v0, s75, 0
	v_lshl_add_u64 v[10:11], v[10:11], 1, v[4:5]
	global_store_dwordx4 v[10:11], v[6:9], off
	ds_read_b32 v0, v96 offset:32
	ds_read_b32 v6, v96 offset:164
	ds_read_b32 v7, v96 offset:296
	ds_read_b32 v8, v96 offset:428
	ds_read_b32 v9, v96 offset:560
	ds_read_b32 v10, v96 offset:692
	ds_read_b32 v11, v96 offset:824
	ds_read_b32 v12, v96 offset:956
	s_waitcnt lgkmcnt(0)
	v_bfe_u32 v13, v0, 16, 1
	v_add3_u32 v0, v0, v13, s33
	v_bfe_u32 v13, v6, 16, 1
	v_lshrrev_b32_e32 v0, 16, v0
	v_add3_u32 v6, v6, v13, s33
	v_and_or_b32 v6, v6, s37, v0
	v_bfe_u32 v0, v7, 16, 1
	v_add3_u32 v0, v7, v0, s33
	v_bfe_u32 v7, v8, 16, 1
	v_lshrrev_b32_e32 v0, 16, v0
	v_add3_u32 v7, v8, v7, s33
	v_and_or_b32 v7, v7, s37, v0
	v_bfe_u32 v0, v9, 16, 1
	v_add3_u32 v0, v9, v0, s33
	v_bfe_u32 v8, v10, 16, 1
	v_lshrrev_b32_e32 v0, 16, v0
	v_add3_u32 v8, v10, v8, s33
	v_and_or_b32 v8, v8, s37, v0
	v_bfe_u32 v0, v11, 16, 1
	v_add3_u32 v0, v11, v0, s33
	v_bfe_u32 v9, v12, 16, 1
	v_lshrrev_b32_e32 v0, 16, v0
	v_add3_u32 v9, v12, v9, s33
	v_and_or_b32 v9, v9, s37, v0
	v_add_u32_e32 v0, s38, v84
	v_mad_i64_i32 v[10:11], s[0:1], v0, s75, 0
	v_lshl_add_u64 v[10:11], v[10:11], 1, v[2:3]
	global_store_dwordx4 v[10:11], v[6:9], off
	ds_read_b32 v0, v91 offset:64
	ds_read_b32 v6, v91 offset:196
	ds_read_b32 v7, v91 offset:328
	ds_read_b32 v8, v91 offset:460
	ds_read_b32 v9, v91 offset:592
	ds_read_b32 v10, v91 offset:724
	ds_read_b32 v11, v91 offset:856
	ds_read_b32 v12, v91 offset:988
	s_waitcnt lgkmcnt(0)
	v_bfe_u32 v13, v0, 16, 1
	v_add3_u32 v0, v0, v13, s33
	v_bfe_u32 v13, v6, 16, 1
	v_lshrrev_b32_e32 v0, 16, v0
	v_add3_u32 v6, v6, v13, s33
	v_and_or_b32 v6, v6, s37, v0
	v_bfe_u32 v0, v7, 16, 1
	v_add3_u32 v0, v7, v0, s33
	v_bfe_u32 v7, v8, 16, 1
	v_lshrrev_b32_e32 v0, 16, v0
	v_add3_u32 v7, v8, v7, s33
	v_and_or_b32 v7, v7, s37, v0
	v_bfe_u32 v0, v9, 16, 1
	v_add3_u32 v0, v9, v0, s33
	v_bfe_u32 v8, v10, 16, 1
	v_lshrrev_b32_e32 v0, 16, v0
	v_add3_u32 v8, v10, v8, s33
	v_and_or_b32 v8, v8, s37, v0
	v_bfe_u32 v0, v11, 16, 1
	v_add3_u32 v0, v11, v0, s33
	v_bfe_u32 v9, v12, 16, 1
	v_lshrrev_b32_e32 v0, 16, v0
	v_add3_u32 v9, v12, v9, s33
	v_and_or_b32 v9, v9, s37, v0
	v_add_u32_e32 v0, s72, v85
	v_mad_i64_i32 v[10:11], s[0:1], v0, s75, 0
	v_lshl_add_u64 v[10:11], v[10:11], 1, v[4:5]
	global_store_dwordx4 v[10:11], v[6:9], off
	ds_read_b32 v0, v96 offset:64
	ds_read_b32 v6, v96 offset:196
	ds_read_b32 v7, v96 offset:328
	ds_read_b32 v8, v96 offset:460
	ds_read_b32 v9, v96 offset:592
	ds_read_b32 v10, v96 offset:724
	ds_read_b32 v11, v96 offset:856
	ds_read_b32 v12, v96 offset:988
	s_waitcnt lgkmcnt(0)
	v_bfe_u32 v13, v0, 16, 1
	v_add3_u32 v0, v0, v13, s33
	v_bfe_u32 v13, v6, 16, 1
	v_lshrrev_b32_e32 v0, 16, v0
	v_add3_u32 v6, v6, v13, s33
	v_and_or_b32 v6, v6, s37, v0
	v_bfe_u32 v0, v7, 16, 1
	v_add3_u32 v0, v7, v0, s33
	v_bfe_u32 v7, v8, 16, 1
	v_lshrrev_b32_e32 v0, 16, v0
	v_add3_u32 v7, v8, v7, s33
	v_and_or_b32 v7, v7, s37, v0
	v_bfe_u32 v0, v9, 16, 1
	v_add3_u32 v0, v9, v0, s33
	v_bfe_u32 v8, v10, 16, 1
	v_lshrrev_b32_e32 v0, 16, v0
	v_add3_u32 v8, v10, v8, s33
	v_and_or_b32 v8, v8, s37, v0
	v_bfe_u32 v0, v11, 16, 1
	v_add3_u32 v0, v11, v0, s33
	v_bfe_u32 v9, v12, 16, 1
	v_lshrrev_b32_e32 v0, 16, v0
	v_add3_u32 v9, v12, v9, s33
	v_and_or_b32 v9, v9, s37, v0
	v_add_u32_e32 v0, s38, v85
	v_mad_i64_i32 v[10:11], s[0:1], v0, s75, 0
	v_lshl_add_u64 v[10:11], v[10:11], 1, v[2:3]
	global_store_dwordx4 v[10:11], v[6:9], off
	ds_read_b32 v0, v91 offset:96
	ds_read_b32 v6, v91 offset:228
	ds_read_b32 v7, v91 offset:360
	ds_read_b32 v8, v91 offset:492
	ds_read_b32 v9, v91 offset:624
	ds_read_b32 v10, v91 offset:756
	ds_read_b32 v11, v91 offset:888
	ds_read_b32 v12, v91 offset:1020
	s_waitcnt lgkmcnt(0)
	v_bfe_u32 v13, v0, 16, 1
	v_add3_u32 v0, v0, v13, s33
	v_bfe_u32 v13, v6, 16, 1
	v_lshrrev_b32_e32 v0, 16, v0
	v_add3_u32 v6, v6, v13, s33
	v_and_or_b32 v6, v6, s37, v0
	v_bfe_u32 v0, v7, 16, 1
	v_add3_u32 v0, v7, v0, s33
	v_bfe_u32 v7, v8, 16, 1
	v_lshrrev_b32_e32 v0, 16, v0
	v_add3_u32 v7, v8, v7, s33
	v_and_or_b32 v7, v7, s37, v0
	v_bfe_u32 v0, v9, 16, 1
	v_add3_u32 v0, v9, v0, s33
	v_bfe_u32 v8, v10, 16, 1
	v_lshrrev_b32_e32 v0, 16, v0
	v_add3_u32 v8, v10, v8, s33
	v_and_or_b32 v8, v8, s37, v0
	v_bfe_u32 v0, v11, 16, 1
	v_add3_u32 v0, v11, v0, s33
	v_bfe_u32 v9, v12, 16, 1
	v_lshrrev_b32_e32 v0, 16, v0
	v_add3_u32 v9, v12, v9, s33
	v_and_or_b32 v9, v9, s37, v0
	v_add_u32_e32 v0, s72, v86
	v_mad_i64_i32 v[10:11], s[0:1], v0, s75, 0
	v_lshl_add_u64 v[4:5], v[10:11], 1, v[4:5]
	global_store_dwordx4 v[4:5], v[6:9], off
	ds_read_b32 v0, v96 offset:96
	ds_read_b32 v4, v96 offset:228
	ds_read_b32 v5, v96 offset:360
	ds_read_b32 v6, v96 offset:492
	ds_read_b32 v7, v96 offset:624
	ds_read_b32 v8, v96 offset:756
	ds_read_b32 v9, v96 offset:888
	ds_read_b32 v10, v96 offset:1020
	s_waitcnt lgkmcnt(0)
	v_bfe_u32 v11, v0, 16, 1
	v_add3_u32 v0, v0, v11, s33
	v_bfe_u32 v11, v4, 16, 1
	v_lshrrev_b32_e32 v0, 16, v0
	v_add3_u32 v4, v4, v11, s33
	v_and_or_b32 v4, v4, s37, v0
	v_bfe_u32 v0, v5, 16, 1
	v_add3_u32 v0, v5, v0, s33
	v_bfe_u32 v5, v6, 16, 1
	v_lshrrev_b32_e32 v0, 16, v0
	v_add3_u32 v5, v6, v5, s33
	v_and_or_b32 v5, v5, s37, v0
	v_bfe_u32 v0, v7, 16, 1
	v_add3_u32 v0, v7, v0, s33
	v_bfe_u32 v6, v8, 16, 1
	v_lshrrev_b32_e32 v0, 16, v0
	v_add3_u32 v6, v8, v6, s33
	v_and_or_b32 v6, v6, s37, v0
	v_bfe_u32 v0, v9, 16, 1
	v_add3_u32 v0, v9, v0, s33
	v_bfe_u32 v7, v10, 16, 1
	v_lshrrev_b32_e32 v0, 16, v0
	v_add3_u32 v7, v10, v7, s33
	v_and_or_b32 v7, v7, s37, v0
	v_add_u32_e32 v0, s38, v86
	v_mad_i64_i32 v[8:9], s[0:1], v0, s75, 0
	v_lshl_add_u64 v[2:3], v[8:9], 1, v[2:3]
	global_store_dwordx4 v[2:3], v[4:7], off
	s_waitcnt lgkmcnt(0)

.LBB0_1126:
	s_waitcnt lgkmcnt(0)
	ds_read_b32 v0, v91
	ds_read_b32 v2, v91 offset:132
	ds_read_b32 v3, v91 offset:264
	ds_read_b32 v4, v91 offset:396
	ds_read_b32 v5, v91 offset:528
	ds_read_b32 v8, v91 offset:660
	ds_read_b32 v9, v91 offset:792
	ds_read_b32 v10, v91 offset:924
	s_waitcnt lgkmcnt(0)
	v_bfe_u32 v11, v0, 16, 1
	v_add3_u32 v0, v0, v11, s33
	s_waitcnt lgkmcnt(6)
	v_bfe_u32 v11, v2, 16, 1
	v_lshrrev_b32_e32 v0, 16, v0
	v_add3_u32 v2, v2, v11, s33
	v_and_or_b32 v2, v2, s37, v0
	s_waitcnt lgkmcnt(5)
	v_bfe_u32 v0, v3, 16, 1
	v_add3_u32 v0, v3, v0, s33
	s_waitcnt lgkmcnt(4)
	v_bfe_u32 v3, v4, 16, 1
	v_lshrrev_b32_e32 v0, 16, v0
	v_add3_u32 v3, v4, v3, s33
	v_and_or_b32 v3, v3, s37, v0
	s_waitcnt lgkmcnt(3)
	v_bfe_u32 v0, v5, 16, 1
	v_add3_u32 v0, v5, v0, s33
	s_waitcnt lgkmcnt(2)
	v_bfe_u32 v4, v8, 16, 1
	v_lshrrev_b32_e32 v0, 16, v0
	v_add3_u32 v4, v8, v4, s33
	v_and_or_b32 v4, v4, s37, v0
	s_waitcnt lgkmcnt(1)
	v_bfe_u32 v0, v9, 16, 1
	v_add3_u32 v0, v9, v0, s33
	s_waitcnt lgkmcnt(0)
	v_bfe_u32 v5, v10, 16, 1
	v_lshrrev_b32_e32 v0, 16, v0
	v_add3_u32 v5, v10, v5, s33
	v_and_or_b32 v5, v5, s37, v0
	v_add_u32_e32 v0, s85, v71
	v_lshl_add_u64 v[6:7], s[28:29], 1, v[78:79]
	v_mad_i64_i32 v[8:9], s[0:1], v0, s75, 0
	v_lshl_add_u64 v[8:9], v[8:9], 1, v[6:7]
	global_store_dwordx4 v[8:9], v[2:5], off
	ds_read_b32 v0, v91 offset:32
	ds_read_b32 v2, v91 offset:164
	ds_read_b32 v3, v91 offset:296
	ds_read_b32 v4, v91 offset:428
	ds_read_b32 v5, v91 offset:560
	ds_read_b32 v8, v91 offset:692
	ds_read_b32 v9, v91 offset:824
	ds_read_b32 v10, v91 offset:956
	s_waitcnt lgkmcnt(0)
	v_bfe_u32 v11, v0, 16, 1
	v_add3_u32 v0, v0, v11, s33
	v_bfe_u32 v11, v2, 16, 1
	v_lshrrev_b32_e32 v0, 16, v0
	v_add3_u32 v2, v2, v11, s33
	v_and_or_b32 v2, v2, s37, v0
	v_bfe_u32 v0, v3, 16, 1
	v_add3_u32 v0, v3, v0, s33
	v_bfe_u32 v3, v4, 16, 1
	v_lshrrev_b32_e32 v0, 16, v0
	v_add3_u32 v3, v4, v3, s33
	v_and_or_b32 v3, v3, s37, v0
	v_bfe_u32 v0, v5, 16, 1
	v_add3_u32 v0, v5, v0, s33
	v_bfe_u32 v4, v8, 16, 1
	v_lshrrev_b32_e32 v0, 16, v0
	v_add3_u32 v4, v8, v4, s33
	v_and_or_b32 v4, v4, s37, v0
	v_bfe_u32 v0, v9, 16, 1
	v_add3_u32 v0, v9, v0, s33
	v_bfe_u32 v5, v10, 16, 1
	v_lshrrev_b32_e32 v0, 16, v0
	v_add3_u32 v5, v10, v5, s33
	v_and_or_b32 v5, v5, s37, v0
	v_add_u32_e32 v0, s85, v84
	v_mad_i64_i32 v[8:9], s[0:1], v0, s75, 0
	v_lshl_add_u64 v[8:9], v[8:9], 1, v[6:7]
	global_store_dwordx4 v[8:9], v[2:5], off
	ds_read_b32 v0, v91 offset:64
	ds_read_b32 v2, v91 offset:196
	ds_read_b32 v3, v91 offset:328
	ds_read_b32 v4, v91 offset:460
	ds_read_b32 v5, v91 offset:592
	ds_read_b32 v8, v91 offset:724
	ds_read_b32 v9, v91 offset:856
	ds_read_b32 v10, v91 offset:988
	s_waitcnt lgkmcnt(0)
	v_bfe_u32 v11, v0, 16, 1
	v_add3_u32 v0, v0, v11, s33
	v_bfe_u32 v11, v2, 16, 1
	v_lshrrev_b32_e32 v0, 16, v0
	v_add3_u32 v2, v2, v11, s33
	v_and_or_b32 v2, v2, s37, v0
	v_bfe_u32 v0, v3, 16, 1
	v_add3_u32 v0, v3, v0, s33
	v_bfe_u32 v3, v4, 16, 1
	v_lshrrev_b32_e32 v0, 16, v0
	v_add3_u32 v3, v4, v3, s33
	v_and_or_b32 v3, v3, s37, v0
	v_bfe_u32 v0, v5, 16, 1
	v_add3_u32 v0, v5, v0, s33
	v_bfe_u32 v4, v8, 16, 1
	v_lshrrev_b32_e32 v0, 16, v0
	v_add3_u32 v4, v8, v4, s33
	v_and_or_b32 v4, v4, s37, v0
	v_bfe_u32 v0, v9, 16, 1
	v_add3_u32 v0, v9, v0, s33
	v_bfe_u32 v5, v10, 16, 1
	v_lshrrev_b32_e32 v0, 16, v0
	v_add3_u32 v5, v10, v5, s33
	v_and_or_b32 v5, v5, s37, v0
	v_add_u32_e32 v0, s85, v85
	v_mad_i64_i32 v[8:9], s[0:1], v0, s75, 0
	v_lshl_add_u64 v[8:9], v[8:9], 1, v[6:7]
	global_store_dwordx4 v[8:9], v[2:5], off
	ds_read_b32 v0, v91 offset:96
	ds_read_b32 v2, v91 offset:228
	ds_read_b32 v3, v91 offset:360
	ds_read_b32 v4, v91 offset:492
	ds_read_b32 v5, v91 offset:624
	ds_read_b32 v8, v91 offset:756
	ds_read_b32 v9, v91 offset:888
	ds_read_b32 v10, v91 offset:1020
	s_waitcnt lgkmcnt(0)
	v_bfe_u32 v11, v0, 16, 1
	v_add3_u32 v0, v0, v11, s33
	v_bfe_u32 v11, v2, 16, 1
	v_lshrrev_b32_e32 v0, 16, v0
	v_add3_u32 v2, v2, v11, s33
	v_and_or_b32 v2, v2, s37, v0
	v_bfe_u32 v0, v3, 16, 1
	v_add3_u32 v0, v3, v0, s33
	v_bfe_u32 v3, v4, 16, 1
	v_lshrrev_b32_e32 v0, 16, v0
	v_add3_u32 v3, v4, v3, s33
	v_and_or_b32 v3, v3, s37, v0
	v_bfe_u32 v0, v5, 16, 1
	v_add3_u32 v0, v5, v0, s33
	v_bfe_u32 v4, v8, 16, 1
	v_lshrrev_b32_e32 v0, 16, v0
	v_add3_u32 v4, v8, v4, s33
	v_and_or_b32 v4, v4, s37, v0
	v_bfe_u32 v0, v9, 16, 1
	v_add3_u32 v0, v9, v0, s33
	v_bfe_u32 v5, v10, 16, 1
	v_lshrrev_b32_e32 v0, 16, v0
	v_add3_u32 v5, v10, v5, s33
	v_and_or_b32 v5, v5, s37, v0
	v_add_u32_e32 v0, s85, v86
	v_mad_i64_i32 v[8:9], s[0:1], v0, s75, 0
	v_lshl_add_u64 v[6:7], v[8:9], 1, v[6:7]
	global_store_dwordx4 v[6:7], v[2:5], off
	s_waitcnt lgkmcnt(0)
	s_andn2_b64 vcc, exec, s[26:27]
	s_cbranch_vccnz .LBB0_1195
	s_and_b64 vcc, exec, s[2:3]
	s_mov_b32 s28, s38
	s_cbranch_vccnz .LBB0_1132
	s_lshl_b32 s26, s80, 6
	s_cmpk_gt_i32 s80, 0x57
	s_mov_b64 s[0:1], -1
	s_cbranch_scc0 .LBB0_1130
	s_add_i32 s0, s26, 0x7fffea00
	s_and_b32 s0, s0, 0x7fffff00
	s_and_b32 s1, s38, 0x60
	s_or_b32 s0, s1, s0
	s_or_b32 s28, s0, 0x80
	s_mov_b64 s[0:1], 0

.LBB0_1194:
	s_waitcnt lgkmcnt(0)
	ds_read_b32 v0, v91
	ds_read_b32 v2, v91 offset:132
	ds_read_b32 v3, v91 offset:264
	ds_read_b32 v4, v91 offset:396
	ds_read_b32 v5, v91 offset:528
	ds_read_b32 v8, v91 offset:660
	ds_read_b32 v9, v91 offset:792
	ds_read_b32 v10, v91 offset:924
	s_waitcnt lgkmcnt(0)
	v_bfe_u32 v11, v0, 16, 1
	v_add3_u32 v0, v0, v11, s33
	v_bfe_u32 v11, v2, 16, 1
	v_lshrrev_b32_e32 v0, 16, v0
	v_add3_u32 v2, v2, v11, s33
	v_and_or_b32 v2, v2, s37, v0
	v_bfe_u32 v0, v3, 16, 1
	v_add3_u32 v0, v3, v0, s33
	v_bfe_u32 v3, v4, 16, 1
	v_lshrrev_b32_e32 v0, 16, v0
	v_add3_u32 v3, v4, v3, s33
	v_and_or_b32 v3, v3, s37, v0
	v_bfe_u32 v0, v5, 16, 1
	v_add3_u32 v0, v5, v0, s33
	v_bfe_u32 v4, v8, 16, 1
	v_lshrrev_b32_e32 v0, 16, v0
	v_add3_u32 v4, v8, v4, s33
	v_and_or_b32 v4, v4, s37, v0
	v_bfe_u32 v0, v9, 16, 1
	v_add3_u32 v0, v9, v0, s33
	v_bfe_u32 v5, v10, 16, 1
	v_lshrrev_b32_e32 v0, 16, v0
	v_add3_u32 v5, v10, v5, s33
	v_and_or_b32 v5, v5, s37, v0
	v_add_u32_e32 v0, s28, v71
	v_lshl_add_u64 v[6:7], s[26:27], 1, v[78:79]
	v_mad_i64_i32 v[8:9], s[0:1], v0, s75, 0
	v_lshl_add_u64 v[8:9], v[8:9], 1, v[6:7]
	global_store_dwordx4 v[8:9], v[2:5], off
	ds_read_b32 v0, v91 offset:32
	ds_read_b32 v2, v91 offset:164
	ds_read_b32 v3, v91 offset:296
	ds_read_b32 v4, v91 offset:428
	ds_read_b32 v5, v91 offset:560
	ds_read_b32 v8, v91 offset:692
	ds_read_b32 v9, v91 offset:824
	ds_read_b32 v10, v91 offset:956
	s_waitcnt lgkmcnt(0)
	v_bfe_u32 v11, v0, 16, 1
	v_add3_u32 v0, v0, v11, s33
	v_bfe_u32 v11, v2, 16, 1
	v_lshrrev_b32_e32 v0, 16, v0
	v_add3_u32 v2, v2, v11, s33
	v_and_or_b32 v2, v2, s37, v0
	v_bfe_u32 v0, v3, 16, 1
	v_add3_u32 v0, v3, v0, s33
	v_bfe_u32 v3, v4, 16, 1
	v_lshrrev_b32_e32 v0, 16, v0
	v_add3_u32 v3, v4, v3, s33
	v_and_or_b32 v3, v3, s37, v0
	v_bfe_u32 v0, v5, 16, 1
	v_add3_u32 v0, v5, v0, s33
	v_bfe_u32 v4, v8, 16, 1
	v_lshrrev_b32_e32 v0, 16, v0
	v_add3_u32 v4, v8, v4, s33
	v_and_or_b32 v4, v4, s37, v0
	v_bfe_u32 v0, v9, 16, 1
	v_add3_u32 v0, v9, v0, s33
	v_bfe_u32 v5, v10, 16, 1
	v_lshrrev_b32_e32 v0, 16, v0
	v_add3_u32 v5, v10, v5, s33
	v_and_or_b32 v5, v5, s37, v0
	v_add_u32_e32 v0, s28, v84
	v_mad_i64_i32 v[8:9], s[0:1], v0, s75, 0
	v_lshl_add_u64 v[8:9], v[8:9], 1, v[6:7]
	global_store_dwordx4 v[8:9], v[2:5], off
	ds_read_b32 v0, v91 offset:64
	ds_read_b32 v2, v91 offset:196
	ds_read_b32 v3, v91 offset:328
	ds_read_b32 v4, v91 offset:460
	ds_read_b32 v5, v91 offset:592
	ds_read_b32 v8, v91 offset:724
	ds_read_b32 v9, v91 offset:856
	ds_read_b32 v10, v91 offset:988
	s_waitcnt lgkmcnt(0)
	v_bfe_u32 v11, v0, 16, 1
	v_add3_u32 v0, v0, v11, s33
	v_bfe_u32 v11, v2, 16, 1
	v_lshrrev_b32_e32 v0, 16, v0
	v_add3_u32 v2, v2, v11, s33
	v_and_or_b32 v2, v2, s37, v0
	v_bfe_u32 v0, v3, 16, 1
	v_add3_u32 v0, v3, v0, s33
	v_bfe_u32 v3, v4, 16, 1
	v_lshrrev_b32_e32 v0, 16, v0
	v_add3_u32 v3, v4, v3, s33
	v_and_or_b32 v3, v3, s37, v0
	v_bfe_u32 v0, v5, 16, 1
	v_add3_u32 v0, v5, v0, s33
	v_bfe_u32 v4, v8, 16, 1
	v_lshrrev_b32_e32 v0, 16, v0
	v_add3_u32 v4, v8, v4, s33
	v_and_or_b32 v4, v4, s37, v0
	v_bfe_u32 v0, v9, 16, 1
	v_add3_u32 v0, v9, v0, s33
	v_bfe_u32 v5, v10, 16, 1
	v_lshrrev_b32_e32 v0, 16, v0
	v_add3_u32 v5, v10, v5, s33
	v_and_or_b32 v5, v5, s37, v0
	v_add_u32_e32 v0, s28, v85
	v_mad_i64_i32 v[8:9], s[0:1], v0, s75, 0
	v_lshl_add_u64 v[8:9], v[8:9], 1, v[6:7]
	global_store_dwordx4 v[8:9], v[2:5], off
	ds_read_b32 v0, v91 offset:96
	ds_read_b32 v2, v91 offset:228
	ds_read_b32 v3, v91 offset:360
	ds_read_b32 v4, v91 offset:492
	ds_read_b32 v5, v91 offset:624
	ds_read_b32 v8, v91 offset:756
	ds_read_b32 v9, v91 offset:888
	ds_read_b32 v10, v91 offset:1020
	s_waitcnt lgkmcnt(0)
	v_bfe_u32 v11, v0, 16, 1
	v_add3_u32 v0, v0, v11, s33
	v_bfe_u32 v11, v2, 16, 1
	v_lshrrev_b32_e32 v0, 16, v0
	v_add3_u32 v2, v2, v11, s33
	v_and_or_b32 v2, v2, s37, v0
	v_bfe_u32 v0, v3, 16, 1
	v_add3_u32 v0, v3, v0, s33
	v_bfe_u32 v3, v4, 16, 1
	v_lshrrev_b32_e32 v0, 16, v0
	v_add3_u32 v3, v4, v3, s33
	v_and_or_b32 v3, v3, s37, v0
	v_bfe_u32 v0, v5, 16, 1
	v_add3_u32 v0, v5, v0, s33
	v_bfe_u32 v4, v8, 16, 1
	v_lshrrev_b32_e32 v0, 16, v0
	v_add3_u32 v4, v8, v4, s33
	v_and_or_b32 v4, v4, s37, v0
	v_bfe_u32 v0, v9, 16, 1
	v_add3_u32 v0, v9, v0, s33
	v_bfe_u32 v5, v10, 16, 1
	v_lshrrev_b32_e32 v0, 16, v0
	v_add3_u32 v5, v10, v5, s33
	v_and_or_b32 v5, v5, s37, v0
	v_add_u32_e32 v0, s28, v86
	v_mad_i64_i32 v[8:9], s[0:1], v0, s75, 0
	v_lshl_add_u64 v[6:7], v[8:9], 1, v[6:7]
	global_store_dwordx4 v[6:7], v[2:5], off
	s_waitcnt lgkmcnt(0)

.LBB0_1214:
	s_ashr_i32 s61, s60, 31
	s_add_i32 s10, s56, s60
	s_cmp_lt_i32 s10, 0x8000
	s_cselect_b64 s[14:15], -1, 0
	s_and_b64 s[0:1], s[14:15], exec
	s_cselect_b32 s0, s10, s60
	s_ashr_i32 s1, s0, 31
	s_lshl_b64 s[16:17], s[0:1], 12
	s_add_i32 s6, s34, s60
	s_cmp_lt_i32 s6, 0x8000
	s_cselect_b64 s[12:13], -1, 0
	s_and_b64 s[0:1], s[12:13], exec
	s_cselect_b32 s0, s6, s60
	s_ashr_i32 s1, s0, 31
	s_lshl_b64 s[20:21], s[0:1], 12
	s_mul_i32 s0, s63, 24
	s_add_i32 s0, s0, s60
	s_cmp_lt_i32 s0, 0x8000
	s_cselect_b64 s[8:9], -1, 0
	s_and_b64 s[24:25], s[8:9], exec
	s_cselect_b32 s24, s0, s60
	s_lshl_b64 s[26:27], s[60:61], 12
	s_waitcnt lgkmcnt(0)
	v_lshl_add_u64 v[2:3], v[50:51], 0, s[26:27]
	global_load_dwordx4 v[56:59], v[2:3], off
	global_load_dwordx4 v[60:63], v[2:3], off offset:1024
	global_load_dwordx4 v[64:67], v[2:3], off offset:2048
	global_load_dwordx4 v[68:71], v[2:3], off offset:3072
	v_lshl_add_u64 v[2:3], v[50:51], 0, s[16:17]
	s_ashr_i32 s25, s24, 31
	global_load_dwordx4 v[46:49], v[2:3], off
	global_load_dwordx4 v[42:45], v[2:3], off offset:1024
	global_load_dwordx4 v[38:41], v[2:3], off offset:2048
	global_load_dwordx4 v[34:37], v[2:3], off offset:3072
	v_lshl_add_u64 v[2:3], v[50:51], 0, s[20:21]
	s_lshl_b64 s[16:17], s[24:25], 12
	global_load_dwordx4 v[30:33], v[2:3], off
	global_load_dwordx4 v[26:29], v[2:3], off offset:1024
	global_load_dwordx4 v[22:25], v[2:3], off offset:2048
	global_load_dwordx4 v[18:21], v[2:3], off offset:3072
	v_lshl_add_u64 v[2:3], v[50:51], 0, s[16:17]
	global_load_dwordx4 v[14:17], v[2:3], off
	global_load_dwordx4 v[10:13], v[2:3], off offset:1024
	global_load_dwordx4 v[6:9], v[2:3], off offset:2048
	s_nop 0
	global_load_dwordx4 v[2:5], v[2:3], off offset:3072
	s_lshl_b64 s[16:17], s[60:61], 11
	v_mov_b32_e32 v0, v222
	v_lshl_add_u64 v[72:73], v[52:53], 0, s[16:17]
	s_waitcnt vmcnt(0)
	v_mul_f32_e32 v82, v57, v57
	v_mul_f32_e32 v83, v59, v59
	v_cvt_pk_bf16_f32 v74, v56, v57
	v_cvt_pk_bf16_f32 v75, v58, v59
	v_mul_f32_e32 v57, v61, v61
	v_mul_f32_e32 v59, v63, v63
	v_cvt_pk_bf16_f32 v76, v60, v61
	v_cvt_pk_bf16_f32 v77, v62, v63
	v_mul_f32_e32 v61, v65, v65
	v_mul_f32_e32 v63, v67, v67
	v_fmac_f32_e32 v82, v56, v56
	v_fmac_f32_e32 v83, v58, v58
	v_fmac_f32_e32 v57, v60, v60
	v_fmac_f32_e32 v59, v62, v62
	v_cvt_pk_bf16_f32 v78, v64, v65
	v_cvt_pk_bf16_f32 v79, v66, v67
	v_mul_f32_e32 v65, v69, v69
	v_mul_f32_e32 v67, v71, v71
	v_cvt_pk_bf16_f32 v80, v68, v69
	v_cvt_pk_bf16_f32 v81, v70, v71
	v_fmac_f32_e32 v61, v64, v64
	v_fmac_f32_e32 v63, v66, v66
	v_add_f32_e32 v56, v82, v83
	v_add_f32_e32 v57, v57, v59
	global_store_dwordx2 v[72:73], v[74:75], off
	global_store_dwordx2 v[72:73], v[76:77], off offset:512
	global_store_dwordx2 v[72:73], v[78:79], off offset:1024
	v_fmac_f32_e32 v65, v68, v68
	v_fmac_f32_e32 v67, v70, v70
	global_store_dwordx2 v[72:73], v[80:81], off offset:1536
	v_add_f32_e32 v58, v61, v63
	v_add_f32_e32 v56, v56, v57
	v_add_f32_e32 v59, v65, v67
	v_lshlrev_b32_e32 v0, 2, v0
	v_add_f32_e32 v56, v56, v58
	v_xor_b32_e32 v0, 4, v0
	v_add_f32_e32 v56, v56, v59
	ds_bpermute_b32 v0, v0, v56
	v_mov_b32_e32 v57, v222
	s_waitcnt lgkmcnt(0)
	v_add_f32_e32 v0, v56, v0
	v_lshlrev_b32_e32 v57, 2, v57
	v_xor_b32_e32 v57, 8, v57
	ds_bpermute_b32 v56, v57, v0
	v_mov_b32_e32 v57, v222
	s_waitcnt lgkmcnt(0)
	v_add_f32_e32 v0, v0, v56
	v_lshlrev_b32_e32 v57, 2, v57
	v_xor_b32_e32 v57, 16, v57
	ds_bpermute_b32 v56, v57, v0
	v_mov_b32_e32 v57, v222
	s_waitcnt lgkmcnt(0)
	v_add_f32_e32 v0, v0, v56
	v_lshlrev_b32_e32 v57, 2, v57
	v_xor_b32_e32 v57, 32, v57
	ds_bpermute_b32 v56, v57, v0
	v_mov_b32_e32 v57, v222
	s_waitcnt lgkmcnt(0)
	v_add_f32_e32 v0, v0, v56
	v_lshlrev_b32_e32 v57, 2, v57
	v_xor_b32_e32 v57, 64, v57
	ds_bpermute_b32 v56, v57, v0
	v_mov_b32_e32 v57, v222
	s_waitcnt lgkmcnt(0)
	v_add_f32_e32 v0, v0, v56
	v_lshlrev_b32_e32 v57, 2, v57
	v_xor_b32_e32 v56, 0x80, v57
	ds_bpermute_b32 v56, v56, v0
	s_and_saveexec_b64 s[16:17], s[2:3]
	s_cbranch_execz .LBB0_1216
	s_lshl_b64 s[20:21], s[60:61], 6
	s_waitcnt lgkmcnt(0)
	v_add_f32_e32 v0, v0, v56
	v_lshl_add_u64 v[58:59], v[54:55], 0, s[20:21]
	v_cndmask_b32_e64 v0, 0, v0, s[4:5]
	global_store_dword v[58:59], v0, off
.LBB0_1216:
	s_or_b64 exec, exec, s[16:17]
	s_andn2_b64 vcc, exec, s[14:15]
	s_cbranch_vccnz .LBB0_1213
	s_ashr_i32 s11, s10, 31
	s_lshl_b64 s[14:15], s[10:11], 11
	v_mul_f32_e32 v0, v47, v47
	s_waitcnt lgkmcnt(0)
	v_lshl_add_u64 v[56:57], v[52:53], 0, s[14:15]
	v_fmac_f32_e32 v0, v46, v46
	v_cvt_pk_bf16_f32 v46, v46, v47
	v_cvt_pk_bf16_f32 v47, v48, v49
	global_store_dwordx2 v[56:57], v[46:47], off
	v_mul_f32_e32 v46, v43, v43
	v_fmac_f32_e32 v46, v42, v42
	v_cvt_pk_bf16_f32 v42, v42, v43
	v_cvt_pk_bf16_f32 v43, v44, v45
	global_store_dwordx2 v[56:57], v[42:43], off offset:512
	v_mul_f32_e32 v42, v39, v39
	v_fmac_f32_e32 v42, v38, v38
	v_cvt_pk_bf16_f32 v38, v38, v39
	v_cvt_pk_bf16_f32 v39, v40, v41
	v_mul_f32_e32 v58, v49, v49
	v_mul_f32_e32 v47, v45, v45
	global_store_dwordx2 v[56:57], v[38:39], off offset:1024
	v_mul_f32_e32 v38, v35, v35
	v_fmac_f32_e32 v58, v48, v48
	v_fmac_f32_e32 v47, v44, v44
	v_mul_f32_e32 v43, v41, v41
	v_fmac_f32_e32 v38, v34, v34
	v_cvt_pk_bf16_f32 v34, v34, v35
	v_cvt_pk_bf16_f32 v35, v36, v37
	v_add_f32_e32 v0, v0, v58
	v_add_f32_e32 v46, v46, v47
	v_fmac_f32_e32 v43, v40, v40
	v_mul_f32_e32 v39, v37, v37
	global_store_dwordx2 v[56:57], v[34:35], off offset:1536
	v_mov_b32_e32 v34, v222
	v_add_f32_e32 v0, v0, v46
	v_add_f32_e32 v42, v42, v43
	v_fmac_f32_e32 v39, v36, v36
	v_add_f32_e32 v0, v0, v42
	v_add_f32_e32 v38, v38, v39
	v_lshlrev_b32_e32 v34, 2, v34
	v_add_f32_e32 v0, v0, v38
	v_xor_b32_e32 v34, 4, v34
	ds_bpermute_b32 v34, v34, v0
	s_waitcnt lgkmcnt(0)
	v_add_f32_e32 v0, v0, v34
	v_mov_b32_e32 v34, v222
	s_nop 0
	v_lshlrev_b32_e32 v34, 2, v34
	v_xor_b32_e32 v34, 8, v34
	ds_bpermute_b32 v34, v34, v0
	s_waitcnt lgkmcnt(0)
	v_add_f32_e32 v0, v0, v34
	v_mov_b32_e32 v34, v222
	s_nop 0
	v_lshlrev_b32_e32 v34, 2, v34
	v_xor_b32_e32 v34, 16, v34
	ds_bpermute_b32 v34, v34, v0
	s_waitcnt lgkmcnt(0)
	v_add_f32_e32 v0, v0, v34
	v_mov_b32_e32 v34, v222
	s_nop 0
	v_lshlrev_b32_e32 v34, 2, v34
	v_xor_b32_e32 v34, 32, v34
	ds_bpermute_b32 v34, v34, v0
	s_waitcnt lgkmcnt(0)
	v_add_f32_e32 v0, v0, v34
	v_mov_b32_e32 v34, v222
	s_nop 0
	v_lshlrev_b32_e32 v34, 2, v34
	v_xor_b32_e32 v34, 64, v34
	ds_bpermute_b32 v34, v34, v0
	s_waitcnt lgkmcnt(0)
	v_add_f32_e32 v0, v0, v34
	v_mov_b32_e32 v34, v222
	s_nop 0
	v_lshlrev_b32_e32 v34, 2, v34
	v_xor_b32_e32 v34, 0x80, v34
	ds_bpermute_b32 v34, v34, v0
	s_and_saveexec_b64 s[14:15], s[2:3]
	s_cbranch_execz .LBB0_1219
	s_lshl_b64 s[10:11], s[10:11], 6
	s_waitcnt lgkmcnt(0)
	v_add_f32_e32 v0, v0, v34
	v_lshl_add_u64 v[36:37], v[54:55], 0, s[10:11]
	v_cndmask_b32_e64 v0, 0, v0, s[4:5]
	global_store_dword v[36:37], v0, off
.LBB0_1219:
	s_or_b64 exec, exec, s[14:15]
	s_andn2_b64 vcc, exec, s[12:13]
	s_cbranch_vccnz .LBB0_1213
	s_ashr_i32 s7, s6, 31
	s_lshl_b64 s[10:11], s[6:7], 11
	v_mul_f32_e32 v0, v31, v31
	s_waitcnt lgkmcnt(0)
	v_lshl_add_u64 v[34:35], v[52:53], 0, s[10:11]
	v_fmac_f32_e32 v0, v30, v30
	v_cvt_pk_bf16_f32 v30, v30, v31
	v_cvt_pk_bf16_f32 v31, v32, v33
	global_store_dwordx2 v[34:35], v[30:31], off
	v_mul_f32_e32 v30, v27, v27
	v_fmac_f32_e32 v30, v26, v26
	v_cvt_pk_bf16_f32 v26, v26, v27
	v_cvt_pk_bf16_f32 v27, v28, v29
	global_store_dwordx2 v[34:35], v[26:27], off offset:512
	v_mul_f32_e32 v26, v23, v23
	v_fmac_f32_e32 v26, v22, v22
	v_cvt_pk_bf16_f32 v22, v22, v23
	v_cvt_pk_bf16_f32 v23, v24, v25
	v_mul_f32_e32 v36, v33, v33
	v_mul_f32_e32 v31, v29, v29
	global_store_dwordx2 v[34:35], v[22:23], off offset:1024
	v_mul_f32_e32 v22, v19, v19
	v_fmac_f32_e32 v36, v32, v32
	v_fmac_f32_e32 v31, v28, v28
	v_mul_f32_e32 v27, v25, v25
	v_fmac_f32_e32 v22, v18, v18
	v_cvt_pk_bf16_f32 v18, v18, v19
	v_cvt_pk_bf16_f32 v19, v20, v21
	v_add_f32_e32 v0, v0, v36
	v_add_f32_e32 v30, v30, v31
	v_fmac_f32_e32 v27, v24, v24
	v_mul_f32_e32 v23, v21, v21
	global_store_dwordx2 v[34:35], v[18:19], off offset:1536
	v_mov_b32_e32 v18, v222
	v_add_f32_e32 v0, v0, v30
	v_add_f32_e32 v26, v26, v27
	v_fmac_f32_e32 v23, v20, v20
	v_add_f32_e32 v0, v0, v26
	v_add_f32_e32 v22, v22, v23
	v_lshlrev_b32_e32 v18, 2, v18
	v_add_f32_e32 v0, v0, v22
	v_xor_b32_e32 v18, 4, v18
	ds_bpermute_b32 v18, v18, v0
	s_waitcnt lgkmcnt(0)
	v_add_f32_e32 v0, v0, v18
	v_mov_b32_e32 v18, v222
	s_nop 0
	v_lshlrev_b32_e32 v18, 2, v18
	v_xor_b32_e32 v18, 8, v18
	ds_bpermute_b32 v18, v18, v0
	s_waitcnt lgkmcnt(0)
	v_add_f32_e32 v0, v0, v18
	v_mov_b32_e32 v18, v222
	s_nop 0
	v_lshlrev_b32_e32 v18, 2, v18
	v_xor_b32_e32 v18, 16, v18
	ds_bpermute_b32 v18, v18, v0
	s_waitcnt lgkmcnt(0)
	v_add_f32_e32 v0, v0, v18
	v_mov_b32_e32 v18, v222
	s_nop 0
	v_lshlrev_b32_e32 v18, 2, v18
	v_xor_b32_e32 v18, 32, v18
	ds_bpermute_b32 v18, v18, v0
	s_waitcnt lgkmcnt(0)
	v_add_f32_e32 v0, v0, v18
	v_mov_b32_e32 v18, v222
	s_nop 0
	v_lshlrev_b32_e32 v18, 2, v18
	v_xor_b32_e32 v18, 64, v18
	ds_bpermute_b32 v18, v18, v0
	s_waitcnt lgkmcnt(0)
	v_add_f32_e32 v0, v0, v18
	v_mov_b32_e32 v18, v222
	s_nop 0
	v_lshlrev_b32_e32 v18, 2, v18
	v_xor_b32_e32 v18, 0x80, v18
	ds_bpermute_b32 v18, v18, v0
	s_and_saveexec_b64 s[10:11], s[2:3]
	s_cbranch_execz .LBB0_1222
	s_lshl_b64 s[6:7], s[6:7], 6
	s_waitcnt lgkmcnt(0)
	v_add_f32_e32 v0, v0, v18
	v_lshl_add_u64 v[20:21], v[54:55], 0, s[6:7]
	v_cndmask_b32_e64 v0, 0, v0, s[4:5]
	global_store_dword v[20:21], v0, off
.LBB0_1222:
	s_or_b64 exec, exec, s[10:11]
	s_andn2_b64 vcc, exec, s[8:9]
	s_cbranch_vccnz .LBB0_1213
	s_ashr_i32 s1, s0, 31
	s_lshl_b64 s[6:7], s[0:1], 11
	v_mul_f32_e32 v0, v15, v15
	s_waitcnt lgkmcnt(0)
	v_lshl_add_u64 v[18:19], v[52:53], 0, s[6:7]
	v_fmac_f32_e32 v0, v14, v14
	v_cvt_pk_bf16_f32 v14, v14, v15
	v_cvt_pk_bf16_f32 v15, v16, v17
	global_store_dwordx2 v[18:19], v[14:15], off
	v_mul_f32_e32 v14, v11, v11
	v_fmac_f32_e32 v14, v10, v10
	v_cvt_pk_bf16_f32 v10, v10, v11
	v_cvt_pk_bf16_f32 v11, v12, v13
	global_store_dwordx2 v[18:19], v[10:11], off offset:512
	v_mul_f32_e32 v10, v7, v7
	v_fmac_f32_e32 v10, v6, v6
	v_cvt_pk_bf16_f32 v6, v6, v7
	v_cvt_pk_bf16_f32 v7, v8, v9
	v_mul_f32_e32 v20, v17, v17
	v_mul_f32_e32 v15, v13, v13
	global_store_dwordx2 v[18:19], v[6:7], off offset:1024
	v_mul_f32_e32 v6, v3, v3
	v_fmac_f32_e32 v20, v16, v16
	v_fmac_f32_e32 v15, v12, v12
	v_mul_f32_e32 v11, v9, v9
	v_fmac_f32_e32 v6, v2, v2
	v_cvt_pk_bf16_f32 v2, v2, v3
	v_cvt_pk_bf16_f32 v3, v4, v5
	v_add_f32_e32 v0, v0, v20
	v_add_f32_e32 v14, v14, v15
	v_fmac_f32_e32 v11, v8, v8
	v_mul_f32_e32 v7, v5, v5
	global_store_dwordx2 v[18:19], v[2:3], off offset:1536
	v_mov_b32_e32 v2, v222
	v_add_f32_e32 v0, v0, v14
	v_add_f32_e32 v10, v10, v11
	v_fmac_f32_e32 v7, v4, v4
	v_add_f32_e32 v0, v0, v10
	v_add_f32_e32 v6, v6, v7
	v_lshlrev_b32_e32 v2, 2, v2
	v_add_f32_e32 v0, v0, v6
	v_xor_b32_e32 v2, 4, v2
	ds_bpermute_b32 v2, v2, v0
	s_waitcnt lgkmcnt(0)
	v_add_f32_e32 v0, v0, v2
	v_mov_b32_e32 v2, v222
	s_nop 0
	v_lshlrev_b32_e32 v2, 2, v2
	v_xor_b32_e32 v2, 8, v2
	ds_bpermute_b32 v2, v2, v0
	s_waitcnt lgkmcnt(0)
	v_add_f32_e32 v0, v0, v2
	v_mov_b32_e32 v2, v222
	s_nop 0
	v_lshlrev_b32_e32 v2, 2, v2
	v_xor_b32_e32 v2, 16, v2
	ds_bpermute_b32 v2, v2, v0
	s_waitcnt lgkmcnt(0)
	v_add_f32_e32 v0, v0, v2
	v_mov_b32_e32 v2, v222
	s_nop 0
	v_lshlrev_b32_e32 v2, 2, v2
	v_xor_b32_e32 v2, 32, v2
	ds_bpermute_b32 v2, v2, v0
	s_waitcnt lgkmcnt(0)
	v_add_f32_e32 v0, v0, v2
	v_mov_b32_e32 v2, v222
	s_nop 0
	v_lshlrev_b32_e32 v2, 2, v2
	v_xor_b32_e32 v2, 64, v2
	ds_bpermute_b32 v2, v2, v0
	s_waitcnt lgkmcnt(0)
	v_add_f32_e32 v0, v0, v2
	v_mov_b32_e32 v2, v222
	s_nop 0
	v_lshlrev_b32_e32 v2, 2, v2
	v_xor_b32_e32 v2, 0x80, v2
	ds_bpermute_b32 v2, v2, v0
	s_and_saveexec_b64 s[6:7], s[2:3]
	s_cbranch_execz .LBB0_1212
	s_lshl_b64 s[0:1], s[0:1], 6
	s_waitcnt lgkmcnt(0)
	v_add_f32_e32 v0, v0, v2
	v_lshl_add_u64 v[4:5], v[54:55], 0, s[0:1]
	v_cndmask_b32_e64 v0, 0, v0, s[4:5]
	global_store_dword v[4:5], v0, off
	s_branch .LBB0_1212

.LBB0_1227:
	v_ashrrev_i32_e32 v6, 5, v3
	v_ashrrev_i32_e32 v7, 31, v6
	v_lshl_add_u64 v[6:7], v[6:7], 2, s[42:43]
	global_load_dword v6, v[6:7], off
	v_and_b32_e32 v7, 62, v0
	v_cvt_f32_ubyte0_e32 v7, v7
	v_mul_f32_e32 v8, 0x3e549a78, v7
	s_mov_b32 s8, 0xc2fc0000
	v_cmp_gt_f32_e32 vcc, s8, v8
	v_add_u32_e32 v3, s2, v3
	v_add_u32_e32 v0, s3, v0
	v_cndmask_b32_e32 v8, 0, v235, vcc
	v_fmac_f32_e32 v8, 0x3e549a78, v7
	v_exp_f32_e32 v7, v8
	v_cndmask_b32_e32 v9, 0, v224, vcc
	v_ldexp_f32 v7, v7, v9
	v_div_scale_f32 v8, s[8:9], v7, v7, 1.0
	v_rcp_f32_e32 v10, v8
	v_div_scale_f32 v9, vcc, 1.0, v7, 1.0
	s_mov_b32 s8, 0xfffff
	v_fma_f32 v11, -v8, v10, 1.0
	v_fmac_f32_e32 v10, v11, v10
	v_mul_f32_e32 v11, v9, v10
	v_fma_f32 v12, -v8, v11, v9
	v_fmac_f32_e32 v11, v12, v10
	v_fma_f32 v8, -v8, v11, v9
	v_div_fmas_f32 v8, v8, v10, v11
	v_div_fixup_f32 v7, v8, v7, 1.0
	v_cmp_lt_i32_e32 vcc, s8, v3
	s_or_b64 s[6:7], vcc, s[6:7]
	s_waitcnt vmcnt(0)
	v_cvt_f32_i32_e32 v6, v6
	v_mul_f32_e32 v6, v7, v6
	v_cvt_f64_f32_e32 v[6:7], v6
	v_mul_f64 v[8:9], v[6:7], s[10:11]
	v_rndne_f64_e32 v[8:9], v[8:9]
	v_fma_f64 v[6:7], v[6:7], s[10:11], -v[8:9]
	v_cvt_f32_f64_e32 v7, v[6:7]
	v_cos_f32_e32 v6, v7
	v_sin_f32_e32 v7, v7
	global_store_dwordx2 v[4:5], v[6:7], off
	v_lshl_add_u64 v[4:5], v[4:5], 0, s[4:5]
	s_andn2_b64 exec, exec, s[6:7]
	s_cbranch_execnz .LBB0_1227

.LBB0_1231:
	v_ashrrev_i32_e32 v3, 8, v4
	v_bfe_u32 v21, v4, 2, 6
	v_ashrrev_i32_e32 v18, 8, v5
	v_ashrrev_i32_e32 v19, 8, v6
	v_ashrrev_i32_e32 v20, 8, v7
	v_bfe_u32 v22, v5, 2, 6
	v_bfe_u32 v23, v6, 2, 6
	v_bfe_u32 v24, v7, 2, 6
	v_cmp_eq_u32_e64 s[2:3], v21, v3
	v_add_u32_e32 v21, 1, v21
	v_cmp_eq_u32_e64 s[4:5], v22, v18
	v_cmp_eq_u32_e64 s[6:7], v23, v19
	v_cmp_eq_u32_e64 s[8:9], v24, v20
	v_add_u32_e32 v24, 1, v24
	v_add_u32_e32 v23, 1, v23
	v_add_u32_e32 v22, 1, v22
	v_cmp_eq_u32_e64 s[12:13], v21, v3
	v_add_u32_e32 v9, -4, v9
	v_cndmask_b32_e64 v25, 0, v236, s[2:3]
	v_cmp_eq_u32_e64 s[14:15], v22, v18
	v_cmp_eq_u32_e64 s[16:17], v23, v19
	v_cmp_eq_u32_e64 s[18:19], v24, v20
	s_or_b64 s[2:3], s[2:3], s[12:13]
	v_ashrrev_i32_e32 v17, 31, v4
	v_mov_b32_e32 v16, v4
	v_cmp_eq_u32_e64 s[10:11], 0, v9
	v_cndmask_b32_e64 v26, 0, v236, s[4:5]
	v_cndmask_b32_e64 v27, 0, v236, s[6:7]
	v_cndmask_b32_e64 v28, 0, v236, s[8:9]
	s_or_b64 s[4:5], s[4:5], s[14:15]
	s_or_b64 s[6:7], s[6:7], s[16:17]
	s_or_b64 s[8:9], s[8:9], s[18:19]
	v_cndmask_b32_e64 v3, 0, v237, s[2:3]
	v_ashrrev_i32_e32 v11, 31, v7
	v_mov_b32_e32 v10, v7
	v_ashrrev_i32_e32 v13, 31, v6
	v_mov_b32_e32 v12, v6
	v_ashrrev_i32_e32 v15, 31, v5
	v_mov_b32_e32 v14, v5
	v_add_u32_e32 v7, s34, v7
	v_add_u32_e32 v6, s31, v6
	v_add_u32_e32 v5, s30, v5
	v_add_u32_e32 v4, s25, v4
	v_lshl_add_u64 v[16:17], v[16:17], 1, s[38:39]
	v_cndmask_b32_e64 v18, 0, v237, s[4:5]
	v_cndmask_b32_e64 v19, 0, v237, s[6:7]
	v_cndmask_b32_e64 v20, 0, v237, s[8:9]
	s_or_b64 s[28:29], s[10:11], s[28:29]
	v_cndmask_b32_e64 v3, v25, v3, s[0:1]
	v_lshl_add_u64 v[14:15], v[14:15], 1, s[38:39]
	v_lshl_add_u64 v[12:13], v[12:13], 1, s[38:39]
	v_lshl_add_u64 v[10:11], v[10:11], 1, s[38:39]
	v_cndmask_b32_e64 v20, v28, v20, s[0:1]
	v_cndmask_b32_e64 v19, v27, v19, s[0:1]
	v_cndmask_b32_e64 v18, v26, v18, s[0:1]
	global_store_short v[16:17], v3, off
	global_store_short v[14:15], v18, off
	global_store_short v[12:13], v19, off
	global_store_short v[10:11], v20, off
	s_andn2_b64 exec, exec, s[28:29]
	s_cbranch_execnz .LBB0_1231
	s_or_b64 exec, exec, s[28:29]
	v_mad_u64_u32 v[4:5], s[0:1], v8, s24, v[2:3]
	v_cmp_ne_u32_e64 s[0:1], v0, v8
	v_readlane_b32 s12, v254, 13
	s_orn2_b64 s[4:5], s[0:1], exec
	v_readlane_b32 s13, v254, 14
	v_readlane_b32 s14, v254, 15
	v_readlane_b32 s15, v254, 16
	v_readlane_b32 s16, v254, 17
	v_readlane_b32 s17, v254, 18
	v_readlane_b32 s18, v254, 19
	v_readlane_b32 s19, v254, 20

.LBB0_1235:
	s_or_b64 exec, exec, s[8:9]
	v_add_u32_e32 v4, s24, v4
	s_movk_i32 s0, 0x3fff
	v_cmp_lt_i32_e64 s[0:1], s0, v4
	global_store_short v[6:7], v0, off
	s_or_b64 s[6:7], s[0:1], s[6:7]
	v_lshl_add_u64 v[6:7], v[6:7], 0, s[4:5]
	s_andn2_b64 exec, exec, s[6:7]
	s_cbranch_execz .LBB0_1240

.LBB0_1242:
	s_add_u32 s8, s10, s6
	s_addc_u32 s9, s11, s7
	global_load_dword v24, v[4:5], off offset:-4096
	global_load_dword v25, v[4:5], off offset:-3072
	global_load_dword v26, v[4:5], off offset:-2048
	global_load_dword v27, v[4:5], off offset:-1024
	global_load_dword v28, v[4:5], off
	global_load_dwordx4 v[6:9], v1, s[8:9] offset:32
	global_load_dwordx4 v[10:13], v1, s[8:9] offset:16
	global_load_dwordx4 v[14:17], v1, s[8:9]
	s_movk_i32 s0, 0xd000
	v_add_co_u32_e32 v18, vcc, s0, v4
	s_movk_i32 s2, 0xe000
	s_mov_b64 s[0:1], vcc
	v_add_co_u32_e32 v20, vcc, s2, v4
	s_mov_b64 s[2:3], vcc
	v_addc_co_u32_e64 v19, vcc, -1, v5, s[0:1]
	s_movk_i32 s0, 0xf000
	v_add_co_u32_e32 v22, vcc, s0, v4
	v_addc_co_u32_e64 v21, s[0:1], -1, v5, s[2:3]
	global_load_dword v29, v[18:19], off offset:-3072
	global_load_dword v30, v[18:19], off offset:-2048
	global_load_dword v31, v[18:19], off offset:-1024
	global_load_dword v32, v[20:21], off offset:-4096
	global_load_dword v33, v[20:21], off offset:-3072
	global_load_dword v34, v[20:21], off offset:-2048
	global_load_dword v35, v[20:21], off offset:-1024
	global_load_dword v36, v[20:21], off
	v_addc_co_u32_e32 v23, vcc, -1, v5, vcc
	global_load_dword v37, v[22:23], off offset:-3072
	global_load_dword v38, v[22:23], off offset:-2048
	s_nop 0
	global_load_dword v22, v[22:23], off offset:-1024
	s_nop 0
	global_load_dwordx4 v[18:21], v1, s[8:9] offset:48
	s_add_u32 s6, s6, 64
	s_addc_u32 s7, s7, 0
	v_lshl_add_u64 v[4:5], v[4:5], 0, s[20:21]
	s_cmpk_eq_i32 s6, 0x2000
	s_waitcnt vmcnt(0)
	v_fmac_f32_e32 v0, v14, v29
	v_fmac_f32_e32 v0, v15, v30
	v_fmac_f32_e32 v0, v16, v31
	v_fmac_f32_e32 v0, v17, v32
	v_fmac_f32_e32 v0, v10, v33
	v_fmac_f32_e32 v0, v11, v34
	v_fmac_f32_e32 v0, v12, v35
	v_fmac_f32_e32 v0, v13, v36
	v_fmac_f32_e32 v0, v6, v37
	v_fmac_f32_e32 v0, v7, v38
	v_fmac_f32_e32 v0, v8, v22
	v_fmac_f32_e32 v0, v9, v24
	v_fmac_f32_e32 v0, v18, v25
	v_fmac_f32_e32 v0, v19, v26
	v_fmac_f32_e32 v0, v20, v27
	v_fmac_f32_e32 v0, v21, v28
	s_cbranch_scc0 .LBB0_1242
	v_readlane_b32 s0, v254, 29
	v_readlane_b32 s1, v254, 30
	s_mov_b32 s79, 0xf800000
	s_mov_b32 s72, 0xf149f2ca
	v_lshl_add_u64 v[2:3], v[2:3], 2, s[0:1]
	s_mov_b64 s[76:77], 0x2000
	global_store_dword v[2:3], v0, off
